# same as v27 without the K-loop hand-off barrier/priority move (component check)
# speedup vs baseline: 1.0104x; 1.0057x over previous
; template <bool GE1 = false>
; __device__ __forceinline__ unsigned gate4_u8(f32x4 a, f32x4 sb) {
;     const f32x4 t = a * (-1.44269504089f) + sb;
;     f32x4 e; e[0] = __builtin_amdgcn_exp2f(t[0]); e[1] = __builtin_amdgcn_exp2f(t[1]); e[2] = __builtin_amdgcn_exp2f(t[2]); e[3] = __builtin_amdgcn_exp2f(t[3]);
;     f32x4 d = e * (1.0f / 255.0f) + (1.0f / 255.0f);
;     if (GE1) { d[0] = fminf(d[0], 1.0f); d[1] = fminf(d[1], 1.0f); d[2] = fminf(d[2], 1.0f); d[3] = fminf(d[3], 1.0f); }
;     f32x4 r; r[0] = __builtin_amdgcn_rcpf(d[0]); r[1] = __builtin_amdgcn_rcpf(d[1]); r[2] = __builtin_amdgcn_rcpf(d[2]); r[3] = __builtin_amdgcn_rcpf(d[3]);
;     if (U8_RND) r = r + 0.5f;
;     unsigned w = 0u;
;     w = __builtin_amdgcn_cvt_pk_u8_f32(r[0], 0, w); w = __builtin_amdgcn_cvt_pk_u8_f32(r[1], 1, w); w = __builtin_amdgcn_cvt_pk_u8_f32(r[2], 2, w); w = __builtin_amdgcn_cvt_pk_u8_f32(r[3], 3, w);
;     __device__ __forceinline__ void epi(const Acc& acc, const GUnit& u, int wr, int wc, int fr_, int fq_) const {
;     ...
;                         if (kind == K_MG) {
;                         w0.x = gate4_u8<true>(acc[ai][bj][0][0], sb[bj][0]); w0.y = gate4_u8<true>(acc[ai][bj][0][1], sb[bj][1]); w0.z = gate4_u8<true>(acc[ai][bj][1][0], sb[bj][0]); w0.w = gate4_u8<true>(acc[ai][bj][1][1], sb[bj][1]);
;                         w1.x = gate4_u8<true>(acc[ai][bj][2][0], sb[bj][0]); w1.y = gate4_u8<true>(acc[ai][bj][2][1], sb[bj][1]); w1.z = gate4_u8<true>(acc[ai][bj][3][0], sb[bj][0]); w1.w = gate4_u8<true>(acc[ai][bj][3][1], sb[bj][1]);
.LBB0_219:
	s_andn2_b64 vcc, exec, s[0:1]
	s_cbranch_vccnz .LBB0_221
	v_max_f32_e32 v144, v230, v230
	v_min_f32_e32 v144, 1.0, v144
	v_max_f32_e32 v145, v231, v231
	v_min_f32_e32 v145, 1.0, v145
	v_max_f32_e32 v146, v228, v228
	v_rcp_f32_e32 v144, v144
	v_min_f32_e32 v146, 1.0, v146
	v_max_f32_e32 v147, v229, v229
	v_rcp_f32_e32 v145, v145
	v_min_f32_e32 v147, 1.0, v147
	v_rcp_f32_e32 v146, v146
	v_rcp_f32_e32 v147, v147
	v_cvt_pk_u8_f32 v144, v144, 0, 0
	v_cvt_pk_u8_f32 v144, v145, 1, v144
	v_pk_fma_f32 v[148:149], v[120:121], s[22:23], v[214:215] op_sel_hi:[1,0,1] neg_lo:[1,0,0] neg_hi:[1,0,0]
	v_cvt_pk_u8_f32 v144, v146, 2, v144
	v_exp_f32_e32 v148, v148
	v_exp_f32_e32 v149, v149
	v_cvt_pk_u8_f32 v144, v147, 3, v144
	v_pk_fma_f32 v[146:147], v[226:227], s[22:23], v[212:213] op_sel_hi:[1,0,1]
	v_pk_fma_f32 v[150:151], v[104:105], s[22:23], v[214:215] op_sel_hi:[1,0,1] neg_lo:[1,0,0] neg_hi:[1,0,0]
	v_exp_f32_e32 v146, v146
	v_exp_f32_e32 v147, v147
	v_pk_fma_f32 v[148:149], v[148:149], s[20:21], s[20:21] op_sel_hi:[1,0,0] clamp
	v_exp_f32_e32 v150, v150
	v_min_f32_e32 v145, 1.0, v148
	v_pk_fma_f32 v[146:147], v[146:147], s[20:21], s[20:21] op_sel_hi:[1,0,0] clamp
	v_rcp_f32_e32 v145, v145
	v_rcp_f32_e32 v148, v149
	v_rcp_f32_e32 v146, v146
	v_rcp_f32_e32 v147, v147
	v_cvt_pk_u8_f32 v145, v145, 0, 0
	v_cvt_pk_u8_f32 v145, v148, 1, v145
	v_pk_fma_f32 v[148:149], v[108:109], s[22:23], v[222:223] op_sel_hi:[1,0,1] neg_lo:[1,0,0] neg_hi:[1,0,0]
	v_cvt_pk_u8_f32 v145, v146, 2, v145
	v_exp_f32_e32 v148, v148
	v_exp_f32_e32 v149, v149
	v_cvt_pk_u8_f32 v145, v147, 3, v145
	v_pk_fma_f32 v[146:147], v[224:225], s[22:23], v[218:219] op_sel_hi:[1,0,1]
	v_exp_f32_e32 v151, v151
	v_exp_f32_e32 v146, v146
	v_exp_f32_e32 v147, v147
	v_pk_fma_f32 v[148:149], v[148:149], s[20:21], s[20:21] op_sel_hi:[1,0,0] clamp
	v_pk_fma_f32 v[150:151], v[150:151], s[20:21], s[20:21] op_sel_hi:[1,0,0] clamp
	v_pk_fma_f32 v[146:147], v[146:147], s[20:21], s[20:21] op_sel_hi:[1,0,0] clamp
	v_rcp_f32_e32 v148, v148
	v_rcp_f32_e32 v149, v149
	v_rcp_f32_e32 v146, v146
	v_cvt_pk_u8_f32 v148, v148, 0, 0
	v_cvt_pk_u8_f32 v148, v149, 1, v148
	v_rcp_f32_e32 v147, v147
	v_cvt_pk_u8_f32 v146, v146, 2, v148
	v_pk_fma_f32 v[148:149], v[220:221], s[22:23], v[212:213] op_sel_hi:[1,0,1]
	v_pk_fma_f32 v[194:195], v[88:89], s[22:23], v[214:215] op_sel_hi:[1,0,1] neg_lo:[1,0,0] neg_hi:[1,0,0]
	v_exp_f32_e32 v148, v148
	v_exp_f32_e32 v149, v149
	v_cvt_pk_u8_f32 v146, v147, 3, v146
	v_min_f32_e32 v147, 1.0, v150
	v_pk_fma_f32 v[148:149], v[148:149], s[20:21], s[20:21] op_sel_hi:[1,0,0] clamp
	v_rcp_f32_e32 v147, v147
	v_rcp_f32_e32 v150, v151
	v_rcp_f32_e32 v148, v148
	v_rcp_f32_e32 v149, v149
	v_cvt_pk_u8_f32 v147, v147, 0, 0
	v_cvt_pk_u8_f32 v147, v150, 1, v147
	v_pk_fma_f32 v[150:151], v[92:93], s[22:23], v[222:223] op_sel_hi:[1,0,1] neg_lo:[1,0,0] neg_hi:[1,0,0]
	v_cvt_pk_u8_f32 v147, v148, 2, v147
	v_exp_f32_e32 v150, v150
	v_exp_f32_e32 v151, v151
	v_cvt_pk_u8_f32 v147, v149, 3, v147
	v_pk_fma_f32 v[148:149], v[216:217], s[22:23], v[218:219] op_sel_hi:[1,0,1]
	v_exp_f32_e32 v194, v194
	v_exp_f32_e32 v148, v148
	v_exp_f32_e32 v149, v149
	v_pk_fma_f32 v[150:151], v[150:151], s[20:21], s[20:21] op_sel_hi:[1,0,0] clamp
	v_exp_f32_e32 v195, v195
	v_pk_fma_f32 v[148:149], v[148:149], s[20:21], s[20:21] op_sel_hi:[1,0,0] clamp
	v_rcp_f32_e32 v150, v150
	v_rcp_f32_e32 v151, v151
	v_rcp_f32_e32 v148, v148
	v_cvt_pk_u8_f32 v150, v150, 0, 0
	v_cvt_pk_u8_f32 v150, v151, 1, v150
	v_rcp_f32_e32 v149, v149
	v_cvt_pk_u8_f32 v148, v148, 2, v150
	v_pk_fma_f32 v[150:151], v[210:211], s[22:23], v[212:213] op_sel_hi:[1,0,1]
	v_pk_fma_f32 v[194:195], v[194:195], s[20:21], s[20:21] op_sel_hi:[1,0,0] clamp
	v_exp_f32_e32 v150, v150
	v_exp_f32_e32 v151, v151
	v_cvt_pk_u8_f32 v148, v149, 3, v148
	v_pk_fma_f32 v[150:151], v[150:151], s[20:21], s[20:21] op_sel_hi:[1,0,0] clamp
	v_rcp_f32_e32 v149, v194
	v_rcp_f32_e32 v165, v195
	v_pk_fma_f32 v[194:195], v[76:77], s[22:23], v[222:223] op_sel_hi:[1,0,1] neg_lo:[1,0,0] neg_hi:[1,0,0]
	v_rcp_f32_e32 v150, v150
	v_exp_f32_e32 v194, v194
	v_exp_f32_e32 v195, v195
	v_rcp_f32_e32 v151, v151
	v_cvt_pk_u8_f32 v149, v149, 0, 0
	v_cvt_pk_u8_f32 v149, v165, 1, v149
	v_cvt_pk_u8_f32 v149, v150, 2, v149
	v_pk_fma_f32 v[194:195], v[194:195], s[20:21], s[20:21] op_sel_hi:[1,0,0] clamp
	v_cvt_pk_u8_f32 v149, v151, 3, v149
	v_pk_fma_f32 v[150:151], v[208:209], s[22:23], v[218:219] op_sel_hi:[1,0,1]
	v_min_f32_e32 v165, 1.0, v194
	v_exp_f32_e32 v150, v150
	v_exp_f32_e32 v151, v151
	v_rcp_f32_e32 v165, v165
	v_rcp_f32_e32 v194, v195
	v_pk_fma_f32 v[150:151], v[150:151], s[20:21], s[20:21] op_sel_hi:[1,0,0] clamp
	v_cvt_pk_u8_f32 v165, v165, 0, 0
	v_cvt_pk_u8_f32 v165, v194, 1, v165
	v_pk_fma_f32 v[194:195], v[206:207], s[22:23], v[212:213] op_sel_hi:[1,0,1]
	v_pk_fma_f32 v[206:207], v[72:73], s[22:23], v[214:215] op_sel_hi:[1,0,1] neg_lo:[1,0,0] neg_hi:[1,0,0]
	v_rcp_f32_e32 v150, v150
	v_exp_f32_e32 v206, v206
	v_exp_f32_e32 v207, v207
	v_exp_f32_e32 v194, v194
	v_exp_f32_e32 v195, v195
	v_rcp_f32_e32 v151, v151
	v_cvt_pk_u8_f32 v150, v150, 2, v165
	v_pk_fma_f32 v[206:207], v[206:207], s[20:21], s[20:21] op_sel_hi:[1,0,0] clamp
	v_pk_fma_f32 v[194:195], v[194:195], s[20:21], s[20:21] op_sel_hi:[1,0,0] clamp
	v_cvt_pk_u8_f32 v150, v151, 3, v150
	v_min_f32_e32 v151, 1.0, v206
	v_rcp_f32_e32 v235, v151
	v_rcp_f32_e32 v236, v207
	v_rcp_f32_e32 v165, v194
	v_min_f32_e32 v233, 1.0, v195

; template <bool GE1 = false>
; __device__ __forceinline__ unsigned gate4_u8(f32x4 a, f32x4 sb) {
;     const f32x4 t = a * (-1.44269504089f) + sb;
;     f32x4 e; e[0] = __builtin_amdgcn_exp2f(t[0]); e[1] = __builtin_amdgcn_exp2f(t[1]); e[2] = __builtin_amdgcn_exp2f(t[2]); e[3] = __builtin_amdgcn_exp2f(t[3]);
;     f32x4 d = e * (1.0f / 255.0f) + (1.0f / 255.0f);
;     if (GE1) { d[0] = fminf(d[0], 1.0f); d[1] = fminf(d[1], 1.0f); d[2] = fminf(d[2], 1.0f); d[3] = fminf(d[3], 1.0f); }
;     f32x4 r; r[0] = __builtin_amdgcn_rcpf(d[0]); r[1] = __builtin_amdgcn_rcpf(d[1]); r[2] = __builtin_amdgcn_rcpf(d[2]); r[3] = __builtin_amdgcn_rcpf(d[3]);
;     if (U8_RND) r = r + 0.5f;
;     unsigned w = 0u;
;     w = __builtin_amdgcn_cvt_pk_u8_f32(r[0], 0, w); w = __builtin_amdgcn_cvt_pk_u8_f32(r[1], 1, w); w = __builtin_amdgcn_cvt_pk_u8_f32(r[2], 2, w); w = __builtin_amdgcn_cvt_pk_u8_f32(r[3], 3, w);
;     __device__ __forceinline__ void epi(const Acc& acc, const GUnit& u, int wr, int wc, int fr_, int fq_) const {
;     ...
;                         if (kind == K_MG) {
;                         w0.x = gate4_u8<true>(acc[ai][bj][0][0], sb[bj][0]); w0.y = gate4_u8<true>(acc[ai][bj][0][1], sb[bj][1]); w0.z = gate4_u8<true>(acc[ai][bj][1][0], sb[bj][0]); w0.w = gate4_u8<true>(acc[ai][bj][1][1], sb[bj][1]);
;                         w1.x = gate4_u8<true>(acc[ai][bj][2][0], sb[bj][0]); w1.y = gate4_u8<true>(acc[ai][bj][2][1], sb[bj][1]); w1.z = gate4_u8<true>(acc[ai][bj][3][0], sb[bj][0]); w1.w = gate4_u8<true>(acc[ai][bj][3][1], sb[bj][1]);
.LBB0_223:
	s_andn2_b64 vcc, exec, s[0:1]
	s_cbranch_vccnz .LBB0_225
	v_max_f32_e32 v144, v240, v240
	v_min_f32_e32 v144, 1.0, v144
	v_max_f32_e32 v145, v241, v241
	v_min_f32_e32 v145, 1.0, v145
	v_max_f32_e32 v146, v238, v238
	v_rcp_f32_e32 v144, v144
	v_min_f32_e32 v146, 1.0, v146
	v_max_f32_e32 v147, v239, v239
	v_rcp_f32_e32 v145, v145
	v_min_f32_e32 v147, 1.0, v147
	v_rcp_f32_e32 v146, v146
	v_rcp_f32_e32 v147, v147
	v_cvt_pk_u8_f32 v144, v144, 0, 0
	v_cvt_pk_u8_f32 v144, v145, 1, v144
	v_pk_fma_f32 v[148:149], v[112:113], s[22:23], v[210:211] op_sel_hi:[1,0,1] neg_lo:[1,0,0] neg_hi:[1,0,0]
	v_cvt_pk_u8_f32 v144, v146, 2, v144
	v_exp_f32_e32 v148, v148
	v_exp_f32_e32 v149, v149
	v_cvt_pk_u8_f32 v144, v147, 3, v144
	v_pk_fma_f32 v[146:147], v[236:237], s[22:23], v[208:209] op_sel_hi:[1,0,1]
	v_pk_fma_f32 v[150:151], v[96:97], s[22:23], v[210:211] op_sel_hi:[1,0,1] neg_lo:[1,0,0] neg_hi:[1,0,0]
	v_exp_f32_e32 v146, v146
	v_exp_f32_e32 v147, v147
	v_pk_fma_f32 v[148:149], v[148:149], s[20:21], s[20:21] op_sel_hi:[1,0,0] clamp
	v_exp_f32_e32 v150, v150
	v_min_f32_e32 v145, 1.0, v148
	v_pk_fma_f32 v[146:147], v[146:147], s[20:21], s[20:21] op_sel_hi:[1,0,0] clamp
	v_rcp_f32_e32 v145, v145
	v_rcp_f32_e32 v148, v149
	v_rcp_f32_e32 v146, v146
	v_rcp_f32_e32 v147, v147
	v_cvt_pk_u8_f32 v145, v145, 0, 0
	v_cvt_pk_u8_f32 v145, v148, 1, v145
	v_pk_fma_f32 v[148:149], v[100:101], s[22:23], v[220:221] op_sel_hi:[1,0,1] neg_lo:[1,0,0] neg_hi:[1,0,0]
	v_cvt_pk_u8_f32 v145, v146, 2, v145
	v_exp_f32_e32 v148, v148
	v_exp_f32_e32 v149, v149
	v_cvt_pk_u8_f32 v145, v147, 3, v145
	v_pk_fma_f32 v[146:147], v[234:235], s[22:23], v[216:217] op_sel_hi:[1,0,1]
	v_exp_f32_e32 v151, v151
	v_exp_f32_e32 v146, v146
	v_exp_f32_e32 v147, v147
	v_pk_fma_f32 v[148:149], v[148:149], s[20:21], s[20:21] op_sel_hi:[1,0,0] clamp
	v_pk_fma_f32 v[150:151], v[150:151], s[20:21], s[20:21] op_sel_hi:[1,0,0] clamp
	v_pk_fma_f32 v[146:147], v[146:147], s[20:21], s[20:21] op_sel_hi:[1,0,0] clamp
	v_rcp_f32_e32 v148, v148
	v_rcp_f32_e32 v149, v149
	v_rcp_f32_e32 v146, v146
	v_cvt_pk_u8_f32 v148, v148, 0, 0
	v_cvt_pk_u8_f32 v148, v149, 1, v148
	v_rcp_f32_e32 v147, v147
	v_cvt_pk_u8_f32 v146, v146, 2, v148
	v_pk_fma_f32 v[148:149], v[232:233], s[22:23], v[208:209] op_sel_hi:[1,0,1]
	v_pk_fma_f32 v[194:195], v[80:81], s[22:23], v[210:211] op_sel_hi:[1,0,1] neg_lo:[1,0,0] neg_hi:[1,0,0]
	v_exp_f32_e32 v148, v148
	v_exp_f32_e32 v149, v149
	v_cvt_pk_u8_f32 v146, v147, 3, v146
	v_min_f32_e32 v147, 1.0, v150
	v_pk_fma_f32 v[148:149], v[148:149], s[20:21], s[20:21] op_sel_hi:[1,0,0] clamp
	v_rcp_f32_e32 v147, v147
	v_rcp_f32_e32 v150, v151
	v_rcp_f32_e32 v148, v148
	v_rcp_f32_e32 v149, v149
	v_cvt_pk_u8_f32 v147, v147, 0, 0
	v_cvt_pk_u8_f32 v147, v150, 1, v147
	v_pk_fma_f32 v[150:151], v[84:85], s[22:23], v[220:221] op_sel_hi:[1,0,1] neg_lo:[1,0,0] neg_hi:[1,0,0]
	v_cvt_pk_u8_f32 v147, v148, 2, v147
	v_exp_f32_e32 v150, v150
	v_exp_f32_e32 v151, v151
	v_cvt_pk_u8_f32 v147, v149, 3, v147
	v_pk_fma_f32 v[148:149], v[230:231], s[22:23], v[216:217] op_sel_hi:[1,0,1]
	v_exp_f32_e32 v194, v194
	v_exp_f32_e32 v148, v148
	v_exp_f32_e32 v149, v149
	v_pk_fma_f32 v[150:151], v[150:151], s[20:21], s[20:21] op_sel_hi:[1,0,0] clamp
	v_exp_f32_e32 v195, v195
	v_pk_fma_f32 v[148:149], v[148:149], s[20:21], s[20:21] op_sel_hi:[1,0,0] clamp
	v_rcp_f32_e32 v150, v150
	v_rcp_f32_e32 v151, v151
	v_rcp_f32_e32 v148, v148
	v_cvt_pk_u8_f32 v150, v150, 0, 0
	v_cvt_pk_u8_f32 v150, v151, 1, v150
	v_rcp_f32_e32 v149, v149
	v_cvt_pk_u8_f32 v148, v148, 2, v150
	v_pk_fma_f32 v[150:151], v[228:229], s[22:23], v[208:209] op_sel_hi:[1,0,1]
	v_pk_fma_f32 v[194:195], v[194:195], s[20:21], s[20:21] op_sel_hi:[1,0,0] clamp
	v_exp_f32_e32 v150, v150
	v_exp_f32_e32 v151, v151
	v_cvt_pk_u8_f32 v148, v149, 3, v148
	v_pk_fma_f32 v[150:151], v[150:151], s[20:21], s[20:21] op_sel_hi:[1,0,0] clamp
	v_rcp_f32_e32 v149, v194
	v_rcp_f32_e32 v165, v195
	v_pk_fma_f32 v[194:195], v[68:69], s[22:23], v[220:221] op_sel_hi:[1,0,1] neg_lo:[1,0,0] neg_hi:[1,0,0]
	v_rcp_f32_e32 v150, v150
	v_exp_f32_e32 v194, v194
	v_exp_f32_e32 v195, v195
	v_rcp_f32_e32 v151, v151
	v_cvt_pk_u8_f32 v149, v149, 0, 0
	v_cvt_pk_u8_f32 v149, v165, 1, v149
	v_cvt_pk_u8_f32 v149, v150, 2, v149
	v_pk_fma_f32 v[194:195], v[194:195], s[20:21], s[20:21] op_sel_hi:[1,0,0] clamp
	v_cvt_pk_u8_f32 v149, v151, 3, v149
	v_pk_fma_f32 v[150:151], v[226:227], s[22:23], v[216:217] op_sel_hi:[1,0,1]
	v_min_f32_e32 v165, 1.0, v194
	v_exp_f32_e32 v150, v150
	v_exp_f32_e32 v151, v151
	v_rcp_f32_e32 v165, v165
	v_rcp_f32_e32 v194, v195
	v_pk_fma_f32 v[150:151], v[150:151], s[20:21], s[20:21] op_sel_hi:[1,0,0] clamp
	v_cvt_pk_u8_f32 v165, v165, 0, 0
	v_cvt_pk_u8_f32 v165, v194, 1, v165
	v_pk_fma_f32 v[194:195], v[224:225], s[22:23], v[208:209] op_sel_hi:[1,0,1]
	v_pk_fma_f32 v[224:225], v[64:65], s[22:23], v[210:211] op_sel_hi:[1,0,1] neg_lo:[1,0,0] neg_hi:[1,0,0]
	v_rcp_f32_e32 v150, v150
	v_exp_f32_e32 v224, v224
	v_exp_f32_e32 v225, v225
	v_exp_f32_e32 v194, v194
	v_exp_f32_e32 v195, v195
	v_rcp_f32_e32 v151, v151
	v_cvt_pk_u8_f32 v150, v150, 2, v165
	v_pk_fma_f32 v[224:225], v[224:225], s[20:21], s[20:21] op_sel_hi:[1,0,0] clamp
	v_pk_fma_f32 v[194:195], v[194:195], s[20:21], s[20:21] op_sel_hi:[1,0,0] clamp
	v_cvt_pk_u8_f32 v150, v151, 3, v150
	v_min_f32_e32 v151, 1.0, v224
	v_rcp_f32_e32 v246, v151
	v_rcp_f32_e32 v247, v225
	v_rcp_f32_e32 v165, v194
	v_min_f32_e32 v243, 1.0, v195

; template <bool GE1 = false>
; __device__ __forceinline__ unsigned gate4_u8(f32x4 a, f32x4 sb) {
;     const f32x4 t = a * (-1.44269504089f) + sb;
;     f32x4 e; e[0] = __builtin_amdgcn_exp2f(t[0]); e[1] = __builtin_amdgcn_exp2f(t[1]); e[2] = __builtin_amdgcn_exp2f(t[2]); e[3] = __builtin_amdgcn_exp2f(t[3]);
;     f32x4 d = e * (1.0f / 255.0f) + (1.0f / 255.0f);
;     if (GE1) { d[0] = fminf(d[0], 1.0f); d[1] = fminf(d[1], 1.0f); d[2] = fminf(d[2], 1.0f); d[3] = fminf(d[3], 1.0f); }
;     f32x4 r; r[0] = __builtin_amdgcn_rcpf(d[0]); r[1] = __builtin_amdgcn_rcpf(d[1]); r[2] = __builtin_amdgcn_rcpf(d[2]); r[3] = __builtin_amdgcn_rcpf(d[3]);
;     if (U8_RND) r = r + 0.5f;
;     unsigned w = 0u;
;     w = __builtin_amdgcn_cvt_pk_u8_f32(r[0], 0, w); w = __builtin_amdgcn_cvt_pk_u8_f32(r[1], 1, w); w = __builtin_amdgcn_cvt_pk_u8_f32(r[2], 2, w); w = __builtin_amdgcn_cvt_pk_u8_f32(r[3], 3, w);
;     __device__ __forceinline__ void epi(const Acc& acc, const GUnit& u, int wr, int wc, int fr_, int fq_) const {
;     ...
;                         if (kind == K_MG) {
;                         w0.x = gate4_u8<true>(acc[ai][bj][0][0], sb[bj][0]); w0.y = gate4_u8<true>(acc[ai][bj][0][1], sb[bj][1]); w0.z = gate4_u8<true>(acc[ai][bj][1][0], sb[bj][0]); w0.w = gate4_u8<true>(acc[ai][bj][1][1], sb[bj][1]);
;                         w1.x = gate4_u8<true>(acc[ai][bj][2][0], sb[bj][0]); w1.y = gate4_u8<true>(acc[ai][bj][2][1], sb[bj][1]); w1.z = gate4_u8<true>(acc[ai][bj][3][0], sb[bj][0]); w1.w = gate4_u8<true>(acc[ai][bj][3][1], sb[bj][1]);
.LBB0_227:
	s_andn2_b64 vcc, exec, s[0:1]
	s_cbranch_vccnz .LBB0_229
	v_max_f32_e32 v144, v240, v240
	v_min_f32_e32 v144, 1.0, v144
	v_max_f32_e32 v145, v241, v241
	v_min_f32_e32 v145, 1.0, v145
	v_max_f32_e32 v146, v238, v238
	v_rcp_f32_e32 v144, v144
	v_min_f32_e32 v146, 1.0, v146
	v_max_f32_e32 v147, v239, v239
	v_rcp_f32_e32 v145, v145
	v_min_f32_e32 v147, 1.0, v147
	v_rcp_f32_e32 v146, v146
	v_rcp_f32_e32 v147, v147
	v_cvt_pk_u8_f32 v144, v144, 0, 0
	v_cvt_pk_u8_f32 v144, v145, 1, v144
	v_pk_fma_f32 v[148:149], v[56:57], s[22:23], v[214:215] op_sel_hi:[1,0,1] neg_lo:[1,0,0] neg_hi:[1,0,0]
	v_cvt_pk_u8_f32 v144, v146, 2, v144
	v_exp_f32_e32 v148, v148
	v_exp_f32_e32 v149, v149
	v_cvt_pk_u8_f32 v144, v147, 3, v144
	v_pk_fma_f32 v[146:147], v[236:237], s[22:23], v[212:213] op_sel_hi:[1,0,1]
	v_pk_fma_f32 v[150:151], v[40:41], s[22:23], v[214:215] op_sel_hi:[1,0,1] neg_lo:[1,0,0] neg_hi:[1,0,0]
	v_exp_f32_e32 v146, v146
	v_exp_f32_e32 v147, v147
	v_pk_fma_f32 v[148:149], v[148:149], s[20:21], s[20:21] op_sel_hi:[1,0,0] clamp
	v_exp_f32_e32 v150, v150
	v_min_f32_e32 v145, 1.0, v148
	v_pk_fma_f32 v[146:147], v[146:147], s[20:21], s[20:21] op_sel_hi:[1,0,0] clamp
	v_rcp_f32_e32 v145, v145
	v_rcp_f32_e32 v148, v149
	v_rcp_f32_e32 v146, v146
	v_rcp_f32_e32 v147, v147
	v_cvt_pk_u8_f32 v145, v145, 0, 0
	v_cvt_pk_u8_f32 v145, v148, 1, v145
	v_pk_fma_f32 v[148:149], v[44:45], s[22:23], v[222:223] op_sel_hi:[1,0,1] neg_lo:[1,0,0] neg_hi:[1,0,0]
	v_cvt_pk_u8_f32 v145, v146, 2, v145
	v_exp_f32_e32 v148, v148
	v_exp_f32_e32 v149, v149
	v_cvt_pk_u8_f32 v145, v147, 3, v145
	v_pk_fma_f32 v[146:147], v[234:235], s[22:23], v[218:219] op_sel_hi:[1,0,1]
	v_exp_f32_e32 v151, v151
	v_exp_f32_e32 v146, v146
	v_exp_f32_e32 v147, v147
	v_pk_fma_f32 v[148:149], v[148:149], s[20:21], s[20:21] op_sel_hi:[1,0,0] clamp
	v_pk_fma_f32 v[150:151], v[150:151], s[20:21], s[20:21] op_sel_hi:[1,0,0] clamp
	v_pk_fma_f32 v[146:147], v[146:147], s[20:21], s[20:21] op_sel_hi:[1,0,0] clamp
	v_rcp_f32_e32 v148, v148
	v_rcp_f32_e32 v149, v149
	v_rcp_f32_e32 v146, v146
	v_cvt_pk_u8_f32 v148, v148, 0, 0
	v_cvt_pk_u8_f32 v148, v149, 1, v148
	v_rcp_f32_e32 v147, v147
	v_cvt_pk_u8_f32 v146, v146, 2, v148
	v_pk_fma_f32 v[148:149], v[232:233], s[22:23], v[212:213] op_sel_hi:[1,0,1]
	v_pk_fma_f32 v[194:195], v[24:25], s[22:23], v[214:215] op_sel_hi:[1,0,1] neg_lo:[1,0,0] neg_hi:[1,0,0]
	v_exp_f32_e32 v148, v148
	v_exp_f32_e32 v149, v149
	v_cvt_pk_u8_f32 v146, v147, 3, v146
	v_min_f32_e32 v147, 1.0, v150
	v_pk_fma_f32 v[148:149], v[148:149], s[20:21], s[20:21] op_sel_hi:[1,0,0] clamp
	v_rcp_f32_e32 v147, v147
	v_rcp_f32_e32 v150, v151
	v_rcp_f32_e32 v148, v148
	v_rcp_f32_e32 v149, v149
	v_cvt_pk_u8_f32 v147, v147, 0, 0
	v_cvt_pk_u8_f32 v147, v150, 1, v147
	v_pk_fma_f32 v[150:151], v[28:29], s[22:23], v[222:223] op_sel_hi:[1,0,1] neg_lo:[1,0,0] neg_hi:[1,0,0]
	v_cvt_pk_u8_f32 v147, v148, 2, v147
	v_exp_f32_e32 v150, v150
	v_exp_f32_e32 v151, v151
	v_cvt_pk_u8_f32 v147, v149, 3, v147
	v_pk_fma_f32 v[148:149], v[230:231], s[22:23], v[218:219] op_sel_hi:[1,0,1]
	v_exp_f32_e32 v194, v194
	v_exp_f32_e32 v148, v148
	v_exp_f32_e32 v149, v149
	v_pk_fma_f32 v[150:151], v[150:151], s[20:21], s[20:21] op_sel_hi:[1,0,0] clamp
	v_exp_f32_e32 v195, v195
	v_pk_fma_f32 v[148:149], v[148:149], s[20:21], s[20:21] op_sel_hi:[1,0,0] clamp
	v_rcp_f32_e32 v150, v150
	v_rcp_f32_e32 v151, v151
	v_rcp_f32_e32 v148, v148
	v_cvt_pk_u8_f32 v150, v150, 0, 0
	v_cvt_pk_u8_f32 v150, v151, 1, v150
	v_rcp_f32_e32 v149, v149
	v_cvt_pk_u8_f32 v148, v148, 2, v150
	v_pk_fma_f32 v[150:151], v[228:229], s[22:23], v[212:213] op_sel_hi:[1,0,1]
	v_pk_fma_f32 v[194:195], v[194:195], s[20:21], s[20:21] op_sel_hi:[1,0,0] clamp
	v_exp_f32_e32 v150, v150
	v_exp_f32_e32 v151, v151
	v_cvt_pk_u8_f32 v148, v149, 3, v148
	v_pk_fma_f32 v[150:151], v[150:151], s[20:21], s[20:21] op_sel_hi:[1,0,0] clamp
	v_rcp_f32_e32 v149, v194
	v_rcp_f32_e32 v165, v195
	v_pk_fma_f32 v[194:195], v[12:13], s[22:23], v[222:223] op_sel_hi:[1,0,1] neg_lo:[1,0,0] neg_hi:[1,0,0]
	v_rcp_f32_e32 v150, v150
	v_exp_f32_e32 v194, v194
	v_exp_f32_e32 v195, v195
	v_rcp_f32_e32 v151, v151
	v_cvt_pk_u8_f32 v149, v149, 0, 0
	v_cvt_pk_u8_f32 v149, v165, 1, v149
	v_cvt_pk_u8_f32 v149, v150, 2, v149
	v_pk_fma_f32 v[194:195], v[194:195], s[20:21], s[20:21] op_sel_hi:[1,0,0] clamp
	v_cvt_pk_u8_f32 v149, v151, 3, v149
	v_pk_fma_f32 v[150:151], v[226:227], s[22:23], v[218:219] op_sel_hi:[1,0,1]
	v_min_f32_e32 v165, 1.0, v194
	v_exp_f32_e32 v150, v150
	v_exp_f32_e32 v151, v151
	v_rcp_f32_e32 v165, v165
	v_rcp_f32_e32 v194, v195
	v_pk_fma_f32 v[150:151], v[150:151], s[20:21], s[20:21] op_sel_hi:[1,0,0] clamp
	v_cvt_pk_u8_f32 v165, v165, 0, 0
	v_cvt_pk_u8_f32 v165, v194, 1, v165
	v_pk_fma_f32 v[194:195], v[224:225], s[22:23], v[212:213] op_sel_hi:[1,0,1]
	v_pk_fma_f32 v[212:213], v[8:9], s[22:23], v[214:215] op_sel_hi:[1,0,1] neg_lo:[1,0,0] neg_hi:[1,0,0]
	v_rcp_f32_e32 v150, v150
	v_exp_f32_e32 v212, v212
	v_exp_f32_e32 v213, v213
	v_exp_f32_e32 v194, v194
	v_exp_f32_e32 v195, v195
	v_rcp_f32_e32 v151, v151
	v_cvt_pk_u8_f32 v150, v150, 2, v165
	v_pk_fma_f32 v[212:213], v[212:213], s[20:21], s[20:21] op_sel_hi:[1,0,0] clamp
	v_pk_fma_f32 v[194:195], v[194:195], s[20:21], s[20:21] op_sel_hi:[1,0,0] clamp
	v_cvt_pk_u8_f32 v150, v151, 3, v150
	v_min_f32_e32 v151, 1.0, v212
	v_rcp_f32_e32 v246, v151
	v_rcp_f32_e32 v247, v213
	v_rcp_f32_e32 v165, v194
	v_min_f32_e32 v243, 1.0, v195

; template <bool GE1 = false>
; __device__ __forceinline__ unsigned gate4_u8(f32x4 a, f32x4 sb) {
;     const f32x4 t = a * (-1.44269504089f) + sb;
;     f32x4 e; e[0] = __builtin_amdgcn_exp2f(t[0]); e[1] = __builtin_amdgcn_exp2f(t[1]); e[2] = __builtin_amdgcn_exp2f(t[2]); e[3] = __builtin_amdgcn_exp2f(t[3]);
;     f32x4 d = e * (1.0f / 255.0f) + (1.0f / 255.0f);
;     if (GE1) { d[0] = fminf(d[0], 1.0f); d[1] = fminf(d[1], 1.0f); d[2] = fminf(d[2], 1.0f); d[3] = fminf(d[3], 1.0f); }
;     f32x4 r; r[0] = __builtin_amdgcn_rcpf(d[0]); r[1] = __builtin_amdgcn_rcpf(d[1]); r[2] = __builtin_amdgcn_rcpf(d[2]); r[3] = __builtin_amdgcn_rcpf(d[3]);
;     if (U8_RND) r = r + 0.5f;
;     unsigned w = 0u;
;     w = __builtin_amdgcn_cvt_pk_u8_f32(r[0], 0, w); w = __builtin_amdgcn_cvt_pk_u8_f32(r[1], 1, w); w = __builtin_amdgcn_cvt_pk_u8_f32(r[2], 2, w); w = __builtin_amdgcn_cvt_pk_u8_f32(r[3], 3, w);
;     __device__ __forceinline__ void epi(const Acc& acc, const GUnit& u, int wr, int wc, int fr_, int fq_) const {
;     ...
;                         if (kind == K_MG) {
;                         w0.x = gate4_u8<true>(acc[ai][bj][0][0], sb[bj][0]); w0.y = gate4_u8<true>(acc[ai][bj][0][1], sb[bj][1]); w0.z = gate4_u8<true>(acc[ai][bj][1][0], sb[bj][0]); w0.w = gate4_u8<true>(acc[ai][bj][1][1], sb[bj][1]);
;                         w1.x = gate4_u8<true>(acc[ai][bj][2][0], sb[bj][0]); w1.y = gate4_u8<true>(acc[ai][bj][2][1], sb[bj][1]); w1.z = gate4_u8<true>(acc[ai][bj][3][0], sb[bj][0]); w1.w = gate4_u8<true>(acc[ai][bj][3][1], sb[bj][1]);
.LBB0_231:
	s_andn2_b64 vcc, exec, s[0:1]
	s_cbranch_vccnz .LBB0_233
	v_max_f32_e32 v144, v232, v232
	v_min_f32_e32 v144, 1.0, v144
	v_max_f32_e32 v145, v233, v233
	v_min_f32_e32 v145, 1.0, v145
	v_max_f32_e32 v146, v230, v230
	v_rcp_f32_e32 v144, v144
	v_min_f32_e32 v146, 1.0, v146
	v_max_f32_e32 v147, v231, v231
	v_rcp_f32_e32 v145, v145
	v_min_f32_e32 v147, 1.0, v147
	v_rcp_f32_e32 v146, v146
	v_rcp_f32_e32 v147, v147
	v_cvt_pk_u8_f32 v144, v144, 0, 0
	v_cvt_pk_u8_f32 v144, v145, 1, v144
	v_pk_fma_f32 v[148:149], v[48:49], s[22:23], v[210:211] op_sel_hi:[1,0,1] neg_lo:[1,0,0] neg_hi:[1,0,0]
	v_cvt_pk_u8_f32 v144, v146, 2, v144
	v_exp_f32_e32 v148, v148
	v_exp_f32_e32 v149, v149
	v_cvt_pk_u8_f32 v144, v147, 3, v144
	v_pk_fma_f32 v[146:147], v[228:229], s[22:23], v[208:209] op_sel_hi:[1,0,1]
	v_pk_fma_f32 v[150:151], v[32:33], s[22:23], v[210:211] op_sel_hi:[1,0,1] neg_lo:[1,0,0] neg_hi:[1,0,0]
	v_exp_f32_e32 v146, v146
	v_exp_f32_e32 v147, v147
	v_pk_fma_f32 v[148:149], v[148:149], s[20:21], s[20:21] op_sel_hi:[1,0,0] clamp
	v_exp_f32_e32 v150, v150
	v_min_f32_e32 v145, 1.0, v148
	v_pk_fma_f32 v[146:147], v[146:147], s[20:21], s[20:21] op_sel_hi:[1,0,0] clamp
	v_rcp_f32_e32 v145, v145
	v_rcp_f32_e32 v148, v149
	v_rcp_f32_e32 v146, v146
	v_rcp_f32_e32 v147, v147
	v_cvt_pk_u8_f32 v145, v145, 0, 0
	v_cvt_pk_u8_f32 v145, v148, 1, v145
	v_pk_fma_f32 v[148:149], v[36:37], s[22:23], v[220:221] op_sel_hi:[1,0,1] neg_lo:[1,0,0] neg_hi:[1,0,0]
	v_cvt_pk_u8_f32 v145, v146, 2, v145
	v_exp_f32_e32 v148, v148
	v_exp_f32_e32 v149, v149
	v_cvt_pk_u8_f32 v145, v147, 3, v145
	v_pk_fma_f32 v[146:147], v[226:227], s[22:23], v[216:217] op_sel_hi:[1,0,1]
	v_exp_f32_e32 v151, v151
	v_exp_f32_e32 v146, v146
	v_exp_f32_e32 v147, v147
	v_pk_fma_f32 v[148:149], v[148:149], s[20:21], s[20:21] op_sel_hi:[1,0,0] clamp
	v_pk_fma_f32 v[150:151], v[150:151], s[20:21], s[20:21] op_sel_hi:[1,0,0] clamp
	v_pk_fma_f32 v[146:147], v[146:147], s[20:21], s[20:21] op_sel_hi:[1,0,0] clamp
	v_rcp_f32_e32 v148, v148
	v_rcp_f32_e32 v149, v149
	v_rcp_f32_e32 v146, v146
	v_cvt_pk_u8_f32 v148, v148, 0, 0
	v_cvt_pk_u8_f32 v148, v149, 1, v148
	v_rcp_f32_e32 v147, v147
	v_cvt_pk_u8_f32 v146, v146, 2, v148
	v_pk_fma_f32 v[148:149], v[224:225], s[22:23], v[208:209] op_sel_hi:[1,0,1]
	v_pk_fma_f32 v[194:195], v[16:17], s[22:23], v[210:211] op_sel_hi:[1,0,1] neg_lo:[1,0,0] neg_hi:[1,0,0]
	v_exp_f32_e32 v148, v148
	v_exp_f32_e32 v149, v149
	v_cvt_pk_u8_f32 v146, v147, 3, v146
	v_min_f32_e32 v147, 1.0, v150
	v_pk_fma_f32 v[148:149], v[148:149], s[20:21], s[20:21] op_sel_hi:[1,0,0] clamp
	v_rcp_f32_e32 v147, v147
	v_rcp_f32_e32 v150, v151
	v_rcp_f32_e32 v148, v148
	v_rcp_f32_e32 v149, v149
	v_cvt_pk_u8_f32 v147, v147, 0, 0
	v_cvt_pk_u8_f32 v147, v150, 1, v147
	v_pk_fma_f32 v[150:151], v[20:21], s[22:23], v[220:221] op_sel_hi:[1,0,1] neg_lo:[1,0,0] neg_hi:[1,0,0]
	v_cvt_pk_u8_f32 v147, v148, 2, v147
	v_exp_f32_e32 v150, v150
	v_exp_f32_e32 v151, v151
	v_cvt_pk_u8_f32 v147, v149, 3, v147
	v_pk_fma_f32 v[148:149], v[222:223], s[22:23], v[216:217] op_sel_hi:[1,0,1]
	v_exp_f32_e32 v194, v194
	v_exp_f32_e32 v148, v148
	v_exp_f32_e32 v149, v149
	v_pk_fma_f32 v[150:151], v[150:151], s[20:21], s[20:21] op_sel_hi:[1,0,0] clamp
	v_exp_f32_e32 v195, v195
	v_pk_fma_f32 v[148:149], v[148:149], s[20:21], s[20:21] op_sel_hi:[1,0,0] clamp
	v_rcp_f32_e32 v150, v150
	v_rcp_f32_e32 v151, v151
	v_rcp_f32_e32 v148, v148
	v_cvt_pk_u8_f32 v150, v150, 0, 0
	v_cvt_pk_u8_f32 v150, v151, 1, v150
	v_rcp_f32_e32 v149, v149
	v_cvt_pk_u8_f32 v148, v148, 2, v150
	v_pk_fma_f32 v[150:151], v[218:219], s[22:23], v[208:209] op_sel_hi:[1,0,1]
	v_pk_fma_f32 v[194:195], v[194:195], s[20:21], s[20:21] op_sel_hi:[1,0,0] clamp
	v_exp_f32_e32 v150, v150
	v_exp_f32_e32 v151, v151
	v_cvt_pk_u8_f32 v148, v149, 3, v148
	v_pk_fma_f32 v[150:151], v[150:151], s[20:21], s[20:21] op_sel_hi:[1,0,0] clamp
	v_rcp_f32_e32 v149, v194
	v_rcp_f32_e32 v165, v195
	v_pk_fma_f32 v[194:195], v[4:5], s[22:23], v[220:221] op_sel_hi:[1,0,1] neg_lo:[1,0,0] neg_hi:[1,0,0]
	v_rcp_f32_e32 v150, v150
	v_exp_f32_e32 v194, v194
	v_exp_f32_e32 v195, v195
	v_rcp_f32_e32 v151, v151
	v_cvt_pk_u8_f32 v149, v149, 0, 0
	v_cvt_pk_u8_f32 v149, v165, 1, v149
	v_cvt_pk_u8_f32 v149, v150, 2, v149
	v_pk_fma_f32 v[194:195], v[194:195], s[20:21], s[20:21] op_sel_hi:[1,0,0] clamp
	v_cvt_pk_u8_f32 v149, v151, 3, v149
	v_pk_fma_f32 v[150:151], v[214:215], s[22:23], v[216:217] op_sel_hi:[1,0,1]
	v_min_f32_e32 v165, 1.0, v194
	v_exp_f32_e32 v150, v150
	v_exp_f32_e32 v151, v151
	v_rcp_f32_e32 v165, v165
	v_rcp_f32_e32 v194, v195
	v_pk_fma_f32 v[150:151], v[150:151], s[20:21], s[20:21] op_sel_hi:[1,0,0] clamp
	v_cvt_pk_u8_f32 v165, v165, 0, 0
	v_cvt_pk_u8_f32 v165, v194, 1, v165
	v_pk_fma_f32 v[194:195], v[212:213], s[22:23], v[208:209] op_sel_hi:[1,0,1]
	v_pk_fma_f32 v[208:209], v[0:1], s[22:23], v[210:211] op_sel_hi:[1,0,1] neg_lo:[1,0,0] neg_hi:[1,0,0]
	v_rcp_f32_e32 v150, v150
	v_exp_f32_e32 v208, v208
	v_exp_f32_e32 v209, v209
	v_exp_f32_e32 v194, v194
	v_exp_f32_e32 v195, v195
	v_rcp_f32_e32 v151, v151
	v_cvt_pk_u8_f32 v150, v150, 2, v165
	v_pk_fma_f32 v[208:209], v[208:209], s[20:21], s[20:21] op_sel_hi:[1,0,0] clamp
	v_pk_fma_f32 v[194:195], v[194:195], s[20:21], s[20:21] op_sel_hi:[1,0,0] clamp
	v_cvt_pk_u8_f32 v150, v151, 3, v150
	v_min_f32_e32 v151, 1.0, v208
	v_rcp_f32_e32 v236, v151
	v_rcp_f32_e32 v237, v209
	v_rcp_f32_e32 v165, v194
	v_min_f32_e32 v235, 1.0, v195

; template <class Prog, bool ALIGN_EPI, bool NHALF = false, bool PITCHED = false, bool SLACK = false>
; __device__ __forceinline__ void gemm_phase(LAS unsigned char* lds, const int pitch, Prog& P, const int wave_, unsigned long long& t_k, unsigned long long& t_e) {
;     ...
;         for (int t = 0; t < nt; t += 2) {
;             const bool last = (t == nt - 2);
;             if constexpr (Prog::HAS_GATE) { if (last && has_next) P.gate(); }
;             int wmode = 0; if constexpr (SLACK) wmode = (t == 0) ? P.first_wmode(cur, ui) : 0;
;             const bool fst = SLACK && (wmode != 0);
;             unsigned voffA2[2] = {voffA[0], voffA[1]}, voffB2[2] = {voffB[0], voffB[1]}; size_t hstep2 = hstep;
;             if constexpr (PITCHED) { if (last) PG8_VOFF(voffA2, voffB2, hstep2, (has_next ? nxt.pitch : cur.pitch)); }
;             const char* a1 = cA + (size_t)(t + 1) * kstep;
;             const char* a2 = last ? nA : cA + (size_t)(t + 2) * kstep; const char* b2 = last ? nB : cB + (size_t)(t + 2) * kstep;
;             const char* a3 = a2 + kstep; const char* b3 = b2 + kstep;
;             if constexpr (NHALF) {
;             PG8_LDB(B0, 0, 0); PG8_SCHED; PG8_LDA(At, 0, 0); PG8_STAGE(PG8_SA(1, 1), a1 + hstep, voffA);
;             PG8_WAIT_V(6); PG8_WAIT_L(0); PG8_BAR; PG8_MMA(0, 0, At, B0); PG8_BAR; PG8_SCHED;
;             PG8_LDA(At, 0, 1); PG8_STAGE(PG8_SB(0, 0), b2, voffB); PG8_STAGE(PG8_SA(0, 0), a2, voffA);
;             PG8_WAIT_V(6); PG8_WAIT_L(0); PG8_BAR; PG8_MMA(1, 0, At, B0); PG8_BAR; PG8_SCHED;
;             PG8_LDB(B0, 1, 0); PG8_SCHED; PG8_LDA(At, 1, 0); PG8_STAGE(PG8_SA(0, 1), a2 + hstep, voffA);
;             PG8_WAIT_V(6); PG8_WAIT_L(0); PG8_BAR; PG8_MMA(0, 0, At, B0); PG8_BAR; PG8_SCHED;
;             PG8_LDA(At, 1, 1); PG8_STAGE(PG8_SB(1, 0), b3, voffB); PG8_STAGE(PG8_SA(1, 0), a3, voffA);
;             PG8_WAIT_V(6); PG8_WAIT_L(0); PG8_BAR; PG8_MMA(1, 0, At, B0); PG8_BAR; PG8_SCHED;
;             } else {
;     ...
;             PG8_LDB(B0, 0, 0); PG8_LDB(B1, 0, 1); PG8_SCHED; PG8_LDA(At, 0, 0); if (!(SLACK && SLACK_PRE && fst)) PG8_STAGE(PG8_SA(1, 1), a1 + hstep, voffA);
;             PG8_WAIT_F; PG8_WAIT_L(0); PG8_BAR; PG8_MMA(0, 0, At, B0); PG8_MMA(0, 1, At, B1); PG8_BAR; PG8_SCHED;
;             PG8_LDA(At, 0, 1); PG8_STAGE(PG8_SB(0, 0), b2, voffB2); PG8_STAGE(PG8_SB(0, 1), b2 + hstep2, voffB2); PG8_STAGE(PG8_SA(0, 0), a2, voffA2);
.LBB0_234:
	s_branch .LBB0_367
	s_nop 0
	s_nop 0
	s_nop 0
	s_nop 0
	s_nop 0
	s_nop 0
	s_nop 0
	s_nop 0
	s_nop 0
	s_nop 0
	s_nop 0
	s_nop 0

; __device__ __forceinline__ unsigned xb_ld(unsigned* p)              { return __hip_atomic_load(p, __ATOMIC_RELAXED, __HIP_MEMORY_SCOPE_AGENT); }
; __device__ __forceinline__ unsigned xb_add(unsigned* p, unsigned v) { return __hip_atomic_fetch_add(p, v, __ATOMIC_RELAXED, __HIP_MEMORY_SCOPE_AGENT); }
; #define XB_SPIN(cond, bar) do { unsigned _sp = 0; while (cond) { __builtin_amdgcn_s_sleep(1); \
;     if ((++_sp & 255u) == 0u) { if (xb_ld(&(bar)[XB_TMO])) break; if (_sp > XB_SPIN_CAP) { atomicAdd(&(bar)[XB_TMO], 1u); break; } } } } while (0)
; __device__ __forceinline__ void xcdl_barrier(const XcdBarrier& b) {
;     ...
;         const unsigned old = xb_add(&bar[XB_LSUB(b.x)], 1u);
;         const unsigned gen = old >> 5;
;         if ((old & 31u) == 31u) xb_add(&bar[XB_LGEN(b.x)], 1u);
;         else XB_SPIN(xb_ld(&bar[XB_LGEN(b.x)]) == gen, bar);
;         __builtin_amdgcn_fence(__ATOMIC_ACQUIRE, "agent");
;         asm volatile("s_waitcnt vmcnt(0)" ::: "memory");
;     }
.LBB0_464:
	s_or_b64 exec, exec, s[0:1]
	s_waitcnt vmcnt(0) lgkmcnt(0)
	s_nop 0
	s_nop 0
	s_waitcnt vmcnt(0)

; #define LAS __attribute__((address_space(3)))
; __device__ __forceinline__ int otid(int wave) { return wave * 64 + olane(); }
; #define BU_LOAD(buf, ib) do { _Pragma("unroll") for (int h = 0; h < 2; ++h) { const int it = (2 * (ib) + h + k2) & 7, l = 16 * w + 2 * it + rp; \
;             _Pragma("unroll") for (int s2 = 0; s2 < 8; ++s2) c4[buf][h][s2] = *(const GAS u32x4*)(z0 + (size_t)l * 2048 + 256 * s2); } } while (0)
; __device__ __forceinline__ void b_unit(Frame& F, int u, bool dry) {
;     unsigned char* ws_ = F.ws; asm volatile("" : "+s"(ws_));
;     const int b = u >> 5, k2 = (u >> 2) & 7, g = u & 3;
;     const int w = F.wave, lane = otid(F.wave) & 63, sg = lane & 31, rp = lane >> 5;
;     LAS unsigned char* Bt = F.lds;
;     {
;         const f32x2* TW = (const f32x2*)(ws_ + WS_TW) + k2 * 256 + 8 * sg; const f32x2* W8 = (const f32x2*)(ws_ + WS_W8);
;         f32x2 tw[8], w8[8];
; #pragma unroll
;         for (int j = 0; j < 8; ++j) { tw[j] = TW[j]; w8[j] = W8[(j * k2) & 7]; }
;         const bf16_t* z0 = (const bf16_t*)(ws_ + WS_ZT) + (size_t)(b * 512 + g * 128) * 2048 + 8 * sg;
;         u32x4 c4[2][2][8];
;     ...
;         BU_LOAD(0, 0);
;         BU_LOAD(1, 1); BU_RED(0, 0);
.LBB0_468:
	s_cmp_le_i32 s66, s16
	s_cselect_b64 s[0:1], -1, 0
	s_and_b64 s[4:5], s[0:1], s[4:5]
	s_andn2_b64 vcc, exec, s[4:5]
	s_cbranch_vccnz .LBB0_562
	s_mov_b64 s[2:3], s[82:83]
	v_readlane_b32 s0, v254, 23
	v_mbcnt_lo_u32_b32 v170, -1, 0
	v_mbcnt_hi_u32_b32 v170, -1, v170
	s_add_u32 s0, s2, s0
	v_and_b32_e32 v18, 31, v170
	s_addc_u32 s1, s3, 0
	v_lshlrev_b32_e32 v192, 6, v18
	v_lshl_add_u64 v[0:1], s[0:1], 0, v[192:193]
	s_mov_b64 s[0:1], 0x1dd0000
	v_lshl_add_u64 v[2:3], v[0:1], 0, s[0:1]
	s_mov_b32 s0, 0x1dd0000
	v_add_co_u32_e32 v0, vcc, s0, v0
	s_add_u32 s6, s2, 0x1dd4000
	s_nop 0
	v_addc_co_u32_e32 v1, vcc, 0, v1, vcc
	s_addc_u32 s7, s3, 0
	flat_load_dwordx4 v[8:11], v[0:1]
	v_mov_b32_e32 v0, s2
	s_mov_b32 s8, 0x1dd4000
	v_readlane_b32 s0, v254, 24
	v_add_co_u32_e32 v0, vcc, s8, v0
	v_mov_b32_e32 v1, s3
	s_add_u32 s0, s6, s0
	v_addc_co_u32_e32 v1, vcc, 0, v1, vcc
	s_addc_u32 s1, s7, 0
	flat_load_dwordx2 v[144:145], v[0:1]
	v_mov_b64_e32 v[0:1], s[0:1]
	v_readlane_b32 s0, v254, 25
	s_add_u32 s0, s6, s0
	s_addc_u32 s1, s7, 0
	flat_load_dwordx2 v[146:147], v[0:1]
	flat_load_dwordx4 v[12:15], v[2:3] offset:16
	v_mov_b64_e32 v[0:1], s[0:1]
	v_readlane_b32 s0, v254, 26
	s_add_u32 s0, s6, s0
	s_addc_u32 s1, s7, 0
	flat_load_dwordx2 v[148:149], v[0:1]
	v_mov_b64_e32 v[0:1], s[0:1]
	v_readlane_b32 s0, v254, 27
	s_add_u32 s0, s6, s0
	s_addc_u32 s1, s7, 0
	flat_load_dwordx2 v[150:151], v[0:1]
	flat_load_dwordx4 v[4:7], v[2:3] offset:32
	v_mov_b64_e32 v[0:1], s[0:1]
	v_readlane_b32 s0, v254, 28
	s_add_u32 s0, s6, s0
	s_addc_u32 s1, s7, 0
	flat_load_dwordx2 v[152:153], v[0:1]
	v_mov_b64_e32 v[0:1], s[0:1]
	v_readlane_b32 s0, v254, 29
	s_add_u32 s0, s6, s0
	s_addc_u32 s1, s7, 0
	v_mov_b64_e32 v[16:17], s[0:1]
	v_readlane_b32 s0, v254, 30
	s_add_u32 s0, s6, s0
	s_addc_u32 s1, s7, 0
	flat_load_dwordx2 v[154:155], v[0:1]
	s_nop 0
	flat_load_dwordx4 v[0:3], v[2:3] offset:48
	v_lshlrev_b32_e32 v192, 4, v18
	flat_load_dwordx2 v[156:157], v[16:17]
	v_mov_b64_e32 v[16:17], s[0:1]
	v_readlane_b32 s0, v253, 43
	v_readlane_b32 s1, v253, 44
	s_add_u32 s0, s2, s0
	s_addc_u32 s1, s3, s1
	flat_load_dwordx2 v[158:159], v[16:17]
	v_lshl_add_u64 v[16:17], s[0:1], 0, v[192:193]
	s_mov_b64 s[0:1], 0x8000000
	v_bfe_u32 v172, v170, 5, 1
	v_lshl_add_u64 v[162:163], v[16:17], 0, s[0:1]
	v_readlane_b32 s0, v253, 45
	v_mov_b32_e32 v139, v193
	v_readlane_b32 s1, v253, 46
	v_or_b32_e32 v138, s0, v172
	v_lshlrev_b64 v[16:17], 12, v[138:139]
	v_lshl_add_u64 v[16:17], v[162:163], 0, v[16:17]
	global_load_dwordx4 v[140:143], v[16:17], off sc1
	global_load_dwordx4 v[174:177], v[16:17], off offset:512 sc1
	global_load_dwordx4 v[72:75], v[16:17], off offset:1024 sc1
	global_load_dwordx4 v[104:107], v[16:17], off offset:1536 sc1
	global_load_dwordx4 v[112:115], v[16:17], off offset:2048 sc1
	global_load_dwordx4 v[116:119], v[16:17], off offset:2560 sc1
	global_load_dwordx4 v[120:123], v[16:17], off offset:3072 sc1
	global_load_dwordx4 v[124:127], v[16:17], off offset:3584 sc1
	v_or_b32_e32 v136, s1, v172
	v_mov_b32_e32 v137, v193
	v_lshlrev_b64 v[16:17], 12, v[136:137]
	v_lshl_add_u64 v[16:17], v[162:163], 0, v[16:17]
	global_load_dwordx4 v[108:111], v[16:17], off sc1
	global_load_dwordx4 v[76:79], v[16:17], off offset:512 sc1
	global_load_dwordx4 v[60:63], v[16:17], off offset:1024 sc1
	global_load_dwordx4 v[56:59], v[16:17], off offset:1536 sc1
	global_load_dwordx4 v[52:55], v[16:17], off offset:2048 sc1
	global_load_dwordx4 v[48:51], v[16:17], off offset:2560 sc1
	global_load_dwordx4 v[44:47], v[16:17], off offset:3072 sc1
	global_load_dwordx4 v[40:43], v[16:17], off offset:3584 sc1
	v_readlane_b32 s1, v253, 47
	v_mov_b32_e32 v167, v193
	v_mov_b32_e32 v165, v193
	v_or_b32_e32 v166, s1, v172
	v_lshlrev_b64 v[16:17], 12, v[166:167]
	v_lshl_add_u64 v[16:17], v[162:163], 0, v[16:17]
	global_load_dwordx4 v[132:135], v[16:17], off sc1
	global_load_dwordx4 v[128:131], v[16:17], off offset:512 sc1
	global_load_dwordx4 v[100:103], v[16:17], off offset:1024 sc1
	global_load_dwordx4 v[96:99], v[16:17], off offset:1536 sc1
	global_load_dwordx4 v[92:95], v[16:17], off offset:2048 sc1
	global_load_dwordx4 v[88:91], v[16:17], off offset:2560 sc1
	global_load_dwordx4 v[84:87], v[16:17], off offset:3072 sc1
	global_load_dwordx4 v[80:83], v[16:17], off offset:3584 sc1
	v_readlane_b32 s1, v253, 48
	s_movk_i32 s6, 0x410
	v_and_b32_e32 v171, 63, v170
	v_or_b32_e32 v164, s1, v172
	v_lshlrev_b64 v[16:17], 12, v[164:165]
	v_lshl_add_u64 v[16:17], v[162:163], 0, v[16:17]
	global_load_dwordx4 v[68:71], v[16:17], off sc1
	global_load_dwordx4 v[64:67], v[16:17], off offset:512 sc1
	global_load_dwordx4 v[36:39], v[16:17], off offset:1024 sc1
	global_load_dwordx4 v[32:35], v[16:17], off offset:1536 sc1
	global_load_dwordx4 v[28:31], v[16:17], off offset:2048 sc1
	global_load_dwordx4 v[24:27], v[16:17], off offset:2560 sc1
	global_load_dwordx4 v[20:23], v[16:17], off offset:3072 sc1
	s_nop 0
	global_load_dwordx4 v[16:19], v[16:17], off offset:3584 sc1
	s_mov_b32 s7, 0x1d90000
	s_mov_b64 s[28:29], s[82:83]
	s_waitcnt vmcnt(0)
	v_lshlrev_b32_e32 v160, 16, v140
	v_and_b32_e32 v161, 0xffff0000, v140
	v_lshlrev_b32_e32 v178, 16, v174
	v_and_b32_e32 v179, 0xffff0000, v174
	s_waitcnt lgkmcnt(0)
	v_pk_fma_f32 v[182:183], v[144:145], v[160:161], 0 op_sel_hi:[0,1,0]
	v_pk_fma_f32 v[160:161], v[144:145], v[160:161], 0 op_sel:[1,0,0] op_sel_hi:[1,1,0]
	v_pk_fma_f32 v[182:183], v[146:147], v[178:179], v[182:183] op_sel_hi:[0,1,1]
	v_pk_fma_f32 v[160:161], v[146:147], v[178:179], v[160:161] op_sel:[1,0,0]
	v_lshlrev_b32_e32 v178, 16, v72
	v_and_b32_e32 v179, 0xffff0000, v72
	v_pk_fma_f32 v[182:183], v[148:149], v[178:179], v[182:183] op_sel_hi:[0,1,1]
	v_pk_fma_f32 v[160:161], v[148:149], v[178:179], v[160:161] op_sel:[1,0,0]
	v_lshlrev_b32_e32 v178, 16, v104
	v_and_b32_e32 v179, 0xffff0000, v104
	v_pk_fma_f32 v[182:183], v[150:151], v[178:179], v[182:183] op_sel_hi:[0,1,1]
	v_pk_fma_f32 v[160:161], v[150:151], v[178:179], v[160:161] op_sel:[1,0,0]
	v_lshlrev_b32_e32 v178, 16, v112
	v_and_b32_e32 v179, 0xffff0000, v112
	v_pk_fma_f32 v[182:183], v[152:153], v[178:179], v[182:183] op_sel_hi:[0,1,1]
	v_pk_fma_f32 v[160:161], v[152:153], v[178:179], v[160:161] op_sel:[1,0,0]
	v_lshlrev_b32_e32 v178, 16, v116
	v_and_b32_e32 v179, 0xffff0000, v116
	v_pk_fma_f32 v[182:183], v[154:155], v[178:179], v[182:183] op_sel_hi:[0,1,1]
	v_pk_fma_f32 v[160:161], v[154:155], v[178:179], v[160:161] op_sel:[1,0,0]
	v_lshlrev_b32_e32 v178, 16, v120
	v_and_b32_e32 v179, 0xffff0000, v120
	v_pk_fma_f32 v[182:183], v[156:157], v[178:179], v[182:183] op_sel_hi:[0,1,1]
	v_pk_fma_f32 v[160:161], v[156:157], v[178:179], v[160:161] op_sel:[1,0,0]
	v_lshlrev_b32_e32 v178, 16, v124
	v_and_b32_e32 v179, 0xffff0000, v124
	v_pk_fma_f32 v[182:183], v[158:159], v[178:179], v[182:183] op_sel_hi:[0,1,1]
	v_pk_fma_f32 v[178:179], v[158:159], v[178:179], v[160:161] op_sel:[1,0,0]
	v_mov_b32_e32 v161, v10
	v_mov_b32_e32 v10, v9
	v_mov_b32_e32 v160, v8
	v_pk_mul_f32 v[8:9], v[10:11], v[178:179]
	v_lshlrev_b32_e32 v140, 16, v141
	v_and_b32_e32 v141, 0xffff0000, v141
	v_pk_fma_f32 v[184:185], v[160:161], v[182:183], v[8:9] neg_lo:[0,0,1] neg_hi:[0,0,1]
	v_pk_mul_f32 v[8:9], v[160:161], v[178:179]
	v_lshlrev_b32_e32 v174, 16, v175
	v_and_b32_e32 v175, 0xffff0000, v175
	v_pk_fma_f32 v[178:179], v[10:11], v[182:183], v[8:9]
	v_pk_fma_f32 v[8:9], v[144:145], v[140:141], 0 op_sel_hi:[0,1,0]
	v_pk_fma_f32 v[140:141], v[144:145], v[140:141], 0 op_sel:[1,0,0] op_sel_hi:[1,1,0]
	v_pk_fma_f32 v[8:9], v[146:147], v[174:175], v[8:9] op_sel_hi:[0,1,1]
	v_pk_fma_f32 v[140:141], v[146:147], v[174:175], v[140:141] op_sel:[1,0,0]
	v_lshlrev_b32_e32 v72, 16, v73
	v_and_b32_e32 v73, 0xffff0000, v73
	v_pk_fma_f32 v[8:9], v[148:149], v[72:73], v[8:9] op_sel_hi:[0,1,1]
	v_pk_fma_f32 v[72:73], v[148:149], v[72:73], v[140:141] op_sel:[1,0,0]
	v_lshlrev_b32_e32 v104, 16, v105
	v_and_b32_e32 v105, 0xffff0000, v105
	v_pk_fma_f32 v[8:9], v[150:151], v[104:105], v[8:9] op_sel_hi:[0,1,1]
	v_pk_fma_f32 v[72:73], v[150:151], v[104:105], v[72:73] op_sel:[1,0,0]
	v_lshlrev_b32_e32 v104, 16, v113
	v_and_b32_e32 v105, 0xffff0000, v113
	v_pk_fma_f32 v[8:9], v[152:153], v[104:105], v[8:9] op_sel_hi:[0,1,1]
	v_pk_fma_f32 v[72:73], v[152:153], v[104:105], v[72:73] op_sel:[1,0,0]
	v_lshlrev_b32_e32 v104, 16, v117
	v_and_b32_e32 v105, 0xffff0000, v117
	v_pk_fma_f32 v[8:9], v[154:155], v[104:105], v[8:9] op_sel_hi:[0,1,1]
	v_pk_fma_f32 v[72:73], v[154:155], v[104:105], v[72:73] op_sel:[1,0,0]
	v_lshlrev_b32_e32 v104, 16, v121
	v_and_b32_e32 v105, 0xffff0000, v121
	v_pk_fma_f32 v[8:9], v[156:157], v[104:105], v[8:9] op_sel_hi:[0,1,1]
	v_pk_fma_f32 v[72:73], v[156:157], v[104:105], v[72:73] op_sel:[1,0,0]
	v_lshlrev_b32_e32 v104, 16, v125
	v_and_b32_e32 v105, 0xffff0000, v125
	v_pk_fma_f32 v[112:113], v[158:159], v[104:105], v[8:9] op_sel_hi:[0,1,1]
	v_pk_fma_f32 v[72:73], v[158:159], v[104:105], v[72:73] op_sel:[1,0,0]
	v_mov_b32_e32 v9, v14
	v_mov_b32_e32 v14, v13
	v_mov_b32_e32 v8, v12
	v_pk_mul_f32 v[12:13], v[14:15], v[72:73]
	v_lshlrev_b32_e32 v168, 16, v142
	v_and_b32_e32 v169, 0xffff0000, v142
	v_pk_fma_f32 v[104:105], v[8:9], v[112:113], v[12:13] neg_lo:[0,0,1] neg_hi:[0,0,1]
	v_pk_mul_f32 v[12:13], v[8:9], v[72:73]
	v_lshlrev_b32_e32 v180, 16, v176
	v_and_b32_e32 v181, 0xffff0000, v176
	v_pk_fma_f32 v[112:113], v[14:15], v[112:113], v[12:13]
	v_pk_fma_f32 v[12:13], v[144:145], v[168:169], 0 op_sel_hi:[0,1,0]
	v_pk_fma_f32 v[72:73], v[144:145], v[168:169], 0 op_sel:[1,0,0] op_sel_hi:[1,1,0]
	v_pk_fma_f32 v[12:13], v[146:147], v[180:181], v[12:13] op_sel_hi:[0,1,1]
	v_pk_fma_f32 v[72:73], v[146:147], v[180:181], v[72:73] op_sel:[1,0,0]
	v_lshlrev_b32_e32 v116, 16, v74
	v_and_b32_e32 v117, 0xffff0000, v74
	v_pk_fma_f32 v[12:13], v[148:149], v[116:117], v[12:13] op_sel_hi:[0,1,1]
	v_pk_fma_f32 v[72:73], v[148:149], v[116:117], v[72:73] op_sel:[1,0,0]
	v_lshlrev_b32_e32 v116, 16, v106
	v_and_b32_e32 v117, 0xffff0000, v106
	v_pk_fma_f32 v[12:13], v[150:151], v[116:117], v[12:13] op_sel_hi:[0,1,1]
	v_pk_fma_f32 v[72:73], v[150:151], v[116:117], v[72:73] op_sel:[1,0,0]
	v_lshlrev_b32_e32 v116, 16, v114
	v_and_b32_e32 v117, 0xffff0000, v114
	v_pk_fma_f32 v[12:13], v[152:153], v[116:117], v[12:13] op_sel_hi:[0,1,1]
	v_pk_fma_f32 v[72:73], v[152:153], v[116:117], v[72:73] op_sel:[1,0,0]
	v_lshlrev_b32_e32 v116, 16, v118
	v_and_b32_e32 v117, 0xffff0000, v118
	v_pk_fma_f32 v[12:13], v[154:155], v[116:117], v[12:13] op_sel_hi:[0,1,1]
	v_pk_fma_f32 v[72:73], v[154:155], v[116:117], v[72:73] op_sel:[1,0,0]
	v_lshlrev_b32_e32 v116, 16, v122
	v_and_b32_e32 v117, 0xffff0000, v122
	v_pk_fma_f32 v[12:13], v[156:157], v[116:117], v[12:13] op_sel_hi:[0,1,1]
	v_pk_fma_f32 v[72:73], v[156:157], v[116:117], v[72:73] op_sel:[1,0,0]
	v_lshlrev_b32_e32 v116, 16, v126
	v_and_b32_e32 v117, 0xffff0000, v126
	v_pk_fma_f32 v[120:121], v[158:159], v[116:117], v[12:13] op_sel_hi:[0,1,1]
	v_pk_fma_f32 v[72:73], v[158:159], v[116:117], v[72:73] op_sel:[1,0,0]
	v_mov_b32_e32 v13, v6
	v_mov_b32_e32 v6, v5
	v_mov_b32_e32 v12, v4
	v_pk_mul_f32 v[4:5], v[6:7], v[72:73]
	v_lshlrev_b32_e32 v142, 16, v143
	v_and_b32_e32 v143, 0xffff0000, v143
	v_pk_fma_f32 v[116:117], v[12:13], v[120:121], v[4:5] neg_lo:[0,0,1] neg_hi:[0,0,1]
	v_pk_mul_f32 v[4:5], v[12:13], v[72:73]
	v_lshlrev_b32_e32 v176, 16, v177
	v_and_b32_e32 v177, 0xffff0000, v177
	v_pk_fma_f32 v[120:121], v[6:7], v[120:121], v[4:5]
	v_pk_fma_f32 v[4:5], v[144:145], v[142:143], 0 op_sel_hi:[0,1,0]
	v_pk_fma_f32 v[72:73], v[144:145], v[142:143], 0 op_sel:[1,0,0] op_sel_hi:[1,1,0]
	v_pk_fma_f32 v[4:5], v[146:147], v[176:177], v[4:5] op_sel_hi:[0,1,1]
	v_pk_fma_f32 v[72:73], v[146:147], v[176:177], v[72:73] op_sel:[1,0,0]
	v_lshlrev_b32_e32 v74, 16, v75
	v_and_b32_e32 v75, 0xffff0000, v75
	v_pk_fma_f32 v[4:5], v[148:149], v[74:75], v[4:5] op_sel_hi:[0,1,1]
	v_pk_fma_f32 v[72:73], v[148:149], v[74:75], v[72:73] op_sel:[1,0,0]
	v_lshlrev_b32_e32 v74, 16, v107
	v_and_b32_e32 v75, 0xffff0000, v107
	v_pk_fma_f32 v[4:5], v[150:151], v[74:75], v[4:5] op_sel_hi:[0,1,1]
	v_pk_fma_f32 v[72:73], v[150:151], v[74:75], v[72:73] op_sel:[1,0,0]
	v_lshlrev_b32_e32 v74, 16, v115
	v_and_b32_e32 v75, 0xffff0000, v115
	v_pk_fma_f32 v[4:5], v[152:153], v[74:75], v[4:5] op_sel_hi:[0,1,1]
	v_pk_fma_f32 v[72:73], v[152:153], v[74:75], v[72:73] op_sel:[1,0,0]
	v_lshlrev_b32_e32 v74, 16, v119
	v_and_b32_e32 v75, 0xffff0000, v119
	v_pk_fma_f32 v[4:5], v[154:155], v[74:75], v[4:5] op_sel_hi:[0,1,1]
	v_pk_fma_f32 v[72:73], v[154:155], v[74:75], v[72:73] op_sel:[1,0,0]
	v_lshlrev_b32_e32 v74, 16, v123
	v_and_b32_e32 v75, 0xffff0000, v123
	v_pk_fma_f32 v[4:5], v[156:157], v[74:75], v[4:5] op_sel_hi:[0,1,1]
	v_pk_fma_f32 v[72:73], v[156:157], v[74:75], v[72:73] op_sel:[1,0,0]
	v_lshlrev_b32_e32 v74, 16, v127
	v_and_b32_e32 v75, 0xffff0000, v127
	v_pk_fma_f32 v[106:107], v[158:159], v[74:75], v[4:5] op_sel_hi:[0,1,1]
	v_pk_fma_f32 v[72:73], v[158:159], v[74:75], v[72:73] op_sel:[1,0,0]
	v_mov_b32_e32 v5, v2
	v_mov_b32_e32 v2, v1
	v_mov_b32_e32 v4, v0
	v_pk_mul_f32 v[0:1], v[2:3], v[72:73]
	v_pk_mul_f32 v[72:73], v[4:5], v[72:73]
	v_pk_fma_f32 v[0:1], v[4:5], v[106:107], v[0:1] neg_lo:[0,0,1] neg_hi:[0,0,1]
	v_pk_fma_f32 v[106:107], v[2:3], v[106:107], v[72:73]
	v_cvt_pk_bf16_f32 v75, v0, v1
	v_mul_lo_u32 v0, v138, s6
	v_cvt_pk_bf16_f32 v72, v184, v185
	v_cvt_pk_bf16_f32 v73, v104, v105
	v_cvt_pk_bf16_f32 v74, v116, v117
	v_add3_u32 v0, 0, v0, v192
	ds_write_b128 v0, v[72:75]
	v_cvt_pk_bf16_f32 v72, v178, v179
	v_cvt_pk_bf16_f32 v73, v112, v113
	v_cvt_pk_bf16_f32 v74, v120, v121
	v_cvt_pk_bf16_f32 v75, v106, v107
	ds_write_b128 v0, v[72:75] offset:512
	v_lshlrev_b32_e32 v0, 16, v108
	v_and_b32_e32 v1, 0xffff0000, v108
	v_lshlrev_b32_e32 v74, 16, v110
	v_and_b32_e32 v75, 0xffff0000, v110
	v_lshlrev_b32_e32 v104, 16, v111
	v_and_b32_e32 v105, 0xffff0000, v111
	v_lshlrev_b32_e32 v106, 16, v76
	v_and_b32_e32 v107, 0xffff0000, v76
	v_pk_fma_f32 v[110:111], v[144:145], v[0:1], 0 op_sel_hi:[0,1,0]
	v_pk_fma_f32 v[0:1], v[144:145], v[0:1], 0 op_sel:[1,0,0] op_sel_hi:[1,1,0]
	v_pk_fma_f32 v[110:111], v[146:147], v[106:107], v[110:111] op_sel_hi:[0,1,1]
	v_pk_fma_f32 v[0:1], v[146:147], v[106:107], v[0:1] op_sel:[1,0,0]
	v_lshlrev_b32_e32 v106, 16, v60
	v_and_b32_e32 v107, 0xffff0000, v60
	v_pk_fma_f32 v[110:111], v[148:149], v[106:107], v[110:111] op_sel_hi:[0,1,1]
	v_pk_fma_f32 v[0:1], v[148:149], v[106:107], v[0:1] op_sel:[1,0,0]
	v_lshlrev_b32_e32 v106, 16, v56
	v_and_b32_e32 v107, 0xffff0000, v56
	v_pk_fma_f32 v[110:111], v[150:151], v[106:107], v[110:111] op_sel_hi:[0,1,1]
	v_pk_fma_f32 v[0:1], v[150:151], v[106:107], v[0:1] op_sel:[1,0,0]
	v_lshlrev_b32_e32 v106, 16, v52
	v_and_b32_e32 v107, 0xffff0000, v52
	v_pk_fma_f32 v[110:111], v[152:153], v[106:107], v[110:111] op_sel_hi:[0,1,1]
	v_pk_fma_f32 v[0:1], v[152:153], v[106:107], v[0:1] op_sel:[1,0,0]
	v_lshlrev_b32_e32 v106, 16, v48
	v_and_b32_e32 v107, 0xffff0000, v48
	v_pk_fma_f32 v[110:111], v[154:155], v[106:107], v[110:111] op_sel_hi:[0,1,1]
	v_pk_fma_f32 v[0:1], v[154:155], v[106:107], v[0:1] op_sel:[1,0,0]
	v_lshlrev_b32_e32 v106, 16, v44
	v_and_b32_e32 v107, 0xffff0000, v44
	v_pk_fma_f32 v[110:111], v[156:157], v[106:107], v[110:111] op_sel_hi:[0,1,1]
	v_pk_fma_f32 v[0:1], v[156:157], v[106:107], v[0:1] op_sel:[1,0,0]
	v_lshlrev_b32_e32 v106, 16, v40
	v_and_b32_e32 v107, 0xffff0000, v40
	v_pk_fma_f32 v[0:1], v[158:159], v[106:107], v[0:1] op_sel:[1,0,0]
	v_lshlrev_b32_e32 v72, 16, v109
	v_and_b32_e32 v73, 0xffff0000, v109
	v_pk_fma_f32 v[110:111], v[158:159], v[106:107], v[110:111] op_sel_hi:[0,1,1]
	v_pk_mul_f32 v[106:107], v[10:11], v[0:1]
	v_pk_mul_f32 v[0:1], v[160:161], v[0:1]
	v_lshlrev_b32_e32 v76, 16, v77
	v_and_b32_e32 v77, 0xffff0000, v77
	v_pk_fma_f32 v[106:107], v[160:161], v[110:111], v[106:107] neg_lo:[0,0,1] neg_hi:[0,0,1]
	v_pk_fma_f32 v[0:1], v[10:11], v[110:111], v[0:1]
	v_pk_fma_f32 v[110:111], v[144:145], v[72:73], 0 op_sel_hi:[0,1,0]
	v_pk_fma_f32 v[72:73], v[144:145], v[72:73], 0 op_sel:[1,0,0] op_sel_hi:[1,1,0]
	v_pk_fma_f32 v[110:111], v[146:147], v[76:77], v[110:111] op_sel_hi:[0,1,1]
	v_pk_fma_f32 v[72:73], v[146:147], v[76:77], v[72:73] op_sel:[1,0,0]
	v_lshlrev_b32_e32 v60, 16, v61
	v_and_b32_e32 v61, 0xffff0000, v61
	v_pk_fma_f32 v[76:77], v[148:149], v[60:61], v[110:111] op_sel_hi:[0,1,1]
	v_pk_fma_f32 v[60:61], v[148:149], v[60:61], v[72:73] op_sel:[1,0,0]
	v_lshlrev_b32_e32 v56, 16, v57
	v_and_b32_e32 v57, 0xffff0000, v57
	v_pk_fma_f32 v[72:73], v[150:151], v[56:57], v[76:77] op_sel_hi:[0,1,1]
	v_pk_fma_f32 v[56:57], v[150:151], v[56:57], v[60:61] op_sel:[1,0,0]
	v_lshlrev_b32_e32 v52, 16, v53
	v_and_b32_e32 v53, 0xffff0000, v53
	v_pk_fma_f32 v[60:61], v[152:153], v[52:53], v[72:73] op_sel_hi:[0,1,1]
	v_pk_fma_f32 v[52:53], v[152:153], v[52:53], v[56:57] op_sel:[1,0,0]
	v_lshlrev_b32_e32 v48, 16, v49
	v_and_b32_e32 v49, 0xffff0000, v49
	v_pk_fma_f32 v[56:57], v[154:155], v[48:49], v[60:61] op_sel_hi:[0,1,1]
	v_pk_fma_f32 v[48:49], v[154:155], v[48:49], v[52:53] op_sel:[1,0,0]
	v_lshlrev_b32_e32 v44, 16, v45
	v_and_b32_e32 v45, 0xffff0000, v45
	v_pk_fma_f32 v[52:53], v[156:157], v[44:45], v[56:57] op_sel_hi:[0,1,1]
	v_pk_fma_f32 v[44:45], v[156:157], v[44:45], v[48:49] op_sel:[1,0,0]
	v_lshlrev_b32_e32 v40, 16, v41
	v_and_b32_e32 v41, 0xffff0000, v41
	v_pk_fma_f32 v[48:49], v[158:159], v[40:41], v[52:53] op_sel_hi:[0,1,1]
	v_pk_fma_f32 v[40:41], v[158:159], v[40:41], v[44:45] op_sel:[1,0,0]
	v_lshlrev_b32_e32 v108, 16, v78
	v_pk_mul_f32 v[44:45], v[14:15], v[40:41]
	v_pk_mul_f32 v[40:41], v[8:9], v[40:41]
	v_and_b32_e32 v109, 0xffff0000, v78
	v_pk_fma_f32 v[44:45], v[8:9], v[48:49], v[44:45] neg_lo:[0,0,1] neg_hi:[0,0,1]
	v_pk_fma_f32 v[48:49], v[14:15], v[48:49], v[40:41]
	v_pk_fma_f32 v[40:41], v[144:145], v[74:75], 0 op_sel_hi:[0,1,0]
	v_pk_fma_f32 v[52:53], v[144:145], v[74:75], 0 op_sel:[1,0,0] op_sel_hi:[1,1,0]
	v_pk_fma_f32 v[40:41], v[146:147], v[108:109], v[40:41] op_sel_hi:[0,1,1]
	v_pk_fma_f32 v[52:53], v[146:147], v[108:109], v[52:53] op_sel:[1,0,0]
	v_lshlrev_b32_e32 v56, 16, v62
	v_and_b32_e32 v57, 0xffff0000, v62
	v_pk_fma_f32 v[40:41], v[148:149], v[56:57], v[40:41] op_sel_hi:[0,1,1]
	v_pk_fma_f32 v[52:53], v[148:149], v[56:57], v[52:53] op_sel:[1,0,0]
	v_lshlrev_b32_e32 v56, 16, v58
	v_and_b32_e32 v57, 0xffff0000, v58
	v_pk_fma_f32 v[40:41], v[150:151], v[56:57], v[40:41] op_sel_hi:[0,1,1]
	v_pk_fma_f32 v[52:53], v[150:151], v[56:57], v[52:53] op_sel:[1,0,0]
	v_lshlrev_b32_e32 v56, 16, v54
	v_and_b32_e32 v57, 0xffff0000, v54
	v_pk_fma_f32 v[40:41], v[152:153], v[56:57], v[40:41] op_sel_hi:[0,1,1]
	v_pk_fma_f32 v[52:53], v[152:153], v[56:57], v[52:53] op_sel:[1,0,0]
	v_lshlrev_b32_e32 v56, 16, v50
	v_and_b32_e32 v57, 0xffff0000, v50
	v_pk_fma_f32 v[40:41], v[154:155], v[56:57], v[40:41] op_sel_hi:[0,1,1]
	v_pk_fma_f32 v[52:53], v[154:155], v[56:57], v[52:53] op_sel:[1,0,0]
	v_lshlrev_b32_e32 v56, 16, v46
	v_and_b32_e32 v57, 0xffff0000, v46
	v_pk_fma_f32 v[40:41], v[156:157], v[56:57], v[40:41] op_sel_hi:[0,1,1]
	v_pk_fma_f32 v[52:53], v[156:157], v[56:57], v[52:53] op_sel:[1,0,0]
	v_lshlrev_b32_e32 v56, 16, v42
	v_and_b32_e32 v57, 0xffff0000, v42
	v_pk_fma_f32 v[52:53], v[158:159], v[56:57], v[52:53] op_sel:[1,0,0]
	v_pk_fma_f32 v[40:41], v[158:159], v[56:57], v[40:41] op_sel_hi:[0,1,1]
	v_pk_mul_f32 v[56:57], v[6:7], v[52:53]
	v_pk_mul_f32 v[52:53], v[12:13], v[52:53]
	v_lshlrev_b32_e32 v78, 16, v79
	v_and_b32_e32 v79, 0xffff0000, v79
	v_pk_fma_f32 v[56:57], v[12:13], v[40:41], v[56:57] neg_lo:[0,0,1] neg_hi:[0,0,1]
	v_pk_fma_f32 v[52:53], v[6:7], v[40:41], v[52:53]
	v_pk_fma_f32 v[40:41], v[144:145], v[104:105], 0 op_sel_hi:[0,1,0]
	v_pk_fma_f32 v[60:61], v[144:145], v[104:105], 0 op_sel:[1,0,0] op_sel_hi:[1,1,0]
	v_pk_fma_f32 v[40:41], v[146:147], v[78:79], v[40:41] op_sel_hi:[0,1,1]
	v_pk_fma_f32 v[60:61], v[146:147], v[78:79], v[60:61] op_sel:[1,0,0]
	v_lshlrev_b32_e32 v62, 16, v63
	v_and_b32_e32 v63, 0xffff0000, v63
	v_pk_fma_f32 v[40:41], v[148:149], v[62:63], v[40:41] op_sel_hi:[0,1,1]
	v_pk_fma_f32 v[60:61], v[148:149], v[62:63], v[60:61] op_sel:[1,0,0]
	v_lshlrev_b32_e32 v58, 16, v59
	v_and_b32_e32 v59, 0xffff0000, v59
	v_pk_fma_f32 v[40:41], v[150:151], v[58:59], v[40:41] op_sel_hi:[0,1,1]
	v_pk_fma_f32 v[58:59], v[150:151], v[58:59], v[60:61] op_sel:[1,0,0]
	v_lshlrev_b32_e32 v54, 16, v55
	v_and_b32_e32 v55, 0xffff0000, v55
	v_lshlrev_b32_e32 v174, 16, v132
	v_and_b32_e32 v175, 0xffff0000, v132
	v_pk_fma_f32 v[40:41], v[152:153], v[54:55], v[40:41] op_sel_hi:[0,1,1]
	v_pk_fma_f32 v[54:55], v[152:153], v[54:55], v[58:59] op_sel:[1,0,0]
	v_lshlrev_b32_e32 v50, 16, v51
	v_and_b32_e32 v51, 0xffff0000, v51
	v_lshlrev_b32_e32 v178, 16, v128
	v_and_b32_e32 v179, 0xffff0000, v128
	v_pk_fma_f32 v[182:183], v[144:145], v[174:175], 0 op_sel_hi:[0,1,0]
	v_pk_fma_f32 v[174:175], v[144:145], v[174:175], 0 op_sel:[1,0,0] op_sel_hi:[1,1,0]
	v_pk_fma_f32 v[40:41], v[154:155], v[50:51], v[40:41] op_sel_hi:[0,1,1]
	v_pk_fma_f32 v[50:51], v[154:155], v[50:51], v[54:55] op_sel:[1,0,0]
	v_lshlrev_b32_e32 v46, 16, v47
	v_and_b32_e32 v47, 0xffff0000, v47
	v_pk_fma_f32 v[182:183], v[146:147], v[178:179], v[182:183] op_sel_hi:[0,1,1]
	v_pk_fma_f32 v[174:175], v[146:147], v[178:179], v[174:175] op_sel:[1,0,0]
	v_lshlrev_b32_e32 v178, 16, v100
	v_and_b32_e32 v179, 0xffff0000, v100
	v_pk_fma_f32 v[40:41], v[156:157], v[46:47], v[40:41] op_sel_hi:[0,1,1]
	v_pk_fma_f32 v[46:47], v[156:157], v[46:47], v[50:51] op_sel:[1,0,0]
	v_lshlrev_b32_e32 v42, 16, v43
	v_and_b32_e32 v43, 0xffff0000, v43
	v_pk_fma_f32 v[182:183], v[148:149], v[178:179], v[182:183] op_sel_hi:[0,1,1]
	v_pk_fma_f32 v[174:175], v[148:149], v[178:179], v[174:175] op_sel:[1,0,0]
	v_lshlrev_b32_e32 v178, 16, v96
	v_and_b32_e32 v179, 0xffff0000, v96
	v_pk_fma_f32 v[40:41], v[158:159], v[42:43], v[40:41] op_sel_hi:[0,1,1]
	v_pk_fma_f32 v[42:43], v[158:159], v[42:43], v[46:47] op_sel:[1,0,0]
	v_pk_fma_f32 v[182:183], v[150:151], v[178:179], v[182:183] op_sel_hi:[0,1,1]
	v_pk_fma_f32 v[174:175], v[150:151], v[178:179], v[174:175] op_sel:[1,0,0]
	v_lshlrev_b32_e32 v178, 16, v92
	v_and_b32_e32 v179, 0xffff0000, v92
	v_pk_mul_f32 v[46:47], v[2:3], v[42:43]
	v_pk_mul_f32 v[42:43], v[4:5], v[42:43]
	v_pk_fma_f32 v[182:183], v[152:153], v[178:179], v[182:183] op_sel_hi:[0,1,1]
	v_pk_fma_f32 v[174:175], v[152:153], v[178:179], v[174:175] op_sel:[1,0,0]
	v_lshlrev_b32_e32 v178, 16, v88
	v_and_b32_e32 v179, 0xffff0000, v88
	v_pk_fma_f32 v[46:47], v[4:5], v[40:41], v[46:47] neg_lo:[0,0,1] neg_hi:[0,0,1]
	v_pk_fma_f32 v[50:51], v[2:3], v[40:41], v[42:43]
	v_cvt_pk_bf16_f32 v41, v44, v45
	v_mul_lo_u32 v44, v136, s6
	v_pk_fma_f32 v[182:183], v[154:155], v[178:179], v[182:183] op_sel_hi:[0,1,1]
	v_pk_fma_f32 v[174:175], v[154:155], v[178:179], v[174:175] op_sel:[1,0,0]
	v_lshlrev_b32_e32 v178, 16, v84
	v_and_b32_e32 v179, 0xffff0000, v84
	v_cvt_pk_bf16_f32 v40, v106, v107
	v_cvt_pk_bf16_f32 v42, v56, v57
	v_cvt_pk_bf16_f32 v43, v46, v47
	v_add3_u32 v44, 0, v44, v192
	v_bitop3_b32 v168, v172, 8, s0 bitop3:0x36
	v_mov_b32_e32 v169, v193
	v_pk_fma_f32 v[182:183], v[156:157], v[178:179], v[182:183] op_sel_hi:[0,1,1]
	v_pk_fma_f32 v[174:175], v[156:157], v[178:179], v[174:175] op_sel:[1,0,0]
	v_lshlrev_b32_e32 v178, 16, v80
	v_and_b32_e32 v179, 0xffff0000, v80
	ds_write_b128 v44, v[40:43]
	v_cvt_pk_bf16_f32 v40, v0, v1
	v_cvt_pk_bf16_f32 v41, v48, v49
	v_cvt_pk_bf16_f32 v42, v52, v53
	v_cvt_pk_bf16_f32 v43, v50, v51
	v_lshlrev_b64 v[0:1], 12, v[168:169]
	v_pk_fma_f32 v[174:175], v[158:159], v[178:179], v[174:175] op_sel:[1,0,0]
	ds_write_b128 v44, v[40:43] offset:512
	v_lshl_add_u64 v[0:1], v[162:163], 0, v[0:1]
	v_lshlrev_b32_e32 v132, 16, v133
	v_and_b32_e32 v133, 0xffff0000, v133
	v_pk_fma_f32 v[182:183], v[158:159], v[178:179], v[182:183] op_sel_hi:[0,1,1]
	v_pk_mul_f32 v[178:179], v[10:11], v[174:175]
	v_pk_mul_f32 v[174:175], v[160:161], v[174:175]
	global_load_dwordx4 v[140:143], v[0:1], off sc1
	global_load_dwordx4 v[136:139], v[0:1], off offset:512 sc1
	global_load_dwordx4 v[124:127], v[0:1], off offset:1024 sc1
	global_load_dwordx4 v[120:123], v[0:1], off offset:1536 sc1
	global_load_dwordx4 v[116:119], v[0:1], off offset:2048 sc1
	global_load_dwordx4 v[112:115], v[0:1], off offset:2560 sc1
	global_load_dwordx4 v[108:111], v[0:1], off offset:3072 sc1
	global_load_dwordx4 v[104:107], v[0:1], off offset:3584 sc1
	v_lshlrev_b32_e32 v128, 16, v129
	v_and_b32_e32 v129, 0xffff0000, v129
	v_pk_fma_f32 v[178:179], v[160:161], v[182:183], v[178:179] neg_lo:[0,0,1] neg_hi:[0,0,1]
	v_pk_fma_f32 v[174:175], v[10:11], v[182:183], v[174:175]
	v_pk_fma_f32 v[182:183], v[144:145], v[132:133], 0 op_sel_hi:[0,1,0]
	v_pk_fma_f32 v[132:133], v[144:145], v[132:133], 0 op_sel:[1,0,0] op_sel_hi:[1,1,0]
	v_pk_fma_f32 v[182:183], v[146:147], v[128:129], v[182:183] op_sel_hi:[0,1,1]
	v_pk_fma_f32 v[128:129], v[146:147], v[128:129], v[132:133] op_sel:[1,0,0]
	v_lshlrev_b32_e32 v100, 16, v101
	v_and_b32_e32 v101, 0xffff0000, v101
	v_pk_fma_f32 v[132:133], v[148:149], v[100:101], v[182:183] op_sel_hi:[0,1,1]
	v_pk_fma_f32 v[100:101], v[148:149], v[100:101], v[128:129] op_sel:[1,0,0]
	v_lshlrev_b32_e32 v96, 16, v97
	v_and_b32_e32 v97, 0xffff0000, v97
	v_pk_fma_f32 v[128:129], v[150:151], v[96:97], v[132:133] op_sel_hi:[0,1,1]
	v_pk_fma_f32 v[96:97], v[150:151], v[96:97], v[100:101] op_sel:[1,0,0]
	v_lshlrev_b32_e32 v92, 16, v93
	v_and_b32_e32 v93, 0xffff0000, v93
	v_pk_fma_f32 v[100:101], v[152:153], v[92:93], v[128:129] op_sel_hi:[0,1,1]
	v_pk_fma_f32 v[92:93], v[152:153], v[92:93], v[96:97] op_sel:[1,0,0]
	v_lshlrev_b32_e32 v88, 16, v89
	v_and_b32_e32 v89, 0xffff0000, v89
	v_pk_fma_f32 v[96:97], v[154:155], v[88:89], v[100:101] op_sel_hi:[0,1,1]
	v_pk_fma_f32 v[88:89], v[154:155], v[88:89], v[92:93] op_sel:[1,0,0]
	v_lshlrev_b32_e32 v84, 16, v85
	v_and_b32_e32 v85, 0xffff0000, v85
	v_pk_fma_f32 v[92:93], v[156:157], v[84:85], v[96:97] op_sel_hi:[0,1,1]
	v_pk_fma_f32 v[84:85], v[156:157], v[84:85], v[88:89] op_sel:[1,0,0]
	v_lshlrev_b32_e32 v80, 16, v81
	v_and_b32_e32 v81, 0xffff0000, v81
	v_pk_fma_f32 v[88:89], v[158:159], v[80:81], v[92:93] op_sel_hi:[0,1,1]
	v_pk_fma_f32 v[80:81], v[158:159], v[80:81], v[84:85] op_sel:[1,0,0]
	v_lshlrev_b32_e32 v176, 16, v134
	v_and_b32_e32 v177, 0xffff0000, v134
	v_pk_mul_f32 v[84:85], v[14:15], v[80:81]
	v_pk_mul_f32 v[80:81], v[8:9], v[80:81]
	v_lshlrev_b32_e32 v180, 16, v130
	v_and_b32_e32 v181, 0xffff0000, v130
	v_pk_fma_f32 v[84:85], v[8:9], v[88:89], v[84:85] neg_lo:[0,0,1] neg_hi:[0,0,1]
	v_pk_fma_f32 v[88:89], v[14:15], v[88:89], v[80:81]
	v_pk_fma_f32 v[80:81], v[144:145], v[176:177], 0 op_sel_hi:[0,1,0]
	v_pk_fma_f32 v[92:93], v[144:145], v[176:177], 0 op_sel:[1,0,0] op_sel_hi:[1,1,0]
	v_pk_fma_f32 v[80:81], v[146:147], v[180:181], v[80:81] op_sel_hi:[0,1,1]
	v_pk_fma_f32 v[92:93], v[146:147], v[180:181], v[92:93] op_sel:[1,0,0]
	v_lshlrev_b32_e32 v96, 16, v102
	v_and_b32_e32 v97, 0xffff0000, v102
	v_pk_fma_f32 v[80:81], v[148:149], v[96:97], v[80:81] op_sel_hi:[0,1,1]
	v_pk_fma_f32 v[92:93], v[148:149], v[96:97], v[92:93] op_sel:[1,0,0]
	v_lshlrev_b32_e32 v96, 16, v98
	v_and_b32_e32 v97, 0xffff0000, v98
	v_pk_fma_f32 v[80:81], v[150:151], v[96:97], v[80:81] op_sel_hi:[0,1,1]
	v_pk_fma_f32 v[92:93], v[150:151], v[96:97], v[92:93] op_sel:[1,0,0]
	v_lshlrev_b32_e32 v96, 16, v94
	v_and_b32_e32 v97, 0xffff0000, v94
	v_pk_fma_f32 v[80:81], v[152:153], v[96:97], v[80:81] op_sel_hi:[0,1,1]
	v_pk_fma_f32 v[92:93], v[152:153], v[96:97], v[92:93] op_sel:[1,0,0]
	v_lshlrev_b32_e32 v96, 16, v90
	v_and_b32_e32 v97, 0xffff0000, v90
	v_pk_fma_f32 v[80:81], v[154:155], v[96:97], v[80:81] op_sel_hi:[0,1,1]
	v_pk_fma_f32 v[92:93], v[154:155], v[96:97], v[92:93] op_sel:[1,0,0]
	v_lshlrev_b32_e32 v96, 16, v86
	v_and_b32_e32 v97, 0xffff0000, v86
	v_pk_fma_f32 v[80:81], v[156:157], v[96:97], v[80:81] op_sel_hi:[0,1,1]
	v_pk_fma_f32 v[92:93], v[156:157], v[96:97], v[92:93] op_sel:[1,0,0]
	v_lshlrev_b32_e32 v96, 16, v82
	v_and_b32_e32 v97, 0xffff0000, v82
	v_pk_fma_f32 v[92:93], v[158:159], v[96:97], v[92:93] op_sel:[1,0,0]
	v_lshlrev_b32_e32 v134, 16, v135
	v_and_b32_e32 v135, 0xffff0000, v135
	v_pk_fma_f32 v[80:81], v[158:159], v[96:97], v[80:81] op_sel_hi:[0,1,1]
	v_pk_mul_f32 v[96:97], v[6:7], v[92:93]
	v_pk_mul_f32 v[92:93], v[12:13], v[92:93]
	v_lshlrev_b32_e32 v130, 16, v131
	v_and_b32_e32 v131, 0xffff0000, v131
	v_pk_fma_f32 v[96:97], v[12:13], v[80:81], v[96:97] neg_lo:[0,0,1] neg_hi:[0,0,1]
	v_pk_fma_f32 v[92:93], v[6:7], v[80:81], v[92:93]
	v_pk_fma_f32 v[80:81], v[144:145], v[134:135], 0 op_sel_hi:[0,1,0]
	v_pk_fma_f32 v[100:101], v[144:145], v[134:135], 0 op_sel:[1,0,0] op_sel_hi:[1,1,0]
	v_pk_fma_f32 v[80:81], v[146:147], v[130:131], v[80:81] op_sel_hi:[0,1,1]
	v_pk_fma_f32 v[100:101], v[146:147], v[130:131], v[100:101] op_sel:[1,0,0]
	v_lshlrev_b32_e32 v102, 16, v103
	v_and_b32_e32 v103, 0xffff0000, v103
	v_pk_fma_f32 v[80:81], v[148:149], v[102:103], v[80:81] op_sel_hi:[0,1,1]
	v_pk_fma_f32 v[100:101], v[148:149], v[102:103], v[100:101] op_sel:[1,0,0]
	v_lshlrev_b32_e32 v98, 16, v99
	v_and_b32_e32 v99, 0xffff0000, v99
	v_pk_fma_f32 v[80:81], v[150:151], v[98:99], v[80:81] op_sel_hi:[0,1,1]
	v_pk_fma_f32 v[98:99], v[150:151], v[98:99], v[100:101] op_sel:[1,0,0]
	v_lshlrev_b32_e32 v94, 16, v95
	v_and_b32_e32 v95, 0xffff0000, v95
	v_pk_fma_f32 v[80:81], v[152:153], v[94:95], v[80:81] op_sel_hi:[0,1,1]
	v_pk_fma_f32 v[94:95], v[152:153], v[94:95], v[98:99] op_sel:[1,0,0]
	v_lshlrev_b32_e32 v90, 16, v91
	v_and_b32_e32 v91, 0xffff0000, v91
	v_pk_fma_f32 v[80:81], v[154:155], v[90:91], v[80:81] op_sel_hi:[0,1,1]
	v_pk_fma_f32 v[90:91], v[154:155], v[90:91], v[94:95] op_sel:[1,0,0]
	v_lshlrev_b32_e32 v86, 16, v87
	v_and_b32_e32 v87, 0xffff0000, v87
	v_pk_fma_f32 v[80:81], v[156:157], v[86:87], v[80:81] op_sel_hi:[0,1,1]
	v_pk_fma_f32 v[86:87], v[156:157], v[86:87], v[90:91] op_sel:[1,0,0]
	v_lshlrev_b32_e32 v82, 16, v83
	v_and_b32_e32 v83, 0xffff0000, v83
	v_readlane_b32 s0, v253, 49
	v_pk_fma_f32 v[80:81], v[158:159], v[82:83], v[80:81] op_sel_hi:[0,1,1]
	v_pk_fma_f32 v[82:83], v[158:159], v[82:83], v[86:87] op_sel:[1,0,0]
	v_or_b32_e32 v0, s0, v172
	v_mov_b32_e32 v1, v193
	v_pk_mul_f32 v[86:87], v[2:3], v[82:83]
	v_lshlrev_b64 v[40:41], 12, v[0:1]
	v_pk_fma_f32 v[86:87], v[4:5], v[80:81], v[86:87] neg_lo:[0,0,1] neg_hi:[0,0,1]
	v_pk_mul_f32 v[82:83], v[4:5], v[82:83]
	v_mul_lo_u32 v1, v166, s6
	v_lshl_add_u64 v[40:41], v[162:163], 0, v[40:41]
	v_pk_fma_f32 v[90:91], v[2:3], v[80:81], v[82:83]
	v_cvt_pk_bf16_f32 v80, v178, v179
	v_cvt_pk_bf16_f32 v81, v84, v85
	v_cvt_pk_bf16_f32 v82, v96, v97
	v_cvt_pk_bf16_f32 v83, v86, v87
	v_add3_u32 v1, 0, v1, v192
	global_load_dwordx4 v[76:79], v[40:41], off sc1
	global_load_dwordx4 v[72:75], v[40:41], off offset:512 sc1
	global_load_dwordx4 v[60:63], v[40:41], off offset:1024 sc1
	global_load_dwordx4 v[56:59], v[40:41], off offset:1536 sc1
	global_load_dwordx4 v[52:55], v[40:41], off offset:2048 sc1
	global_load_dwordx4 v[48:51], v[40:41], off offset:2560 sc1
	global_load_dwordx4 v[44:47], v[40:41], off offset:3072 sc1
	s_nop 0
	global_load_dwordx4 v[40:43], v[40:41], off offset:3584 sc1
	ds_write_b128 v1, v[80:83]
	v_cvt_pk_bf16_f32 v80, v174, v175
	v_cvt_pk_bf16_f32 v81, v88, v89
	v_cvt_pk_bf16_f32 v82, v92, v93
	v_cvt_pk_bf16_f32 v83, v90, v91
	ds_write_b128 v1, v[80:83] offset:512
	v_lshlrev_b32_e32 v80, 16, v68
	v_and_b32_e32 v81, 0xffff0000, v68
	v_lshlrev_b32_e32 v84, 16, v64
	v_and_b32_e32 v85, 0xffff0000, v64
	v_pk_fma_f32 v[88:89], v[144:145], v[80:81], 0 op_sel_hi:[0,1,0]
	v_pk_fma_f32 v[80:81], v[144:145], v[80:81], 0 op_sel:[1,0,0] op_sel_hi:[1,1,0]
	v_pk_fma_f32 v[88:89], v[146:147], v[84:85], v[88:89] op_sel_hi:[0,1,1]
	v_pk_fma_f32 v[80:81], v[146:147], v[84:85], v[80:81] op_sel:[1,0,0]
	v_lshlrev_b32_e32 v84, 16, v36
	v_and_b32_e32 v85, 0xffff0000, v36
	v_pk_fma_f32 v[88:89], v[148:149], v[84:85], v[88:89] op_sel_hi:[0,1,1]
	v_pk_fma_f32 v[80:81], v[148:149], v[84:85], v[80:81] op_sel:[1,0,0]
	v_lshlrev_b32_e32 v84, 16, v32
	v_and_b32_e32 v85, 0xffff0000, v32
	v_pk_fma_f32 v[88:89], v[150:151], v[84:85], v[88:89] op_sel_hi:[0,1,1]
	v_pk_fma_f32 v[80:81], v[150:151], v[84:85], v[80:81] op_sel:[1,0,0]
	v_lshlrev_b32_e32 v84, 16, v28
	v_and_b32_e32 v85, 0xffff0000, v28
	v_pk_fma_f32 v[88:89], v[152:153], v[84:85], v[88:89] op_sel_hi:[0,1,1]
	v_pk_fma_f32 v[80:81], v[152:153], v[84:85], v[80:81] op_sel:[1,0,0]
	v_lshlrev_b32_e32 v84, 16, v24
	v_and_b32_e32 v85, 0xffff0000, v24
	v_pk_fma_f32 v[88:89], v[154:155], v[84:85], v[88:89] op_sel_hi:[0,1,1]
	v_pk_fma_f32 v[80:81], v[154:155], v[84:85], v[80:81] op_sel:[1,0,0]
	v_lshlrev_b32_e32 v84, 16, v20
	v_and_b32_e32 v85, 0xffff0000, v20
	v_pk_fma_f32 v[88:89], v[156:157], v[84:85], v[88:89] op_sel_hi:[0,1,1]
	v_pk_fma_f32 v[80:81], v[156:157], v[84:85], v[80:81] op_sel:[1,0,0]
	v_lshlrev_b32_e32 v84, 16, v16
	v_and_b32_e32 v85, 0xffff0000, v16
	v_pk_fma_f32 v[80:81], v[158:159], v[84:85], v[80:81] op_sel:[1,0,0]
	v_lshlrev_b32_e32 v68, 16, v69
	v_and_b32_e32 v69, 0xffff0000, v69
	v_pk_fma_f32 v[88:89], v[158:159], v[84:85], v[88:89] op_sel_hi:[0,1,1]
	v_pk_mul_f32 v[84:85], v[10:11], v[80:81]
	v_pk_mul_f32 v[80:81], v[160:161], v[80:81]
	v_lshlrev_b32_e32 v64, 16, v65
	v_and_b32_e32 v65, 0xffff0000, v65
	v_pk_fma_f32 v[84:85], v[160:161], v[88:89], v[84:85] neg_lo:[0,0,1] neg_hi:[0,0,1]
	v_pk_fma_f32 v[80:81], v[10:11], v[88:89], v[80:81]
	v_pk_fma_f32 v[88:89], v[144:145], v[68:69], 0 op_sel_hi:[0,1,0]
	v_pk_fma_f32 v[68:69], v[144:145], v[68:69], 0 op_sel:[1,0,0] op_sel_hi:[1,1,0]
	v_pk_fma_f32 v[88:89], v[146:147], v[64:65], v[88:89] op_sel_hi:[0,1,1]
	v_pk_fma_f32 v[64:65], v[146:147], v[64:65], v[68:69] op_sel:[1,0,0]
	v_lshlrev_b32_e32 v36, 16, v37
	v_and_b32_e32 v37, 0xffff0000, v37
	v_pk_fma_f32 v[68:69], v[148:149], v[36:37], v[88:89] op_sel_hi:[0,1,1]
	v_pk_fma_f32 v[36:37], v[148:149], v[36:37], v[64:65] op_sel:[1,0,0]
	v_lshlrev_b32_e32 v32, 16, v33
	v_and_b32_e32 v33, 0xffff0000, v33
	v_pk_fma_f32 v[64:65], v[150:151], v[32:33], v[68:69] op_sel_hi:[0,1,1]
	v_pk_fma_f32 v[32:33], v[150:151], v[32:33], v[36:37] op_sel:[1,0,0]
	v_lshlrev_b32_e32 v28, 16, v29
	v_and_b32_e32 v29, 0xffff0000, v29
	v_pk_fma_f32 v[36:37], v[152:153], v[28:29], v[64:65] op_sel_hi:[0,1,1]
	v_pk_fma_f32 v[28:29], v[152:153], v[28:29], v[32:33] op_sel:[1,0,0]
	v_lshlrev_b32_e32 v24, 16, v25
	v_and_b32_e32 v25, 0xffff0000, v25
	v_pk_fma_f32 v[32:33], v[154:155], v[24:25], v[36:37] op_sel_hi:[0,1,1]
	v_pk_fma_f32 v[24:25], v[154:155], v[24:25], v[28:29] op_sel:[1,0,0]
	v_lshlrev_b32_e32 v20, 16, v21
	v_and_b32_e32 v21, 0xffff0000, v21
	v_pk_fma_f32 v[28:29], v[156:157], v[20:21], v[32:33] op_sel_hi:[0,1,1]
	v_pk_fma_f32 v[20:21], v[156:157], v[20:21], v[24:25] op_sel:[1,0,0]
	v_lshlrev_b32_e32 v16, 16, v17
	v_and_b32_e32 v17, 0xffff0000, v17
	v_pk_fma_f32 v[24:25], v[158:159], v[16:17], v[28:29] op_sel_hi:[0,1,1]
	v_pk_fma_f32 v[16:17], v[158:159], v[16:17], v[20:21] op_sel:[1,0,0]
	v_lshlrev_b32_e32 v82, 16, v70
	v_and_b32_e32 v83, 0xffff0000, v70
	v_pk_mul_f32 v[20:21], v[14:15], v[16:17]
	v_pk_mul_f32 v[16:17], v[8:9], v[16:17]
	v_lshlrev_b32_e32 v86, 16, v66
	v_and_b32_e32 v87, 0xffff0000, v66
	v_pk_fma_f32 v[20:21], v[8:9], v[24:25], v[20:21] neg_lo:[0,0,1] neg_hi:[0,0,1]
	v_pk_fma_f32 v[24:25], v[14:15], v[24:25], v[16:17]
	v_pk_fma_f32 v[16:17], v[144:145], v[82:83], 0 op_sel_hi:[0,1,0]
	v_pk_fma_f32 v[28:29], v[144:145], v[82:83], 0 op_sel:[1,0,0] op_sel_hi:[1,1,0]
	v_pk_fma_f32 v[16:17], v[146:147], v[86:87], v[16:17] op_sel_hi:[0,1,1]
	v_pk_fma_f32 v[28:29], v[146:147], v[86:87], v[28:29] op_sel:[1,0,0]
	v_lshlrev_b32_e32 v32, 16, v38
	v_and_b32_e32 v33, 0xffff0000, v38
	v_pk_fma_f32 v[16:17], v[148:149], v[32:33], v[16:17] op_sel_hi:[0,1,1]
	v_pk_fma_f32 v[28:29], v[148:149], v[32:33], v[28:29] op_sel:[1,0,0]
	v_lshlrev_b32_e32 v32, 16, v34
	v_and_b32_e32 v33, 0xffff0000, v34
	v_pk_fma_f32 v[16:17], v[150:151], v[32:33], v[16:17] op_sel_hi:[0,1,1]
	v_pk_fma_f32 v[28:29], v[150:151], v[32:33], v[28:29] op_sel:[1,0,0]
	v_lshlrev_b32_e32 v32, 16, v30
	v_and_b32_e32 v33, 0xffff0000, v30
	v_pk_fma_f32 v[16:17], v[152:153], v[32:33], v[16:17] op_sel_hi:[0,1,1]
	v_pk_fma_f32 v[28:29], v[152:153], v[32:33], v[28:29] op_sel:[1,0,0]
	v_lshlrev_b32_e32 v32, 16, v26
	v_and_b32_e32 v33, 0xffff0000, v26
	v_pk_fma_f32 v[16:17], v[154:155], v[32:33], v[16:17] op_sel_hi:[0,1,1]
	v_pk_fma_f32 v[28:29], v[154:155], v[32:33], v[28:29] op_sel:[1,0,0]
	v_lshlrev_b32_e32 v32, 16, v22
	v_and_b32_e32 v33, 0xffff0000, v22
	v_pk_fma_f32 v[16:17], v[156:157], v[32:33], v[16:17] op_sel_hi:[0,1,1]
	v_pk_fma_f32 v[28:29], v[156:157], v[32:33], v[28:29] op_sel:[1,0,0]
	v_lshlrev_b32_e32 v32, 16, v18
	v_and_b32_e32 v33, 0xffff0000, v18
	v_pk_fma_f32 v[28:29], v[158:159], v[32:33], v[28:29] op_sel:[1,0,0]
	v_lshlrev_b32_e32 v70, 16, v71
	v_and_b32_e32 v71, 0xffff0000, v71
	v_pk_fma_f32 v[16:17], v[158:159], v[32:33], v[16:17] op_sel_hi:[0,1,1]
	v_pk_mul_f32 v[32:33], v[6:7], v[28:29]
	v_pk_mul_f32 v[28:29], v[12:13], v[28:29]
	v_lshlrev_b32_e32 v66, 16, v67
	v_and_b32_e32 v67, 0xffff0000, v67
	v_pk_fma_f32 v[32:33], v[12:13], v[16:17], v[32:33] neg_lo:[0,0,1] neg_hi:[0,0,1]
	v_pk_fma_f32 v[28:29], v[6:7], v[16:17], v[28:29]
	v_pk_fma_f32 v[16:17], v[144:145], v[70:71], 0 op_sel_hi:[0,1,0]
	v_pk_fma_f32 v[36:37], v[144:145], v[70:71], 0 op_sel:[1,0,0] op_sel_hi:[1,1,0]
	v_pk_fma_f32 v[16:17], v[146:147], v[66:67], v[16:17] op_sel_hi:[0,1,1]
	v_pk_fma_f32 v[36:37], v[146:147], v[66:67], v[36:37] op_sel:[1,0,0]
	v_lshlrev_b32_e32 v38, 16, v39
	v_and_b32_e32 v39, 0xffff0000, v39
	v_pk_fma_f32 v[16:17], v[148:149], v[38:39], v[16:17] op_sel_hi:[0,1,1]
	v_pk_fma_f32 v[36:37], v[148:149], v[38:39], v[36:37] op_sel:[1,0,0]
	v_lshlrev_b32_e32 v34, 16, v35
	v_and_b32_e32 v35, 0xffff0000, v35
	v_pk_fma_f32 v[16:17], v[150:151], v[34:35], v[16:17] op_sel_hi:[0,1,1]
	v_pk_fma_f32 v[34:35], v[150:151], v[34:35], v[36:37] op_sel:[1,0,0]
	v_lshlrev_b32_e32 v30, 16, v31
	v_and_b32_e32 v31, 0xffff0000, v31
	v_pk_fma_f32 v[16:17], v[152:153], v[30:31], v[16:17] op_sel_hi:[0,1,1]
	v_pk_fma_f32 v[30:31], v[152:153], v[30:31], v[34:35] op_sel:[1,0,0]
	v_lshlrev_b32_e32 v26, 16, v27
	v_and_b32_e32 v27, 0xffff0000, v27
	v_pk_fma_f32 v[16:17], v[154:155], v[26:27], v[16:17] op_sel_hi:[0,1,1]
	v_pk_fma_f32 v[26:27], v[154:155], v[26:27], v[30:31] op_sel:[1,0,0]
	v_lshlrev_b32_e32 v22, 16, v23
	v_and_b32_e32 v23, 0xffff0000, v23
	v_pk_fma_f32 v[16:17], v[156:157], v[22:23], v[16:17] op_sel_hi:[0,1,1]
	v_pk_fma_f32 v[22:23], v[156:157], v[22:23], v[26:27] op_sel:[1,0,0]
	v_lshlrev_b32_e32 v18, 16, v19
	v_and_b32_e32 v19, 0xffff0000, v19
	v_pk_fma_f32 v[16:17], v[158:159], v[18:19], v[16:17] op_sel_hi:[0,1,1]
	v_pk_fma_f32 v[18:19], v[158:159], v[18:19], v[22:23] op_sel:[1,0,0]
	v_mul_lo_u32 v1, v164, s6
	v_pk_mul_f32 v[22:23], v[2:3], v[18:19]
	v_pk_mul_f32 v[18:19], v[4:5], v[18:19]
	v_pk_fma_f32 v[22:23], v[4:5], v[16:17], v[22:23] neg_lo:[0,0,1] neg_hi:[0,0,1]
	v_pk_fma_f32 v[26:27], v[2:3], v[16:17], v[18:19]
	v_cvt_pk_bf16_f32 v16, v84, v85
	v_cvt_pk_bf16_f32 v17, v20, v21
	v_cvt_pk_bf16_f32 v18, v32, v33
	v_cvt_pk_bf16_f32 v19, v22, v23
	v_add3_u32 v1, 0, v1, v192
	v_readlane_b32 s0, v253, 50
	ds_write_b128 v1, v[16:19]
	v_cvt_pk_bf16_f32 v16, v80, v81
	v_cvt_pk_bf16_f32 v17, v24, v25
	v_cvt_pk_bf16_f32 v18, v28, v29
	v_cvt_pk_bf16_f32 v19, v26, v27
	v_or_b32_e32 v166, s0, v172
	ds_write_b128 v1, v[16:19] offset:512
	v_lshlrev_b64 v[16:17], 12, v[166:167]
	v_readlane_b32 s0, v253, 52
	v_lshl_add_u64 v[16:17], v[162:163], 0, v[16:17]
	global_load_dwordx4 v[132:135], v[16:17], off sc1
	global_load_dwordx4 v[128:131], v[16:17], off offset:512 sc1
	global_load_dwordx4 v[100:103], v[16:17], off offset:1024 sc1
	global_load_dwordx4 v[96:99], v[16:17], off offset:1536 sc1
	global_load_dwordx4 v[92:95], v[16:17], off offset:2048 sc1
	global_load_dwordx4 v[88:91], v[16:17], off offset:2560 sc1
	global_load_dwordx4 v[84:87], v[16:17], off offset:3072 sc1
	global_load_dwordx4 v[80:83], v[16:17], off offset:3584 sc1
	v_or_b32_e32 v164, s0, v172
	v_lshlrev_b64 v[16:17], 12, v[164:165]
	v_lshl_add_u64 v[16:17], v[162:163], 0, v[16:17]
	s_waitcnt vmcnt(23)
	v_lshlrev_b32_e32 v162, 16, v140
	v_and_b32_e32 v163, 0xffff0000, v140
	s_waitcnt vmcnt(22)
	v_lshlrev_b32_e32 v174, 16, v136
	v_and_b32_e32 v175, 0xffff0000, v136
	v_pk_fma_f32 v[178:179], v[144:145], v[162:163], 0 op_sel_hi:[0,1,0]
	v_pk_fma_f32 v[162:163], v[144:145], v[162:163], 0 op_sel:[1,0,0] op_sel_hi:[1,1,0]
	v_pk_fma_f32 v[178:179], v[146:147], v[174:175], v[178:179] op_sel_hi:[0,1,1]
	v_pk_fma_f32 v[162:163], v[146:147], v[174:175], v[162:163] op_sel:[1,0,0]
	s_waitcnt vmcnt(21)
	v_lshlrev_b32_e32 v174, 16, v124
	v_and_b32_e32 v175, 0xffff0000, v124
	v_pk_fma_f32 v[178:179], v[148:149], v[174:175], v[178:179] op_sel_hi:[0,1,1]
	v_pk_fma_f32 v[162:163], v[148:149], v[174:175], v[162:163] op_sel:[1,0,0]
	s_waitcnt vmcnt(20)
	v_lshlrev_b32_e32 v174, 16, v120
	v_and_b32_e32 v175, 0xffff0000, v120
	v_pk_fma_f32 v[178:179], v[150:151], v[174:175], v[178:179] op_sel_hi:[0,1,1]
	v_pk_fma_f32 v[162:163], v[150:151], v[174:175], v[162:163] op_sel:[1,0,0]
	s_waitcnt vmcnt(19)
	v_lshlrev_b32_e32 v174, 16, v116
	v_and_b32_e32 v175, 0xffff0000, v116
	v_pk_fma_f32 v[178:179], v[152:153], v[174:175], v[178:179] op_sel_hi:[0,1,1]
	v_pk_fma_f32 v[162:163], v[152:153], v[174:175], v[162:163] op_sel:[1,0,0]
	s_waitcnt vmcnt(18)
	v_lshlrev_b32_e32 v174, 16, v112
	v_and_b32_e32 v175, 0xffff0000, v112
	v_pk_fma_f32 v[178:179], v[154:155], v[174:175], v[178:179] op_sel_hi:[0,1,1]
	v_pk_fma_f32 v[162:163], v[154:155], v[174:175], v[162:163] op_sel:[1,0,0]
	s_waitcnt vmcnt(17)
	v_lshlrev_b32_e32 v174, 16, v108
	v_and_b32_e32 v175, 0xffff0000, v108
	v_pk_fma_f32 v[178:179], v[156:157], v[174:175], v[178:179] op_sel_hi:[0,1,1]
	v_pk_fma_f32 v[162:163], v[156:157], v[174:175], v[162:163] op_sel:[1,0,0]
	s_waitcnt vmcnt(16)
	v_lshlrev_b32_e32 v174, 16, v104
	v_and_b32_e32 v175, 0xffff0000, v104
	v_pk_fma_f32 v[162:163], v[158:159], v[174:175], v[162:163] op_sel:[1,0,0]
	v_lshlrev_b32_e32 v140, 16, v141
	v_and_b32_e32 v141, 0xffff0000, v141
	v_pk_fma_f32 v[178:179], v[158:159], v[174:175], v[178:179] op_sel_hi:[0,1,1]
	v_pk_mul_f32 v[174:175], v[10:11], v[162:163]
	v_pk_mul_f32 v[162:163], v[160:161], v[162:163]
	v_lshlrev_b32_e32 v136, 16, v137
	v_and_b32_e32 v137, 0xffff0000, v137
	v_pk_fma_f32 v[174:175], v[160:161], v[178:179], v[174:175] neg_lo:[0,0,1] neg_hi:[0,0,1]
	v_pk_fma_f32 v[162:163], v[10:11], v[178:179], v[162:163]
	v_pk_fma_f32 v[178:179], v[144:145], v[140:141], 0 op_sel_hi:[0,1,0]
	v_pk_fma_f32 v[140:141], v[144:145], v[140:141], 0 op_sel:[1,0,0] op_sel_hi:[1,1,0]
	v_pk_fma_f32 v[178:179], v[146:147], v[136:137], v[178:179] op_sel_hi:[0,1,1]
	v_pk_fma_f32 v[136:137], v[146:147], v[136:137], v[140:141] op_sel:[1,0,0]
	v_lshlrev_b32_e32 v124, 16, v125
	v_and_b32_e32 v125, 0xffff0000, v125
	v_pk_fma_f32 v[140:141], v[148:149], v[124:125], v[178:179] op_sel_hi:[0,1,1]
	v_pk_fma_f32 v[124:125], v[148:149], v[124:125], v[136:137] op_sel:[1,0,0]
	v_lshlrev_b32_e32 v120, 16, v121
	v_and_b32_e32 v121, 0xffff0000, v121
	v_pk_fma_f32 v[136:137], v[150:151], v[120:121], v[140:141] op_sel_hi:[0,1,1]
	v_pk_fma_f32 v[120:121], v[150:151], v[120:121], v[124:125] op_sel:[1,0,0]
	v_lshlrev_b32_e32 v116, 16, v117
	v_and_b32_e32 v117, 0xffff0000, v117
	v_pk_fma_f32 v[124:125], v[152:153], v[116:117], v[136:137] op_sel_hi:[0,1,1]
	v_pk_fma_f32 v[116:117], v[152:153], v[116:117], v[120:121] op_sel:[1,0,0]
	v_lshlrev_b32_e32 v112, 16, v113
	v_and_b32_e32 v113, 0xffff0000, v113
	v_pk_fma_f32 v[120:121], v[154:155], v[112:113], v[124:125] op_sel_hi:[0,1,1]
	v_pk_fma_f32 v[112:113], v[154:155], v[112:113], v[116:117] op_sel:[1,0,0]
	v_lshlrev_b32_e32 v108, 16, v109
	v_and_b32_e32 v109, 0xffff0000, v109
	v_pk_fma_f32 v[116:117], v[156:157], v[108:109], v[120:121] op_sel_hi:[0,1,1]
	v_pk_fma_f32 v[108:109], v[156:157], v[108:109], v[112:113] op_sel:[1,0,0]
	v_lshlrev_b32_e32 v104, 16, v105
	v_and_b32_e32 v105, 0xffff0000, v105
	v_pk_fma_f32 v[112:113], v[158:159], v[104:105], v[116:117] op_sel_hi:[0,1,1]
	v_pk_fma_f32 v[104:105], v[158:159], v[104:105], v[108:109] op_sel:[1,0,0]
	v_lshlrev_b32_e32 v172, 16, v142
	v_and_b32_e32 v173, 0xffff0000, v142
	v_pk_mul_f32 v[108:109], v[14:15], v[104:105]
	v_pk_mul_f32 v[104:105], v[8:9], v[104:105]
	v_lshlrev_b32_e32 v176, 16, v138
	v_and_b32_e32 v177, 0xffff0000, v138
	v_pk_fma_f32 v[108:109], v[8:9], v[112:113], v[108:109] neg_lo:[0,0,1] neg_hi:[0,0,1]
	v_pk_fma_f32 v[112:113], v[14:15], v[112:113], v[104:105]
	v_pk_fma_f32 v[104:105], v[144:145], v[172:173], 0 op_sel_hi:[0,1,0]
	v_pk_fma_f32 v[116:117], v[144:145], v[172:173], 0 op_sel:[1,0,0] op_sel_hi:[1,1,0]
	v_pk_fma_f32 v[104:105], v[146:147], v[176:177], v[104:105] op_sel_hi:[0,1,1]
	v_pk_fma_f32 v[116:117], v[146:147], v[176:177], v[116:117] op_sel:[1,0,0]
	v_lshlrev_b32_e32 v120, 16, v126
	v_and_b32_e32 v121, 0xffff0000, v126
	v_pk_fma_f32 v[104:105], v[148:149], v[120:121], v[104:105] op_sel_hi:[0,1,1]
	v_pk_fma_f32 v[116:117], v[148:149], v[120:121], v[116:117] op_sel:[1,0,0]
	v_lshlrev_b32_e32 v120, 16, v122
	v_and_b32_e32 v121, 0xffff0000, v122
	v_pk_fma_f32 v[104:105], v[150:151], v[120:121], v[104:105] op_sel_hi:[0,1,1]
	v_pk_fma_f32 v[116:117], v[150:151], v[120:121], v[116:117] op_sel:[1,0,0]
	v_lshlrev_b32_e32 v120, 16, v118
	v_and_b32_e32 v121, 0xffff0000, v118
	v_pk_fma_f32 v[104:105], v[152:153], v[120:121], v[104:105] op_sel_hi:[0,1,1]
	v_pk_fma_f32 v[116:117], v[152:153], v[120:121], v[116:117] op_sel:[1,0,0]
	v_lshlrev_b32_e32 v120, 16, v114
	v_and_b32_e32 v121, 0xffff0000, v114
	v_pk_fma_f32 v[104:105], v[154:155], v[120:121], v[104:105] op_sel_hi:[0,1,1]
	v_pk_fma_f32 v[116:117], v[154:155], v[120:121], v[116:117] op_sel:[1,0,0]
	v_lshlrev_b32_e32 v120, 16, v110
	v_and_b32_e32 v121, 0xffff0000, v110
	v_pk_fma_f32 v[104:105], v[156:157], v[120:121], v[104:105] op_sel_hi:[0,1,1]
	v_pk_fma_f32 v[116:117], v[156:157], v[120:121], v[116:117] op_sel:[1,0,0]
	v_lshlrev_b32_e32 v120, 16, v106
	v_and_b32_e32 v121, 0xffff0000, v106
	v_pk_fma_f32 v[116:117], v[158:159], v[120:121], v[116:117] op_sel:[1,0,0]
	v_lshlrev_b32_e32 v142, 16, v143
	v_and_b32_e32 v143, 0xffff0000, v143
	v_pk_fma_f32 v[104:105], v[158:159], v[120:121], v[104:105] op_sel_hi:[0,1,1]
	v_pk_mul_f32 v[120:121], v[6:7], v[116:117]
	v_pk_mul_f32 v[116:117], v[12:13], v[116:117]
	v_lshlrev_b32_e32 v138, 16, v139
	v_and_b32_e32 v139, 0xffff0000, v139
	v_pk_fma_f32 v[120:121], v[12:13], v[104:105], v[120:121] neg_lo:[0,0,1] neg_hi:[0,0,1]
	v_pk_fma_f32 v[116:117], v[6:7], v[104:105], v[116:117]
	v_pk_fma_f32 v[104:105], v[144:145], v[142:143], 0 op_sel_hi:[0,1,0]
	v_pk_fma_f32 v[124:125], v[144:145], v[142:143], 0 op_sel:[1,0,0] op_sel_hi:[1,1,0]
	v_pk_fma_f32 v[104:105], v[146:147], v[138:139], v[104:105] op_sel_hi:[0,1,1]
	v_pk_fma_f32 v[124:125], v[146:147], v[138:139], v[124:125] op_sel:[1,0,0]
	v_lshlrev_b32_e32 v126, 16, v127
	v_and_b32_e32 v127, 0xffff0000, v127
	v_pk_fma_f32 v[104:105], v[148:149], v[126:127], v[104:105] op_sel_hi:[0,1,1]
	v_pk_fma_f32 v[124:125], v[148:149], v[126:127], v[124:125] op_sel:[1,0,0]
	v_lshlrev_b32_e32 v122, 16, v123
	v_and_b32_e32 v123, 0xffff0000, v123
	v_pk_fma_f32 v[104:105], v[150:151], v[122:123], v[104:105] op_sel_hi:[0,1,1]
	v_pk_fma_f32 v[122:123], v[150:151], v[122:123], v[124:125] op_sel:[1,0,0]
	v_lshlrev_b32_e32 v118, 16, v119
	v_and_b32_e32 v119, 0xffff0000, v119
	v_pk_fma_f32 v[104:105], v[152:153], v[118:119], v[104:105] op_sel_hi:[0,1,1]
	v_pk_fma_f32 v[118:119], v[152:153], v[118:119], v[122:123] op_sel:[1,0,0]
	v_lshlrev_b32_e32 v114, 16, v115
	v_and_b32_e32 v115, 0xffff0000, v115
	v_pk_fma_f32 v[104:105], v[154:155], v[114:115], v[104:105] op_sel_hi:[0,1,1]
	v_pk_fma_f32 v[114:115], v[154:155], v[114:115], v[118:119] op_sel:[1,0,0]
	v_lshlrev_b32_e32 v110, 16, v111
	v_and_b32_e32 v111, 0xffff0000, v111
	v_pk_fma_f32 v[104:105], v[156:157], v[110:111], v[104:105] op_sel_hi:[0,1,1]
	v_pk_fma_f32 v[110:111], v[156:157], v[110:111], v[114:115] op_sel:[1,0,0]
	v_lshlrev_b32_e32 v106, 16, v107
	v_and_b32_e32 v107, 0xffff0000, v107
	v_pk_fma_f32 v[104:105], v[158:159], v[106:107], v[104:105] op_sel_hi:[0,1,1]
	v_pk_fma_f32 v[106:107], v[158:159], v[106:107], v[110:111] op_sel:[1,0,0]
	v_mul_lo_u32 v1, v168, s6
	v_pk_mul_f32 v[110:111], v[2:3], v[106:107]
	v_pk_mul_f32 v[106:107], v[4:5], v[106:107]
	v_pk_fma_f32 v[110:111], v[4:5], v[104:105], v[110:111] neg_lo:[0,0,1] neg_hi:[0,0,1]
	v_pk_fma_f32 v[114:115], v[2:3], v[104:105], v[106:107]
	v_cvt_pk_bf16_f32 v104, v174, v175
	v_cvt_pk_bf16_f32 v105, v108, v109
	v_cvt_pk_bf16_f32 v106, v120, v121
	v_cvt_pk_bf16_f32 v107, v110, v111
	v_add3_u32 v1, 0, v1, v192
	global_load_dwordx4 v[68:71], v[16:17], off sc1
	global_load_dwordx4 v[64:67], v[16:17], off offset:512 sc1
	global_load_dwordx4 v[36:39], v[16:17], off offset:1024 sc1
	global_load_dwordx4 v[32:35], v[16:17], off offset:1536 sc1
	global_load_dwordx4 v[28:31], v[16:17], off offset:2048 sc1
	global_load_dwordx4 v[24:27], v[16:17], off offset:2560 sc1
	global_load_dwordx4 v[20:23], v[16:17], off offset:3072 sc1
	s_nop 0
	global_load_dwordx4 v[16:19], v[16:17], off offset:3584 sc1
	ds_write_b128 v1, v[104:107]
	v_cvt_pk_bf16_f32 v104, v162, v163
	v_cvt_pk_bf16_f32 v105, v112, v113
	v_cvt_pk_bf16_f32 v106, v116, v117
	v_cvt_pk_bf16_f32 v107, v114, v115
	ds_write_b128 v1, v[104:107] offset:512
	s_waitcnt vmcnt(23)
	v_lshlrev_b32_e32 v104, 16, v76
	v_and_b32_e32 v105, 0xffff0000, v76
	s_waitcnt vmcnt(22)
	v_lshlrev_b32_e32 v108, 16, v72
	v_and_b32_e32 v109, 0xffff0000, v72
	v_pk_fma_f32 v[112:113], v[144:145], v[104:105], 0 op_sel_hi:[0,1,0]
	v_pk_fma_f32 v[104:105], v[144:145], v[104:105], 0 op_sel:[1,0,0] op_sel_hi:[1,1,0]
	v_pk_fma_f32 v[112:113], v[146:147], v[108:109], v[112:113] op_sel_hi:[0,1,1]
	v_pk_fma_f32 v[104:105], v[146:147], v[108:109], v[104:105] op_sel:[1,0,0]
	s_waitcnt vmcnt(21)
	v_lshlrev_b32_e32 v108, 16, v60
	v_and_b32_e32 v109, 0xffff0000, v60
	v_pk_fma_f32 v[112:113], v[148:149], v[108:109], v[112:113] op_sel_hi:[0,1,1]
	v_pk_fma_f32 v[104:105], v[148:149], v[108:109], v[104:105] op_sel:[1,0,0]
	s_waitcnt vmcnt(20)
	v_lshlrev_b32_e32 v108, 16, v56
	v_and_b32_e32 v109, 0xffff0000, v56
	v_pk_fma_f32 v[112:113], v[150:151], v[108:109], v[112:113] op_sel_hi:[0,1,1]
	v_pk_fma_f32 v[104:105], v[150:151], v[108:109], v[104:105] op_sel:[1,0,0]
	s_waitcnt vmcnt(19)
	v_lshlrev_b32_e32 v108, 16, v52
	v_and_b32_e32 v109, 0xffff0000, v52
	v_pk_fma_f32 v[112:113], v[152:153], v[108:109], v[112:113] op_sel_hi:[0,1,1]
	v_pk_fma_f32 v[104:105], v[152:153], v[108:109], v[104:105] op_sel:[1,0,0]
	s_waitcnt vmcnt(18)
	v_lshlrev_b32_e32 v108, 16, v48
	v_and_b32_e32 v109, 0xffff0000, v48
	v_pk_fma_f32 v[112:113], v[154:155], v[108:109], v[112:113] op_sel_hi:[0,1,1]
	v_pk_fma_f32 v[104:105], v[154:155], v[108:109], v[104:105] op_sel:[1,0,0]
	s_waitcnt vmcnt(17)
	v_lshlrev_b32_e32 v108, 16, v44
	v_and_b32_e32 v109, 0xffff0000, v44
	v_pk_fma_f32 v[112:113], v[156:157], v[108:109], v[112:113] op_sel_hi:[0,1,1]
	v_pk_fma_f32 v[104:105], v[156:157], v[108:109], v[104:105] op_sel:[1,0,0]
	s_waitcnt vmcnt(16)
	v_lshlrev_b32_e32 v108, 16, v40
	v_and_b32_e32 v109, 0xffff0000, v40
	v_pk_fma_f32 v[104:105], v[158:159], v[108:109], v[104:105] op_sel:[1,0,0]
	v_lshlrev_b32_e32 v76, 16, v77
	v_and_b32_e32 v77, 0xffff0000, v77
	v_pk_fma_f32 v[112:113], v[158:159], v[108:109], v[112:113] op_sel_hi:[0,1,1]
	v_pk_mul_f32 v[108:109], v[10:11], v[104:105]
	v_pk_mul_f32 v[104:105], v[160:161], v[104:105]
	v_lshlrev_b32_e32 v72, 16, v73
	v_and_b32_e32 v73, 0xffff0000, v73
	v_pk_fma_f32 v[108:109], v[160:161], v[112:113], v[108:109] neg_lo:[0,0,1] neg_hi:[0,0,1]
	v_pk_fma_f32 v[104:105], v[10:11], v[112:113], v[104:105]
	v_pk_fma_f32 v[112:113], v[144:145], v[76:77], 0 op_sel_hi:[0,1,0]
	v_pk_fma_f32 v[76:77], v[144:145], v[76:77], 0 op_sel:[1,0,0] op_sel_hi:[1,1,0]
	v_pk_fma_f32 v[112:113], v[146:147], v[72:73], v[112:113] op_sel_hi:[0,1,1]
	v_pk_fma_f32 v[72:73], v[146:147], v[72:73], v[76:77] op_sel:[1,0,0]
	v_lshlrev_b32_e32 v60, 16, v61
	v_and_b32_e32 v61, 0xffff0000, v61
	v_pk_fma_f32 v[76:77], v[148:149], v[60:61], v[112:113] op_sel_hi:[0,1,1]
	v_pk_fma_f32 v[60:61], v[148:149], v[60:61], v[72:73] op_sel:[1,0,0]
	v_lshlrev_b32_e32 v56, 16, v57
	v_and_b32_e32 v57, 0xffff0000, v57
	v_pk_fma_f32 v[72:73], v[150:151], v[56:57], v[76:77] op_sel_hi:[0,1,1]
	v_pk_fma_f32 v[56:57], v[150:151], v[56:57], v[60:61] op_sel:[1,0,0]
	v_lshlrev_b32_e32 v52, 16, v53
	v_and_b32_e32 v53, 0xffff0000, v53
	v_pk_fma_f32 v[60:61], v[152:153], v[52:53], v[72:73] op_sel_hi:[0,1,1]
	v_pk_fma_f32 v[52:53], v[152:153], v[52:53], v[56:57] op_sel:[1,0,0]
	v_lshlrev_b32_e32 v48, 16, v49
	v_and_b32_e32 v49, 0xffff0000, v49
	v_pk_fma_f32 v[56:57], v[154:155], v[48:49], v[60:61] op_sel_hi:[0,1,1]
	v_pk_fma_f32 v[48:49], v[154:155], v[48:49], v[52:53] op_sel:[1,0,0]
	v_lshlrev_b32_e32 v44, 16, v45
	v_and_b32_e32 v45, 0xffff0000, v45
	v_pk_fma_f32 v[52:53], v[156:157], v[44:45], v[56:57] op_sel_hi:[0,1,1]
	v_pk_fma_f32 v[44:45], v[156:157], v[44:45], v[48:49] op_sel:[1,0,0]
	v_lshlrev_b32_e32 v40, 16, v41
	v_and_b32_e32 v41, 0xffff0000, v41
	v_pk_fma_f32 v[48:49], v[158:159], v[40:41], v[52:53] op_sel_hi:[0,1,1]
	v_pk_fma_f32 v[40:41], v[158:159], v[40:41], v[44:45] op_sel:[1,0,0]
	v_lshlrev_b32_e32 v106, 16, v78
	v_and_b32_e32 v107, 0xffff0000, v78
	v_pk_mul_f32 v[44:45], v[14:15], v[40:41]
	v_pk_mul_f32 v[40:41], v[8:9], v[40:41]
	v_lshlrev_b32_e32 v110, 16, v74
	v_and_b32_e32 v111, 0xffff0000, v74
	v_pk_fma_f32 v[44:45], v[8:9], v[48:49], v[44:45] neg_lo:[0,0,1] neg_hi:[0,0,1]
	v_pk_fma_f32 v[48:49], v[14:15], v[48:49], v[40:41]
	v_pk_fma_f32 v[40:41], v[144:145], v[106:107], 0 op_sel_hi:[0,1,0]
	v_pk_fma_f32 v[52:53], v[144:145], v[106:107], 0 op_sel:[1,0,0] op_sel_hi:[1,1,0]
	v_pk_fma_f32 v[40:41], v[146:147], v[110:111], v[40:41] op_sel_hi:[0,1,1]
	v_pk_fma_f32 v[52:53], v[146:147], v[110:111], v[52:53] op_sel:[1,0,0]
	v_lshlrev_b32_e32 v56, 16, v62
	v_and_b32_e32 v57, 0xffff0000, v62
	v_pk_fma_f32 v[40:41], v[148:149], v[56:57], v[40:41] op_sel_hi:[0,1,1]
	v_pk_fma_f32 v[52:53], v[148:149], v[56:57], v[52:53] op_sel:[1,0,0]
	v_lshlrev_b32_e32 v56, 16, v58
	v_and_b32_e32 v57, 0xffff0000, v58
	v_pk_fma_f32 v[40:41], v[150:151], v[56:57], v[40:41] op_sel_hi:[0,1,1]
	v_pk_fma_f32 v[52:53], v[150:151], v[56:57], v[52:53] op_sel:[1,0,0]
	v_lshlrev_b32_e32 v56, 16, v54
	v_and_b32_e32 v57, 0xffff0000, v54
	v_pk_fma_f32 v[40:41], v[152:153], v[56:57], v[40:41] op_sel_hi:[0,1,1]
	v_pk_fma_f32 v[52:53], v[152:153], v[56:57], v[52:53] op_sel:[1,0,0]
	v_lshlrev_b32_e32 v56, 16, v50
	v_and_b32_e32 v57, 0xffff0000, v50
	v_pk_fma_f32 v[40:41], v[154:155], v[56:57], v[40:41] op_sel_hi:[0,1,1]
	v_pk_fma_f32 v[52:53], v[154:155], v[56:57], v[52:53] op_sel:[1,0,0]
	v_lshlrev_b32_e32 v56, 16, v46
	v_and_b32_e32 v57, 0xffff0000, v46
	v_pk_fma_f32 v[40:41], v[156:157], v[56:57], v[40:41] op_sel_hi:[0,1,1]
	v_pk_fma_f32 v[52:53], v[156:157], v[56:57], v[52:53] op_sel:[1,0,0]
	v_lshlrev_b32_e32 v56, 16, v42
	v_and_b32_e32 v57, 0xffff0000, v42
	v_pk_fma_f32 v[52:53], v[158:159], v[56:57], v[52:53] op_sel:[1,0,0]
	v_lshlrev_b32_e32 v78, 16, v79
	v_and_b32_e32 v79, 0xffff0000, v79
	v_pk_fma_f32 v[40:41], v[158:159], v[56:57], v[40:41] op_sel_hi:[0,1,1]
	v_pk_mul_f32 v[56:57], v[6:7], v[52:53]
	v_pk_mul_f32 v[52:53], v[12:13], v[52:53]
	v_lshlrev_b32_e32 v74, 16, v75
	v_and_b32_e32 v75, 0xffff0000, v75
	v_pk_fma_f32 v[56:57], v[12:13], v[40:41], v[56:57] neg_lo:[0,0,1] neg_hi:[0,0,1]
	v_pk_fma_f32 v[52:53], v[6:7], v[40:41], v[52:53]
	v_pk_fma_f32 v[40:41], v[144:145], v[78:79], 0 op_sel_hi:[0,1,0]
	v_pk_fma_f32 v[60:61], v[144:145], v[78:79], 0 op_sel:[1,0,0] op_sel_hi:[1,1,0]
	v_pk_fma_f32 v[40:41], v[146:147], v[74:75], v[40:41] op_sel_hi:[0,1,1]
	v_pk_fma_f32 v[60:61], v[146:147], v[74:75], v[60:61] op_sel:[1,0,0]
	v_lshlrev_b32_e32 v62, 16, v63
	v_and_b32_e32 v63, 0xffff0000, v63
	v_pk_fma_f32 v[40:41], v[148:149], v[62:63], v[40:41] op_sel_hi:[0,1,1]
	v_pk_fma_f32 v[60:61], v[148:149], v[62:63], v[60:61] op_sel:[1,0,0]
	v_lshlrev_b32_e32 v58, 16, v59
	v_and_b32_e32 v59, 0xffff0000, v59
	v_pk_fma_f32 v[40:41], v[150:151], v[58:59], v[40:41] op_sel_hi:[0,1,1]
	v_pk_fma_f32 v[58:59], v[150:151], v[58:59], v[60:61] op_sel:[1,0,0]
	v_lshlrev_b32_e32 v54, 16, v55
	v_and_b32_e32 v55, 0xffff0000, v55
	v_pk_fma_f32 v[40:41], v[152:153], v[54:55], v[40:41] op_sel_hi:[0,1,1]
	v_pk_fma_f32 v[54:55], v[152:153], v[54:55], v[58:59] op_sel:[1,0,0]
	v_lshlrev_b32_e32 v50, 16, v51
	v_and_b32_e32 v51, 0xffff0000, v51
	v_pk_fma_f32 v[40:41], v[154:155], v[50:51], v[40:41] op_sel_hi:[0,1,1]
	v_pk_fma_f32 v[50:51], v[154:155], v[50:51], v[54:55] op_sel:[1,0,0]
	v_lshlrev_b32_e32 v46, 16, v47
	v_and_b32_e32 v47, 0xffff0000, v47
	v_pk_fma_f32 v[40:41], v[156:157], v[46:47], v[40:41] op_sel_hi:[0,1,1]
	v_pk_fma_f32 v[46:47], v[156:157], v[46:47], v[50:51] op_sel:[1,0,0]
	v_lshlrev_b32_e32 v42, 16, v43
	v_and_b32_e32 v43, 0xffff0000, v43
	v_pk_fma_f32 v[40:41], v[158:159], v[42:43], v[40:41] op_sel_hi:[0,1,1]
	v_pk_fma_f32 v[42:43], v[158:159], v[42:43], v[46:47] op_sel:[1,0,0]
	v_mul_lo_u32 v0, v0, s6
	v_pk_mul_f32 v[46:47], v[2:3], v[42:43]
	v_pk_mul_f32 v[42:43], v[4:5], v[42:43]
	v_pk_fma_f32 v[46:47], v[4:5], v[40:41], v[46:47] neg_lo:[0,0,1] neg_hi:[0,0,1]
	v_pk_fma_f32 v[50:51], v[2:3], v[40:41], v[42:43]
	v_cvt_pk_bf16_f32 v40, v108, v109
	v_cvt_pk_bf16_f32 v41, v44, v45
	v_cvt_pk_bf16_f32 v42, v56, v57
	v_cvt_pk_bf16_f32 v43, v46, v47
	v_add3_u32 v0, 0, v0, v192
	ds_write_b128 v0, v[40:43]
	v_cvt_pk_bf16_f32 v40, v104, v105
	v_cvt_pk_bf16_f32 v41, v48, v49
	v_cvt_pk_bf16_f32 v42, v52, v53
	v_cvt_pk_bf16_f32 v43, v50, v51
	ds_write_b128 v0, v[40:43] offset:512
	s_waitcnt vmcnt(15)
	v_lshlrev_b32_e32 v0, 16, v132
	v_and_b32_e32 v1, 0xffff0000, v132
	s_waitcnt vmcnt(14)
	v_lshlrev_b32_e32 v46, 16, v128
	v_and_b32_e32 v47, 0xffff0000, v128
	v_pk_fma_f32 v[54:55], v[144:145], v[0:1], 0 op_sel_hi:[0,1,0]
	v_pk_fma_f32 v[0:1], v[144:145], v[0:1], 0 op_sel:[1,0,0] op_sel_hi:[1,1,0]
	v_pk_fma_f32 v[54:55], v[146:147], v[46:47], v[54:55] op_sel_hi:[0,1,1]
	v_pk_fma_f32 v[0:1], v[146:147], v[46:47], v[0:1] op_sel:[1,0,0]
	s_waitcnt vmcnt(13)
	v_lshlrev_b32_e32 v46, 16, v100
	v_and_b32_e32 v47, 0xffff0000, v100
	v_pk_fma_f32 v[54:55], v[148:149], v[46:47], v[54:55] op_sel_hi:[0,1,1]
	v_pk_fma_f32 v[0:1], v[148:149], v[46:47], v[0:1] op_sel:[1,0,0]
	s_waitcnt vmcnt(12)
	v_lshlrev_b32_e32 v46, 16, v96
	v_and_b32_e32 v47, 0xffff0000, v96
	v_pk_fma_f32 v[54:55], v[150:151], v[46:47], v[54:55] op_sel_hi:[0,1,1]
	v_pk_fma_f32 v[0:1], v[150:151], v[46:47], v[0:1] op_sel:[1,0,0]
	s_waitcnt vmcnt(11)
	v_lshlrev_b32_e32 v46, 16, v92
	v_and_b32_e32 v47, 0xffff0000, v92
	v_pk_fma_f32 v[54:55], v[152:153], v[46:47], v[54:55] op_sel_hi:[0,1,1]
	v_pk_fma_f32 v[0:1], v[152:153], v[46:47], v[0:1] op_sel:[1,0,0]
	s_waitcnt vmcnt(10)
	v_lshlrev_b32_e32 v46, 16, v88
	v_and_b32_e32 v47, 0xffff0000, v88
	v_pk_fma_f32 v[54:55], v[154:155], v[46:47], v[54:55] op_sel_hi:[0,1,1]
	v_pk_fma_f32 v[0:1], v[154:155], v[46:47], v[0:1] op_sel:[1,0,0]
	s_waitcnt vmcnt(9)
	v_lshlrev_b32_e32 v46, 16, v84
	v_and_b32_e32 v47, 0xffff0000, v84
	v_pk_fma_f32 v[54:55], v[156:157], v[46:47], v[54:55] op_sel_hi:[0,1,1]
	v_pk_fma_f32 v[0:1], v[156:157], v[46:47], v[0:1] op_sel:[1,0,0]
	s_waitcnt vmcnt(8)
	v_lshlrev_b32_e32 v46, 16, v80
	v_and_b32_e32 v47, 0xffff0000, v80
	v_pk_fma_f32 v[0:1], v[158:159], v[46:47], v[0:1] op_sel:[1,0,0]
	v_lshlrev_b32_e32 v40, 16, v133
	v_and_b32_e32 v41, 0xffff0000, v133
	v_pk_fma_f32 v[54:55], v[158:159], v[46:47], v[54:55] op_sel_hi:[0,1,1]
	v_pk_mul_f32 v[46:47], v[10:11], v[0:1]
	v_pk_mul_f32 v[0:1], v[160:161], v[0:1]
	v_lshlrev_b32_e32 v48, 16, v129
	v_and_b32_e32 v49, 0xffff0000, v129
	v_pk_fma_f32 v[46:47], v[160:161], v[54:55], v[46:47] neg_lo:[0,0,1] neg_hi:[0,0,1]
	v_pk_fma_f32 v[0:1], v[10:11], v[54:55], v[0:1]
	v_pk_fma_f32 v[54:55], v[144:145], v[40:41], 0 op_sel_hi:[0,1,0]
	v_pk_fma_f32 v[40:41], v[144:145], v[40:41], 0 op_sel:[1,0,0] op_sel_hi:[1,1,0]
	v_pk_fma_f32 v[54:55], v[146:147], v[48:49], v[54:55] op_sel_hi:[0,1,1]
	v_pk_fma_f32 v[40:41], v[146:147], v[48:49], v[40:41] op_sel:[1,0,0]
	v_lshlrev_b32_e32 v48, 16, v101
	v_and_b32_e32 v49, 0xffff0000, v101
	v_pk_fma_f32 v[54:55], v[148:149], v[48:49], v[54:55] op_sel_hi:[0,1,1]
	v_pk_fma_f32 v[40:41], v[148:149], v[48:49], v[40:41] op_sel:[1,0,0]
	v_lshlrev_b32_e32 v48, 16, v97
	v_and_b32_e32 v49, 0xffff0000, v97
	v_pk_fma_f32 v[54:55], v[150:151], v[48:49], v[54:55] op_sel_hi:[0,1,1]
	v_pk_fma_f32 v[40:41], v[150:151], v[48:49], v[40:41] op_sel:[1,0,0]
	v_lshlrev_b32_e32 v48, 16, v93
	v_and_b32_e32 v49, 0xffff0000, v93
	v_pk_fma_f32 v[54:55], v[152:153], v[48:49], v[54:55] op_sel_hi:[0,1,1]
	v_pk_fma_f32 v[40:41], v[152:153], v[48:49], v[40:41] op_sel:[1,0,0]
	v_lshlrev_b32_e32 v48, 16, v89
	v_and_b32_e32 v49, 0xffff0000, v89
	v_pk_fma_f32 v[54:55], v[154:155], v[48:49], v[54:55] op_sel_hi:[0,1,1]
	v_pk_fma_f32 v[40:41], v[154:155], v[48:49], v[40:41] op_sel:[1,0,0]
	v_lshlrev_b32_e32 v48, 16, v85
	v_and_b32_e32 v49, 0xffff0000, v85
	v_pk_fma_f32 v[54:55], v[156:157], v[48:49], v[54:55] op_sel_hi:[0,1,1]
	v_pk_fma_f32 v[40:41], v[156:157], v[48:49], v[40:41] op_sel:[1,0,0]
	v_lshlrev_b32_e32 v48, 16, v81
	v_and_b32_e32 v49, 0xffff0000, v81
	v_pk_fma_f32 v[40:41], v[158:159], v[48:49], v[40:41] op_sel:[1,0,0]
	v_lshlrev_b32_e32 v42, 16, v134
	v_and_b32_e32 v43, 0xffff0000, v134
	v_pk_fma_f32 v[54:55], v[158:159], v[48:49], v[54:55] op_sel_hi:[0,1,1]
	v_pk_mul_f32 v[48:49], v[14:15], v[40:41]
	v_pk_mul_f32 v[40:41], v[8:9], v[40:41]
	v_lshlrev_b32_e32 v50, 16, v130
	v_and_b32_e32 v51, 0xffff0000, v130
	v_pk_fma_f32 v[48:49], v[8:9], v[54:55], v[48:49] neg_lo:[0,0,1] neg_hi:[0,0,1]
	v_pk_fma_f32 v[54:55], v[14:15], v[54:55], v[40:41]
	v_pk_fma_f32 v[40:41], v[144:145], v[42:43], 0 op_sel_hi:[0,1,0]
	v_pk_fma_f32 v[42:43], v[144:145], v[42:43], 0 op_sel:[1,0,0] op_sel_hi:[1,1,0]
	v_pk_fma_f32 v[40:41], v[146:147], v[50:51], v[40:41] op_sel_hi:[0,1,1]
	v_pk_fma_f32 v[42:43], v[146:147], v[50:51], v[42:43] op_sel:[1,0,0]
	v_lshlrev_b32_e32 v50, 16, v102
	v_and_b32_e32 v51, 0xffff0000, v102
	v_pk_fma_f32 v[40:41], v[148:149], v[50:51], v[40:41] op_sel_hi:[0,1,1]
	v_pk_fma_f32 v[42:43], v[148:149], v[50:51], v[42:43] op_sel:[1,0,0]
	v_lshlrev_b32_e32 v50, 16, v98
	v_and_b32_e32 v51, 0xffff0000, v98
	v_pk_fma_f32 v[40:41], v[150:151], v[50:51], v[40:41] op_sel_hi:[0,1,1]
	v_pk_fma_f32 v[42:43], v[150:151], v[50:51], v[42:43] op_sel:[1,0,0]
	v_lshlrev_b32_e32 v50, 16, v94
	v_and_b32_e32 v51, 0xffff0000, v94
	v_pk_fma_f32 v[40:41], v[152:153], v[50:51], v[40:41] op_sel_hi:[0,1,1]
	v_pk_fma_f32 v[42:43], v[152:153], v[50:51], v[42:43] op_sel:[1,0,0]
	v_lshlrev_b32_e32 v50, 16, v90
	v_and_b32_e32 v51, 0xffff0000, v90
	v_pk_fma_f32 v[40:41], v[154:155], v[50:51], v[40:41] op_sel_hi:[0,1,1]
	v_pk_fma_f32 v[42:43], v[154:155], v[50:51], v[42:43] op_sel:[1,0,0]
	v_lshlrev_b32_e32 v50, 16, v86
	v_and_b32_e32 v51, 0xffff0000, v86
	v_pk_fma_f32 v[40:41], v[156:157], v[50:51], v[40:41] op_sel_hi:[0,1,1]
	v_pk_fma_f32 v[42:43], v[156:157], v[50:51], v[42:43] op_sel:[1,0,0]
	v_lshlrev_b32_e32 v50, 16, v82
	v_and_b32_e32 v51, 0xffff0000, v82
	v_pk_fma_f32 v[42:43], v[158:159], v[50:51], v[42:43] op_sel:[1,0,0]
	v_lshlrev_b32_e32 v44, 16, v135
	v_and_b32_e32 v45, 0xffff0000, v135
	v_pk_fma_f32 v[40:41], v[158:159], v[50:51], v[40:41] op_sel_hi:[0,1,1]
	v_pk_mul_f32 v[50:51], v[6:7], v[42:43]
	v_pk_mul_f32 v[42:43], v[12:13], v[42:43]
	v_lshlrev_b32_e32 v52, 16, v131
	v_and_b32_e32 v53, 0xffff0000, v131
	v_pk_fma_f32 v[50:51], v[12:13], v[40:41], v[50:51] neg_lo:[0,0,1] neg_hi:[0,0,1]
	v_pk_fma_f32 v[56:57], v[6:7], v[40:41], v[42:43]
	v_pk_fma_f32 v[40:41], v[144:145], v[44:45], 0 op_sel_hi:[0,1,0]
	v_pk_fma_f32 v[42:43], v[144:145], v[44:45], 0 op_sel:[1,0,0] op_sel_hi:[1,1,0]
	v_pk_fma_f32 v[40:41], v[146:147], v[52:53], v[40:41] op_sel_hi:[0,1,1]
	v_pk_fma_f32 v[42:43], v[146:147], v[52:53], v[42:43] op_sel:[1,0,0]
	v_lshlrev_b32_e32 v44, 16, v103
	v_and_b32_e32 v45, 0xffff0000, v103
	v_pk_fma_f32 v[40:41], v[148:149], v[44:45], v[40:41] op_sel_hi:[0,1,1]
	v_pk_fma_f32 v[42:43], v[148:149], v[44:45], v[42:43] op_sel:[1,0,0]
	v_lshlrev_b32_e32 v44, 16, v99
	v_and_b32_e32 v45, 0xffff0000, v99
	v_pk_fma_f32 v[40:41], v[150:151], v[44:45], v[40:41] op_sel_hi:[0,1,1]
	v_pk_fma_f32 v[42:43], v[150:151], v[44:45], v[42:43] op_sel:[1,0,0]
	v_lshlrev_b32_e32 v44, 16, v95
	v_and_b32_e32 v45, 0xffff0000, v95
	v_pk_fma_f32 v[40:41], v[152:153], v[44:45], v[40:41] op_sel_hi:[0,1,1]
	v_pk_fma_f32 v[42:43], v[152:153], v[44:45], v[42:43] op_sel:[1,0,0]
	v_lshlrev_b32_e32 v44, 16, v91
	v_and_b32_e32 v45, 0xffff0000, v91
	v_pk_fma_f32 v[40:41], v[154:155], v[44:45], v[40:41] op_sel_hi:[0,1,1]
	v_pk_fma_f32 v[42:43], v[154:155], v[44:45], v[42:43] op_sel:[1,0,0]
	v_lshlrev_b32_e32 v44, 16, v87
	v_and_b32_e32 v45, 0xffff0000, v87
	v_pk_fma_f32 v[40:41], v[156:157], v[44:45], v[40:41] op_sel_hi:[0,1,1]
	v_pk_fma_f32 v[42:43], v[156:157], v[44:45], v[42:43] op_sel:[1,0,0]
	v_lshlrev_b32_e32 v44, 16, v83
	v_and_b32_e32 v45, 0xffff0000, v83
	v_pk_fma_f32 v[42:43], v[158:159], v[44:45], v[42:43] op_sel:[1,0,0]
	v_pk_fma_f32 v[40:41], v[158:159], v[44:45], v[40:41] op_sel_hi:[0,1,1]
	v_pk_mul_f32 v[44:45], v[2:3], v[42:43]
	v_pk_mul_f32 v[42:43], v[4:5], v[42:43]
	v_pk_fma_f32 v[44:45], v[4:5], v[40:41], v[44:45] neg_lo:[0,0,1] neg_hi:[0,0,1]
	v_pk_fma_f32 v[52:53], v[2:3], v[40:41], v[42:43]
	v_cvt_pk_bf16_f32 v43, v44, v45
	v_mul_lo_u32 v44, v166, s6
	v_cvt_pk_bf16_f32 v40, v46, v47
	v_cvt_pk_bf16_f32 v41, v48, v49
	v_cvt_pk_bf16_f32 v42, v50, v51
	v_add3_u32 v44, 0, v44, v192
	ds_write_b128 v44, v[40:43]
	v_cvt_pk_bf16_f32 v40, v0, v1
	s_waitcnt vmcnt(7)
	v_lshlrev_b32_e32 v0, 16, v68
	v_and_b32_e32 v1, 0xffff0000, v68
	v_cvt_pk_bf16_f32 v41, v54, v55
	s_waitcnt vmcnt(6)
	v_lshlrev_b32_e32 v46, 16, v64
	v_and_b32_e32 v47, 0xffff0000, v64
	v_pk_fma_f32 v[54:55], v[144:145], v[0:1], 0 op_sel_hi:[0,1,0]
	v_pk_fma_f32 v[0:1], v[144:145], v[0:1], 0 op_sel:[1,0,0] op_sel_hi:[1,1,0]
	v_pk_fma_f32 v[54:55], v[146:147], v[46:47], v[54:55] op_sel_hi:[0,1,1]
	v_pk_fma_f32 v[0:1], v[146:147], v[46:47], v[0:1] op_sel:[1,0,0]
	s_waitcnt vmcnt(5)
	v_lshlrev_b32_e32 v46, 16, v36
	v_and_b32_e32 v47, 0xffff0000, v36
	v_pk_fma_f32 v[54:55], v[148:149], v[46:47], v[54:55] op_sel_hi:[0,1,1]
	v_pk_fma_f32 v[0:1], v[148:149], v[46:47], v[0:1] op_sel:[1,0,0]
	s_waitcnt vmcnt(4)
	v_lshlrev_b32_e32 v46, 16, v32
	v_and_b32_e32 v47, 0xffff0000, v32
	v_pk_fma_f32 v[54:55], v[150:151], v[46:47], v[54:55] op_sel_hi:[0,1,1]
	v_pk_fma_f32 v[0:1], v[150:151], v[46:47], v[0:1] op_sel:[1,0,0]
	s_waitcnt vmcnt(3)
	v_lshlrev_b32_e32 v46, 16, v28
	v_and_b32_e32 v47, 0xffff0000, v28
	v_pk_fma_f32 v[54:55], v[152:153], v[46:47], v[54:55] op_sel_hi:[0,1,1]
	v_pk_fma_f32 v[0:1], v[152:153], v[46:47], v[0:1] op_sel:[1,0,0]
	s_waitcnt vmcnt(2)
	v_lshlrev_b32_e32 v46, 16, v24
	v_and_b32_e32 v47, 0xffff0000, v24
	v_pk_fma_f32 v[54:55], v[154:155], v[46:47], v[54:55] op_sel_hi:[0,1,1]
	v_pk_fma_f32 v[0:1], v[154:155], v[46:47], v[0:1] op_sel:[1,0,0]
	s_waitcnt vmcnt(1)
	v_lshlrev_b32_e32 v46, 16, v20
	v_and_b32_e32 v47, 0xffff0000, v20
	v_pk_fma_f32 v[54:55], v[156:157], v[46:47], v[54:55] op_sel_hi:[0,1,1]
	v_pk_fma_f32 v[0:1], v[156:157], v[46:47], v[0:1] op_sel:[1,0,0]
	s_waitcnt vmcnt(0)
	v_lshlrev_b32_e32 v46, 16, v16
	v_and_b32_e32 v47, 0xffff0000, v16
	v_cvt_pk_bf16_f32 v42, v56, v57
	v_cvt_pk_bf16_f32 v43, v52, v53
	v_pk_fma_f32 v[0:1], v[158:159], v[46:47], v[0:1] op_sel:[1,0,0]
	ds_write_b128 v44, v[40:43] offset:512
	v_lshlrev_b32_e32 v40, 16, v69
	v_and_b32_e32 v41, 0xffff0000, v69
	v_pk_fma_f32 v[54:55], v[158:159], v[46:47], v[54:55] op_sel_hi:[0,1,1]
	v_pk_mul_f32 v[46:47], v[10:11], v[0:1]
	v_pk_mul_f32 v[0:1], v[160:161], v[0:1]
	v_lshlrev_b32_e32 v48, 16, v65
	v_and_b32_e32 v49, 0xffff0000, v65
	v_pk_fma_f32 v[10:11], v[10:11], v[54:55], v[0:1]
	v_pk_fma_f32 v[0:1], v[144:145], v[40:41], 0 op_sel_hi:[0,1,0]
	v_pk_fma_f32 v[40:41], v[144:145], v[40:41], 0 op_sel:[1,0,0] op_sel_hi:[1,1,0]
	v_pk_fma_f32 v[0:1], v[146:147], v[48:49], v[0:1] op_sel_hi:[0,1,1]
	v_pk_fma_f32 v[40:41], v[146:147], v[48:49], v[40:41] op_sel:[1,0,0]
	v_lshlrev_b32_e32 v36, 16, v37
	v_and_b32_e32 v37, 0xffff0000, v37
	v_pk_fma_f32 v[0:1], v[148:149], v[36:37], v[0:1] op_sel_hi:[0,1,1]
	v_pk_fma_f32 v[36:37], v[148:149], v[36:37], v[40:41] op_sel:[1,0,0]
	v_lshlrev_b32_e32 v32, 16, v33
	v_and_b32_e32 v33, 0xffff0000, v33
	v_pk_fma_f32 v[0:1], v[150:151], v[32:33], v[0:1] op_sel_hi:[0,1,1]
	v_pk_fma_f32 v[32:33], v[150:151], v[32:33], v[36:37] op_sel:[1,0,0]
	v_lshlrev_b32_e32 v28, 16, v29
	v_and_b32_e32 v29, 0xffff0000, v29
	v_pk_fma_f32 v[0:1], v[152:153], v[28:29], v[0:1] op_sel_hi:[0,1,1]
	v_pk_fma_f32 v[28:29], v[152:153], v[28:29], v[32:33] op_sel:[1,0,0]
	v_lshlrev_b32_e32 v24, 16, v25
	v_and_b32_e32 v25, 0xffff0000, v25
	v_pk_fma_f32 v[0:1], v[154:155], v[24:25], v[0:1] op_sel_hi:[0,1,1]
; __device__ __forceinline__ void b_unit(Frame& F, int u, bool dry) {
;     ...
;     __syncthreads();
	v_pk_fma_f32 v[24:25], v[154:155], v[24:25], v[28:29] op_sel:[1,0,0]
	v_lshlrev_b32_e32 v20, 16, v21
	v_and_b32_e32 v21, 0xffff0000, v21
	v_pk_fma_f32 v[0:1], v[156:157], v[20:21], v[0:1] op_sel_hi:[0,1,1]
	v_pk_fma_f32 v[20:21], v[156:157], v[20:21], v[24:25] op_sel:[1,0,0]
	v_lshlrev_b32_e32 v16, 16, v17
	v_and_b32_e32 v17, 0xffff0000, v17
	v_pk_fma_f32 v[0:1], v[158:159], v[16:17], v[0:1] op_sel_hi:[0,1,1]
	v_pk_fma_f32 v[16:17], v[158:159], v[16:17], v[20:21] op_sel:[1,0,0]
	v_lshlrev_b32_e32 v42, 16, v70
	v_pk_mul_f32 v[20:21], v[14:15], v[16:17]
	v_and_b32_e32 v43, 0xffff0000, v70
	v_pk_fma_f32 v[20:21], v[8:9], v[0:1], v[20:21] neg_lo:[0,0,1] neg_hi:[0,0,1]
	v_pk_mul_f32 v[8:9], v[8:9], v[16:17]
	v_lshlrev_b32_e32 v50, 16, v66
	v_and_b32_e32 v51, 0xffff0000, v66
	v_pk_fma_f32 v[8:9], v[14:15], v[0:1], v[8:9]
	v_pk_fma_f32 v[0:1], v[144:145], v[42:43], 0 op_sel_hi:[0,1,0]
	v_pk_fma_f32 v[14:15], v[144:145], v[42:43], 0 op_sel:[1,0,0] op_sel_hi:[1,1,0]
	v_pk_fma_f32 v[0:1], v[146:147], v[50:51], v[0:1] op_sel_hi:[0,1,1]
	v_pk_fma_f32 v[14:15], v[146:147], v[50:51], v[14:15] op_sel:[1,0,0]
	v_lshlrev_b32_e32 v16, 16, v38
	v_and_b32_e32 v17, 0xffff0000, v38
	v_pk_fma_f32 v[0:1], v[148:149], v[16:17], v[0:1] op_sel_hi:[0,1,1]
	v_pk_fma_f32 v[14:15], v[148:149], v[16:17], v[14:15] op_sel:[1,0,0]
	v_lshlrev_b32_e32 v16, 16, v34
	v_and_b32_e32 v17, 0xffff0000, v34
	v_pk_fma_f32 v[0:1], v[150:151], v[16:17], v[0:1] op_sel_hi:[0,1,1]
	v_pk_fma_f32 v[14:15], v[150:151], v[16:17], v[14:15] op_sel:[1,0,0]
	v_lshlrev_b32_e32 v16, 16, v30
	v_and_b32_e32 v17, 0xffff0000, v30
	v_pk_fma_f32 v[0:1], v[152:153], v[16:17], v[0:1] op_sel_hi:[0,1,1]
	v_pk_fma_f32 v[14:15], v[152:153], v[16:17], v[14:15] op_sel:[1,0,0]
	v_lshlrev_b32_e32 v16, 16, v26
	v_and_b32_e32 v17, 0xffff0000, v26
	v_pk_fma_f32 v[0:1], v[154:155], v[16:17], v[0:1] op_sel_hi:[0,1,1]
	v_pk_fma_f32 v[14:15], v[154:155], v[16:17], v[14:15] op_sel:[1,0,0]
	v_lshlrev_b32_e32 v16, 16, v22
	v_and_b32_e32 v17, 0xffff0000, v22
	v_pk_fma_f32 v[0:1], v[156:157], v[16:17], v[0:1] op_sel_hi:[0,1,1]
	v_pk_fma_f32 v[14:15], v[156:157], v[16:17], v[14:15] op_sel:[1,0,0]
	v_lshlrev_b32_e32 v16, 16, v18
	v_and_b32_e32 v17, 0xffff0000, v18
	v_pk_fma_f32 v[14:15], v[158:159], v[16:17], v[14:15] op_sel:[1,0,0]
	v_pk_fma_f32 v[0:1], v[158:159], v[16:17], v[0:1] op_sel_hi:[0,1,1]
	v_pk_mul_f32 v[16:17], v[6:7], v[14:15]
	v_lshlrev_b32_e32 v44, 16, v71
	v_and_b32_e32 v45, 0xffff0000, v71
	v_pk_fma_f32 v[16:17], v[12:13], v[0:1], v[16:17] neg_lo:[0,0,1] neg_hi:[0,0,1]
	v_pk_mul_f32 v[12:13], v[12:13], v[14:15]
	v_lshlrev_b32_e32 v52, 16, v67
	v_and_b32_e32 v53, 0xffff0000, v67
	v_pk_fma_f32 v[6:7], v[6:7], v[0:1], v[12:13]
	v_pk_fma_f32 v[0:1], v[144:145], v[44:45], 0 op_sel_hi:[0,1,0]
	v_pk_fma_f32 v[12:13], v[144:145], v[44:45], 0 op_sel:[1,0,0] op_sel_hi:[1,1,0]
	v_pk_fma_f32 v[0:1], v[146:147], v[52:53], v[0:1] op_sel_hi:[0,1,1]
	v_pk_fma_f32 v[12:13], v[146:147], v[52:53], v[12:13] op_sel:[1,0,0]
	v_lshlrev_b32_e32 v14, 16, v39
	v_and_b32_e32 v15, 0xffff0000, v39
	v_pk_fma_f32 v[0:1], v[148:149], v[14:15], v[0:1] op_sel_hi:[0,1,1]
	v_pk_fma_f32 v[12:13], v[148:149], v[14:15], v[12:13] op_sel:[1,0,0]
	v_lshlrev_b32_e32 v14, 16, v35
	v_and_b32_e32 v15, 0xffff0000, v35
	v_pk_fma_f32 v[0:1], v[150:151], v[14:15], v[0:1] op_sel_hi:[0,1,1]
	v_pk_fma_f32 v[12:13], v[150:151], v[14:15], v[12:13] op_sel:[1,0,0]
	v_lshlrev_b32_e32 v14, 16, v31
	v_and_b32_e32 v15, 0xffff0000, v31
	v_pk_fma_f32 v[0:1], v[152:153], v[14:15], v[0:1] op_sel_hi:[0,1,1]
	v_pk_fma_f32 v[12:13], v[152:153], v[14:15], v[12:13] op_sel:[1,0,0]
	v_lshlrev_b32_e32 v14, 16, v27
	v_and_b32_e32 v15, 0xffff0000, v27
	v_pk_fma_f32 v[0:1], v[154:155], v[14:15], v[0:1] op_sel_hi:[0,1,1]
	v_pk_fma_f32 v[12:13], v[154:155], v[14:15], v[12:13] op_sel:[1,0,0]
	v_lshlrev_b32_e32 v14, 16, v23
	v_and_b32_e32 v15, 0xffff0000, v23
	v_pk_fma_f32 v[0:1], v[156:157], v[14:15], v[0:1] op_sel_hi:[0,1,1]
	v_pk_fma_f32 v[12:13], v[156:157], v[14:15], v[12:13] op_sel:[1,0,0]
	v_lshlrev_b32_e32 v14, 16, v19
	v_and_b32_e32 v15, 0xffff0000, v19
	v_pk_fma_f32 v[12:13], v[158:159], v[14:15], v[12:13] op_sel:[1,0,0]
	v_pk_fma_f32 v[0:1], v[158:159], v[14:15], v[0:1] op_sel_hi:[0,1,1]
	v_pk_mul_f32 v[14:15], v[2:3], v[12:13]
	v_pk_fma_f32 v[46:47], v[160:161], v[54:55], v[46:47] neg_lo:[0,0,1] neg_hi:[0,0,1]
	v_pk_fma_f32 v[14:15], v[4:5], v[0:1], v[14:15] neg_lo:[0,0,1] neg_hi:[0,0,1]
	v_pk_mul_f32 v[4:5], v[4:5], v[12:13]
	v_mul_lo_u32 v12, v164, s6
	v_pk_fma_f32 v[4:5], v[2:3], v[0:1], v[4:5]
	v_cvt_pk_bf16_f32 v0, v46, v47
	v_cvt_pk_bf16_f32 v1, v20, v21
	v_cvt_pk_bf16_f32 v2, v16, v17
	v_cvt_pk_bf16_f32 v3, v14, v15
	v_add3_u32 v12, 0, v12, v192
	ds_write_b128 v12, v[0:3]
	v_cvt_pk_bf16_f32 v0, v10, v11
	v_cvt_pk_bf16_f32 v1, v8, v9
	v_cvt_pk_bf16_f32 v2, v6, v7
	v_cvt_pk_bf16_f32 v3, v4, v5
	v_lshlrev_b32_e32 v192, 4, v171
	ds_write_b128 v12, v[0:3] offset:512
	v_lshl_add_u64 v[0:1], s[2:3], 0, v[192:193]
	v_add_co_u32_e32 v4, vcc, s7, v0
	s_waitcnt lgkmcnt(0)
	s_nop 0
	v_addc_co_u32_e32 v5, vcc, 0, v1, vcc
	s_barrier
; #define LAS __attribute__((address_space(3)))
; #define GAS __attribute__((address_space(1)))
; __device__ __forceinline__ unsigned cvtpk(float lo, float hi) { f32x2 v = {lo, hi}; bf16x2_t b = __builtin_convertvector(v, bf16x2_t); return __builtin_bit_cast(unsigned, b); }
; __device__ __forceinline__ void b_unit(Frame& F, int u, bool dry) {
;     ...
;         const bf16x8 Wr = *(const GAS bf16x8*)(ws_ + WS_W16F + (size_t)lane * 16), Wi = *(const GAS bf16x8*)(ws_ + WS_W16F + 1024 + (size_t)lane * 16);
;         f32x2 t2[4];
; #pragma unroll
;         for (int j = 0; j < 4; ++j) t2[j] = *(const GAS f32x2*)(ws_ + WS_TW2 + (size_t)(lane * 4 + j) * 8);
;         const f32x4 zero4 = (f32x4){0.f, 0.f, 0.f, 0.f};
;         const unsigned rbase = (unsigned)(size_t)Bt + (unsigned)(16 * w) * 1040u + (unsigned)(fq >> 1) * 512u + (unsigned)(16 * (8 * (fq & 1) + (fr >> 2)) + 4 * (fr & 3)) * 2u;
;         u32x2 q0[16], q1[16];
;     ...
;         BU_TR8(0); BU_TR8(8);
;     ...
;         LAS unsigned char* vrow = Bt + (size_t)(16 * w) * 1040 + 64 * fr + 8 * fq;
; #pragma unroll
;         for (int i = 0; i < 16; ++i) {
;             u32x4 f4; f4.x = q0[i].x; f4.y = q0[i].y; f4.z = q1[i].x; f4.w = q1[i].y;
;             const bf16x8 frag = __builtin_bit_cast(bf16x8, f4);
;             const f32x4 dr = __builtin_amdgcn_mfma_f32_16x16x32_bf16(frag, Wr, zero4, 0, 0, 0), di = __builtin_amdgcn_mfma_f32_16x16x32_bf16(frag, Wi, zero4, 0, 0, 0);
;             float vr[4], vi[4];
; #pragma unroll
;             for (int j = 0; j < 4; ++j) { vr[j] = dr[j] * t2[j].x + di[j] * t2[j].y; vi[j] = di[j] * t2[j].x - dr[j] * t2[j].y; }
;             u32x2 o; o.x = cvtpk(vr[0], vr[1]); o.y = cvtpk(vr[2], vr[3]); *(LAS u32x2*)(vrow + i * 1040) = o;
;             o.x = cvtpk(vi[0], vi[1]); o.y = cvtpk(vi[2], vi[3]); *(LAS u32x2*)(vrow + i * 1040 + 32) = o;
;         }
	global_load_dwordx4 v[0:3], v[4:5], off
	s_nop 0
	global_load_dwordx4 v[4:7], v[4:5], off offset:1024
	v_lshlrev_b32_e32 v8, 5, v171
	v_mov_b32_e32 v9, v193
	v_lshl_add_u64 v[8:9], s[2:3], 0, v[8:9]
	s_mov_b64 s[0:1], 0x1d90800
	v_lshl_add_u64 v[10:11], v[8:9], 0, s[0:1]
	v_add_co_u32_e32 v8, vcc, s7, v8
	v_lshrrev_b32_e32 v17, 1, v170
	s_nop 0
	v_addc_co_u32_e32 v9, vcc, 0, v9, vcc
	global_load_dwordx4 v[12:15], v[8:9], off offset:2048
	s_nop 0
	global_load_dwordx4 v[8:11], v[10:11], off offset:16
	v_bfe_u32 v18, v170, 2, 2
	v_and_b32_e32 v76, 24, v17
	v_and_or_b32 v17, v17, 8, v18
	v_lshlrev_b32_e32 v18, 3, v170
	v_and_b32_e32 v18, 24, v18
	v_readlane_b32 s0, v253, 54
	v_and_b32_e32 v16, 0x200, v192
	v_lshlrev_b32_e32 v17, 5, v17
	v_add_u32_e32 v18, s0, v18
	v_add3_u32 v64, v18, v16, v17
	ds_read_b64_tr_b16 v[82:83], v64 offset:0
	ds_read_b64_tr_b16 v[84:85], v64 offset:0+128
	ds_read_b64_tr_b16 v[78:79], v64 offset:0+1040
	ds_read_b64_tr_b16 v[80:81], v64 offset:0+1040+128
	ds_read_b64_tr_b16 v[72:73], v64 offset:0+2080
	ds_read_b64_tr_b16 v[74:75], v64 offset:0+2080+128
	ds_read_b64_tr_b16 v[68:69], v64 offset:0+3120
	ds_read_b64_tr_b16 v[70:71], v64 offset:0+3120+128
	ds_read_b64_tr_b16 v[60:61], v64 offset:0+4160
	ds_read_b64_tr_b16 v[62:63], v64 offset:0+4160+128
	ds_read_b64_tr_b16 v[56:57], v64 offset:0+5200
	ds_read_b64_tr_b16 v[58:59], v64 offset:0+5200+128
	ds_read_b64_tr_b16 v[52:53], v64 offset:0+6240
	ds_read_b64_tr_b16 v[54:55], v64 offset:0+6240+128
	ds_read_b64_tr_b16 v[48:49], v64 offset:0+7280
	ds_read_b64_tr_b16 v[50:51], v64 offset:0+7280+128
	s_waitcnt lgkmcnt(0)
	v_and_b32_e32 v77, 15, v170
	s_waitcnt vmcnt(3)
	v_mfma_f32_16x16x32_bf16 v[86:89], v[82:85], v[0:3], 0
	ds_read_b64_tr_b16 v[44:45], v64 offset:0x2080
	ds_read_b64_tr_b16 v[46:47], v64 offset:0x2080+128
	ds_read_b64_tr_b16 v[40:41], v64 offset:0x2080+1040
	ds_read_b64_tr_b16 v[42:43], v64 offset:0x2080+1040+128
	ds_read_b64_tr_b16 v[36:37], v64 offset:0x2080+2080
	ds_read_b64_tr_b16 v[38:39], v64 offset:0x2080+2080+128
	ds_read_b64_tr_b16 v[32:33], v64 offset:0x2080+3120
	ds_read_b64_tr_b16 v[34:35], v64 offset:0x2080+3120+128
	ds_read_b64_tr_b16 v[28:29], v64 offset:0x2080+4160
	ds_read_b64_tr_b16 v[30:31], v64 offset:0x2080+4160+128
	ds_read_b64_tr_b16 v[24:25], v64 offset:0x2080+5200
	ds_read_b64_tr_b16 v[26:27], v64 offset:0x2080+5200+128
	ds_read_b64_tr_b16 v[20:21], v64 offset:0x2080+6240
	ds_read_b64_tr_b16 v[22:23], v64 offset:0x2080+6240+128
	ds_read_b64_tr_b16 v[16:17], v64 offset:0x2080+7280
	ds_read_b64_tr_b16 v[18:19], v64 offset:0x2080+7280+128
	s_waitcnt lgkmcnt(0)
	v_lshlrev_b32_e32 v64, 6, v77
	v_add3_u32 v66, s0, v64, v76
	s_waitcnt vmcnt(2)
	v_mfma_f32_16x16x32_bf16 v[82:85], v[82:85], v[4:7], 0
	v_add_u32_e32 v67, 0x800, v66
	v_readlane_b32 s0, v253, 60
	v_lshlrev_b32_e32 v192, 1, v76
	s_waitcnt vmcnt(1)
	v_mov_b32_e32 v65, v14
	v_mov_b32_e32 v14, v13
	v_mov_b32_e32 v64, v12
	s_nop 0
	v_pk_mul_f32 v[12:13], v[14:15], v[82:83]
	s_nop 0
	v_pk_fma_f32 v[90:91], v[64:65], v[86:87], v[12:13]
	v_pk_mul_f32 v[12:13], v[14:15], v[86:87]
	s_nop 0
	v_pk_fma_f32 v[82:83], v[64:65], v[82:83], v[12:13] neg_lo:[0,0,1] neg_hi:[0,0,1]
	s_waitcnt vmcnt(0)
	v_mov_b32_e32 v13, v10
	v_mov_b32_e32 v10, v9
	v_mov_b32_e32 v12, v8
	v_pk_mul_f32 v[8:9], v[10:11], v[84:85]
	v_pk_mul_f32 v[86:87], v[10:11], v[88:89]
	v_pk_fma_f32 v[8:9], v[12:13], v[88:89], v[8:9]
	v_pk_fma_f32 v[84:85], v[12:13], v[84:85], v[86:87] neg_lo:[0,0,1] neg_hi:[0,0,1]
	v_cvt_pk_bf16_f32 v87, v8, v9
	v_cvt_pk_bf16_f32 v8, v82, v83
	v_cvt_pk_bf16_f32 v9, v84, v85
	v_mfma_f32_16x16x32_bf16 v[82:85], v[78:81], v[0:3], 0
	v_cvt_pk_bf16_f32 v86, v90, v91
	ds_write2_b64 v66, v[86:87], v[8:9] offset1:4
	v_mfma_f32_16x16x32_bf16 v[78:81], v[78:81], v[4:7], 0
	s_nop 7
	v_pk_mul_f32 v[8:9], v[14:15], v[78:79]
	s_nop 0
	v_pk_fma_f32 v[8:9], v[64:65], v[82:83], v[8:9]
	v_pk_mul_f32 v[82:83], v[14:15], v[82:83]
	v_cvt_pk_bf16_f32 v8, v8, v9
	v_pk_fma_f32 v[78:79], v[64:65], v[78:79], v[82:83] neg_lo:[0,0,1] neg_hi:[0,0,1]
	v_pk_mul_f32 v[82:83], v[10:11], v[80:81]
	v_cvt_pk_bf16_f32 v78, v78, v79
	v_pk_fma_f32 v[82:83], v[12:13], v[84:85], v[82:83]
	v_pk_mul_f32 v[84:85], v[10:11], v[84:85]
	v_cvt_pk_bf16_f32 v9, v82, v83
	v_pk_fma_f32 v[80:81], v[12:13], v[80:81], v[84:85] neg_lo:[0,0,1] neg_hi:[0,0,1]
	s_nop 0
	v_cvt_pk_bf16_f32 v79, v80, v81
	ds_write2_b64 v66, v[8:9], v[78:79] offset0:130 offset1:134
	v_mfma_f32_16x16x32_bf16 v[78:81], v[72:75], v[0:3], 0
	v_mfma_f32_16x16x32_bf16 v[72:75], v[72:75], v[4:7], 0
	s_nop 7
	v_pk_mul_f32 v[8:9], v[14:15], v[72:73]
	s_nop 0
	v_pk_fma_f32 v[8:9], v[64:65], v[78:79], v[8:9]
	v_pk_mul_f32 v[78:79], v[14:15], v[78:79]
	v_cvt_pk_bf16_f32 v8, v8, v9
	v_pk_fma_f32 v[72:73], v[64:65], v[72:73], v[78:79] neg_lo:[0,0,1] neg_hi:[0,0,1]
	v_pk_mul_f32 v[78:79], v[10:11], v[74:75]
	v_cvt_pk_bf16_f32 v72, v72, v73
	v_pk_fma_f32 v[78:79], v[12:13], v[80:81], v[78:79]
	v_pk_mul_f32 v[80:81], v[10:11], v[80:81]
	v_cvt_pk_bf16_f32 v9, v78, v79
	v_pk_fma_f32 v[74:75], v[12:13], v[74:75], v[80:81] neg_lo:[0,0,1] neg_hi:[0,0,1]
	s_nop 0
	v_cvt_pk_bf16_f32 v73, v74, v75
	ds_write2_b64 v67, v[8:9], v[72:73] offset0:4 offset1:8
	v_mfma_f32_16x16x32_bf16 v[72:75], v[68:71], v[0:3], 0
	v_mfma_f32_16x16x32_bf16 v[68:71], v[68:71], v[4:7], 0
	s_nop 7
	v_pk_mul_f32 v[8:9], v[14:15], v[68:69]
	s_nop 0
	v_pk_fma_f32 v[8:9], v[64:65], v[72:73], v[8:9]
	v_pk_mul_f32 v[72:73], v[14:15], v[72:73]
	v_cvt_pk_bf16_f32 v8, v8, v9
	v_pk_fma_f32 v[68:69], v[64:65], v[68:69], v[72:73] neg_lo:[0,0,1] neg_hi:[0,0,1]
	v_pk_mul_f32 v[72:73], v[10:11], v[70:71]
	v_cvt_pk_bf16_f32 v68, v68, v69
; #define LAS __attribute__((address_space(3)))
; __device__ __forceinline__ unsigned cvtpk(float lo, float hi) { f32x2 v = {lo, hi}; bf16x2_t b = __builtin_convertvector(v, bf16x2_t); return __builtin_bit_cast(unsigned, b); }
; __device__ __forceinline__ void b_unit(Frame& F, int u, bool dry) {
;     ...
;         for (int i = 0; i < 16; ++i) {
;             u32x4 f4; f4.x = q0[i].x; f4.y = q0[i].y; f4.z = q1[i].x; f4.w = q1[i].y;
;             const bf16x8 frag = __builtin_bit_cast(bf16x8, f4);
;             const f32x4 dr = __builtin_amdgcn_mfma_f32_16x16x32_bf16(frag, Wr, zero4, 0, 0, 0), di = __builtin_amdgcn_mfma_f32_16x16x32_bf16(frag, Wi, zero4, 0, 0, 0);
;             float vr[4], vi[4];
; #pragma unroll
;             for (int j = 0; j < 4; ++j) { vr[j] = dr[j] * t2[j].x + di[j] * t2[j].y; vi[j] = di[j] * t2[j].x - dr[j] * t2[j].y; }
;             u32x2 o; o.x = cvtpk(vr[0], vr[1]); o.y = cvtpk(vr[2], vr[3]); *(LAS u32x2*)(vrow + i * 1040) = o;
;             o.x = cvtpk(vi[0], vi[1]); o.y = cvtpk(vi[2], vi[3]); *(LAS u32x2*)(vrow + i * 1040 + 32) = o;
;         }
	v_pk_fma_f32 v[72:73], v[12:13], v[74:75], v[72:73]
	v_pk_mul_f32 v[74:75], v[10:11], v[74:75]
	v_cvt_pk_bf16_f32 v9, v72, v73
	v_pk_fma_f32 v[70:71], v[12:13], v[70:71], v[74:75] neg_lo:[0,0,1] neg_hi:[0,0,1]
	s_nop 0
	v_cvt_pk_bf16_f32 v69, v70, v71
	ds_write2_b64 v67, v[8:9], v[68:69] offset0:134 offset1:138
	v_mfma_f32_16x16x32_bf16 v[68:71], v[60:63], v[0:3], 0
	v_add_u32_e32 v67, 0x1000, v66
	v_mfma_f32_16x16x32_bf16 v[60:63], v[60:63], v[4:7], 0
	s_nop 7
	v_pk_mul_f32 v[8:9], v[14:15], v[60:61]
	s_nop 0
	v_pk_fma_f32 v[8:9], v[64:65], v[68:69], v[8:9]
	v_pk_mul_f32 v[68:69], v[14:15], v[68:69]
	v_cvt_pk_bf16_f32 v8, v8, v9
	v_pk_fma_f32 v[60:61], v[64:65], v[60:61], v[68:69] neg_lo:[0,0,1] neg_hi:[0,0,1]
	v_pk_mul_f32 v[68:69], v[10:11], v[62:63]
	v_cvt_pk_bf16_f32 v60, v60, v61
	v_pk_fma_f32 v[68:69], v[12:13], v[70:71], v[68:69]
	v_pk_mul_f32 v[70:71], v[10:11], v[70:71]
	v_cvt_pk_bf16_f32 v9, v68, v69
	v_pk_fma_f32 v[62:63], v[12:13], v[62:63], v[70:71] neg_lo:[0,0,1] neg_hi:[0,0,1]
	s_nop 0
	v_cvt_pk_bf16_f32 v61, v62, v63
	ds_write2_b64 v67, v[8:9], v[60:61] offset0:8 offset1:12
	v_mfma_f32_16x16x32_bf16 v[60:63], v[56:59], v[0:3], 0
	v_mfma_f32_16x16x32_bf16 v[56:59], v[56:59], v[4:7], 0
	s_nop 7
	v_pk_mul_f32 v[8:9], v[14:15], v[56:57]
	s_nop 0
	v_pk_fma_f32 v[8:9], v[64:65], v[60:61], v[8:9]
	v_pk_mul_f32 v[60:61], v[14:15], v[60:61]
	v_cvt_pk_bf16_f32 v8, v8, v9
	v_pk_fma_f32 v[56:57], v[64:65], v[56:57], v[60:61] neg_lo:[0,0,1] neg_hi:[0,0,1]
	v_pk_mul_f32 v[60:61], v[10:11], v[58:59]
	v_cvt_pk_bf16_f32 v56, v56, v57
	v_pk_fma_f32 v[60:61], v[12:13], v[62:63], v[60:61]
	v_pk_mul_f32 v[62:63], v[10:11], v[62:63]
	v_cvt_pk_bf16_f32 v9, v60, v61
	v_pk_fma_f32 v[58:59], v[12:13], v[58:59], v[62:63] neg_lo:[0,0,1] neg_hi:[0,0,1]
	s_nop 0
	v_cvt_pk_bf16_f32 v57, v58, v59
	ds_write2_b64 v67, v[8:9], v[56:57] offset0:138 offset1:142
	v_mfma_f32_16x16x32_bf16 v[56:59], v[52:55], v[0:3], 0
	v_mfma_f32_16x16x32_bf16 v[52:55], v[52:55], v[4:7], 0
	s_nop 7
	v_pk_mul_f32 v[8:9], v[14:15], v[52:53]
	s_nop 0
	v_pk_fma_f32 v[8:9], v[64:65], v[56:57], v[8:9]
	v_pk_mul_f32 v[56:57], v[14:15], v[56:57]
	v_cvt_pk_bf16_f32 v8, v8, v9
	v_pk_fma_f32 v[52:53], v[64:65], v[52:53], v[56:57] neg_lo:[0,0,1] neg_hi:[0,0,1]
	v_pk_mul_f32 v[56:57], v[10:11], v[54:55]
	v_cvt_pk_bf16_f32 v52, v52, v53
	v_pk_fma_f32 v[56:57], v[12:13], v[58:59], v[56:57]
	v_pk_mul_f32 v[58:59], v[10:11], v[58:59]
	v_cvt_pk_bf16_f32 v9, v56, v57
	v_pk_fma_f32 v[54:55], v[12:13], v[54:55], v[58:59] neg_lo:[0,0,1] neg_hi:[0,0,1]
	v_add_u32_e32 v56, 0x1800, v66
	v_cvt_pk_bf16_f32 v53, v54, v55
	ds_write2_b64 v56, v[8:9], v[52:53] offset0:12 offset1:16
	v_mfma_f32_16x16x32_bf16 v[52:55], v[48:51], v[0:3], 0
	v_mfma_f32_16x16x32_bf16 v[48:51], v[48:51], v[4:7], 0
	s_nop 7
	v_pk_mul_f32 v[8:9], v[14:15], v[48:49]
	s_nop 0
	v_pk_fma_f32 v[8:9], v[64:65], v[52:53], v[8:9]
	v_pk_mul_f32 v[52:53], v[14:15], v[52:53]
	v_cvt_pk_bf16_f32 v8, v8, v9
	v_pk_fma_f32 v[48:49], v[64:65], v[48:49], v[52:53] neg_lo:[0,0,1] neg_hi:[0,0,1]
	v_pk_mul_f32 v[52:53], v[10:11], v[50:51]
	v_cvt_pk_bf16_f32 v48, v48, v49
	v_pk_fma_f32 v[52:53], v[12:13], v[54:55], v[52:53]
	v_pk_mul_f32 v[54:55], v[10:11], v[54:55]
	v_cvt_pk_bf16_f32 v9, v52, v53
	v_pk_fma_f32 v[50:51], v[12:13], v[50:51], v[54:55] neg_lo:[0,0,1] neg_hi:[0,0,1]
	v_mov_b32_e32 v52, 0x1c700
	v_cvt_pk_bf16_f32 v49, v50, v51
	ds_write2_b64 v56, v[8:9], v[48:49] offset0:142 offset1:146
	v_mfma_f32_16x16x32_bf16 v[48:51], v[44:47], v[0:3], 0
	v_mad_u32_u24 v134, v77, s6, v52
	v_mfma_f32_16x16x32_bf16 v[44:47], v[44:47], v[4:7], 0
	s_nop 7
	v_pk_mul_f32 v[8:9], v[14:15], v[44:45]
	s_nop 0
	v_pk_fma_f32 v[8:9], v[64:65], v[48:49], v[8:9]
	v_pk_mul_f32 v[48:49], v[14:15], v[48:49]
	v_cvt_pk_bf16_f32 v8, v8, v9
	v_pk_fma_f32 v[44:45], v[64:65], v[44:45], v[48:49] neg_lo:[0,0,1] neg_hi:[0,0,1]
	v_pk_mul_f32 v[48:49], v[10:11], v[46:47]
	v_cvt_pk_bf16_f32 v44, v44, v45
	v_pk_fma_f32 v[48:49], v[12:13], v[50:51], v[48:49]
	v_pk_mul_f32 v[50:51], v[10:11], v[50:51]
	v_cvt_pk_bf16_f32 v9, v48, v49
	v_pk_fma_f32 v[46:47], v[12:13], v[46:47], v[50:51] neg_lo:[0,0,1] neg_hi:[0,0,1]
	v_add_u32_e32 v48, 0x2000, v66
	v_cvt_pk_bf16_f32 v45, v46, v47
	ds_write2_b64 v48, v[8:9], v[44:45] offset0:16 offset1:20
	v_mfma_f32_16x16x32_bf16 v[44:47], v[40:43], v[0:3], 0
	v_mfma_f32_16x16x32_bf16 v[40:43], v[40:43], v[4:7], 0
	s_nop 7
	v_pk_mul_f32 v[8:9], v[14:15], v[40:41]
	s_nop 0
	v_pk_fma_f32 v[8:9], v[64:65], v[44:45], v[8:9]
	v_pk_mul_f32 v[44:45], v[14:15], v[44:45]
	v_cvt_pk_bf16_f32 v8, v8, v9
	v_pk_fma_f32 v[40:41], v[64:65], v[40:41], v[44:45] neg_lo:[0,0,1] neg_hi:[0,0,1]
	v_pk_mul_f32 v[44:45], v[10:11], v[42:43]
	v_cvt_pk_bf16_f32 v40, v40, v41
	v_pk_fma_f32 v[44:45], v[12:13], v[46:47], v[44:45]
	v_pk_mul_f32 v[46:47], v[10:11], v[46:47]
	v_cvt_pk_bf16_f32 v9, v44, v45
	v_pk_fma_f32 v[42:43], v[12:13], v[42:43], v[46:47] neg_lo:[0,0,1] neg_hi:[0,0,1]
	s_nop 0
	v_cvt_pk_bf16_f32 v41, v42, v43
	ds_write2_b64 v48, v[8:9], v[40:41] offset0:146 offset1:150
	v_mfma_f32_16x16x32_bf16 v[40:43], v[36:39], v[0:3], 0
	v_mfma_f32_16x16x32_bf16 v[36:39], v[36:39], v[4:7], 0
	s_nop 7
	v_pk_mul_f32 v[8:9], v[14:15], v[36:37]
	s_nop 0
	v_pk_fma_f32 v[8:9], v[64:65], v[40:41], v[8:9]
	v_pk_mul_f32 v[40:41], v[14:15], v[40:41]
	v_cvt_pk_bf16_f32 v8, v8, v9
	v_pk_fma_f32 v[36:37], v[64:65], v[36:37], v[40:41] neg_lo:[0,0,1] neg_hi:[0,0,1]
	v_pk_mul_f32 v[40:41], v[10:11], v[38:39]
	v_cvt_pk_bf16_f32 v36, v36, v37
	v_pk_fma_f32 v[40:41], v[12:13], v[42:43], v[40:41]
	v_pk_mul_f32 v[42:43], v[10:11], v[42:43]
	v_cvt_pk_bf16_f32 v9, v40, v41
; #define LAS __attribute__((address_space(3)))
; __device__ __forceinline__ unsigned cvtpk(float lo, float hi) { f32x2 v = {lo, hi}; bf16x2_t b = __builtin_convertvector(v, bf16x2_t); return __builtin_bit_cast(unsigned, b); }
; __device__ __forceinline__ void b_unit(Frame& F, int u, bool dry) {
;     ...
; #pragma unroll
;         for (int i = 0; i < 16; ++i) {
;             u32x4 f4; f4.x = q0[i].x; f4.y = q0[i].y; f4.z = q1[i].x; f4.w = q1[i].y;
;             const bf16x8 frag = __builtin_bit_cast(bf16x8, f4);
;             const f32x4 dr = __builtin_amdgcn_mfma_f32_16x16x32_bf16(frag, Wr, zero4, 0, 0, 0), di = __builtin_amdgcn_mfma_f32_16x16x32_bf16(frag, Wi, zero4, 0, 0, 0);
;             float vr[4], vi[4];
; #pragma unroll
;             for (int j = 0; j < 4; ++j) { vr[j] = dr[j] * t2[j].x + di[j] * t2[j].y; vi[j] = di[j] * t2[j].x - dr[j] * t2[j].y; }
;             u32x2 o; o.x = cvtpk(vr[0], vr[1]); o.y = cvtpk(vr[2], vr[3]); *(LAS u32x2*)(vrow + i * 1040) = o;
;             o.x = cvtpk(vi[0], vi[1]); o.y = cvtpk(vi[2], vi[3]); *(LAS u32x2*)(vrow + i * 1040 + 32) = o;
;         }
;         __syncthreads();
; #pragma unroll
;         for (int cc = 0; cc < 2; ++cc)
; #pragma unroll
;             for (int lb = 0; lb < 8; ++lb) {
;                 const bf16x8 frag = *(const LAS bf16x8*)(Bt + (size_t)(16 * lb + fr) * 1040 + 64 * (2 * w + cc) + 16 * fq);
;                 ur[cc][lb] = __builtin_amdgcn_mfma_f32_16x16x32_bf16(frag, Wr, zero4, 0, 0, 0);
;                 ui[cc][lb] = __builtin_amdgcn_mfma_f32_16x16x32_bf16(frag, Wi, zero4, 0, 0, 0);
;             }
	v_pk_fma_f32 v[38:39], v[12:13], v[38:39], v[42:43] neg_lo:[0,0,1] neg_hi:[0,0,1]
	v_add_u32_e32 v40, 0x2800, v66
	v_cvt_pk_bf16_f32 v37, v38, v39
	ds_write2_b64 v40, v[8:9], v[36:37] offset0:20 offset1:24
	v_mfma_f32_16x16x32_bf16 v[36:39], v[32:35], v[0:3], 0
	v_mfma_f32_16x16x32_bf16 v[32:35], v[32:35], v[4:7], 0
	s_nop 7
	v_pk_mul_f32 v[8:9], v[14:15], v[32:33]
	s_nop 0
	v_pk_fma_f32 v[8:9], v[64:65], v[36:37], v[8:9]
	v_pk_mul_f32 v[36:37], v[14:15], v[36:37]
	v_cvt_pk_bf16_f32 v8, v8, v9
	v_pk_fma_f32 v[32:33], v[64:65], v[32:33], v[36:37] neg_lo:[0,0,1] neg_hi:[0,0,1]
	v_pk_mul_f32 v[36:37], v[10:11], v[34:35]
	v_cvt_pk_bf16_f32 v32, v32, v33
	v_pk_fma_f32 v[36:37], v[12:13], v[38:39], v[36:37]
	v_pk_mul_f32 v[38:39], v[10:11], v[38:39]
	v_cvt_pk_bf16_f32 v9, v36, v37
	v_pk_fma_f32 v[34:35], v[12:13], v[34:35], v[38:39] neg_lo:[0,0,1] neg_hi:[0,0,1]
	s_nop 0
	v_cvt_pk_bf16_f32 v33, v34, v35
	ds_write2_b64 v40, v[8:9], v[32:33] offset0:150 offset1:154
	v_mfma_f32_16x16x32_bf16 v[32:35], v[28:31], v[0:3], 0
	v_mov_b32_e32 v40, 0x14500
	v_mad_u32_u24 v118, v77, s6, v40
	v_mfma_f32_16x16x32_bf16 v[28:31], v[28:31], v[4:7], 0
	s_nop 7
	v_pk_mul_f32 v[8:9], v[14:15], v[28:29]
	s_nop 0
	v_pk_fma_f32 v[8:9], v[64:65], v[32:33], v[8:9]
	v_pk_mul_f32 v[32:33], v[14:15], v[32:33]
	v_cvt_pk_bf16_f32 v8, v8, v9
	v_pk_fma_f32 v[28:29], v[64:65], v[28:29], v[32:33] neg_lo:[0,0,1] neg_hi:[0,0,1]
	v_pk_mul_f32 v[32:33], v[10:11], v[30:31]
	v_cvt_pk_bf16_f32 v28, v28, v29
	v_pk_fma_f32 v[32:33], v[12:13], v[34:35], v[32:33]
	v_pk_mul_f32 v[34:35], v[10:11], v[34:35]
	v_cvt_pk_bf16_f32 v9, v32, v33
	v_pk_fma_f32 v[30:31], v[12:13], v[30:31], v[34:35] neg_lo:[0,0,1] neg_hi:[0,0,1]
	v_add_u32_e32 v32, 0x3000, v66
	v_cvt_pk_bf16_f32 v29, v30, v31
	ds_write2_b64 v32, v[8:9], v[28:29] offset0:24 offset1:28
	v_mfma_f32_16x16x32_bf16 v[28:31], v[24:27], v[0:3], 0
	v_mfma_f32_16x16x32_bf16 v[24:27], v[24:27], v[4:7], 0
	s_nop 7
	v_pk_mul_f32 v[8:9], v[14:15], v[24:25]
	s_nop 0
	v_pk_fma_f32 v[8:9], v[64:65], v[28:29], v[8:9]
	v_pk_mul_f32 v[28:29], v[14:15], v[28:29]
	v_cvt_pk_bf16_f32 v8, v8, v9
	v_pk_fma_f32 v[24:25], v[64:65], v[24:25], v[28:29] neg_lo:[0,0,1] neg_hi:[0,0,1]
	v_pk_mul_f32 v[28:29], v[10:11], v[26:27]
	v_cvt_pk_bf16_f32 v24, v24, v25
	v_pk_fma_f32 v[28:29], v[12:13], v[30:31], v[28:29]
	v_pk_mul_f32 v[30:31], v[10:11], v[30:31]
	v_cvt_pk_bf16_f32 v9, v28, v29
	v_pk_fma_f32 v[26:27], v[12:13], v[26:27], v[30:31] neg_lo:[0,0,1] neg_hi:[0,0,1]
	s_nop 0
	v_cvt_pk_bf16_f32 v25, v26, v27
	ds_write2_b64 v32, v[8:9], v[24:25] offset0:154 offset1:158
	v_mfma_f32_16x16x32_bf16 v[24:27], v[20:23], v[0:3], 0
	v_mfma_f32_16x16x32_bf16 v[20:23], v[20:23], v[4:7], 0
	s_nop 7
	v_pk_mul_f32 v[8:9], v[14:15], v[20:21]
	s_nop 0
	v_pk_fma_f32 v[8:9], v[64:65], v[24:25], v[8:9]
	v_pk_mul_f32 v[24:25], v[14:15], v[24:25]
	v_cvt_pk_bf16_f32 v8, v8, v9
	v_pk_fma_f32 v[20:21], v[64:65], v[20:21], v[24:25] neg_lo:[0,0,1] neg_hi:[0,0,1]
	v_pk_mul_f32 v[24:25], v[10:11], v[22:23]
	v_cvt_pk_bf16_f32 v20, v20, v21
	v_pk_fma_f32 v[24:25], v[12:13], v[26:27], v[24:25]
	v_pk_mul_f32 v[26:27], v[10:11], v[26:27]
	v_cvt_pk_bf16_f32 v9, v24, v25
	v_pk_fma_f32 v[22:23], v[12:13], v[22:23], v[26:27] neg_lo:[0,0,1] neg_hi:[0,0,1]
	v_add_u32_e32 v24, 0x3800, v66
	v_cvt_pk_bf16_f32 v21, v22, v23
	ds_write2_b64 v24, v[8:9], v[20:21] offset0:28 offset1:32
	v_mfma_f32_16x16x32_bf16 v[20:23], v[16:19], v[0:3], 0
	v_mfma_f32_16x16x32_bf16 v[16:19], v[16:19], v[4:7], 0
	s_nop 7
	v_pk_mul_f32 v[8:9], v[14:15], v[16:17]
	v_pk_mul_f32 v[14:15], v[14:15], v[20:21]
	v_pk_fma_f32 v[8:9], v[64:65], v[20:21], v[8:9]
	v_pk_fma_f32 v[14:15], v[64:65], v[16:17], v[14:15] neg_lo:[0,0,1] neg_hi:[0,0,1]
	v_pk_mul_f32 v[16:17], v[10:11], v[18:19]
	v_pk_mul_f32 v[10:11], v[10:11], v[22:23]
	v_pk_fma_f32 v[16:17], v[12:13], v[22:23], v[16:17]
	v_pk_fma_f32 v[10:11], v[12:13], v[18:19], v[10:11] neg_lo:[0,0,1] neg_hi:[0,0,1]
	v_cvt_pk_bf16_f32 v8, v8, v9
	v_cvt_pk_bf16_f32 v9, v16, v17
	v_cvt_pk_bf16_f32 v12, v14, v15
	v_cvt_pk_bf16_f32 v13, v10, v11
	ds_write2_b64 v24, v[8:9], v[12:13] offset0:158 offset1:162
	v_and_b32_e32 v8, 48, v170
	v_mov_b32_e32 v16, 0x10400
	v_add_u32_e32 v78, s0, v8
	v_mad_u32_u24 v110, v77, s6, v16
	v_add_u32_e32 v16, v78, v110
	v_add_u32_e32 v40, v78, v118
	s_waitcnt lgkmcnt(0)
	s_barrier
	ds_read_b128 v[16:19], v16
	ds_read_b128 v[40:43], v40
	s_waitcnt lgkmcnt(0)
	v_mfma_f32_16x16x32_bf16 v[64:67], v[40:43], v[0:3], 0
	v_add_u32_e32 v52, v78, v134
	ds_read_b128 v[52:55], v52
	v_mad_u32_u24 v102, v77, s6, v78
	v_mfma_f32_16x16x32_bf16 v[56:59], v[40:43], v[4:7], 0
	v_mov_b32_e32 v40, 0x18600
	v_mad_u32_u24 v126, v77, s6, v40
	v_add_u32_e32 v40, v78, v126
	ds_read_b128 v[40:43], v40
	ds_read_b128 v[8:11], v102
	s_waitcnt lgkmcnt(2)
	v_mfma_f32_16x16x32_bf16 v[72:75], v[52:55], v[0:3], 0
	v_add_u32_e32 v135, 64, v78
	ds_read_b128 v[12:15], v102 offset:49920
	s_mov_b32 s0, 0x1dd6000
	v_mfma_f32_16x16x32_bf16 v[68:71], v[52:55], v[4:7], 0
	ds_read_b128 v[52:55], v102 offset:64
	s_waitcnt lgkmcnt(2)
	v_mfma_f32_16x16x32_bf16 v[36:39], v[8:11], v[0:3], 0
	v_mfma_f32_16x16x32_bf16 v[20:23], v[8:11], v[4:7], 0
	ds_read_b128 v[8:11], v102 offset:16640
	s_waitcnt lgkmcnt(1)
	v_mfma_f32_16x16x32_bf16 v[78:81], v[52:55], v[0:3], 0
	v_mfma_f32_16x16x32_bf16 v[82:85], v[52:55], v[4:7], 0
	ds_read_b128 v[52:55], v102 offset:16704
	s_waitcnt lgkmcnt(1)
	v_mfma_f32_16x16x32_bf16 v[48:51], v[8:11], v[0:3], 0
	v_mfma_f32_16x16x32_bf16 v[24:27], v[8:11], v[4:7], 0
	ds_read_b128 v[8:11], v102 offset:33280
	s_waitcnt lgkmcnt(1)
	v_mfma_f32_16x16x32_bf16 v[86:89], v[52:55], v[0:3], 0
	v_mfma_f32_16x16x32_bf16 v[90:93], v[52:55], v[4:7], 0
	ds_read_b128 v[52:55], v102 offset:33344
	s_waitcnt lgkmcnt(0)
	v_mfma_f32_16x16x32_bf16 v[94:97], v[52:55], v[0:3], 0
	v_mfma_f32_16x16x32_bf16 v[98:101], v[52:55], v[4:7], 0
	ds_read_b128 v[52:55], v102 offset:49984
	s_waitcnt lgkmcnt(0)
	v_mfma_f32_16x16x32_bf16 v[102:105], v[52:55], v[0:3], 0
	v_mfma_f32_16x16x32_bf16 v[106:109], v[52:55], v[4:7], 0
	v_add_u32_e32 v52, v135, v110
	ds_read_b128 v[52:55], v52
	s_waitcnt lgkmcnt(0)
	v_mfma_f32_16x16x32_bf16 v[110:113], v[52:55], v[0:3], 0
	v_mfma_f32_16x16x32_bf16 v[114:117], v[52:55], v[4:7], 0
	v_add_u32_e32 v52, v135, v118
	ds_read_b128 v[52:55], v52
	s_waitcnt lgkmcnt(0)
	v_mfma_f32_16x16x32_bf16 v[118:121], v[52:55], v[0:3], 0
	v_mfma_f32_16x16x32_bf16 v[122:125], v[52:55], v[4:7], 0
	v_add_u32_e32 v52, v135, v126
	ds_read_b128 v[52:55], v52
	s_waitcnt lgkmcnt(0)
	v_mfma_f32_16x16x32_bf16 v[126:129], v[52:55], v[0:3], 0
	v_mfma_f32_16x16x32_bf16 v[130:133], v[52:55], v[4:7], 0
	v_add_u32_e32 v52, v135, v134
	ds_read_b128 v[52:55], v52
	s_waitcnt lgkmcnt(0)
	v_mfma_f32_16x16x32_bf16 v[44:47], v[16:19], v[0:3], 0
	s_barrier
; #define LAS __attribute__((address_space(3)))
; #define GAS __attribute__((address_space(1)))
; __device__ __forceinline__ unsigned cvtpk(float lo, float hi) { f32x2 v = {lo, hi}; bf16x2_t b = __builtin_convertvector(v, bf16x2_t); return __builtin_bit_cast(unsigned, b); }
; __device__ __forceinline__ void b_unit(Frame& F, int u, bool dry) {
;     ...
; #pragma unroll
;         for (int cc = 0; cc < 2; ++cc)
; #pragma unroll
;             for (int lb = 0; lb < 8; ++lb) {
;                 const bf16x8 frag = *(const LAS bf16x8*)(Bt + (size_t)(16 * lb + fr) * 1040 + 64 * (2 * w + cc) + 16 * fq);
;                 ur[cc][lb] = __builtin_amdgcn_mfma_f32_16x16x32_bf16(frag, Wr, zero4, 0, 0, 0);
;                 ui[cc][lb] = __builtin_amdgcn_mfma_f32_16x16x32_bf16(frag, Wi, zero4, 0, 0, 0);
;             }
;     }
;     bf16x8 yr[2][4], yi[2][4];
; #pragma unroll
;     for (int mb = 0; mb < 2; ++mb)
; #pragma unroll
;         for (int t = 0; t < 4; ++t) {
;             u32x4 p; p.x = cvtpk(ur[mb][2 * t][0], ur[mb][2 * t][1]); p.y = cvtpk(ur[mb][2 * t][2], ur[mb][2 * t][3]); p.z = cvtpk(ur[mb][2 * t + 1][0], ur[mb][2 * t + 1][1]); p.w = cvtpk(ur[mb][2 * t + 1][2], ur[mb][2 * t + 1][3]);
;             yr[mb][t] = __builtin_bit_cast(bf16x8, p);
;             p.x = cvtpk(ui[mb][2 * t][0], ui[mb][2 * t][1]); p.y = cvtpk(ui[mb][2 * t][2], ui[mb][2 * t][3]); p.z = cvtpk(ui[mb][2 * t + 1][0], ui[mb][2 * t + 1][1]); p.w = cvtpk(ui[mb][2 * t + 1][2], ui[mb][2 * t + 1][3]);
;             yi[mb][t] = __builtin_bit_cast(bf16x8, p);
;         }
;     bf16_t* SBG = (bf16_t*)(ws_ + WS_SBG);
;     __syncthreads();
;     {   const GAS u32x4* src = (const GAS u32x4*)(ws_ + WS_GT) + (w * 64 + lane); u32x4 tv[8];
; #pragma unroll
;         for (int i = 0; i < 8; ++i) tv[i] = src[i * 512];
; #pragma unroll
;         for (int i = 0; i < 8; ++i) *(LAS u32x4*)(Bt + (size_t)(i * 512 + w * 64 + lane) * 16) = tv[i]; }
;     u32x4 sbq[4][2];
; #pragma unroll
;     for (int p = 0; p < 4; ++p)
; #pragma unroll
;         for (int mb = 0; mb < 2; ++mb) { const int k1 = 2 * w + mb + 16 * fr; const size_t tok = (size_t)b * SEQ + 8 * k1 + k2; sbq[p][mb] = *(const GAS u32x4*)(SBG + tok * 512 + g * 128 + 32 * p + 8 * fq); }
;     __syncthreads();
	v_mfma_f32_16x16x32_bf16 v[60:63], v[40:43], v[0:3], 0
	v_mfma_f32_16x16x32_bf16 v[40:43], v[40:43], v[4:7], 0
	v_mfma_f32_16x16x32_bf16 v[134:137], v[52:55], v[0:3], 0
	v_mfma_f32_16x16x32_bf16 v[138:141], v[52:55], v[4:7], 0
	v_cvt_pk_bf16_f32 v54, v48, v49
	v_cvt_pk_bf16_f32 v48, v20, v21
	s_nop 0
	v_cvt_pk_bf16_f32 v20, v44, v45
	v_cvt_pk_bf16_f32 v44, v98, v99
	v_or_b32_e32 v98, s70, v171
	v_ashrrev_i32_e32 v99, 31, v98
	v_mfma_f32_16x16x32_bf16 v[28:31], v[8:11], v[0:3], 0
	v_cvt_pk_bf16_f32 v49, v22, v23
	v_cvt_pk_bf16_f32 v22, v64, v65
	v_cvt_pk_bf16_f32 v53, v38, v39
	v_mfma_f32_16x16x32_bf16 v[32:35], v[12:15], v[0:3], 0
	v_cvt_pk_bf16_f32 v0, v40, v41
	v_cvt_pk_bf16_f32 v40, v94, v95
	v_lshl_add_u64 v[94:95], v[98:99], 4, s[2:3]
	v_mfma_f32_16x16x32_bf16 v[8:11], v[8:11], v[4:7], 0
	v_add_co_u32_e32 v64, vcc, s8, v94
	v_cvt_pk_bf16_f32 v2, v68, v69
	s_nop 0
	v_addc_co_u32_e32 v65, vcc, 0, v95, vcc
	v_mfma_f32_16x16x32_bf16 v[16:19], v[16:19], v[4:7], 0
	v_add_co_u32_e32 v68, vcc, s0, v94
	s_mov_b32 s0, 0x1dd8000
	s_nop 0
	v_addc_co_u32_e32 v69, vcc, 0, v95, vcc
	v_cvt_pk_bf16_f32 v38, v32, v33
	v_cvt_pk_bf16_f32 v33, v10, v11
	v_cvt_pk_bf16_f32 v10, v72, v73
	v_add_co_u32_e32 v72, vcc, s0, v94
	s_mov_b32 s0, 0x1dda000
	s_nop 0
	v_addc_co_u32_e32 v73, vcc, 0, v95, vcc
	v_cvt_pk_bf16_f32 v16, v16, v17
	v_cvt_pk_bf16_f32 v17, v18, v19
	v_cvt_pk_bf16_f32 v18, v56, v57
	v_cvt_pk_bf16_f32 v56, v78, v79
	v_add_co_u32_e32 v78, vcc, s0, v94
	s_mov_b32 s0, 0x1ddc000
	s_nop 0
	v_addc_co_u32_e32 v79, vcc, 0, v95, vcc
	v_cvt_pk_bf16_f32 v32, v8, v9
	v_cvt_pk_bf16_f32 v8, v60, v61
	v_cvt_pk_bf16_f32 v60, v82, v83
	v_add_co_u32_e32 v82, vcc, s0, v94
	v_cvt_pk_bf16_f32 v23, v66, v67
	global_load_dwordx4 v[64:67], v[64:65], off offset:64
	v_addc_co_u32_e32 v83, vcc, 0, v95, vcc
	s_mov_b32 s0, 0x1dde000
	v_cvt_pk_bf16_f32 v19, v58, v59
	v_cvt_pk_bf16_f32 v3, v70, v71
	v_cvt_pk_bf16_f32 v58, v86, v87
	global_load_dwordx4 v[68:71], v[68:69], off offset:64
	v_add_co_u32_e32 v86, vcc, s0, v94
	v_cvt_pk_bf16_f32 v11, v74, v75
	global_load_dwordx4 v[72:75], v[72:73], off offset:64
	v_addc_co_u32_e32 v87, vcc, 0, v95, vcc
	s_mov_b32 s0, 0x1de0000
	v_cvt_pk_bf16_f32 v9, v62, v63
	v_cvt_pk_bf16_f32 v57, v80, v81
	v_cvt_pk_bf16_f32 v62, v90, v91
	global_load_dwordx4 v[78:81], v[78:79], off offset:64
	v_add_co_u32_e32 v90, vcc, s0, v94
	v_cvt_pk_bf16_f32 v61, v84, v85
	global_load_dwordx4 v[82:85], v[82:83], off offset:64
	v_addc_co_u32_e32 v91, vcc, 0, v95, vcc
	s_mov_b32 s0, 0x1de2000
	v_cvt_pk_bf16_f32 v59, v88, v89
	global_load_dwordx4 v[86:89], v[86:87], off offset:64
	v_add_co_u32_e32 v94, vcc, s0, v94
	v_cvt_pk_bf16_f32 v63, v92, v93
	global_load_dwordx4 v[90:93], v[90:91], off offset:64
	v_addc_co_u32_e32 v95, vcc, 0, v95, vcc
	v_cvt_pk_bf16_f32 v41, v96, v97
	global_load_dwordx4 v[94:97], v[94:95], off offset:64
	v_lshl_add_u32 v98, v98, 4, 0
	v_readlane_b32 s0, v253, 51
	s_waitcnt vmcnt(7)
	ds_write_b128 v98, v[64:67]
	s_waitcnt vmcnt(6)
	ds_write_b128 v98, v[68:71] offset:8192
	s_waitcnt vmcnt(5)
	ds_write_b128 v98, v[72:75] offset:16384
	s_waitcnt vmcnt(4)
	ds_write_b128 v98, v[78:81] offset:24576
	s_waitcnt vmcnt(3)
	ds_write_b128 v98, v[82:85] offset:32768
	s_waitcnt vmcnt(2)
	ds_write_b128 v98, v[86:89] offset:40960
	s_waitcnt vmcnt(1)
	ds_write_b128 v98, v[90:93] offset:49152
	s_waitcnt vmcnt(0)
	ds_write_b128 v98, v[94:97] offset:57344
	v_lshl_add_u32 v64, v77, 7, s0
	v_readlane_b32 s0, v254, 31
	s_add_u32 s0, s2, s0
	s_addc_u32 s1, s3, 0
	v_lshl_add_u64 v[66:67], s[0:1], 0, v[192:193]
	s_mov_b64 s[0:1], 0xa000000
	v_lshl_add_u64 v[66:67], v[66:67], 0, s[0:1]
	v_readlane_b32 s0, v254, 21
	v_mov_b32_e32 v65, v193
	v_readlane_b32 s1, v254, 22
	v_or_b32_e32 v192, 8, v64
	v_cvt_pk_bf16_f32 v45, v100, v101
	v_lshl_add_u64 v[68:69], s[0:1], 0, v[64:65]
	v_lshlrev_b64 v[68:69], 10, v[68:69]
	v_lshl_add_u64 v[98:99], v[66:67], 0, v[68:69]
	global_load_dwordx4 v[92:95], v[98:99], off sc1
	v_lshl_add_u64 v[64:65], s[0:1], 0, v[192:193]
	v_lshlrev_b32_e32 v100, 4, v170
	v_lshlrev_b64 v[64:65], 10, v[64:65]
	v_and_b32_e32 v100, 0x3f0, v100
	v_lshl_add_u64 v[96:97], v[66:67], 0, v[64:65]
	v_add_u32_e32 v100, 0, v100
	v_cvt_pk_bf16_f32 v21, v46, v47
	v_cvt_pk_bf16_f32 v1, v42, v43
	v_cvt_pk_bf16_f32 v42, v102, v103
	v_cvt_pk_bf16_f32 v43, v104, v105
	v_cvt_pk_bf16_f32 v46, v106, v107
	v_cvt_pk_bf16_f32 v47, v108, v109
	global_load_dwordx4 v[88:91], v[96:97], off sc1
	global_load_dwordx4 v[84:87], v[98:99], off offset:64 sc1
	global_load_dwordx4 v[80:83], v[96:97], off offset:64 sc1
	global_load_dwordx4 v[76:79], v[98:99], off offset:128 sc1
	global_load_dwordx4 v[72:75], v[96:97], off offset:128 sc1
	global_load_dwordx4 v[68:71], v[98:99], off offset:192 sc1
	global_load_dwordx4 v[64:67], v[96:97], off offset:192 sc1
	s_waitcnt lgkmcnt(0)
	s_barrier
; #define LAS __attribute__((address_space(3)))
; #define GAS __attribute__((address_space(1)))
; __device__ __forceinline__ unsigned cvtpk(float lo, float hi) { f32x2 v = {lo, hi}; bf16x2_t b = __builtin_convertvector(v, bf16x2_t); return __builtin_bit_cast(unsigned, b); }
; __device__ __forceinline__ float bflo(unsigned w) { return __uint_as_float(w << 16); }
; __device__ __forceinline__ float bfhi(unsigned w) { return __uint_as_float(w & 0xffff0000u); }
; __device__ __forceinline__ void b_unit(Frame& F, int u, bool dry) {
;     ...
;     const LAS unsigned char* XF = Bt + (size_t)(fq * 16 + fr) * 16;
; #pragma unroll
;     for (int p = 0; p < 4; ++p) {
;         f32x4 o3[2][2];
; #pragma unroll
;         for (int h = 0; h < 2; ++h) { const int lb = 2 * p + h;
;             o3[h][0] = (f32x4){0.f, 0.f, 0.f, 0.f}; o3[h][1] = (f32x4){0.f, 0.f, 0.f, 0.f};
; #pragma unroll
;             for (int t = 0; t < 4; ++t) {
;                 const bf16x8 xc = *(const LAS bf16x8*)(XF + (size_t)((lb * 4 + t) * 2 + 0) * 1024), xs = *(const LAS bf16x8*)(XF + (size_t)((lb * 4 + t) * 2 + 1) * 1024);
; #pragma unroll
;                 for (int mb = 0; mb < 2; ++mb) { o3[h][mb] = __builtin_amdgcn_mfma_f32_16x16x32_bf16(xc, yr[mb][t], o3[h][mb], 0, 0, 0); o3[h][mb] = __builtin_amdgcn_mfma_f32_16x16x32_bf16(xs, yi[mb][t], o3[h][mb], 0, 0, 0); }
;             }
;         }
; #pragma unroll
;         for (int mb = 0; mb < 2; ++mb) { const int k1 = 2 * w + mb + 16 * fr; const size_t tok = (size_t)b * SEQ + 8 * k1 + k2; const u32x4 sb = sbq[p][mb]; const f32x4 a0 = o3[0][mb] * 0.001953125f, a1 = o3[1][mb] * 0.001953125f;
;             u32x4 o; o.x = cvtpk(bflo(sb.x) * a0[0], bfhi(sb.x) * a0[1]); o.y = cvtpk(bflo(sb.y) * a0[2], bfhi(sb.y) * a0[3]); o.z = cvtpk(bflo(sb.z) * a1[0], bfhi(sb.z) * a1[1]); o.w = cvtpk(bflo(sb.w) * a1[2], bfhi(sb.w) * a1[3]);
;             if (!dry) *(GAS u32x4*)(SBG + tok * 512 + g * 128 + 32 * p + 8 * fq) = o; }
	ds_read_b128 v[102:105], v100
	ds_read_b128 v[106:109], v100 offset:1024
	v_cvt_pk_bf16_f32 v52, v36, v37
	v_cvt_pk_bf16_f32 v55, v50, v51
	v_cvt_pk_bf16_f32 v50, v24, v25
	v_cvt_pk_bf16_f32 v24, v110, v111
	v_cvt_pk_bf16_f32 v25, v112, v113
	s_waitcnt lgkmcnt(1)
	v_mfma_f32_16x16x32_bf16 v[110:113], v[102:105], v[52:55], 0
	v_cvt_pk_bf16_f32 v51, v26, v27
	v_cvt_pk_bf16_f32 v36, v28, v29
	v_cvt_pk_bf16_f32 v28, v114, v115
	v_mfma_f32_16x16x32_bf16 v[102:105], v[102:105], v[56:59], 0
	v_cvt_pk_bf16_f32 v29, v116, v117
	v_cvt_pk_bf16_f32 v37, v30, v31
	v_cvt_pk_bf16_f32 v39, v34, v35
	s_waitcnt lgkmcnt(0)
	v_mfma_f32_16x16x32_bf16 v[110:113], v[106:109], v[48:51], v[110:113]
	v_cvt_pk_bf16_f32 v26, v118, v119
	v_cvt_pk_bf16_f32 v27, v120, v121
	v_cvt_pk_bf16_f32 v30, v122, v123
	v_mfma_f32_16x16x32_bf16 v[102:105], v[106:109], v[60:63], v[102:105]
	ds_read_b128 v[106:109], v100 offset:2048
	ds_read_b128 v[114:117], v100 offset:3072
	v_cvt_pk_bf16_f32 v31, v124, v125
	s_mov_b32 s0, 0x3b000000
	v_mfma_f32_16x16x32_bf16 v[12:15], v[12:15], v[4:7], 0
	v_cvt_pk_bf16_f32 v4, v130, v131
	v_cvt_pk_bf16_f32 v5, v132, v133
	v_cvt_pk_bf16_f32 v6, v138, v139
	s_waitcnt lgkmcnt(1)
	v_mfma_f32_16x16x32_bf16 v[110:113], v[106:109], v[36:39], v[110:113]
	v_cvt_pk_bf16_f32 v7, v140, v141
	s_nop 1
	v_cvt_pk_bf16_f32 v34, v12, v13
	v_cvt_pk_bf16_f32 v35, v14, v15
	v_mfma_f32_16x16x32_bf16 v[102:105], v[106:109], v[40:43], v[102:105]
	v_cvt_pk_bf16_f32 v12, v126, v127
	v_cvt_pk_bf16_f32 v13, v128, v129
	v_cvt_pk_bf16_f32 v14, v134, v135
	s_waitcnt lgkmcnt(0)
	v_mfma_f32_16x16x32_bf16 v[110:113], v[114:117], v[32:35], v[110:113]
	v_cvt_pk_bf16_f32 v15, v136, v137
	v_mfma_f32_16x16x32_bf16 v[102:105], v[114:117], v[44:47], v[102:105]
	ds_read_b128 v[106:109], v100 offset:4096
	ds_read_b128 v[114:117], v100 offset:5120
	s_waitcnt lgkmcnt(1)
	v_mfma_f32_16x16x32_bf16 v[110:113], v[106:109], v[20:23], v[110:113]
	v_mfma_f32_16x16x32_bf16 v[102:105], v[106:109], v[24:27], v[102:105]
	s_waitcnt lgkmcnt(0)
	v_mfma_f32_16x16x32_bf16 v[110:113], v[114:117], v[16:19], v[110:113]
	v_mfma_f32_16x16x32_bf16 v[102:105], v[114:117], v[28:31], v[102:105]
	ds_read_b128 v[106:109], v100 offset:6144
	ds_read_b128 v[114:117], v100 offset:7168
	s_waitcnt lgkmcnt(1)
	v_mfma_f32_16x16x32_bf16 v[110:113], v[106:109], v[8:11], v[110:113]
	v_mfma_f32_16x16x32_bf16 v[102:105], v[106:109], v[12:15], v[102:105]
	s_waitcnt lgkmcnt(0)
	v_mfma_f32_16x16x32_bf16 v[110:113], v[114:117], v[0:3], v[110:113]
	v_mfma_f32_16x16x32_bf16 v[102:105], v[114:117], v[4:7], v[102:105]
	ds_read_b128 v[106:109], v100 offset:8192
	ds_read_b128 v[114:117], v100 offset:9216
	s_nop 4
	v_pk_mul_f32 v[110:111], v[110:111], s[0:1] op_sel_hi:[1,0]
	v_pk_mul_f32 v[112:113], v[112:113], s[0:1] op_sel_hi:[1,0]
	s_waitcnt lgkmcnt(1)
	v_mfma_f32_16x16x32_bf16 v[118:121], v[106:109], v[52:55], 0
	v_mfma_f32_16x16x32_bf16 v[106:109], v[106:109], v[56:59], 0
	s_waitcnt lgkmcnt(0)
	v_mfma_f32_16x16x32_bf16 v[118:121], v[114:117], v[48:51], v[118:121]
	v_mfma_f32_16x16x32_bf16 v[106:109], v[114:117], v[60:63], v[106:109]
	ds_read_b128 v[114:117], v100 offset:10240
	ds_read_b128 v[122:125], v100 offset:11264
	s_waitcnt lgkmcnt(1)
	v_mfma_f32_16x16x32_bf16 v[118:121], v[114:117], v[36:39], v[118:121]
	v_mfma_f32_16x16x32_bf16 v[106:109], v[114:117], v[40:43], v[106:109]
	s_waitcnt lgkmcnt(0)
	v_mfma_f32_16x16x32_bf16 v[118:121], v[122:125], v[32:35], v[118:121]
	v_mfma_f32_16x16x32_bf16 v[106:109], v[122:125], v[44:47], v[106:109]
	ds_read_b128 v[114:117], v100 offset:12288
	ds_read_b128 v[122:125], v100 offset:13312
	s_waitcnt lgkmcnt(1)
	v_mfma_f32_16x16x32_bf16 v[118:121], v[114:117], v[20:23], v[118:121]
	v_mfma_f32_16x16x32_bf16 v[106:109], v[114:117], v[24:27], v[106:109]
	s_waitcnt lgkmcnt(0)
	v_mfma_f32_16x16x32_bf16 v[118:121], v[122:125], v[16:19], v[118:121]
	v_mfma_f32_16x16x32_bf16 v[106:109], v[122:125], v[28:31], v[106:109]
	ds_read_b128 v[114:117], v100 offset:14336
	ds_read_b128 v[122:125], v100 offset:15360
	s_waitcnt lgkmcnt(1)
	v_mfma_f32_16x16x32_bf16 v[118:121], v[114:117], v[8:11], v[118:121]
	s_waitcnt lgkmcnt(0)
	v_mfma_f32_16x16x32_bf16 v[118:121], v[122:125], v[0:3], v[118:121]
	v_mfma_f32_16x16x32_bf16 v[106:109], v[114:117], v[12:15], v[106:109]
	v_mfma_f32_16x16x32_bf16 v[106:109], v[122:125], v[4:7], v[106:109]
	s_nop 5
	v_mul_f32_e64 v116, v118, s0
	v_mul_f32_e64 v117, v119, s0
	s_waitcnt vmcnt(7)
	v_lshlrev_b32_e32 v118, 16, v92
	v_and_b32_e32 v119, 0xffff0000, v92
	v_pk_mul_f32 v[110:111], v[110:111], v[118:119]
	v_pk_mul_f32 v[114:115], v[120:121], s[0:1] op_sel_hi:[1,0]
	v_cvt_pk_bf16_f32 v92, v110, v111
	v_lshlrev_b32_e32 v110, 16, v93
	v_and_b32_e32 v111, 0xffff0000, v93
	v_pk_mul_f32 v[110:111], v[112:113], v[110:111]
	s_nop 0
	v_cvt_pk_bf16_f32 v93, v110, v111
	v_lshlrev_b32_e32 v110, 16, v94
	v_and_b32_e32 v111, 0xffff0000, v94
	v_pk_mul_f32 v[110:111], v[116:117], v[110:111]
	s_nop 0
	v_cvt_pk_bf16_f32 v94, v110, v111
	v_lshlrev_b32_e32 v110, 16, v95
	v_and_b32_e32 v111, 0xffff0000, v95
	v_pk_mul_f32 v[110:111], v[114:115], v[110:111]
	s_nop 0
	v_cvt_pk_bf16_f32 v95, v110, v111
	global_store_dwordx4 v[98:99], v[92:95], off
	s_nop 1
	v_pk_mul_f32 v[92:93], v[104:105], s[0:1] op_sel_hi:[1,0]
	v_pk_mul_f32 v[94:95], v[102:103], s[0:1] op_sel_hi:[1,0]
	v_pk_mul_f32 v[104:105], v[106:107], s[0:1] op_sel_hi:[1,0]
	s_waitcnt vmcnt(7)
; #define LAS __attribute__((address_space(3)))
; #define GAS __attribute__((address_space(1)))
; __device__ __forceinline__ unsigned cvtpk(float lo, float hi) { f32x2 v = {lo, hi}; bf16x2_t b = __builtin_convertvector(v, bf16x2_t); return __builtin_bit_cast(unsigned, b); }
; __device__ __forceinline__ float bflo(unsigned w) { return __uint_as_float(w << 16); }
; __device__ __forceinline__ float bfhi(unsigned w) { return __uint_as_float(w & 0xffff0000u); }
; __device__ __forceinline__ void b_unit(Frame& F, int u, bool dry) {
;     ...
;     const LAS unsigned char* XF = Bt + (size_t)(fq * 16 + fr) * 16;
; #pragma unroll
;     for (int p = 0; p < 4; ++p) {
;         f32x4 o3[2][2];
; #pragma unroll
;         for (int h = 0; h < 2; ++h) { const int lb = 2 * p + h;
;             o3[h][0] = (f32x4){0.f, 0.f, 0.f, 0.f}; o3[h][1] = (f32x4){0.f, 0.f, 0.f, 0.f};
; #pragma unroll
;             for (int t = 0; t < 4; ++t) {
;                 const bf16x8 xc = *(const LAS bf16x8*)(XF + (size_t)((lb * 4 + t) * 2 + 0) * 1024), xs = *(const LAS bf16x8*)(XF + (size_t)((lb * 4 + t) * 2 + 1) * 1024);
; #pragma unroll
;                 for (int mb = 0; mb < 2; ++mb) { o3[h][mb] = __builtin_amdgcn_mfma_f32_16x16x32_bf16(xc, yr[mb][t], o3[h][mb], 0, 0, 0); o3[h][mb] = __builtin_amdgcn_mfma_f32_16x16x32_bf16(xs, yi[mb][t], o3[h][mb], 0, 0, 0); }
;             }
;         }
; #pragma unroll
;         for (int mb = 0; mb < 2; ++mb) { const int k1 = 2 * w + mb + 16 * fr; const size_t tok = (size_t)b * SEQ + 8 * k1 + k2; const u32x4 sb = sbq[p][mb]; const f32x4 a0 = o3[0][mb] * 0.001953125f, a1 = o3[1][mb] * 0.001953125f;
;             u32x4 o; o.x = cvtpk(bflo(sb.x) * a0[0], bfhi(sb.x) * a0[1]); o.y = cvtpk(bflo(sb.y) * a0[2], bfhi(sb.y) * a0[3]); o.z = cvtpk(bflo(sb.z) * a1[0], bfhi(sb.z) * a1[1]); o.w = cvtpk(bflo(sb.w) * a1[2], bfhi(sb.w) * a1[3]);
;             if (!dry) *(GAS u32x4*)(SBG + tok * 512 + g * 128 + 32 * p + 8 * fq) = o; }
	v_lshlrev_b32_e32 v106, 16, v88
	v_and_b32_e32 v107, 0xffff0000, v88
	v_pk_mul_f32 v[94:95], v[94:95], v[106:107]
	v_pk_mul_f32 v[102:103], v[108:109], s[0:1] op_sel_hi:[1,0]
	v_cvt_pk_bf16_f32 v88, v94, v95
	v_lshlrev_b32_e32 v94, 16, v89
	v_and_b32_e32 v95, 0xffff0000, v89
	v_pk_mul_f32 v[92:93], v[92:93], v[94:95]
	s_nop 0
	v_cvt_pk_bf16_f32 v89, v92, v93
	v_lshlrev_b32_e32 v92, 16, v90
	v_and_b32_e32 v93, 0xffff0000, v90
	v_pk_mul_f32 v[92:93], v[104:105], v[92:93]
	s_nop 0
	v_cvt_pk_bf16_f32 v90, v92, v93
	v_lshlrev_b32_e32 v92, 16, v91
	v_and_b32_e32 v93, 0xffff0000, v91
	v_pk_mul_f32 v[92:93], v[102:103], v[92:93]
	s_nop 0
	v_cvt_pk_bf16_f32 v91, v92, v93
	global_store_dwordx4 v[96:97], v[88:91], off
	ds_read_b128 v[88:91], v100 offset:16384
	ds_read_b128 v[92:95], v100 offset:17408
	s_waitcnt lgkmcnt(1)
	v_mfma_f32_16x16x32_bf16 v[102:105], v[88:91], v[52:55], 0
	v_mfma_f32_16x16x32_bf16 v[88:91], v[88:91], v[56:59], 0
	s_waitcnt lgkmcnt(0)
	v_mfma_f32_16x16x32_bf16 v[102:105], v[92:95], v[48:51], v[102:105]
	v_mfma_f32_16x16x32_bf16 v[88:91], v[92:95], v[60:63], v[88:91]
	ds_read_b128 v[92:95], v100 offset:18432
	ds_read_b128 v[106:109], v100 offset:19456
	s_waitcnt lgkmcnt(1)
	v_mfma_f32_16x16x32_bf16 v[102:105], v[92:95], v[36:39], v[102:105]
	v_mfma_f32_16x16x32_bf16 v[88:91], v[92:95], v[40:43], v[88:91]
	s_waitcnt lgkmcnt(0)
	v_mfma_f32_16x16x32_bf16 v[102:105], v[106:109], v[32:35], v[102:105]
	v_mfma_f32_16x16x32_bf16 v[88:91], v[106:109], v[44:47], v[88:91]
	ds_read_b128 v[92:95], v100 offset:20480
	ds_read_b128 v[106:109], v100 offset:21504
	s_waitcnt lgkmcnt(1)
	v_mfma_f32_16x16x32_bf16 v[102:105], v[92:95], v[20:23], v[102:105]
	v_mfma_f32_16x16x32_bf16 v[88:91], v[92:95], v[24:27], v[88:91]
	s_waitcnt lgkmcnt(0)
	v_mfma_f32_16x16x32_bf16 v[102:105], v[106:109], v[16:19], v[102:105]
	v_mfma_f32_16x16x32_bf16 v[88:91], v[106:109], v[28:31], v[88:91]
	ds_read_b128 v[92:95], v100 offset:22528
	ds_read_b128 v[106:109], v100 offset:23552
	s_waitcnt lgkmcnt(1)
	v_mfma_f32_16x16x32_bf16 v[102:105], v[92:95], v[8:11], v[102:105]
	v_mfma_f32_16x16x32_bf16 v[88:91], v[92:95], v[12:15], v[88:91]
	s_waitcnt lgkmcnt(0)
	v_mfma_f32_16x16x32_bf16 v[102:105], v[106:109], v[0:3], v[102:105]
	v_mfma_f32_16x16x32_bf16 v[88:91], v[106:109], v[4:7], v[88:91]
	ds_read_b128 v[92:95], v100 offset:24576
	ds_read_b128 v[106:109], v100 offset:25600
	s_nop 4
	v_pk_mul_f32 v[102:103], v[102:103], s[0:1] op_sel_hi:[1,0]
	v_pk_mul_f32 v[104:105], v[104:105], s[0:1] op_sel_hi:[1,0]
	s_waitcnt lgkmcnt(1)
	v_mfma_f32_16x16x32_bf16 v[110:113], v[92:95], v[52:55], 0
	v_mfma_f32_16x16x32_bf16 v[92:95], v[92:95], v[56:59], 0
	s_waitcnt lgkmcnt(0)
	v_mfma_f32_16x16x32_bf16 v[110:113], v[106:109], v[48:51], v[110:113]
	v_mfma_f32_16x16x32_bf16 v[92:95], v[106:109], v[60:63], v[92:95]
	ds_read_b128 v[106:109], v100 offset:26624
	ds_read_b128 v[114:117], v100 offset:27648
	s_waitcnt lgkmcnt(1)
	v_mfma_f32_16x16x32_bf16 v[110:113], v[106:109], v[36:39], v[110:113]
	v_mfma_f32_16x16x32_bf16 v[92:95], v[106:109], v[40:43], v[92:95]
	s_waitcnt lgkmcnt(0)
	v_mfma_f32_16x16x32_bf16 v[110:113], v[114:117], v[32:35], v[110:113]
	v_mfma_f32_16x16x32_bf16 v[92:95], v[114:117], v[44:47], v[92:95]
	ds_read_b128 v[106:109], v100 offset:28672
	ds_read_b128 v[114:117], v100 offset:29696
	s_waitcnt lgkmcnt(1)
	v_mfma_f32_16x16x32_bf16 v[110:113], v[106:109], v[20:23], v[110:113]
	v_mfma_f32_16x16x32_bf16 v[92:95], v[106:109], v[24:27], v[92:95]
	s_waitcnt lgkmcnt(0)
	v_mfma_f32_16x16x32_bf16 v[110:113], v[114:117], v[16:19], v[110:113]
	v_mfma_f32_16x16x32_bf16 v[92:95], v[114:117], v[28:31], v[92:95]
	ds_read_b128 v[106:109], v100 offset:30720
	ds_read_b128 v[114:117], v100 offset:31744
	s_waitcnt lgkmcnt(1)
	v_mfma_f32_16x16x32_bf16 v[110:113], v[106:109], v[8:11], v[110:113]
	s_waitcnt lgkmcnt(0)
	v_mfma_f32_16x16x32_bf16 v[110:113], v[114:117], v[0:3], v[110:113]
	v_mfma_f32_16x16x32_bf16 v[92:95], v[106:109], v[12:15], v[92:95]
	v_mfma_f32_16x16x32_bf16 v[92:95], v[114:117], v[4:7], v[92:95]
	s_nop 5
	v_mul_f32_e64 v108, v110, s0
	v_mul_f32_e64 v109, v111, s0
	s_waitcnt vmcnt(7)
	v_lshlrev_b32_e32 v110, 16, v84
	v_and_b32_e32 v111, 0xffff0000, v84
	v_pk_mul_f32 v[102:103], v[102:103], v[110:111]
	v_pk_mul_f32 v[106:107], v[112:113], s[0:1] op_sel_hi:[1,0]
	v_cvt_pk_bf16_f32 v84, v102, v103
	v_lshlrev_b32_e32 v102, 16, v85
	v_and_b32_e32 v103, 0xffff0000, v85
	v_pk_mul_f32 v[102:103], v[104:105], v[102:103]
	s_nop 0
	v_cvt_pk_bf16_f32 v85, v102, v103
	v_lshlrev_b32_e32 v102, 16, v86
	v_and_b32_e32 v103, 0xffff0000, v86
	v_pk_mul_f32 v[102:103], v[108:109], v[102:103]
	s_nop 0
	v_cvt_pk_bf16_f32 v86, v102, v103
	v_lshlrev_b32_e32 v102, 16, v87
	v_and_b32_e32 v103, 0xffff0000, v87
	v_pk_mul_f32 v[102:103], v[106:107], v[102:103]
	s_nop 0
	v_cvt_pk_bf16_f32 v87, v102, v103
	global_store_dwordx4 v[98:99], v[84:87], off offset:64
	s_nop 1
	v_pk_mul_f32 v[84:85], v[90:91], s[0:1] op_sel_hi:[1,0]
	v_pk_mul_f32 v[86:87], v[88:89], s[0:1] op_sel_hi:[1,0]
	v_pk_mul_f32 v[90:91], v[92:93], s[0:1] op_sel_hi:[1,0]
	s_waitcnt vmcnt(7)
	v_lshlrev_b32_e32 v92, 16, v80
	v_and_b32_e32 v93, 0xffff0000, v80
	v_pk_mul_f32 v[86:87], v[86:87], v[92:93]
	v_pk_mul_f32 v[88:89], v[94:95], s[0:1] op_sel_hi:[1,0]
	v_cvt_pk_bf16_f32 v80, v86, v87
	v_lshlrev_b32_e32 v86, 16, v81
	v_and_b32_e32 v87, 0xffff0000, v81
	v_pk_mul_f32 v[84:85], v[84:85], v[86:87]
	s_nop 0
	v_cvt_pk_bf16_f32 v81, v84, v85
	v_lshlrev_b32_e32 v84, 16, v82
	v_and_b32_e32 v85, 0xffff0000, v82
	v_pk_mul_f32 v[84:85], v[90:91], v[84:85]
	s_nop 0
	v_cvt_pk_bf16_f32 v82, v84, v85
	v_lshlrev_b32_e32 v84, 16, v83
	v_and_b32_e32 v85, 0xffff0000, v83
	v_pk_mul_f32 v[84:85], v[88:89], v[84:85]
	s_nop 0
	v_cvt_pk_bf16_f32 v83, v84, v85
	global_store_dwordx4 v[96:97], v[80:83], off offset:64
	ds_read_b128 v[80:83], v100 offset:32768
	ds_read_b128 v[84:87], v100 offset:33792
	s_waitcnt lgkmcnt(1)
; #define LAS __attribute__((address_space(3)))
; #define GAS __attribute__((address_space(1)))
; __device__ __forceinline__ unsigned cvtpk(float lo, float hi) { f32x2 v = {lo, hi}; bf16x2_t b = __builtin_convertvector(v, bf16x2_t); return __builtin_bit_cast(unsigned, b); }
; __device__ __forceinline__ float bflo(unsigned w) { return __uint_as_float(w << 16); }
; __device__ __forceinline__ float bfhi(unsigned w) { return __uint_as_float(w & 0xffff0000u); }
; __device__ __forceinline__ void b_unit(Frame& F, int u, bool dry) {
;     ...
;     const LAS unsigned char* XF = Bt + (size_t)(fq * 16 + fr) * 16;
; #pragma unroll
;     for (int p = 0; p < 4; ++p) {
;         f32x4 o3[2][2];
; #pragma unroll
;         for (int h = 0; h < 2; ++h) { const int lb = 2 * p + h;
;             o3[h][0] = (f32x4){0.f, 0.f, 0.f, 0.f}; o3[h][1] = (f32x4){0.f, 0.f, 0.f, 0.f};
; #pragma unroll
;             for (int t = 0; t < 4; ++t) {
;                 const bf16x8 xc = *(const LAS bf16x8*)(XF + (size_t)((lb * 4 + t) * 2 + 0) * 1024), xs = *(const LAS bf16x8*)(XF + (size_t)((lb * 4 + t) * 2 + 1) * 1024);
; #pragma unroll
;                 for (int mb = 0; mb < 2; ++mb) { o3[h][mb] = __builtin_amdgcn_mfma_f32_16x16x32_bf16(xc, yr[mb][t], o3[h][mb], 0, 0, 0); o3[h][mb] = __builtin_amdgcn_mfma_f32_16x16x32_bf16(xs, yi[mb][t], o3[h][mb], 0, 0, 0); }
;             }
;         }
; #pragma unroll
;         for (int mb = 0; mb < 2; ++mb) { const int k1 = 2 * w + mb + 16 * fr; const size_t tok = (size_t)b * SEQ + 8 * k1 + k2; const u32x4 sb = sbq[p][mb]; const f32x4 a0 = o3[0][mb] * 0.001953125f, a1 = o3[1][mb] * 0.001953125f;
;             u32x4 o; o.x = cvtpk(bflo(sb.x) * a0[0], bfhi(sb.x) * a0[1]); o.y = cvtpk(bflo(sb.y) * a0[2], bfhi(sb.y) * a0[3]); o.z = cvtpk(bflo(sb.z) * a1[0], bfhi(sb.z) * a1[1]); o.w = cvtpk(bflo(sb.w) * a1[2], bfhi(sb.w) * a1[3]);
;             if (!dry) *(GAS u32x4*)(SBG + tok * 512 + g * 128 + 32 * p + 8 * fq) = o; }
	v_mfma_f32_16x16x32_bf16 v[88:91], v[80:83], v[52:55], 0
	v_mfma_f32_16x16x32_bf16 v[80:83], v[80:83], v[56:59], 0
	s_waitcnt lgkmcnt(0)
	v_mfma_f32_16x16x32_bf16 v[88:91], v[84:87], v[48:51], v[88:91]
	v_mfma_f32_16x16x32_bf16 v[80:83], v[84:87], v[60:63], v[80:83]
	ds_read_b128 v[84:87], v100 offset:34816
	ds_read_b128 v[92:95], v100 offset:35840
	s_waitcnt lgkmcnt(1)
	v_mfma_f32_16x16x32_bf16 v[88:91], v[84:87], v[36:39], v[88:91]
	v_mfma_f32_16x16x32_bf16 v[80:83], v[84:87], v[40:43], v[80:83]
	s_waitcnt lgkmcnt(0)
	v_mfma_f32_16x16x32_bf16 v[88:91], v[92:95], v[32:35], v[88:91]
	v_mfma_f32_16x16x32_bf16 v[80:83], v[92:95], v[44:47], v[80:83]
	ds_read_b128 v[84:87], v100 offset:36864
	ds_read_b128 v[92:95], v100 offset:37888
	s_waitcnt lgkmcnt(1)
	v_mfma_f32_16x16x32_bf16 v[88:91], v[84:87], v[20:23], v[88:91]
	v_mfma_f32_16x16x32_bf16 v[80:83], v[84:87], v[24:27], v[80:83]
	s_waitcnt lgkmcnt(0)
	v_mfma_f32_16x16x32_bf16 v[88:91], v[92:95], v[16:19], v[88:91]
	v_mfma_f32_16x16x32_bf16 v[80:83], v[92:95], v[28:31], v[80:83]
	ds_read_b128 v[92:95], v100 offset:38912
	ds_read_b128 v[102:105], v100 offset:39936
	s_waitcnt lgkmcnt(1)
	v_mfma_f32_16x16x32_bf16 v[84:87], v[92:95], v[8:11], v[88:91]
	v_mfma_f32_16x16x32_bf16 v[80:83], v[92:95], v[12:15], v[80:83]
	s_nop 1
	ds_read_b128 v[88:91], v100 offset:40960
	ds_read_b128 v[92:95], v100 offset:41984
	s_waitcnt lgkmcnt(2)
	v_mfma_f32_16x16x32_bf16 v[84:87], v[102:105], v[0:3], v[84:87]
	v_mfma_f32_16x16x32_bf16 v[80:83], v[102:105], v[4:7], v[80:83]
	s_waitcnt lgkmcnt(1)
	v_mfma_f32_16x16x32_bf16 v[102:105], v[88:91], v[52:55], 0
	s_nop 4
	v_mul_f32_e64 v84, v84, s0
	v_mul_f32_e64 v85, v85, s0
	v_pk_mul_f32 v[86:87], v[86:87], s[0:1] op_sel_hi:[1,0]
	v_mfma_f32_16x16x32_bf16 v[88:91], v[88:91], v[56:59], 0
	s_waitcnt lgkmcnt(0)
	v_mfma_f32_16x16x32_bf16 v[102:105], v[92:95], v[48:51], v[102:105]
	v_mfma_f32_16x16x32_bf16 v[88:91], v[92:95], v[60:63], v[88:91]
	ds_read_b128 v[92:95], v100 offset:43008
	ds_read_b128 v[106:109], v100 offset:44032
	s_waitcnt lgkmcnt(1)
	v_mfma_f32_16x16x32_bf16 v[102:105], v[92:95], v[36:39], v[102:105]
	v_mfma_f32_16x16x32_bf16 v[88:91], v[92:95], v[40:43], v[88:91]
	s_waitcnt lgkmcnt(0)
	v_mfma_f32_16x16x32_bf16 v[102:105], v[106:109], v[32:35], v[102:105]
	v_mfma_f32_16x16x32_bf16 v[88:91], v[106:109], v[44:47], v[88:91]
	ds_read_b128 v[92:95], v100 offset:45056
	ds_read_b128 v[106:109], v100 offset:46080
	s_waitcnt lgkmcnt(1)
	v_mfma_f32_16x16x32_bf16 v[102:105], v[92:95], v[20:23], v[102:105]
	v_mfma_f32_16x16x32_bf16 v[88:91], v[92:95], v[24:27], v[88:91]
	s_waitcnt lgkmcnt(0)
	v_mfma_f32_16x16x32_bf16 v[102:105], v[106:109], v[16:19], v[102:105]
	v_mfma_f32_16x16x32_bf16 v[88:91], v[106:109], v[28:31], v[88:91]
	ds_read_b128 v[92:95], v100 offset:47104
	ds_read_b128 v[106:109], v100 offset:48128
	s_waitcnt lgkmcnt(1)
	v_mfma_f32_16x16x32_bf16 v[102:105], v[92:95], v[8:11], v[102:105]
	s_waitcnt lgkmcnt(0)
	v_mfma_f32_16x16x32_bf16 v[102:105], v[106:109], v[0:3], v[102:105]
	v_mfma_f32_16x16x32_bf16 v[88:91], v[92:95], v[12:15], v[88:91]
	v_mfma_f32_16x16x32_bf16 v[88:91], v[106:109], v[4:7], v[88:91]
	s_nop 5
	v_mul_f32_e64 v94, v102, s0
	v_mul_f32_e64 v95, v103, s0
	s_waitcnt vmcnt(7)
	v_lshlrev_b32_e32 v102, 16, v76
	v_and_b32_e32 v103, 0xffff0000, v76
	v_pk_mul_f32 v[84:85], v[84:85], v[102:103]
	v_pk_mul_f32 v[92:93], v[104:105], s[0:1] op_sel_hi:[1,0]
	v_cvt_pk_bf16_f32 v76, v84, v85
	v_lshlrev_b32_e32 v84, 16, v77
	v_and_b32_e32 v85, 0xffff0000, v77
	v_pk_mul_f32 v[84:85], v[86:87], v[84:85]
	s_nop 0
	v_cvt_pk_bf16_f32 v77, v84, v85
	v_lshlrev_b32_e32 v84, 16, v78
	v_and_b32_e32 v85, 0xffff0000, v78
	v_pk_mul_f32 v[84:85], v[94:95], v[84:85]
	s_nop 0
	v_cvt_pk_bf16_f32 v78, v84, v85
	v_lshlrev_b32_e32 v84, 16, v79
	v_and_b32_e32 v85, 0xffff0000, v79
	v_pk_mul_f32 v[84:85], v[92:93], v[84:85]
	s_nop 0
	v_cvt_pk_bf16_f32 v79, v84, v85
	global_store_dwordx4 v[98:99], v[76:79], off offset:128
	s_waitcnt vmcnt(7)
	v_lshlrev_b32_e32 v84, 16, v72
	v_and_b32_e32 v85, 0xffff0000, v72
	v_pk_mul_f32 v[78:79], v[80:81], s[0:1] op_sel_hi:[1,0]
	v_pk_mul_f32 v[76:77], v[82:83], s[0:1] op_sel_hi:[1,0]
	v_pk_mul_f32 v[78:79], v[78:79], v[84:85]
	v_pk_mul_f32 v[82:83], v[88:89], s[0:1] op_sel_hi:[1,0]
	v_cvt_pk_bf16_f32 v72, v78, v79
	v_lshlrev_b32_e32 v78, 16, v73
	v_and_b32_e32 v79, 0xffff0000, v73
	v_pk_mul_f32 v[76:77], v[76:77], v[78:79]
	v_pk_mul_f32 v[80:81], v[90:91], s[0:1] op_sel_hi:[1,0]
	v_cvt_pk_bf16_f32 v73, v76, v77
	v_lshlrev_b32_e32 v76, 16, v74
	v_and_b32_e32 v77, 0xffff0000, v74
	v_pk_mul_f32 v[76:77], v[82:83], v[76:77]
	s_nop 0
	v_cvt_pk_bf16_f32 v74, v76, v77
	v_lshlrev_b32_e32 v76, 16, v75
	v_and_b32_e32 v77, 0xffff0000, v75
	v_pk_mul_f32 v[76:77], v[80:81], v[76:77]
	s_nop 0
	v_cvt_pk_bf16_f32 v75, v76, v77
	global_store_dwordx4 v[96:97], v[72:75], off offset:128
	ds_read_b128 v[72:75], v100 offset:49152
	ds_read_b128 v[76:79], v100 offset:50176
	s_waitcnt lgkmcnt(1)
	v_mfma_f32_16x16x32_bf16 v[80:83], v[72:75], v[52:55], 0
	v_mfma_f32_16x16x32_bf16 v[72:75], v[72:75], v[56:59], 0
	s_waitcnt lgkmcnt(0)
	v_mfma_f32_16x16x32_bf16 v[80:83], v[76:79], v[48:51], v[80:83]
	v_mfma_f32_16x16x32_bf16 v[72:75], v[76:79], v[60:63], v[72:75]
	ds_read_b128 v[76:79], v100 offset:51200
	ds_read_b128 v[84:87], v100 offset:52224
	s_waitcnt lgkmcnt(1)
	v_mfma_f32_16x16x32_bf16 v[80:83], v[76:79], v[36:39], v[80:83]
	v_mfma_f32_16x16x32_bf16 v[72:75], v[76:79], v[40:43], v[72:75]
	s_waitcnt lgkmcnt(0)
	v_mfma_f32_16x16x32_bf16 v[80:83], v[84:87], v[32:35], v[80:83]
	v_mfma_f32_16x16x32_bf16 v[72:75], v[84:87], v[44:47], v[72:75]
	ds_read_b128 v[76:79], v100 offset:53248
	ds_read_b128 v[84:87], v100 offset:54272
	s_waitcnt lgkmcnt(1)
; #define LAS __attribute__((address_space(3)))
; __device__ __forceinline__ void a_unit(Frame& F, int L, int u, bool dry) {
;     ...
;     const int b = u >> 5, chunk = (u >> 1) & 15, qh = u & 1;
;     const int w = F.wave, lane = otid(F.wave) & 63, tg = lane & 15, cr = lane >> 4, fr = lane & 15, fq = lane >> 4;
;     const bf16_t* gvt = (const bf16_t*)(ws_ + WS_GVT) + (size_t)((b * 16 + chunk) * 512) * 128;
;     LAS unsigned char* VT = F.lds + w * 17408;
;     LAS float* part = (LAS float*)(F.lds + 139264);
;     const bf16_t* Wh = (const bf16_t*)(ws_ + WS_AWS) + (size_t)((L * 8 + w) * 2 + qh) * 8192 + (size_t)lane * 8;
;     float s[8], q[8];
; #pragma unroll
;     for (int j = 0; j < 8; ++j) { s[j] = 0.f; q[j] = 0.f; }
;     u32x4 raw[16];
;     {
; #pragma unroll
;         for (int i = 0; i < 16; ++i) raw[i] = *(const GAS u32x4*)(gvt + (size_t)(64 * w + 4 * i + cr) * 128 + 8 * tg);
; __device__ __forceinline__ void b_unit(Frame& F, int u, bool dry) {
;     ...
;     const LAS unsigned char* XF = Bt + (size_t)(fq * 16 + fr) * 16;
; #pragma unroll
;     for (int p = 0; p < 4; ++p) {
;         f32x4 o3[2][2];
; #pragma unroll
;         for (int h = 0; h < 2; ++h) { const int lb = 2 * p + h;
;             o3[h][0] = (f32x4){0.f, 0.f, 0.f, 0.f}; o3[h][1] = (f32x4){0.f, 0.f, 0.f, 0.f};
; #pragma unroll
;             for (int t = 0; t < 4; ++t) {
;                 const bf16x8 xc = *(const LAS bf16x8*)(XF + (size_t)((lb * 4 + t) * 2 + 0) * 1024), xs = *(const LAS bf16x8*)(XF + (size_t)((lb * 4 + t) * 2 + 1) * 1024);
; #pragma unroll
;                 for (int mb = 0; mb < 2; ++mb) { o3[h][mb] = __builtin_amdgcn_mfma_f32_16x16x32_bf16(xc, yr[mb][t], o3[h][mb], 0, 0, 0); o3[h][mb] = __builtin_amdgcn_mfma_f32_16x16x32_bf16(xs, yi[mb][t], o3[h][mb], 0, 0, 0); }
;             }
;         }
; #pragma unroll
;         for (int mb = 0; mb < 2; ++mb) { const int k1 = 2 * w + mb + 16 * fr; const size_t tok = (size_t)b * SEQ + 8 * k1 + k2; const u32x4 sb = sbq[p][mb]; const f32x4 a0 = o3[0][mb] * 0.001953125f, a1 = o3[1][mb] * 0.001953125f;
;             u32x4 o; o.x = cvtpk(bflo(sb.x) * a0[0], bfhi(sb.x) * a0[1]); o.y = cvtpk(bflo(sb.y) * a0[2], bfhi(sb.y) * a0[3]); o.z = cvtpk(bflo(sb.z) * a1[0], bfhi(sb.z) * a1[1]); o.w = cvtpk(bflo(sb.w) * a1[2], bfhi(sb.w) * a1[3]);
;             if (!dry) *(GAS u32x4*)(SBG + tok * 512 + g * 128 + 32 * p + 8 * fq) = o; }
;     }
	v_mfma_f32_16x16x32_bf16 v[80:83], v[76:79], v[20:23], v[80:83]
	v_mfma_f32_16x16x32_bf16 v[72:75], v[76:79], v[24:27], v[72:75]
	s_waitcnt lgkmcnt(0)
	v_mfma_f32_16x16x32_bf16 v[80:83], v[84:87], v[16:19], v[80:83]
	v_mfma_f32_16x16x32_bf16 v[72:75], v[84:87], v[28:31], v[72:75]
	ds_read_b128 v[84:87], v100 offset:55296
	ds_read_b128 v[88:91], v100 offset:56320
	s_waitcnt lgkmcnt(1)
	v_mfma_f32_16x16x32_bf16 v[76:79], v[84:87], v[8:11], v[80:83]
	v_mfma_f32_16x16x32_bf16 v[72:75], v[84:87], v[12:15], v[72:75]
	s_nop 1
	ds_read_b128 v[80:83], v100 offset:57344
	ds_read_b128 v[84:87], v100 offset:58368
	s_waitcnt lgkmcnt(1)
	v_mfma_f32_16x16x32_bf16 v[52:55], v[80:83], v[52:55], 0
	s_waitcnt lgkmcnt(0)
	v_mfma_f32_16x16x32_bf16 v[48:51], v[84:87], v[48:51], v[52:55]
	v_mfma_f32_16x16x32_bf16 v[52:55], v[80:83], v[56:59], 0
	v_mfma_f32_16x16x32_bf16 v[52:55], v[84:87], v[60:63], v[52:55]
	ds_read_b128 v[56:59], v100 offset:59392
	ds_read_b128 v[60:63], v100 offset:60416
	s_waitcnt lgkmcnt(1)
	v_mfma_f32_16x16x32_bf16 v[36:39], v[56:59], v[36:39], v[48:51]
	s_waitcnt lgkmcnt(0)
	v_mfma_f32_16x16x32_bf16 v[32:35], v[60:63], v[32:35], v[36:39]
	v_mfma_f32_16x16x32_bf16 v[36:39], v[56:59], v[40:43], v[52:55]
	v_mfma_f32_16x16x32_bf16 v[36:39], v[60:63], v[44:47], v[36:39]
	ds_read_b128 v[40:43], v100 offset:61440
	ds_read_b128 v[44:47], v100 offset:62464
	v_mov_b32_e32 v53, v193
	s_waitcnt lgkmcnt(1)
	v_mfma_f32_16x16x32_bf16 v[20:23], v[40:43], v[20:23], v[32:35]
	s_waitcnt lgkmcnt(0)
	v_mfma_f32_16x16x32_bf16 v[16:19], v[44:47], v[16:19], v[20:23]
	v_mfma_f32_16x16x32_bf16 v[20:23], v[40:43], v[24:27], v[36:39]
	v_mfma_f32_16x16x32_bf16 v[20:23], v[44:47], v[28:31], v[20:23]
	ds_read_b128 v[24:27], v100 offset:63488
	ds_read_b128 v[28:31], v100 offset:64512
	s_waitcnt lgkmcnt(1)
	v_mfma_f32_16x16x32_bf16 v[8:11], v[24:27], v[8:11], v[16:19]
	v_mfma_f32_16x16x32_bf16 v[76:79], v[88:91], v[0:3], v[76:79]
	s_waitcnt lgkmcnt(0)
	v_mfma_f32_16x16x32_bf16 v[0:3], v[28:31], v[0:3], v[8:11]
	v_mfma_f32_16x16x32_bf16 v[8:11], v[24:27], v[12:15], v[20:23]
	v_mfma_f32_16x16x32_bf16 v[72:75], v[88:91], v[4:7], v[72:75]
	s_nop 5
	v_mul_f32_e64 v12, v2, s0
	v_mul_f32_e64 v13, v3, s0
	v_pk_mul_f32 v[2:3], v[0:1], s[0:1] op_sel_hi:[1,0]
	s_waitcnt vmcnt(7)
	v_lshlrev_b32_e32 v0, 16, v68
	v_mfma_f32_16x16x32_bf16 v[4:7], v[28:31], v[4:7], v[8:11]
	v_and_b32_e32 v1, 0xffff0000, v68
	s_nop 1
	v_pk_mul_f32 v[10:11], v[76:77], s[0:1] op_sel_hi:[1,0]
	v_pk_mul_f32 v[8:9], v[78:79], s[0:1] op_sel_hi:[1,0]
	v_pk_mul_f32 v[0:1], v[10:11], v[0:1]
	v_lshlrev_b32_e32 v10, 16, v69
	v_and_b32_e32 v11, 0xffff0000, v69
	v_pk_mul_f32 v[8:9], v[8:9], v[10:11]
	v_cvt_pk_bf16_f32 v0, v0, v1
	v_cvt_pk_bf16_f32 v1, v8, v9
	v_lshlrev_b32_e32 v8, 16, v70
	v_and_b32_e32 v9, 0xffff0000, v70
	v_pk_mul_f32 v[2:3], v[2:3], v[8:9]
	v_lshlrev_b32_e32 v8, 16, v71
	v_and_b32_e32 v9, 0xffff0000, v71
	v_pk_mul_f32 v[8:9], v[12:13], v[8:9]
	v_cvt_pk_bf16_f32 v2, v2, v3
	v_cvt_pk_bf16_f32 v3, v8, v9
	global_store_dwordx4 v[98:99], v[0:3], off offset:192
	s_waitcnt vmcnt(7)
	v_lshlrev_b32_e32 v8, 16, v64
	v_and_b32_e32 v9, 0xffff0000, v64
	v_pk_mul_f32 v[0:1], v[72:73], s[0:1] op_sel_hi:[1,0]
	v_pk_mul_f32 v[2:3], v[74:75], s[0:1] op_sel_hi:[1,0]
	v_pk_mul_f32 v[0:1], v[0:1], v[8:9]
	v_lshlrev_b32_e32 v8, 16, v65
	v_and_b32_e32 v9, 0xffff0000, v65
	v_pk_mul_f32 v[2:3], v[2:3], v[8:9]
	v_pk_mul_f32 v[4:5], v[4:5], s[0:1] op_sel_hi:[1,0]
	v_cvt_pk_bf16_f32 v0, v0, v1
	v_cvt_pk_bf16_f32 v1, v2, v3
	v_lshlrev_b32_e32 v2, 16, v66
	v_and_b32_e32 v3, 0xffff0000, v66
	v_pk_mul_f32 v[6:7], v[6:7], s[0:1] op_sel_hi:[1,0]
	v_pk_mul_f32 v[2:3], v[4:5], v[2:3]
	v_lshlrev_b32_e32 v4, 16, v67
	v_and_b32_e32 v5, 0xffff0000, v67
	v_pk_mul_f32 v[4:5], v[6:7], v[4:5]
	v_cvt_pk_bf16_f32 v2, v2, v3
	v_cvt_pk_bf16_f32 v3, v4, v5
	v_readlane_b32 s0, v253, 55
	global_store_dwordx4 v[96:97], v[0:3], off offset:192
	s_barrier
	v_mbcnt_lo_u32_b32 v176, -1, 0
	v_mbcnt_hi_u32_b32 v176, -1, v176
	v_readlane_b32 s1, v253, 56
	v_bfe_u32 v173, v176, 4, 2
	v_and_b32_e32 v190, 15, v176
	s_add_u32 s0, s28, s0
	s_addc_u32 s1, s29, s1
	v_or_b32_e32 v0, s70, v173
	v_lshlrev_b32_e32 v52, 4, v190
	v_lshl_add_u64 v[2:3], s[0:1], 0, v[52:53]
	s_mov_b64 s[0:1], 0x6000000
	v_ashrrev_i32_e32 v1, 31, v0
	v_lshl_add_u64 v[2:3], v[2:3], 0, s[0:1]
	v_lshlrev_b64 v[4:5], 8, v[0:1]
	v_lshl_add_u64 v[4:5], v[2:3], 0, v[4:5]
	global_load_dwordx4 v[56:59], v[4:5], off sc1
	v_or_b32_e32 v4, 4, v0
	v_ashrrev_i32_e32 v5, 31, v4
	v_lshlrev_b64 v[4:5], 8, v[4:5]
	v_lshl_add_u64 v[4:5], v[2:3], 0, v[4:5]
	global_load_dwordx4 v[60:63], v[4:5], off sc1
	v_or_b32_e32 v4, 8, v0
	v_ashrrev_i32_e32 v5, 31, v4
	v_lshlrev_b64 v[4:5], 8, v[4:5]
	v_lshl_add_u64 v[4:5], v[2:3], 0, v[4:5]
	global_load_dwordx4 v[70:73], v[4:5], off sc1
	v_or_b32_e32 v4, 12, v0
	v_ashrrev_i32_e32 v5, 31, v4
	v_lshlrev_b64 v[4:5], 8, v[4:5]
	v_lshl_add_u64 v[4:5], v[2:3], 0, v[4:5]
	global_load_dwordx4 v[48:51], v[4:5], off sc1
	v_or_b32_e32 v4, 16, v0
	v_ashrrev_i32_e32 v5, 31, v4
	v_lshlrev_b64 v[4:5], 8, v[4:5]
	v_lshl_add_u64 v[4:5], v[2:3], 0, v[4:5]
	global_load_dwordx4 v[44:47], v[4:5], off sc1
	v_or_b32_e32 v4, 20, v0
	v_ashrrev_i32_e32 v5, 31, v4
	v_lshlrev_b64 v[4:5], 8, v[4:5]
	v_lshl_add_u64 v[4:5], v[2:3], 0, v[4:5]
	global_load_dwordx4 v[40:43], v[4:5], off sc1
	v_or_b32_e32 v4, 24, v0
	v_ashrrev_i32_e32 v5, 31, v4
	v_lshlrev_b64 v[4:5], 8, v[4:5]
	v_lshl_add_u64 v[4:5], v[2:3], 0, v[4:5]
	global_load_dwordx4 v[36:39], v[4:5], off sc1
	v_or_b32_e32 v4, 28, v0
	v_ashrrev_i32_e32 v5, 31, v4
	v_lshlrev_b64 v[4:5], 8, v[4:5]
	v_lshl_add_u64 v[4:5], v[2:3], 0, v[4:5]
; #define GAS __attribute__((address_space(1)))
; __device__ __forceinline__ float bflo(unsigned w) { return __uint_as_float(w << 16); }
; __device__ __forceinline__ float bfhi(unsigned w) { return __uint_as_float(w & 0xffff0000u); }
; __device__ __forceinline__ void a_unit(Frame& F, int L, int u, bool dry) {
;     ...
;         for (int i = 0; i < 16; ++i) raw[i] = *(const GAS u32x4*)(gvt + (size_t)(64 * w + 4 * i + cr) * 128 + 8 * tg);
; #pragma unroll
;         for (int i = 0; i < 16; ++i)
; #pragma unroll
;             for (int jj = 0; jj < 4; ++jj) { const float lo = bflo(raw[i][jj]), hi = bfhi(raw[i][jj]); s[2 * jj] += lo; q[2 * jj] = fmaf(lo, lo, q[2 * jj]); s[2 * jj + 1] += hi; q[2 * jj + 1] = fmaf(hi, hi, q[2 * jj + 1]); }
	global_load_dwordx4 v[32:35], v[4:5], off sc1
	v_or_b32_e32 v4, 32, v0
	v_ashrrev_i32_e32 v5, 31, v4
	v_lshlrev_b64 v[4:5], 8, v[4:5]
	v_lshl_add_u64 v[4:5], v[2:3], 0, v[4:5]
	global_load_dwordx4 v[28:31], v[4:5], off sc1
	v_or_b32_e32 v4, 36, v0
	v_ashrrev_i32_e32 v5, 31, v4
	v_lshlrev_b64 v[4:5], 8, v[4:5]
	v_lshl_add_u64 v[4:5], v[2:3], 0, v[4:5]
	global_load_dwordx4 v[24:27], v[4:5], off sc1
	v_or_b32_e32 v4, 40, v0
	v_ashrrev_i32_e32 v5, 31, v4
	v_lshlrev_b64 v[4:5], 8, v[4:5]
	v_lshl_add_u64 v[4:5], v[2:3], 0, v[4:5]
	global_load_dwordx4 v[20:23], v[4:5], off sc1
	v_or_b32_e32 v4, 44, v0
	v_ashrrev_i32_e32 v5, 31, v4
	v_lshlrev_b64 v[4:5], 8, v[4:5]
	v_lshl_add_u64 v[4:5], v[2:3], 0, v[4:5]
	global_load_dwordx4 v[16:19], v[4:5], off sc1
	v_or_b32_e32 v4, 48, v0
	v_ashrrev_i32_e32 v5, 31, v4
	v_lshlrev_b64 v[4:5], 8, v[4:5]
	v_lshl_add_u64 v[4:5], v[2:3], 0, v[4:5]
	global_load_dwordx4 v[12:15], v[4:5], off sc1
	v_or_b32_e32 v4, 52, v0
	v_ashrrev_i32_e32 v5, 31, v4
	v_lshlrev_b64 v[4:5], 8, v[4:5]
	v_lshl_add_u64 v[4:5], v[2:3], 0, v[4:5]
	global_load_dwordx4 v[8:11], v[4:5], off sc1
	v_or_b32_e32 v4, 56, v0
	v_ashrrev_i32_e32 v5, 31, v4
	v_or_b32_e32 v0, 60, v0
	v_lshlrev_b64 v[4:5], 8, v[4:5]
	v_ashrrev_i32_e32 v1, 31, v0
	v_lshl_add_u64 v[4:5], v[2:3], 0, v[4:5]
	v_lshlrev_b64 v[0:1], 8, v[0:1]
	global_load_dwordx4 v[4:7], v[4:5], off sc1
	v_lshl_add_u64 v[0:1], v[2:3], 0, v[0:1]
	global_load_dwordx4 v[0:3], v[0:1], off sc1
	v_and_b32_e32 v162, 63, v176
	v_cmp_gt_u32_e32 vcc, 16, v162
	s_waitcnt vmcnt(15)
	v_lshlrev_b32_e32 v64, 16, v57
	v_lshlrev_b32_e32 v156, 16, v56
	v_and_b32_e32 v157, 0xffff0000, v56
	v_and_b32_e32 v65, 0xffff0000, v57
	v_add_f32_e32 v68, 0, v64
	v_lshlrev_b32_e32 v56, 16, v58
	s_waitcnt vmcnt(14)
	v_lshlrev_b32_e32 v54, 16, v60
	v_and_b32_e32 v55, 0xffff0000, v60
	v_lshlrev_b32_e32 v60, 16, v61
	v_add_f32_e32 v66, 0, v156
	v_add_f32_e32 v69, 0, v65
	v_and_b32_e32 v57, 0xffff0000, v58
	v_add_f32_e32 v74, 0, v56
	v_lshlrev_b32_e32 v58, 16, v59
	v_and_b32_e32 v61, 0xffff0000, v61
	v_add_f32_e32 v80, v68, v60
	v_lshlrev_b32_e32 v68, 16, v62
	v_add_f32_e32 v67, 0, v157
	v_add_f32_e32 v75, 0, v57
	v_add_f32_e32 v76, 0, v58
	v_add_f32_e32 v66, v66, v54
	v_add_f32_e32 v81, v69, v61
	v_and_b32_e32 v69, 0xffff0000, v62
	v_add_f32_e32 v62, v74, v68
	v_lshlrev_b32_e32 v74, 16, v63
	s_waitcnt vmcnt(13)
	v_lshlrev_b32_e32 v78, 16, v70
	v_and_b32_e32 v59, 0xffff0000, v59
	v_add_f32_e32 v67, v67, v55
	v_add_f32_e32 v84, v75, v69
	v_and_b32_e32 v75, 0xffff0000, v63
	v_add_f32_e32 v63, v76, v74
	v_and_b32_e32 v79, 0xffff0000, v70
	v_add_f32_e32 v66, v66, v78
	v_lshlrev_b32_e32 v82, 16, v71
	v_lshlrev_b32_e32 v90, 16, v72
	v_lshlrev_b32_e32 v98, 16, v73
	s_waitcnt vmcnt(12)
	v_lshlrev_b32_e32 v100, 16, v48
	v_add_f32_e32 v77, 0, v59
	v_add_f32_e32 v67, v67, v79
	v_and_b32_e32 v83, 0xffff0000, v71
	v_add_f32_e32 v70, v80, v82
	v_add_f32_e32 v62, v62, v90
	v_add_f32_e32 v63, v63, v98
	v_and_b32_e32 v101, 0xffff0000, v48
	v_add_f32_e32 v48, v66, v100
	v_lshlrev_b32_e32 v114, 16, v49
	v_lshlrev_b32_e32 v126, 16, v50
	v_lshlrev_b32_e32 v136, 16, v51
	s_waitcnt vmcnt(11)
	v_lshlrev_b32_e32 v130, 16, v44
	v_add_f32_e32 v76, v77, v75
	v_add_f32_e32 v71, v81, v83
	v_and_b32_e32 v91, 0xffff0000, v72
	v_and_b32_e32 v99, 0xffff0000, v73
	v_add_f32_e32 v66, v67, v101
	v_and_b32_e32 v115, 0xffff0000, v49
	v_add_f32_e32 v49, v70, v114
	v_and_b32_e32 v127, 0xffff0000, v50
	v_add_f32_e32 v50, v62, v126
	v_and_b32_e32 v137, 0xffff0000, v51
	v_add_f32_e32 v51, v63, v136
	v_and_b32_e32 v131, 0xffff0000, v44
	v_add_f32_e32 v44, v48, v130
	v_lshlrev_b32_e32 v138, 16, v45
	v_lshlrev_b32_e32 v144, 16, v46
	v_lshlrev_b32_e32 v118, 16, v47
	s_waitcnt vmcnt(10)
	v_lshlrev_b32_e32 v120, 16, v40
	v_fma_f32 v158, v58, v58, 0
	v_add_f32_e32 v72, v84, v91
	v_add_f32_e32 v73, v76, v99
	v_add_f32_e32 v67, v71, v115
	v_add_f32_e32 v48, v66, v131
	v_and_b32_e32 v139, 0xffff0000, v45
	v_add_f32_e32 v45, v49, v138
	v_and_b32_e32 v145, 0xffff0000, v46
	v_add_f32_e32 v46, v50, v144
	v_and_b32_e32 v119, 0xffff0000, v47
	v_add_f32_e32 v47, v51, v118
	v_and_b32_e32 v121, 0xffff0000, v40
	v_add_f32_e32 v40, v44, v120
	v_lshlrev_b32_e32 v132, 16, v41
	v_lshlrev_b32_e32 v140, 16, v42
	v_lshlrev_b32_e32 v112, 16, v43
	s_waitcnt vmcnt(9)
	v_lshlrev_b32_e32 v116, 16, v36
	v_fma_f32 v165, v156, v156, 0
	v_fma_f32 v164, v157, v157, 0
	v_fma_f32 v163, v64, v64, 0
	v_fma_f32 v161, v65, v65, 0
	v_fma_f32 v160, v56, v56, 0
	v_fma_f32 v159, v57, v57, 0
	v_fmac_f32_e32 v158, v74, v74
	v_add_f32_e32 v62, v72, v127
	v_add_f32_e32 v63, v73, v137
	v_add_f32_e32 v49, v67, v139
	v_add_f32_e32 v44, v48, v121
	v_and_b32_e32 v133, 0xffff0000, v41
	v_add_f32_e32 v41, v45, v132
	v_and_b32_e32 v141, 0xffff0000, v42
	v_add_f32_e32 v42, v46, v140
	v_and_b32_e32 v113, 0xffff0000, v43
	v_add_f32_e32 v43, v47, v112
	v_and_b32_e32 v117, 0xffff0000, v36
	v_add_f32_e32 v36, v40, v116
	v_lshlrev_b32_e32 v128, 16, v37
	v_lshlrev_b32_e32 v96, 16, v38
	v_lshlrev_b32_e32 v108, 16, v39
	s_waitcnt vmcnt(8)
	v_lshlrev_b32_e32 v110, 16, v32
	v_fma_f32 v53, v59, v59, 0
	v_fmac_f32_e32 v165, v54, v54
	v_fmac_f32_e32 v164, v55, v55
	v_fmac_f32_e32 v163, v60, v60
	v_fmac_f32_e32 v161, v61, v61
	v_fmac_f32_e32 v160, v68, v68
	v_fmac_f32_e32 v159, v69, v69
	v_fmac_f32_e32 v158, v98, v98
	v_add_f32_e32 v50, v62, v145
	v_add_f32_e32 v51, v63, v119
	v_add_f32_e32 v45, v49, v133
	v_add_f32_e32 v40, v44, v117
	v_and_b32_e32 v129, 0xffff0000, v37
	v_add_f32_e32 v37, v41, v128
	v_and_b32_e32 v97, 0xffff0000, v38
	v_add_f32_e32 v38, v42, v96
	v_and_b32_e32 v109, 0xffff0000, v39
	v_add_f32_e32 v39, v43, v108
	v_and_b32_e32 v111, 0xffff0000, v32
	v_add_f32_e32 v32, v36, v110
	v_lshlrev_b32_e32 v86, 16, v33
	v_lshlrev_b32_e32 v92, 16, v34
	v_lshlrev_b32_e32 v104, 16, v35
	s_waitcnt vmcnt(7)
; __device__ __forceinline__ float bflo(unsigned w) { return __uint_as_float(w << 16); }
; __device__ __forceinline__ float bfhi(unsigned w) { return __uint_as_float(w & 0xffff0000u); }
; __device__ __forceinline__ void a_unit(Frame& F, int L, int u, bool dry) {
;     ...
;         for (int i = 0; i < 16; ++i)
; #pragma unroll
;             for (int jj = 0; jj < 4; ++jj) { const float lo = bflo(raw[i][jj]), hi = bfhi(raw[i][jj]); s[2 * jj] += lo; q[2 * jj] = fmaf(lo, lo, q[2 * jj]); s[2 * jj + 1] += hi; q[2 * jj + 1] = fmaf(hi, hi, q[2 * jj + 1]); }
	v_lshlrev_b32_e32 v102, 16, v28
	v_fmac_f32_e32 v53, v75, v75
	v_fmac_f32_e32 v165, v78, v78
	v_fmac_f32_e32 v164, v79, v79
	v_fmac_f32_e32 v163, v82, v82
	v_fmac_f32_e32 v161, v83, v83
	v_fmac_f32_e32 v160, v90, v90
	v_fmac_f32_e32 v159, v91, v91
	v_fmac_f32_e32 v158, v136, v136
	v_add_f32_e32 v46, v50, v141
	v_add_f32_e32 v47, v51, v113
	v_add_f32_e32 v41, v45, v129
	v_add_f32_e32 v36, v40, v111
	v_and_b32_e32 v87, 0xffff0000, v33
	v_add_f32_e32 v33, v37, v86
	v_and_b32_e32 v93, 0xffff0000, v34
	v_add_f32_e32 v34, v38, v92
	v_and_b32_e32 v105, 0xffff0000, v35
	v_add_f32_e32 v35, v39, v104
	v_and_b32_e32 v103, 0xffff0000, v28
	v_add_f32_e32 v28, v32, v102
	v_lshlrev_b32_e32 v194, 16, v29
	v_lshlrev_b32_e32 v32, 16, v30
	v_lshlrev_b32_e32 v244, 16, v31
	v_fmac_f32_e32 v53, v99, v99
	v_fmac_f32_e32 v165, v100, v100
	v_fmac_f32_e32 v164, v101, v101
	v_fmac_f32_e32 v163, v114, v114
	v_fmac_f32_e32 v161, v115, v115
	v_fmac_f32_e32 v160, v126, v126
	v_fmac_f32_e32 v159, v127, v127
	v_fmac_f32_e32 v158, v118, v118
	v_add_f32_e32 v42, v46, v97
	v_add_f32_e32 v43, v47, v109
	v_add_f32_e32 v37, v41, v87
	v_add_f32_e32 v36, v36, v103
	v_and_b32_e32 v195, 0xffff0000, v29
	v_add_f32_e32 v29, v33, v194
	v_and_b32_e32 v33, 0xffff0000, v30
	v_add_f32_e32 v30, v34, v32
	v_and_b32_e32 v245, 0xffff0000, v31
	v_add_f32_e32 v31, v35, v244
	s_waitcnt vmcnt(6)
	v_lshlrev_b32_e32 v34, 16, v24
	v_and_b32_e32 v35, 0xffff0000, v24
	v_fmac_f32_e32 v53, v137, v137
	v_fmac_f32_e32 v165, v130, v130
	v_fmac_f32_e32 v164, v131, v131
	v_fmac_f32_e32 v163, v138, v138
	v_fmac_f32_e32 v161, v139, v139
	v_fmac_f32_e32 v160, v144, v144
	v_fmac_f32_e32 v159, v145, v145
	v_fmac_f32_e32 v158, v112, v112
	v_add_f32_e32 v38, v42, v93
	v_add_f32_e32 v39, v43, v105
	v_add_f32_e32 v40, v37, v195
	v_add_f32_e32 v24, v28, v34
	v_add_f32_e32 v28, v36, v35
	v_lshlrev_b32_e32 v36, 16, v25
	v_and_b32_e32 v37, 0xffff0000, v25
	v_fmac_f32_e32 v53, v119, v119
	v_fmac_f32_e32 v165, v120, v120
	v_fmac_f32_e32 v164, v121, v121
	v_fmac_f32_e32 v163, v132, v132
	v_fmac_f32_e32 v161, v133, v133
	v_fmac_f32_e32 v160, v140, v140
	v_fmac_f32_e32 v159, v141, v141
	v_fmac_f32_e32 v158, v108, v108
	v_add_f32_e32 v41, v38, v33
	v_add_f32_e32 v42, v39, v245
	v_add_f32_e32 v25, v29, v36
	v_add_f32_e32 v29, v40, v37
	v_lshlrev_b32_e32 v38, 16, v26
	v_and_b32_e32 v39, 0xffff0000, v26
	v_lshlrev_b32_e32 v40, 16, v27
	v_fmac_f32_e32 v53, v113, v113
	v_fmac_f32_e32 v165, v116, v116
	v_fmac_f32_e32 v164, v117, v117
	v_fmac_f32_e32 v163, v128, v128
	v_fmac_f32_e32 v161, v129, v129
	v_fmac_f32_e32 v160, v96, v96
	v_fmac_f32_e32 v159, v97, v97
	v_fmac_f32_e32 v158, v104, v104
	v_add_f32_e32 v26, v30, v38
	v_add_f32_e32 v30, v41, v39
	v_and_b32_e32 v41, 0xffff0000, v27
	v_add_f32_e32 v27, v31, v40
	s_waitcnt vmcnt(5)
	v_lshlrev_b32_e32 v48, 16, v23
	v_fmac_f32_e32 v53, v109, v109
	v_fmac_f32_e32 v165, v110, v110
	v_fmac_f32_e32 v164, v111, v111
	v_fmac_f32_e32 v163, v86, v86
	v_fmac_f32_e32 v161, v87, v87
	v_fmac_f32_e32 v160, v92, v92
	v_fmac_f32_e32 v159, v93, v93
	v_fmac_f32_e32 v158, v244, v244
	v_add_f32_e32 v31, v42, v41
	v_lshlrev_b32_e32 v42, 16, v20
	v_and_b32_e32 v43, 0xffff0000, v20
	v_lshlrev_b32_e32 v44, 16, v21
	v_and_b32_e32 v45, 0xffff0000, v21
	v_lshlrev_b32_e32 v46, 16, v22
	v_and_b32_e32 v47, 0xffff0000, v22
	v_and_b32_e32 v49, 0xffff0000, v23
	v_add_f32_e32 v23, v27, v48
	s_waitcnt vmcnt(4)
	v_lshlrev_b32_e32 v76, 16, v19
	v_fmac_f32_e32 v53, v105, v105
	v_fmac_f32_e32 v165, v102, v102
	v_fmac_f32_e32 v164, v103, v103
	v_fmac_f32_e32 v163, v194, v194
	v_fmac_f32_e32 v161, v195, v195
	v_fmac_f32_e32 v160, v32, v32
	v_fmac_f32_e32 v159, v33, v33
	v_fmac_f32_e32 v158, v40, v40
	v_add_f32_e32 v20, v24, v42
	v_add_f32_e32 v24, v28, v43
	v_add_f32_e32 v21, v25, v44
	v_add_f32_e32 v25, v29, v45
	v_add_f32_e32 v22, v26, v46
	v_add_f32_e32 v26, v30, v47
	v_lshlrev_b32_e32 v50, 16, v16
	v_and_b32_e32 v51, 0xffff0000, v16
	v_lshlrev_b32_e32 v62, 16, v17
	v_and_b32_e32 v63, 0xffff0000, v17
	v_lshlrev_b32_e32 v70, 16, v18
	v_and_b32_e32 v71, 0xffff0000, v18
	v_and_b32_e32 v77, 0xffff0000, v19
	v_add_f32_e32 v19, v23, v76
	s_waitcnt vmcnt(3)
	v_lshlrev_b32_e32 v84, 16, v15
	v_fmac_f32_e32 v53, v245, v245
	v_fmac_f32_e32 v165, v34, v34
	v_fmac_f32_e32 v164, v35, v35
	v_fmac_f32_e32 v163, v36, v36
	v_fmac_f32_e32 v161, v37, v37
	v_fmac_f32_e32 v160, v38, v38
	v_fmac_f32_e32 v159, v39, v39
	v_fmac_f32_e32 v158, v48, v48
	v_add_f32_e32 v27, v31, v49
	v_add_f32_e32 v16, v20, v50
	v_add_f32_e32 v20, v24, v51
	v_add_f32_e32 v17, v21, v62
	v_add_f32_e32 v21, v25, v63
	v_add_f32_e32 v18, v22, v70
	v_add_f32_e32 v22, v26, v71
	v_lshlrev_b32_e32 v66, 16, v12
	v_and_b32_e32 v67, 0xffff0000, v12
	v_lshlrev_b32_e32 v72, 16, v13
	v_and_b32_e32 v73, 0xffff0000, v13
	v_lshlrev_b32_e32 v80, 16, v14
	v_and_b32_e32 v81, 0xffff0000, v14
	v_and_b32_e32 v85, 0xffff0000, v15
	v_add_f32_e32 v15, v19, v84
	s_waitcnt vmcnt(2)
	v_lshlrev_b32_e32 v122, 16, v11
	v_fmac_f32_e32 v53, v41, v41
	v_fmac_f32_e32 v165, v42, v42
	v_fmac_f32_e32 v164, v43, v43
	v_fmac_f32_e32 v163, v44, v44
	v_fmac_f32_e32 v161, v45, v45
	v_fmac_f32_e32 v160, v46, v46
	v_fmac_f32_e32 v159, v47, v47
	v_fmac_f32_e32 v158, v76, v76
	v_add_f32_e32 v23, v27, v77
	v_add_f32_e32 v12, v16, v66
	v_add_f32_e32 v16, v20, v67
	v_add_f32_e32 v13, v17, v72
	v_add_f32_e32 v17, v21, v73
	v_add_f32_e32 v14, v18, v80
	v_add_f32_e32 v18, v22, v81
	v_lshlrev_b32_e32 v88, 16, v8
	v_and_b32_e32 v89, 0xffff0000, v8
	v_lshlrev_b32_e32 v94, 16, v9
	v_and_b32_e32 v95, 0xffff0000, v9
	v_lshlrev_b32_e32 v106, 16, v10
	v_and_b32_e32 v107, 0xffff0000, v10
	v_and_b32_e32 v123, 0xffff0000, v11
	v_add_f32_e32 v11, v15, v122
	s_waitcnt vmcnt(1)
; #define LAS __attribute__((address_space(3)))
; __device__ __forceinline__ float xsum16(float v) { float a = v, b = v; asm("s_nop 1\n\tv_permlane16_swap_b32 %0, %1" : "+v"(a), "+v"(b)); return a + b; }
; __device__ __forceinline__ float xsum32(float v) { float a = v, b = v; asm("s_nop 1\n\tv_permlane32_swap_b32 %0, %1" : "+v"(a), "+v"(b)); return a + b; }
; __device__ __forceinline__ float bflo(unsigned w) { return __uint_as_float(w << 16); }
; __device__ __forceinline__ float bfhi(unsigned w) { return __uint_as_float(w & 0xffff0000u); }
; __device__ __forceinline__ void a_unit(Frame& F, int L, int u, bool dry) {
;     ...
;             for (int jj = 0; jj < 4; ++jj) { const float lo = bflo(raw[i][jj]), hi = bfhi(raw[i][jj]); s[2 * jj] += lo; q[2 * jj] = fmaf(lo, lo, q[2 * jj]); s[2 * jj + 1] += hi; q[2 * jj + 1] = fmaf(hi, hi, q[2 * jj + 1]); }
;     }
; #pragma unroll
;     for (int j = 0; j < 8; ++j) { s[j] = xsum32(xsum16(s[j])); q[j] = xsum32(xsum16(q[j])); }
;     if (cr == 0) {
; #pragma unroll
;         for (int j = 0; j < 8; ++j) *(LAS f32x2*)(part + (w * 128 + 8 * tg + j) * 2) = (f32x2){s[j], q[j]};
;     }
	v_lshlrev_b32_e32 v146, 16, v7
	v_fmac_f32_e32 v53, v49, v49
	v_fmac_f32_e32 v165, v50, v50
	v_fmac_f32_e32 v164, v51, v51
	v_fmac_f32_e32 v163, v62, v62
	v_fmac_f32_e32 v161, v63, v63
	v_fmac_f32_e32 v160, v70, v70
	v_fmac_f32_e32 v159, v71, v71
	v_fmac_f32_e32 v158, v84, v84
	v_add_f32_e32 v19, v23, v85
	v_add_f32_e32 v8, v12, v88
	v_add_f32_e32 v12, v16, v89
	v_add_f32_e32 v9, v13, v94
	v_add_f32_e32 v13, v17, v95
	v_add_f32_e32 v10, v14, v106
	v_add_f32_e32 v14, v18, v107
	v_lshlrev_b32_e32 v124, 16, v4
	v_and_b32_e32 v125, 0xffff0000, v4
	v_lshlrev_b32_e32 v134, 16, v5
	v_and_b32_e32 v135, 0xffff0000, v5
	v_lshlrev_b32_e32 v142, 16, v6
	v_and_b32_e32 v143, 0xffff0000, v6
	v_and_b32_e32 v147, 0xffff0000, v7
	v_add_f32_e32 v7, v11, v146
	s_waitcnt vmcnt(0)
	v_lshlrev_b32_e32 v154, 16, v3
	v_fmac_f32_e32 v53, v77, v77
	v_fmac_f32_e32 v165, v66, v66
	v_fmac_f32_e32 v164, v67, v67
	v_fmac_f32_e32 v163, v72, v72
	v_fmac_f32_e32 v161, v73, v73
	v_fmac_f32_e32 v160, v80, v80
	v_fmac_f32_e32 v159, v81, v81
	v_fmac_f32_e32 v158, v122, v122
	v_add_f32_e32 v15, v19, v123
	v_add_f32_e32 v4, v8, v124
	v_add_f32_e32 v8, v12, v125
	v_add_f32_e32 v5, v9, v134
	v_add_f32_e32 v9, v13, v135
	v_add_f32_e32 v6, v10, v142
	v_add_f32_e32 v10, v14, v143
	v_lshlrev_b32_e32 v148, 16, v0
	v_and_b32_e32 v149, 0xffff0000, v0
	v_lshlrev_b32_e32 v150, 16, v1
	v_and_b32_e32 v151, 0xffff0000, v1
	v_lshlrev_b32_e32 v152, 16, v2
	v_and_b32_e32 v153, 0xffff0000, v2
	v_add_f32_e32 v24, v7, v154
	v_fmac_f32_e32 v53, v85, v85
	v_fmac_f32_e32 v165, v88, v88
	v_fmac_f32_e32 v164, v89, v89
	v_fmac_f32_e32 v163, v94, v94
	v_fmac_f32_e32 v161, v95, v95
	v_fmac_f32_e32 v160, v106, v106
	v_fmac_f32_e32 v159, v107, v107
	v_fmac_f32_e32 v158, v146, v146
	v_add_f32_e32 v11, v15, v147
	v_add_f32_e32 v0, v4, v148
	v_add_f32_e32 v4, v8, v149
	v_add_f32_e32 v8, v5, v150
	v_add_f32_e32 v12, v9, v151
	v_add_f32_e32 v16, v6, v152
	v_add_f32_e32 v20, v10, v153
	v_and_b32_e32 v155, 0xffff0000, v3
	v_mov_b32_e32 v25, v24
	v_fmac_f32_e32 v53, v123, v123
	v_fmac_f32_e32 v165, v124, v124
	v_fmac_f32_e32 v164, v125, v125
	v_fmac_f32_e32 v163, v134, v134
	v_fmac_f32_e32 v161, v135, v135
	v_fmac_f32_e32 v160, v142, v142
	v_fmac_f32_e32 v159, v143, v143
	v_fmac_f32_e32 v158, v154, v154
	v_add_f32_e32 v28, v11, v155
	v_mov_b32_e32 v1, v0
	v_mov_b32_e32 v5, v4
	v_mov_b32_e32 v9, v8
	v_mov_b32_e32 v13, v12
	v_mov_b32_e32 v17, v16
	v_mov_b32_e32 v21, v20
	s_nop 1
	v_permlane16_swap_b32 v24, v25
	v_fmac_f32_e32 v53, v147, v147
	v_fmac_f32_e32 v165, v148, v148
	v_fmac_f32_e32 v164, v149, v149
	v_fmac_f32_e32 v163, v150, v150
	v_fmac_f32_e32 v161, v151, v151
	v_fmac_f32_e32 v160, v152, v152
	v_fmac_f32_e32 v159, v153, v153
	s_nop 1
	v_permlane16_swap_b32 v0, v1
	s_nop 1
	v_permlane16_swap_b32 v4, v5
	s_nop 1
	v_permlane16_swap_b32 v8, v9
	s_nop 1
	v_permlane16_swap_b32 v12, v13
	s_nop 1
	v_permlane16_swap_b32 v16, v17
	s_nop 1
	v_permlane16_swap_b32 v20, v21
	v_add_f32_e32 v24, v24, v25
	v_mov_b32_e32 v25, v158
	v_mov_b32_e32 v29, v28
	v_fmac_f32_e32 v53, v155, v155
	v_add_f32_e32 v0, v0, v1
	v_mov_b32_e32 v1, v165
	v_add_f32_e32 v4, v4, v5
	v_mov_b32_e32 v5, v164
	v_add_f32_e32 v8, v8, v9
	v_mov_b32_e32 v9, v163
	v_add_f32_e32 v12, v12, v13
	v_mov_b32_e32 v13, v161
	v_add_f32_e32 v16, v16, v17
	v_mov_b32_e32 v17, v160
	v_add_f32_e32 v20, v20, v21
	v_mov_b32_e32 v21, v159
	s_nop 1
	v_permlane16_swap_b32 v158, v25
	s_nop 1
	v_permlane16_swap_b32 v28, v29
	s_nop 1
	v_permlane16_swap_b32 v165, v1
	s_nop 1
	v_permlane16_swap_b32 v164, v5
	s_nop 1
	v_permlane16_swap_b32 v163, v9
	s_nop 1
	v_permlane16_swap_b32 v161, v13
	s_nop 1
	v_permlane16_swap_b32 v160, v17
	s_nop 1
	v_permlane16_swap_b32 v159, v21
	s_nop 0
	v_add_f32_e32 v25, v158, v25
	v_add_f32_e32 v158, v28, v29
	v_mov_b32_e32 v28, v53
	v_add_f32_e32 v1, v165, v1
	v_add_f32_e32 v5, v164, v5
	v_add_f32_e32 v9, v163, v9
	v_add_f32_e32 v13, v161, v13
	v_add_f32_e32 v17, v160, v17
	v_add_f32_e32 v21, v159, v21
	s_nop 1
	v_permlane16_swap_b32 v53, v28
	v_mov_b32_e32 v2, v0
	v_add_f32_e32 v159, v53, v28
	v_mov_b32_e32 v3, v1
	v_mov_b32_e32 v6, v4
	v_mov_b32_e32 v7, v5
	v_mov_b32_e32 v10, v8
	v_mov_b32_e32 v11, v9
	v_mov_b32_e32 v14, v12
	v_mov_b32_e32 v15, v13
	v_mov_b32_e32 v18, v16
	v_mov_b32_e32 v19, v17
	v_mov_b32_e32 v22, v20
	v_mov_b32_e32 v23, v21
	v_mov_b32_e32 v26, v24
	v_mov_b32_e32 v27, v25
	v_mov_b32_e32 v160, v158
	v_mov_b32_e32 v161, v159
	s_nop 1
	v_permlane32_swap_b32 v0, v2
	s_nop 1
	v_permlane32_swap_b32 v1, v3
	s_nop 1
	v_permlane32_swap_b32 v4, v6
	s_nop 1
	v_permlane32_swap_b32 v5, v7
	s_nop 1
	v_permlane32_swap_b32 v8, v10
	s_nop 1
	v_permlane32_swap_b32 v9, v11
	s_nop 1
	v_permlane32_swap_b32 v12, v14
	s_nop 1
	v_permlane32_swap_b32 v13, v15
	s_nop 1
	v_permlane32_swap_b32 v16, v18
	s_nop 1
	v_permlane32_swap_b32 v17, v19
	s_nop 1
	v_permlane32_swap_b32 v20, v22
	s_nop 1
	v_permlane32_swap_b32 v21, v23
	s_nop 1
	v_permlane32_swap_b32 v24, v26
	s_nop 1
	v_permlane32_swap_b32 v25, v27
	s_nop 1
	v_permlane32_swap_b32 v158, v160
	s_nop 1
	v_permlane32_swap_b32 v159, v161
	s_and_saveexec_b64 s[0:1], vcc
	s_cbranch_execz .LBB0_471
	v_lshlrev_b32_e32 v28, 3, v190
	v_readlane_b32 s2, v253, 59
	v_pk_add_f32 v[2:3], v[0:1], v[2:3]
	v_pk_add_f32 v[4:5], v[4:5], v[6:7]
	v_or_b32_e32 v0, s2, v28
	v_lshl_add_u32 v0, v0, 3, 0
	v_add_u32_e32 v0, 0x22000, v0
	v_pk_add_f32 v[160:161], v[158:159], v[160:161]
	v_pk_add_f32 v[158:159], v[24:25], v[26:27]
	v_pk_add_f32 v[20:21], v[20:21], v[22:23]
	v_pk_add_f32 v[18:19], v[16:17], v[18:19]
	v_pk_add_f32 v[12:13], v[12:13], v[14:15]
	v_pk_add_f32 v[10:11], v[8:9], v[10:11]
	ds_write_b128 v0, v[2:5]
	ds_write_b128 v0, v[10:13] offset:16
	ds_write_b128 v0, v[18:21] offset:32
	ds_write_b128 v0, v[158:161] offset:48
; #define LAS __attribute__((address_space(3)))
; __device__ __forceinline__ void a_unit(Frame& F, int L, int u, bool dry) {
;     ...
;     __syncthreads();
;     float mu[8], rs[8];
; #pragma unroll
;     for (int j = 0; j < 8; ++j) { float S = 0.f, Q = 0.f;
; #pragma unroll
;         for (int ww = 0; ww < 8; ++ww) { const f32x2 p = *(const LAS f32x2*)(part + (ww * 128 + 8 * tg + j) * 2); S += p.x; Q += p.y; }
;         mu[j] = __builtin_ldexpf(S, -9); rs[j] = rsqrtf(fmaxf(__builtin_ldexpf(Q, -9) - mu[j] * mu[j], 0.f) + LN_EPS); }
;     const float* lng = kin(4) + L * 512 + 64 * w; const float* lnb = kin(5) + L * 512 + 64 * w;
.LBB0_471:
	s_or_b64 exec, exec, s[0:1]
	v_lshl_add_u32 v26, v190, 6, 0
	v_add_u32_e32 v0, 0x22000, v26
	v_lshlrev_b32_e32 v192, 4, v162
	s_waitcnt lgkmcnt(0)
	s_barrier
	ds_read_b128 v[160:163], v0
	v_add_u32_e32 v4, 0x22400, v26
	ds_read_b128 v[164:167], v0 offset:16
	ds_read_b128 v[178:181], v0 offset:32
	ds_read_b128 v[0:3], v0 offset:48
	ds_read_b128 v[182:185], v4
	ds_read_b128 v[186:189], v4 offset:16
	ds_read_b128 v[196:199], v4 offset:32
	ds_read_b128 v[4:7], v4 offset:48
	s_waitcnt lgkmcnt(7)
	v_add_f32_e32 v8, 0, v160
	v_add_f32_e32 v9, 0, v161
	v_add_u32_e32 v29, 0x23800, v26
	s_waitcnt lgkmcnt(3)
	v_add_f32_e32 v12, v8, v182
	v_add_u32_e32 v8, 0x22800, v26
	ds_read_b128 v[200:203], v8
	v_add_f32_e32 v13, v9, v183
	ds_read_b128 v[204:207], v8 offset:16
	ds_read_b128 v[208:211], v8 offset:32
	ds_read_b128 v[8:11], v8 offset:48
	v_add_f32_e32 v30, 0, v162
	v_add_f32_e32 v31, 0, v163
	s_waitcnt lgkmcnt(3)
	v_add_f32_e32 v16, v12, v200
	v_add_u32_e32 v12, 0x22c00, v26
	ds_read_b128 v[212:215], v12
	v_add_f32_e32 v17, v13, v201
	ds_read_b128 v[216:219], v12 offset:16
	ds_read_b128 v[220:223], v12 offset:32
	ds_read_b128 v[12:15], v12 offset:48
	v_add_f32_e32 v30, v30, v184
	v_add_f32_e32 v31, v31, v185
	s_waitcnt lgkmcnt(3)
	v_add_f32_e32 v20, v16, v212
	v_add_u32_e32 v16, 0x23000, v26
	ds_read_b128 v[224:227], v16
	v_add_f32_e32 v21, v17, v213
	ds_read_b128 v[228:231], v16 offset:16
	ds_read_b128 v[232:235], v16 offset:32
	ds_read_b128 v[16:19], v16 offset:48
	v_add_f32_e32 v30, v30, v202
	v_add_f32_e32 v31, v31, v203
	s_waitcnt lgkmcnt(3)
	v_add_f32_e32 v27, v20, v224
	v_add_u32_e32 v20, 0x23400, v26
	ds_read_b128 v[236:239], v20
	v_add_f32_e32 v28, v21, v225
	ds_read_b128 v[240:243], v20 offset:16
	ds_read_b128 v[246:249], v20 offset:32
	ds_read_b128 v[20:23], v20 offset:48
	ds_read_b128 v[160:163], v29
	ds_read_b128 v[168:171], v29 offset:16
	ds_read_b128 v[182:185], v29 offset:32
	ds_read_b128 v[200:203], v29 offset:48
	s_waitcnt lgkmcnt(7)
	v_add_f32_e32 v28, v28, v237
	v_add_u32_e32 v26, 0x23c00, v26
	s_waitcnt lgkmcnt(3)
	v_add_f32_e32 v53, v28, v161
	v_add_f32_e32 v28, v30, v214
	v_add_f32_e32 v29, v31, v215
	v_add_f32_e32 v28, v28, v226
	v_add_f32_e32 v29, v29, v227
	ds_read_b128 v[212:215], v26
	ds_read_b128 v[224:227], v26 offset:16
	v_add_f32_e32 v27, v27, v236
	v_add_f32_e32 v27, v27, v160
	v_add_f32_e32 v28, v28, v238
	v_add_f32_e32 v29, v29, v239
	s_lshl_b32 s0, s58, 3
	v_readlane_b32 s1, v253, 2
	v_add_f32_e32 v161, v28, v162
	v_add_f32_e32 v162, v29, v163
	ds_read_b128 v[236:239], v26 offset:32
	ds_read_b128 v[28:31], v26 offset:48
	s_waitcnt lgkmcnt(3)
	v_add_f32_e32 v26, v27, v212
	v_add_f32_e32 v27, v53, v213
	s_add_i32 s0, s0, s1
	v_ldexp_f32 v160, v26, -9
	v_ldexp_f32 v26, v27, -9
	s_lshl_b32 s1, s0, 1
	v_readlane_b32 s2, v253, 53
	v_fma_f32 v26, -v160, v160, v26
	s_or_b32 s78, s1, s2
	s_mov_b32 s1, s79
	v_max_f32_e32 v212, 0, v26
	v_add_f32_e32 v26, v161, v214
	v_add_f32_e32 v27, v162, v215
	s_lshl_b64 s[2:3], s[78:79], 14
	s_lshl_b32 s78, s58, 9
	s_lshl_b64 s[42:43], s[0:1], 9
	v_ldexp_f32 v161, v26, -9
	v_ldexp_f32 v26, v27, -9
	s_add_u32 s0, s28, s2
	v_fma_f32 v26, -v161, v161, v26
	s_addc_u32 s1, s29, s3
	v_max_f32_e32 v213, 0, v26
	v_add_f32_e32 v26, 0, v164
	v_add_f32_e32 v27, 0, v165
	v_lshl_add_u64 v[158:159], s[0:1], 0, v[192:193]
	s_mov_b64 s[0:1], 0x1d00000
	v_add_f32_e32 v26, v26, v186
	v_add_f32_e32 v27, v27, v187
	v_lshl_add_u64 v[24:25], v[158:159], 0, s[0:1]
	v_add_f32_e32 v26, v26, v204
	v_add_f32_e32 v27, v27, v205
	s_mov_b64 s[0:1], s[72:73]
	v_add_f32_e32 v26, v26, v216
	v_add_f32_e32 v27, v27, v217
	v_add_f32_e32 v26, v26, v228
	v_add_f32_e32 v27, v27, v229
	s_load_dwordx2 s[0:1], s[0:1], 0x20
	v_add_f32_e32 v26, v26, v240
	v_add_f32_e32 v27, v27, v241
	v_add_f32_e32 v26, v26, v168
	v_add_f32_e32 v27, v27, v169
	s_mov_b64 s[2:3], s[72:73]
	s_waitcnt lgkmcnt(0)
	v_add_f32_e32 v26, v26, v224
	v_add_f32_e32 v27, v27, v225
	v_add_f32_e32 v0, 0, v0
	v_add_f32_e32 v1, 0, v1
	v_ldexp_f32 v162, v26, -9
	v_ldexp_f32 v26, v27, -9
	s_lshl_b64 s[30:31], s[78:79], 2
	s_load_dwordx2 s[2:3], s[2:3], 0x28
	v_add_f32_e32 v0, v0, v4
	v_add_f32_e32 v1, v1, v5
	v_fma_f32 v26, -v162, v162, v26
	s_add_u32 s6, s0, s30
	v_add_f32_e32 v0, v0, v8
	v_add_f32_e32 v1, v1, v9
	v_max_f32_e32 v174, 0, v26
	v_add_f32_e32 v26, 0, v166
	s_addc_u32 s7, s1, s31
	s_lshl_b64 s[0:1], s[70:71], 2
	v_add_f32_e32 v0, v0, v12
	v_add_f32_e32 v1, v1, v13
	v_add_f32_e32 v26, v26, v188
	s_add_u32 s44, s6, s0
	v_add_f32_e32 v0, v0, v16
	v_add_f32_e32 v1, v1, v17
	v_add_f32_e32 v26, v26, v206
	s_addc_u32 s45, s7, s1
	v_add_f32_e32 v0, v0, v20
	v_add_f32_e32 v1, v1, v21
	v_add_f32_e32 v26, v26, v218
	s_waitcnt lgkmcnt(0)
; #define LAS __attribute__((address_space(3)))
; __device__ __forceinline__ void a_unit(Frame& F, int L, int u, bool dry) {
;     ...
;     for (int j = 0; j < 8; ++j) { float S = 0.f, Q = 0.f;
; #pragma unroll
;         for (int ww = 0; ww < 8; ++ww) { const f32x2 p = *(const LAS f32x2*)(part + (ww * 128 + 8 * tg + j) * 2); S += p.x; Q += p.y; }
;         mu[j] = __builtin_ldexpf(S, -9); rs[j] = rsqrtf(fmaxf(__builtin_ldexpf(Q, -9) - mu[j] * mu[j], 0.f) + LN_EPS); }
;     const float* lng = kin(4) + L * 512 + 64 * w; const float* lnb = kin(5) + L * 512 + 64 * w;
;     bf16x8 af[4][4];
;     {
; #pragma unroll
;         for (int i = 0; i < 16; ++i) { const int cl = 4 * i + cr; const float g = lng[cl], bb = lnb[cl];
	s_add_u32 s2, s2, s30
	v_add_f32_e32 v0, v0, v200
	v_add_f32_e32 v1, v1, v201
	v_add_f32_e32 v27, 0, v167
	v_add_f32_e32 v26, v26, v230
	s_addc_u32 s3, s3, s31
	v_add_f32_e32 v0, v0, v28
	v_add_f32_e32 v1, v1, v29
	v_add_f32_e32 v27, v27, v189
	v_add_f32_e32 v26, v26, v242
	s_add_u32 s64, s2, s0
	v_lshlrev_b32_e32 v177, 2, v173
	v_ldexp_f32 v166, v0, -9
	v_ldexp_f32 v0, v1, -9
	v_add_f32_e32 v1, 0, v2
	v_add_f32_e32 v2, 0, v3
	v_add_f32_e32 v27, v27, v207
	v_add_f32_e32 v26, v26, v170
	s_addc_u32 s65, s3, s1
	global_load_dword v170, v177, s[44:45]
	global_load_dword v172, v177, s[64:65]
	v_add_f32_e32 v1, v1, v6
	v_add_f32_e32 v2, v2, v7
	v_add_f32_e32 v27, v27, v219
	v_add_f32_e32 v1, v1, v10
	v_add_f32_e32 v2, v2, v11
	v_add_f32_e32 v27, v27, v231
	v_add_f32_e32 v1, v1, v14
	v_add_f32_e32 v2, v2, v15
	v_add_f32_e32 v27, v27, v243
	v_add_f32_e32 v1, v1, v18
	v_add_f32_e32 v2, v2, v19
	v_add_f32_e32 v27, v27, v171
	v_add_f32_e32 v1, v1, v22
	v_add_f32_e32 v2, v2, v23
	global_load_dword v4, v177, s[44:45] offset:16
	global_load_dword v6, v177, s[64:65] offset:16
	v_add_f32_e32 v26, v26, v226
	v_add_f32_e32 v27, v27, v227
	v_add_f32_e32 v1, v1, v202
	v_add_f32_e32 v2, v2, v203
	s_mov_b32 s6, 0x3727c5ac
	v_ldexp_f32 v163, v26, -9
	v_ldexp_f32 v26, v27, -9
	v_add_f32_e32 v1, v1, v30
	v_add_f32_e32 v5, v2, v31
	v_pk_add_f32 v[2:3], v[212:213], s[6:7] op_sel_hi:[1,0]
	s_mov_b32 s0, 0x800000
	v_fma_f32 v26, -v163, v163, v26
	v_ldexp_f32 v167, v1, -9
	v_mul_f32_e32 v1, 0x4b800000, v2
	v_cmp_gt_f32_e32 vcc, s0, v2
	v_max_f32_e32 v175, 0, v26
	v_add_f32_e32 v26, 0, v178
	v_add_f32_e32 v27, 0, v179
	v_cndmask_b32_e32 v1, v2, v1, vcc
	global_load_dword v10, v177, s[44:45] offset:32
	global_load_dword v18, v177, s[64:65] offset:32
	v_add_f32_e32 v26, v26, v196
	v_add_f32_e32 v27, v27, v197
	v_rsq_f32_e32 v2, v1
	v_mul_f32_e32 v1, 0x4b800000, v3
	v_cmp_gt_f32_e64 s[2:3], s0, v3
	v_add_f32_e32 v26, v26, v208
	v_add_f32_e32 v27, v27, v209
	v_cndmask_b32_e64 v1, v3, v1, s[2:3]
	v_add_f32_e32 v26, v26, v220
	v_add_f32_e32 v27, v27, v221
	v_rsq_f32_e32 v3, v1
	v_add_f32_e32 v26, v26, v232
	v_add_f32_e32 v27, v27, v233
	v_add_f32_e32 v26, v26, v246
	v_add_f32_e32 v27, v27, v247
	v_add_f32_e32 v26, v26, v182
	v_add_f32_e32 v27, v27, v183
	s_mov_b32 s8, 0x45800000
	v_add_f32_e32 v26, v26, v236
	v_add_f32_e32 v27, v27, v237
	v_pk_mul_f32 v[8:9], v[2:3], s[8:9] op_sel_hi:[1,0]
	v_ldexp_f32 v164, v26, -9
	v_ldexp_f32 v26, v27, -9
	v_add_f32_e32 v27, 0, v180
	v_cndmask_b32_e64 v169, v3, v9, s[2:3]
	v_cndmask_b32_e32 v168, v2, v8, vcc
	v_pk_add_f32 v[8:9], v[174:175], s[6:7] op_sel_hi:[1,0]
	global_load_dword v20, v177, s[44:45] offset:48
	global_load_dword v22, v177, s[44:45] offset:64
	global_load_dword v28, v177, s[44:45] offset:80
	global_load_dword v16, v177, s[44:45] offset:96
	global_load_dword v12, v177, s[44:45] offset:112
	global_load_dword v30, v177, s[64:65] offset:48
	global_load_dword v174, v177, s[64:65] offset:64
	global_load_dword v178, v177, s[64:65] offset:80
	global_load_dword v180, v177, s[64:65] offset:96
	global_load_dword v14, v177, s[64:65] offset:112
	v_add_f32_e32 v53, 0, v181
	v_add_f32_e32 v27, v27, v198
	v_add_f32_e32 v53, v53, v199
	v_add_f32_e32 v27, v27, v210
	v_add_f32_e32 v53, v53, v211
	v_ldexp_f32 v1, v5, -9
	v_mul_f32_e32 v5, 0x4b800000, v8
	v_cmp_gt_f32_e32 vcc, s0, v8
	v_add_f32_e32 v27, v27, v222
	v_add_f32_e32 v53, v53, v223
	v_cndmask_b32_e32 v5, v8, v5, vcc
	v_add_f32_e32 v27, v27, v234
	v_add_f32_e32 v53, v53, v235
	v_rsq_f32_e32 v8, v5
	v_mul_f32_e32 v5, 0x4b800000, v9
	v_cmp_gt_f32_e64 s[38:39], s0, v9
	v_add_f32_e32 v27, v27, v248
	v_add_f32_e32 v53, v53, v249
	v_cndmask_b32_e64 v5, v9, v5, s[38:39]
	v_add_f32_e32 v27, v27, v184
	v_add_f32_e32 v53, v53, v185
	v_rsq_f32_e32 v9, v5
	v_add_f32_e32 v27, v27, v238
	v_add_f32_e32 v53, v53, v239
	v_ldexp_f32 v165, v27, -9
	v_ldexp_f32 v27, v53, -9
	v_fma_f32 v26, -v164, v164, v26
	v_fma_f32 v27, -v165, v165, v27
	v_max_f32_e32 v26, 0, v26
	v_max_f32_e32 v27, 0, v27
	v_pk_add_f32 v[2:3], v[156:157], v[160:161] neg_lo:[0,1] neg_hi:[0,1]
	v_pk_mul_f32 v[156:157], v[8:9], s[8:9] op_sel_hi:[1,0]
	v_fma_f32 v0, -v166, v166, v0
	v_cndmask_b32_e64 v157, v9, v157, s[38:39]
	v_cndmask_b32_e32 v156, v8, v156, vcc
	v_pk_add_f32 v[8:9], v[26:27], s[6:7] op_sel_hi:[1,0]
	v_fma_f32 v1, -v167, v167, v1
	v_mul_f32_e32 v5, 0x4b800000, v8
	v_cmp_gt_f32_e32 vcc, s0, v8
	v_cmp_gt_f32_e64 s[2:3], s0, v9
	v_max_f32_e32 v0, 0, v0
	v_cndmask_b32_e32 v5, v8, v5, vcc
	v_rsq_f32_e32 v8, v5
	v_mul_f32_e32 v5, 0x4b800000, v9
	v_cndmask_b32_e64 v5, v9, v5, s[2:3]
	v_rsq_f32_e32 v9, v5
	v_max_f32_e32 v1, 0, v1
	v_pk_add_f32 v[26:27], v[64:65], v[162:163] neg_lo:[0,1] neg_hi:[0,1]
	v_pk_add_f32 v[0:1], v[0:1], s[6:7] op_sel_hi:[1,0]
	v_pk_mul_f32 v[64:65], v[8:9], s[8:9] op_sel_hi:[1,0]
	v_mul_f32_e32 v5, 0x4b800000, v0
	v_cndmask_b32_e32 v64, v8, v64, vcc
	v_cmp_gt_f32_e32 vcc, s0, v0
	v_cndmask_b32_e64 v65, v9, v65, s[2:3]
	v_cmp_gt_f32_e64 s[2:3], s0, v1
	v_cndmask_b32_e32 v0, v0, v5, vcc
	v_mul_f32_e32 v5, 0x4b800000, v1
	v_cndmask_b32_e64 v1, v1, v5, s[2:3]
	v_rsq_f32_e32 v0, v0
	v_rsq_f32_e32 v1, v1
	v_pk_add_f32 v[8:9], v[56:57], v[164:165] neg_lo:[0,1] neg_hi:[0,1]
	v_pk_mul_f32 v[2:3], v[2:3], v[168:169]
	v_pk_mul_f32 v[26:27], v[26:27], v[156:157]
	v_pk_mul_f32 v[56:57], v[0:1], s[8:9] op_sel_hi:[1,0]
	v_pk_mul_f32 v[8:9], v[8:9], v[64:65]
	v_cndmask_b32_e64 v57, v1, v57, s[2:3]
	v_cndmask_b32_e32 v56, v0, v56, vcc
	v_pk_add_f32 v[0:1], v[58:59], v[166:167] neg_lo:[0,1] neg_hi:[0,1]
	s_waitcnt vmcnt(14)
; #define LAS __attribute__((address_space(3)))
; #define GAS __attribute__((address_space(1)))
; __device__ __forceinline__ unsigned cvtpk(float lo, float hi) { f32x2 v = {lo, hi}; bf16x2_t b = __builtin_convertvector(v, bf16x2_t); return __builtin_bit_cast(unsigned, b); }
; __device__ __forceinline__ float bflo(unsigned w) { return __uint_as_float(w << 16); }
; __device__ __forceinline__ float bfhi(unsigned w) { return __uint_as_float(w & 0xffff0000u); }
; __device__ __forceinline__ void a_unit(Frame& F, int L, int u, bool dry) {
;     ...
;         for (int i = 0; i < 16; ++i) { const int cl = 4 * i + cr; const float g = lng[cl], bb = lnb[cl];
;             float v[8];
; #pragma unroll
;             for (int jj = 0; jj < 4; ++jj) { v[2 * jj] = (bflo(raw[i][jj]) - mu[2 * jj]) * rs[2 * jj] * g + bb; v[2 * jj + 1] = (bfhi(raw[i][jj]) - mu[2 * jj + 1]) * rs[2 * jj + 1] * g + bb; }
;             u32x4 o; o.x = cvtpk(v[0], v[1]); o.y = cvtpk(v[2], v[3]); o.z = cvtpk(v[4], v[5]); o.w = cvtpk(v[6], v[7]);
;             *(LAS u32x4*)(VT + (((cl >> 5) * 2 + ((cl >> 2) & 1)) * 16 + ((cl >> 3) & 3) * 4 + (cl & 3)) * 272 + tg * 16) = o;
;             if ((i & 3) == 3) {
; #pragma unroll
;                 for (int qb = 0; qb < 4; ++qb) af[i >> 2][qb] = *(const GAS bf16x8*)(Wh + (size_t)((i >> 2) * 4 + qb) * 512); } }
	v_pk_fma_f32 v[2:3], v[2:3], v[170:171], v[172:173] op_sel_hi:[1,0,0]
	v_pk_mul_f32 v[0:1], v[0:1], v[56:57]
	v_pk_fma_f32 v[26:27], v[26:27], v[170:171], v[172:173] op_sel_hi:[1,0,0]
	v_pk_fma_f32 v[8:9], v[8:9], v[170:171], v[172:173] op_sel_hi:[1,0,0]
	v_pk_fma_f32 v[58:59], v[170:171], v[0:1], v[172:173] op_sel_hi:[0,1,0]
	v_mul_u32_u24_e32 v5, 0x110, v173
	v_readlane_b32 s1, v253, 57
	v_cvt_pk_bf16_f32 v0, v2, v3
	v_cvt_pk_bf16_f32 v1, v26, v27
	v_cvt_pk_bf16_f32 v2, v8, v9
	v_cvt_pk_bf16_f32 v3, v58, v59
	v_add3_u32 v59, s1, v52, v5
	ds_write_b128 v59, v[0:3]
	v_pk_add_f32 v[0:1], v[54:55], v[160:161] neg_lo:[0,1] neg_hi:[0,1]
	v_pk_add_f32 v[2:3], v[60:61], v[162:163] neg_lo:[0,1] neg_hi:[0,1]
	v_pk_add_f32 v[8:9], v[68:69], v[164:165] neg_lo:[0,1] neg_hi:[0,1]
	v_pk_add_f32 v[26:27], v[74:75], v[166:167] neg_lo:[0,1] neg_hi:[0,1]
	v_pk_mul_f32 v[0:1], v[0:1], v[168:169]
	v_pk_mul_f32 v[2:3], v[2:3], v[156:157]
	v_pk_mul_f32 v[8:9], v[8:9], v[64:65]
	v_pk_mul_f32 v[26:27], v[26:27], v[56:57]
	s_waitcnt vmcnt(12)
	v_pk_fma_f32 v[0:1], v[0:1], v[4:5], v[6:7] op_sel_hi:[1,0,0]
	v_pk_fma_f32 v[2:3], v[2:3], v[4:5], v[6:7] op_sel_hi:[1,0,0]
	v_pk_fma_f32 v[8:9], v[8:9], v[4:5], v[6:7] op_sel_hi:[1,0,0]
	v_pk_fma_f32 v[4:5], v[26:27], v[4:5], v[6:7] op_sel_hi:[1,0,0]
	v_cvt_pk_bf16_f32 v0, v0, v1
	v_cvt_pk_bf16_f32 v1, v2, v3
	v_cvt_pk_bf16_f32 v2, v8, v9
	v_cvt_pk_bf16_f32 v3, v4, v5
	ds_write_b128 v59, v[0:3] offset:4352
	v_pk_add_f32 v[0:1], v[78:79], v[160:161] neg_lo:[0,1] neg_hi:[0,1]
	v_pk_add_f32 v[2:3], v[82:83], v[162:163] neg_lo:[0,1] neg_hi:[0,1]
	v_pk_add_f32 v[4:5], v[90:91], v[164:165] neg_lo:[0,1] neg_hi:[0,1]
	v_pk_add_f32 v[6:7], v[98:99], v[166:167] neg_lo:[0,1] neg_hi:[0,1]
	v_pk_mul_f32 v[0:1], v[0:1], v[168:169]
	v_pk_mul_f32 v[2:3], v[2:3], v[156:157]
	v_pk_mul_f32 v[4:5], v[4:5], v[64:65]
	v_pk_mul_f32 v[6:7], v[6:7], v[56:57]
	s_waitcnt vmcnt(10)
	v_pk_fma_f32 v[0:1], v[0:1], v[10:11], v[18:19] op_sel_hi:[1,0,0]
	v_pk_fma_f32 v[2:3], v[2:3], v[10:11], v[18:19] op_sel_hi:[1,0,0]
	v_pk_fma_f32 v[4:5], v[4:5], v[10:11], v[18:19] op_sel_hi:[1,0,0]
	v_pk_fma_f32 v[6:7], v[6:7], v[10:11], v[18:19] op_sel_hi:[1,0,0]
	v_cvt_pk_bf16_f32 v0, v0, v1
	v_cvt_pk_bf16_f32 v1, v2, v3
	v_cvt_pk_bf16_f32 v2, v4, v5
	v_cvt_pk_bf16_f32 v3, v6, v7
	ds_write_b128 v59, v[0:3] offset:1088
	v_pk_add_f32 v[0:1], v[100:101], v[160:161] neg_lo:[0,1] neg_hi:[0,1]
	v_pk_add_f32 v[2:3], v[114:115], v[162:163] neg_lo:[0,1] neg_hi:[0,1]
	v_pk_add_f32 v[4:5], v[126:127], v[164:165] neg_lo:[0,1] neg_hi:[0,1]
	v_pk_add_f32 v[6:7], v[136:137], v[166:167] neg_lo:[0,1] neg_hi:[0,1]
	v_pk_mul_f32 v[0:1], v[0:1], v[168:169]
	v_pk_mul_f32 v[2:3], v[2:3], v[156:157]
	v_pk_mul_f32 v[4:5], v[4:5], v[64:65]
	v_pk_mul_f32 v[6:7], v[6:7], v[56:57]
	s_waitcnt vmcnt(4)
	v_pk_fma_f32 v[0:1], v[0:1], v[20:21], v[30:31] op_sel_hi:[1,0,0]
	v_pk_fma_f32 v[2:3], v[2:3], v[20:21], v[30:31] op_sel_hi:[1,0,0]
	v_pk_fma_f32 v[4:5], v[4:5], v[20:21], v[30:31] op_sel_hi:[1,0,0]
	v_pk_fma_f32 v[6:7], v[6:7], v[20:21], v[30:31] op_sel_hi:[1,0,0]
	v_cvt_pk_bf16_f32 v0, v0, v1
	v_cvt_pk_bf16_f32 v1, v2, v3
	v_cvt_pk_bf16_f32 v2, v4, v5
	v_cvt_pk_bf16_f32 v3, v6, v7
	ds_write_b128 v59, v[0:3] offset:5440
	global_load_dwordx4 v[8:11], v[24:25], off offset:1024
	global_load_dwordx4 v[4:7], v[24:25], off offset:2048
	global_load_dwordx4 v[0:3], v[24:25], off offset:3072
	v_pk_add_f32 v[18:19], v[130:131], v[160:161] neg_lo:[0,1] neg_hi:[0,1]
	v_pk_add_f32 v[20:21], v[138:139], v[162:163] neg_lo:[0,1] neg_hi:[0,1]
	v_pk_add_f32 v[24:25], v[144:145], v[164:165] neg_lo:[0,1] neg_hi:[0,1]
	v_pk_add_f32 v[26:27], v[118:119], v[166:167] neg_lo:[0,1] neg_hi:[0,1]
	v_pk_mul_f32 v[18:19], v[18:19], v[168:169]
	v_pk_mul_f32 v[20:21], v[20:21], v[156:157]
	v_pk_mul_f32 v[24:25], v[24:25], v[64:65]
	global_load_dword v54, v177, s[44:45] offset:128
	global_load_dword v58, v177, s[64:65] offset:128
	v_pk_mul_f32 v[26:27], v[26:27], v[56:57]
	s_waitcnt vmcnt(8)
	v_pk_fma_f32 v[18:19], v[18:19], v[22:23], v[174:175] op_sel_hi:[1,0,0]
	v_pk_fma_f32 v[20:21], v[20:21], v[22:23], v[174:175] op_sel_hi:[1,0,0]
	v_pk_fma_f32 v[24:25], v[24:25], v[22:23], v[174:175] op_sel_hi:[1,0,0]
	v_pk_fma_f32 v[22:23], v[26:27], v[22:23], v[174:175] op_sel_hi:[1,0,0]
	v_cvt_pk_bf16_f32 v18, v18, v19
	v_cvt_pk_bf16_f32 v19, v20, v21
	v_cvt_pk_bf16_f32 v20, v24, v25
	v_cvt_pk_bf16_f32 v21, v22, v23
	ds_write_b128 v59, v[18:21] offset:2176
	v_pk_add_f32 v[18:19], v[120:121], v[160:161] neg_lo:[0,1] neg_hi:[0,1]
	v_pk_add_f32 v[20:21], v[132:133], v[162:163] neg_lo:[0,1] neg_hi:[0,1]
	v_pk_add_f32 v[22:23], v[140:141], v[164:165] neg_lo:[0,1] neg_hi:[0,1]
	v_pk_add_f32 v[24:25], v[112:113], v[166:167] neg_lo:[0,1] neg_hi:[0,1]
	v_pk_mul_f32 v[18:19], v[18:19], v[168:169]
	v_pk_mul_f32 v[20:21], v[20:21], v[156:157]
	global_load_dword v60, v177, s[44:45] offset:144
	global_load_dword v68, v177, s[64:65] offset:144
	v_pk_mul_f32 v[22:23], v[22:23], v[64:65]
	v_pk_mul_f32 v[24:25], v[24:25], v[56:57]
	s_waitcnt vmcnt(9)
	v_pk_fma_f32 v[18:19], v[18:19], v[28:29], v[178:179] op_sel_hi:[1,0,0]
	v_pk_fma_f32 v[20:21], v[20:21], v[28:29], v[178:179] op_sel_hi:[1,0,0]
	v_pk_fma_f32 v[22:23], v[22:23], v[28:29], v[178:179] op_sel_hi:[1,0,0]
	v_pk_fma_f32 v[24:25], v[24:25], v[28:29], v[178:179] op_sel_hi:[1,0,0]
	v_cvt_pk_bf16_f32 v18, v18, v19
	v_cvt_pk_bf16_f32 v19, v20, v21
	v_cvt_pk_bf16_f32 v20, v22, v23
	v_cvt_pk_bf16_f32 v21, v24, v25
	ds_write_b128 v59, v[18:21] offset:6528
	v_pk_add_f32 v[18:19], v[116:117], v[160:161] neg_lo:[0,1] neg_hi:[0,1]
	v_pk_add_f32 v[20:21], v[128:129], v[162:163] neg_lo:[0,1] neg_hi:[0,1]
	v_pk_add_f32 v[22:23], v[96:97], v[164:165] neg_lo:[0,1] neg_hi:[0,1]
	v_pk_add_f32 v[24:25], v[108:109], v[166:167] neg_lo:[0,1] neg_hi:[0,1]
	v_pk_mul_f32 v[18:19], v[18:19], v[168:169]
	v_pk_mul_f32 v[20:21], v[20:21], v[156:157]
	global_load_dword v74, v177, s[44:45] offset:160
	global_load_dword v78, v177, s[64:65] offset:160
	v_pk_mul_f32 v[22:23], v[22:23], v[64:65]
	v_pk_mul_f32 v[24:25], v[24:25], v[56:57]
	s_waitcnt vmcnt(10)
; #define LAS __attribute__((address_space(3)))
; #define GAS __attribute__((address_space(1)))
; __device__ __forceinline__ unsigned cvtpk(float lo, float hi) { f32x2 v = {lo, hi}; bf16x2_t b = __builtin_convertvector(v, bf16x2_t); return __builtin_bit_cast(unsigned, b); }
; __device__ __forceinline__ float bflo(unsigned w) { return __uint_as_float(w << 16); }
; __device__ __forceinline__ float bfhi(unsigned w) { return __uint_as_float(w & 0xffff0000u); }
; __device__ __forceinline__ void a_unit(Frame& F, int L, int u, bool dry) {
;     ...
;         for (int i = 0; i < 16; ++i) { const int cl = 4 * i + cr; const float g = lng[cl], bb = lnb[cl];
;             float v[8];
; #pragma unroll
;             for (int jj = 0; jj < 4; ++jj) { v[2 * jj] = (bflo(raw[i][jj]) - mu[2 * jj]) * rs[2 * jj] * g + bb; v[2 * jj + 1] = (bfhi(raw[i][jj]) - mu[2 * jj + 1]) * rs[2 * jj + 1] * g + bb; }
;             u32x4 o; o.x = cvtpk(v[0], v[1]); o.y = cvtpk(v[2], v[3]); o.z = cvtpk(v[4], v[5]); o.w = cvtpk(v[6], v[7]);
;             *(LAS u32x4*)(VT + (((cl >> 5) * 2 + ((cl >> 2) & 1)) * 16 + ((cl >> 3) & 3) * 4 + (cl & 3)) * 272 + tg * 16) = o;
;             if ((i & 3) == 3) {
; #pragma unroll
;                 for (int qb = 0; qb < 4; ++qb) af[i >> 2][qb] = *(const GAS bf16x8*)(Wh + (size_t)((i >> 2) * 4 + qb) * 512); } }
	v_pk_fma_f32 v[18:19], v[18:19], v[16:17], v[180:181] op_sel_hi:[1,0,0]
	v_pk_fma_f32 v[20:21], v[20:21], v[16:17], v[180:181] op_sel_hi:[1,0,0]
	v_pk_fma_f32 v[22:23], v[22:23], v[16:17], v[180:181] op_sel_hi:[1,0,0]
	v_pk_fma_f32 v[24:25], v[24:25], v[16:17], v[180:181] op_sel_hi:[1,0,0]
	v_cvt_pk_bf16_f32 v16, v18, v19
	v_cvt_pk_bf16_f32 v17, v20, v21
	v_cvt_pk_bf16_f32 v18, v22, v23
	v_cvt_pk_bf16_f32 v19, v24, v25
	ds_write_b128 v59, v[16:19] offset:3264
	v_pk_add_f32 v[16:17], v[110:111], v[160:161] neg_lo:[0,1] neg_hi:[0,1]
	global_load_dword v82, v177, s[44:45] offset:176
	global_load_dword v90, v177, s[64:65] offset:176
	v_pk_add_f32 v[18:19], v[86:87], v[162:163] neg_lo:[0,1] neg_hi:[0,1]
	v_pk_add_f32 v[20:21], v[92:93], v[164:165] neg_lo:[0,1] neg_hi:[0,1]
	v_pk_add_f32 v[22:23], v[104:105], v[166:167] neg_lo:[0,1] neg_hi:[0,1]
	v_pk_mul_f32 v[16:17], v[16:17], v[168:169]
	v_pk_mul_f32 v[18:19], v[18:19], v[156:157]
	v_pk_mul_f32 v[20:21], v[20:21], v[64:65]
	v_pk_mul_f32 v[22:23], v[22:23], v[56:57]
	s_mov_b32 s0, 0x1d01000
	s_waitcnt vmcnt(11)
	v_pk_fma_f32 v[16:17], v[16:17], v[12:13], v[14:15] op_sel_hi:[1,0,0]
	v_pk_fma_f32 v[18:19], v[18:19], v[12:13], v[14:15] op_sel_hi:[1,0,0]
	v_pk_fma_f32 v[20:21], v[20:21], v[12:13], v[14:15] op_sel_hi:[1,0,0]
	v_pk_fma_f32 v[22:23], v[22:23], v[12:13], v[14:15] op_sel_hi:[1,0,0]
	v_add_co_u32_e32 v52, vcc, s0, v158
	v_cvt_pk_bf16_f32 v12, v16, v17
	v_cvt_pk_bf16_f32 v13, v18, v19
	v_cvt_pk_bf16_f32 v14, v20, v21
	v_cvt_pk_bf16_f32 v15, v22, v23
	v_addc_co_u32_e32 v53, vcc, 0, v159, vcc
	ds_write_b128 v59, v[12:15] offset:7616
	global_load_dwordx4 v[24:27], v[52:53], off
	global_load_dwordx4 v[20:23], v[52:53], off offset:1024
	global_load_dwordx4 v[16:19], v[52:53], off offset:2048
	global_load_dwordx4 v[12:15], v[52:53], off offset:3072
	v_pk_add_f32 v[28:29], v[102:103], v[160:161] neg_lo:[0,1] neg_hi:[0,1]
	global_load_dword v86, v177, s[44:45] offset:192
	global_load_dword v92, v177, s[44:45] offset:208
	global_load_dword v96, v177, s[44:45] offset:224
	global_load_dword v98, v177, s[44:45] offset:240
	global_load_dword v100, v177, s[64:65] offset:192
	global_load_dword v102, v177, s[64:65] offset:208
	global_load_dword v104, v177, s[64:65] offset:224
	global_load_dword v108, v177, s[64:65] offset:240
	v_pk_add_f32 v[30:31], v[194:195], v[162:163] neg_lo:[0,1] neg_hi:[0,1]
	v_pk_add_f32 v[32:33], v[32:33], v[164:165] neg_lo:[0,1] neg_hi:[0,1]
	v_pk_add_f32 v[110:111], v[244:245], v[166:167] neg_lo:[0,1] neg_hi:[0,1]
	v_pk_mul_f32 v[28:29], v[28:29], v[168:169]
	v_pk_mul_f32 v[30:31], v[30:31], v[156:157]
	v_pk_mul_f32 v[32:33], v[32:33], v[64:65]
	v_pk_mul_f32 v[110:111], v[110:111], v[56:57]
	s_waitcnt vmcnt(18)
	v_pk_fma_f32 v[28:29], v[28:29], v[54:55], v[58:59] op_sel_hi:[1,0,0]
	v_pk_fma_f32 v[30:31], v[30:31], v[54:55], v[58:59] op_sel_hi:[1,0,0]
	v_pk_fma_f32 v[32:33], v[32:33], v[54:55], v[58:59] op_sel_hi:[1,0,0]
	v_pk_fma_f32 v[54:55], v[110:111], v[54:55], v[58:59] op_sel_hi:[1,0,0]
	v_cvt_pk_bf16_f32 v28, v28, v29
	v_cvt_pk_bf16_f32 v29, v30, v31
	v_cvt_pk_bf16_f32 v30, v32, v33
	v_cvt_pk_bf16_f32 v31, v54, v55
	ds_write_b128 v59, v[28:31] offset:8704
	v_pk_add_f32 v[28:29], v[34:35], v[160:161] neg_lo:[0,1] neg_hi:[0,1]
	v_pk_add_f32 v[30:31], v[36:37], v[162:163] neg_lo:[0,1] neg_hi:[0,1]
	v_pk_add_f32 v[32:33], v[38:39], v[164:165] neg_lo:[0,1] neg_hi:[0,1]
	v_pk_add_f32 v[34:35], v[40:41], v[166:167] neg_lo:[0,1] neg_hi:[0,1]
	v_pk_mul_f32 v[28:29], v[28:29], v[168:169]
	v_pk_mul_f32 v[30:31], v[30:31], v[156:157]
	v_pk_mul_f32 v[32:33], v[32:33], v[64:65]
	v_pk_mul_f32 v[34:35], v[34:35], v[56:57]
	s_waitcnt vmcnt(16)
	v_pk_fma_f32 v[28:29], v[28:29], v[60:61], v[68:69] op_sel_hi:[1,0,0]
	v_pk_fma_f32 v[30:31], v[30:31], v[60:61], v[68:69] op_sel_hi:[1,0,0]
	v_pk_fma_f32 v[32:33], v[32:33], v[60:61], v[68:69] op_sel_hi:[1,0,0]
	v_pk_fma_f32 v[34:35], v[34:35], v[60:61], v[68:69] op_sel_hi:[1,0,0]
	v_cvt_pk_bf16_f32 v28, v28, v29
	v_cvt_pk_bf16_f32 v29, v30, v31
	v_cvt_pk_bf16_f32 v30, v32, v33
	v_cvt_pk_bf16_f32 v31, v34, v35
	ds_write_b128 v59, v[28:31] offset:13056
	v_pk_add_f32 v[28:29], v[42:43], v[160:161] neg_lo:[0,1] neg_hi:[0,1]
	v_pk_add_f32 v[30:31], v[44:45], v[162:163] neg_lo:[0,1] neg_hi:[0,1]
	v_pk_add_f32 v[32:33], v[46:47], v[164:165] neg_lo:[0,1] neg_hi:[0,1]
	v_pk_add_f32 v[34:35], v[48:49], v[166:167] neg_lo:[0,1] neg_hi:[0,1]
	v_pk_mul_f32 v[28:29], v[28:29], v[168:169]
	v_pk_mul_f32 v[30:31], v[30:31], v[156:157]
	v_pk_mul_f32 v[32:33], v[32:33], v[64:65]
	v_pk_mul_f32 v[34:35], v[34:35], v[56:57]
	s_mov_b32 s0, 0x1d02000
	s_waitcnt vmcnt(14)
	v_pk_fma_f32 v[28:29], v[28:29], v[74:75], v[78:79] op_sel_hi:[1,0,0]
	v_pk_fma_f32 v[30:31], v[30:31], v[74:75], v[78:79] op_sel_hi:[1,0,0]
	v_pk_fma_f32 v[32:33], v[32:33], v[74:75], v[78:79] op_sel_hi:[1,0,0]
	v_pk_fma_f32 v[34:35], v[34:35], v[74:75], v[78:79] op_sel_hi:[1,0,0]
	v_cvt_pk_bf16_f32 v28, v28, v29
	v_cvt_pk_bf16_f32 v29, v30, v31
	v_cvt_pk_bf16_f32 v30, v32, v33
	v_cvt_pk_bf16_f32 v31, v34, v35
	ds_write_b128 v59, v[28:31] offset:9792
	v_pk_add_f32 v[28:29], v[50:51], v[160:161] neg_lo:[0,1] neg_hi:[0,1]
	v_pk_add_f32 v[30:31], v[62:63], v[162:163] neg_lo:[0,1] neg_hi:[0,1]
	v_pk_add_f32 v[32:33], v[70:71], v[164:165] neg_lo:[0,1] neg_hi:[0,1]
	v_pk_add_f32 v[34:35], v[76:77], v[166:167] neg_lo:[0,1] neg_hi:[0,1]
	v_pk_mul_f32 v[28:29], v[28:29], v[168:169]
	v_pk_mul_f32 v[30:31], v[30:31], v[156:157]
	v_pk_mul_f32 v[32:33], v[32:33], v[64:65]
	v_pk_mul_f32 v[34:35], v[34:35], v[56:57]
	s_waitcnt vmcnt(12)
; #define LAS __attribute__((address_space(3)))
; #define GAS __attribute__((address_space(1)))
; __device__ __forceinline__ unsigned cvtpk(float lo, float hi) { f32x2 v = {lo, hi}; bf16x2_t b = __builtin_convertvector(v, bf16x2_t); return __builtin_bit_cast(unsigned, b); }
; __device__ __forceinline__ float bflo(unsigned w) { return __uint_as_float(w << 16); }
; __device__ __forceinline__ float bfhi(unsigned w) { return __uint_as_float(w & 0xffff0000u); }
; __device__ __forceinline__ void a_unit(Frame& F, int L, int u, bool dry) {
;     ...
;         for (int i = 0; i < 16; ++i) { const int cl = 4 * i + cr; const float g = lng[cl], bb = lnb[cl];
;             float v[8];
; #pragma unroll
;             for (int jj = 0; jj < 4; ++jj) { v[2 * jj] = (bflo(raw[i][jj]) - mu[2 * jj]) * rs[2 * jj] * g + bb; v[2 * jj + 1] = (bfhi(raw[i][jj]) - mu[2 * jj + 1]) * rs[2 * jj + 1] * g + bb; }
;             u32x4 o; o.x = cvtpk(v[0], v[1]); o.y = cvtpk(v[2], v[3]); o.z = cvtpk(v[4], v[5]); o.w = cvtpk(v[6], v[7]);
;             *(LAS u32x4*)(VT + (((cl >> 5) * 2 + ((cl >> 2) & 1)) * 16 + ((cl >> 3) & 3) * 4 + (cl & 3)) * 272 + tg * 16) = o;
;             if ((i & 3) == 3) {
; #pragma unroll
;                 for (int qb = 0; qb < 4; ++qb) af[i >> 2][qb] = *(const GAS bf16x8*)(Wh + (size_t)((i >> 2) * 4 + qb) * 512); } }
;     }
;     asm volatile("s_waitcnt lgkmcnt(0)" ::: "memory");
;     f32x4 acc[4][4];
; #pragma unroll
;     for (int a = 0; a < 4; ++a)
; #pragma unroll
;         for (int c = 0; c < 4; ++c) acc[a][c] = (f32x4){0.f, 0.f, 0.f, 0.f};
; #pragma unroll
;     for (int ks = 0; ks < 4; ++ks) {
;         bf16x8 bfv[4];
; #pragma unroll
;         for (int nb = 0; nb < 4; ++nb) bfv[nb] = *(const LAS bf16x8*)(VT + (nb * 16 + fr) * 272 + (ks * 32 + 8 * fq) * 2);
; #pragma unroll
;         for (int qb = 0; qb < 4; ++qb)
; #pragma unroll
;             for (int nb = 0; nb < 4; ++nb) acc[qb][nb] = __builtin_amdgcn_mfma_f32_16x16x32_bf16(bfv[nb], af[ks][qb], acc[qb][nb], 0, 0, 0);
	v_pk_fma_f32 v[28:29], v[28:29], v[82:83], v[90:91] op_sel_hi:[1,0,0]
	v_pk_fma_f32 v[30:31], v[30:31], v[82:83], v[90:91] op_sel_hi:[1,0,0]
	v_pk_fma_f32 v[32:33], v[32:33], v[82:83], v[90:91] op_sel_hi:[1,0,0]
	v_pk_fma_f32 v[34:35], v[34:35], v[82:83], v[90:91] op_sel_hi:[1,0,0]
	v_pk_add_f32 v[44:45], v[66:67], v[160:161] neg_lo:[0,1] neg_hi:[0,1]
	v_pk_add_f32 v[46:47], v[72:73], v[162:163] neg_lo:[0,1] neg_hi:[0,1]
	v_pk_add_f32 v[48:49], v[80:81], v[164:165] neg_lo:[0,1] neg_hi:[0,1]
	v_pk_add_f32 v[50:51], v[84:85], v[166:167] neg_lo:[0,1] neg_hi:[0,1]
	v_cvt_pk_bf16_f32 v28, v28, v29
	v_cvt_pk_bf16_f32 v29, v30, v31
	v_cvt_pk_bf16_f32 v30, v32, v33
	v_cvt_pk_bf16_f32 v31, v34, v35
	v_add_co_u32_e32 v40, vcc, s0, v158
	v_pk_mul_f32 v[44:45], v[44:45], v[168:169]
	v_pk_mul_f32 v[46:47], v[46:47], v[156:157]
	v_pk_mul_f32 v[48:49], v[48:49], v[64:65]
	v_pk_mul_f32 v[50:51], v[50:51], v[56:57]
	ds_write_b128 v59, v[28:31] offset:14144
	v_addc_co_u32_e32 v41, vcc, 0, v159, vcc
	s_waitcnt vmcnt(3)
	v_pk_fma_f32 v[44:45], v[44:45], v[86:87], v[100:101] op_sel_hi:[1,0,0]
	v_pk_fma_f32 v[46:47], v[46:47], v[86:87], v[100:101] op_sel_hi:[1,0,0]
	v_pk_fma_f32 v[48:49], v[48:49], v[86:87], v[100:101] op_sel_hi:[1,0,0]
	v_pk_fma_f32 v[50:51], v[50:51], v[86:87], v[100:101] op_sel_hi:[1,0,0]
	global_load_dwordx4 v[28:31], v[40:41], off offset:1024
	global_load_dwordx4 v[32:35], v[40:41], off offset:2048
	global_load_dwordx4 v[36:39], v[52:53], off offset:-4096
	s_nop 0
	global_load_dwordx4 v[40:43], v[40:41], off offset:3072
	v_cvt_pk_bf16_f32 v44, v44, v45
	v_cvt_pk_bf16_f32 v45, v46, v47
	v_cvt_pk_bf16_f32 v46, v48, v49
	v_cvt_pk_bf16_f32 v47, v50, v51
	ds_write_b128 v59, v[44:47] offset:10880
	v_pk_add_f32 v[44:45], v[88:89], v[160:161] neg_lo:[0,1] neg_hi:[0,1]
	v_pk_add_f32 v[46:47], v[94:95], v[162:163] neg_lo:[0,1] neg_hi:[0,1]
	v_pk_add_f32 v[48:49], v[106:107], v[164:165] neg_lo:[0,1] neg_hi:[0,1]
	v_pk_add_f32 v[50:51], v[122:123], v[166:167] neg_lo:[0,1] neg_hi:[0,1]
	v_pk_mul_f32 v[44:45], v[44:45], v[168:169]
	v_pk_mul_f32 v[46:47], v[46:47], v[156:157]
	v_pk_mul_f32 v[48:49], v[48:49], v[64:65]
	v_pk_mul_f32 v[50:51], v[50:51], v[56:57]
	s_waitcnt vmcnt(6)
	v_pk_fma_f32 v[44:45], v[44:45], v[92:93], v[102:103] op_sel_hi:[1,0,0]
	v_pk_fma_f32 v[46:47], v[46:47], v[92:93], v[102:103] op_sel_hi:[1,0,0]
	v_pk_fma_f32 v[48:49], v[48:49], v[92:93], v[102:103] op_sel_hi:[1,0,0]
	v_pk_fma_f32 v[50:51], v[50:51], v[92:93], v[102:103] op_sel_hi:[1,0,0]
	v_cvt_pk_bf16_f32 v44, v44, v45
	v_cvt_pk_bf16_f32 v45, v46, v47
	v_cvt_pk_bf16_f32 v46, v48, v49
	v_cvt_pk_bf16_f32 v47, v50, v51
	ds_write_b128 v59, v[44:47] offset:15232
	v_pk_add_f32 v[44:45], v[124:125], v[160:161] neg_lo:[0,1] neg_hi:[0,1]
	v_pk_add_f32 v[46:47], v[134:135], v[162:163] neg_lo:[0,1] neg_hi:[0,1]
	v_pk_add_f32 v[48:49], v[142:143], v[164:165] neg_lo:[0,1] neg_hi:[0,1]
	v_pk_add_f32 v[50:51], v[146:147], v[166:167] neg_lo:[0,1] neg_hi:[0,1]
	v_pk_mul_f32 v[44:45], v[44:45], v[168:169]
	v_pk_mul_f32 v[46:47], v[46:47], v[156:157]
	v_pk_mul_f32 v[48:49], v[48:49], v[64:65]
	v_pk_mul_f32 v[50:51], v[50:51], v[56:57]
	s_waitcnt vmcnt(5)
	v_pk_fma_f32 v[44:45], v[44:45], v[96:97], v[104:105] op_sel_hi:[1,0,0]
	v_pk_fma_f32 v[46:47], v[46:47], v[96:97], v[104:105] op_sel_hi:[1,0,0]
	v_pk_fma_f32 v[48:49], v[48:49], v[96:97], v[104:105] op_sel_hi:[1,0,0]
	v_pk_fma_f32 v[50:51], v[50:51], v[96:97], v[104:105] op_sel_hi:[1,0,0]
	v_cvt_pk_bf16_f32 v44, v44, v45
	v_cvt_pk_bf16_f32 v45, v46, v47
	v_cvt_pk_bf16_f32 v46, v48, v49
	v_cvt_pk_bf16_f32 v47, v50, v51
	ds_write_b128 v59, v[44:47] offset:11968
	v_pk_add_f32 v[44:45], v[148:149], v[160:161] neg_lo:[0,1] neg_hi:[0,1]
	v_pk_add_f32 v[46:47], v[150:151], v[162:163] neg_lo:[0,1] neg_hi:[0,1]
	v_pk_add_f32 v[48:49], v[152:153], v[164:165] neg_lo:[0,1] neg_hi:[0,1]
	v_pk_add_f32 v[50:51], v[154:155], v[166:167] neg_lo:[0,1] neg_hi:[0,1]
	v_pk_mul_f32 v[44:45], v[44:45], v[168:169]
	v_pk_mul_f32 v[46:47], v[46:47], v[156:157]
	v_pk_mul_f32 v[48:49], v[48:49], v[64:65]
	v_pk_mul_f32 v[50:51], v[50:51], v[56:57]
	s_mov_b32 s0, 0x1d03000
	s_waitcnt vmcnt(4)
	v_pk_fma_f32 v[44:45], v[44:45], v[98:99], v[108:109] op_sel_hi:[1,0,0]
	v_pk_fma_f32 v[46:47], v[46:47], v[98:99], v[108:109] op_sel_hi:[1,0,0]
	v_pk_fma_f32 v[48:49], v[48:49], v[98:99], v[108:109] op_sel_hi:[1,0,0]
	v_pk_fma_f32 v[50:51], v[50:51], v[98:99], v[108:109] op_sel_hi:[1,0,0]
	v_add_co_u32_e32 v60, vcc, s0, v158
	v_cvt_pk_bf16_f32 v44, v44, v45
	v_cvt_pk_bf16_f32 v45, v46, v47
	v_cvt_pk_bf16_f32 v46, v48, v49
	v_cvt_pk_bf16_f32 v47, v50, v51
	v_addc_co_u32_e32 v61, vcc, 0, v159, vcc
	ds_write_b128 v59, v[44:47] offset:16320
	global_load_dwordx4 v[44:47], v[60:61], off offset:3072
	global_load_dwordx4 v[48:51], v[60:61], off offset:2048
	global_load_dwordx4 v[52:55], v[60:61], off offset:1024
	global_load_dwordx4 v[56:59], v[60:61], off offset:-4096
	s_nop 0
	global_load_dwordx4 v[60:63], v[60:61], off
	v_and_b32_e32 v64, 48, v176
	v_mul_u32_u24_e32 v65, 0x110, v190
	s_waitcnt lgkmcnt(0)
	v_add3_u32 v132, s1, v64, v65
	ds_read_b128 v[64:67], v132
	ds_read_b128 v[68:71], v132 offset:64
	ds_read_b128 v[76:79], v132 offset:4352
	ds_read_b128 v[80:83], v132 offset:4416
	ds_read_b128 v[88:91], v132 offset:8704
	ds_read_b128 v[92:95], v132 offset:8768
	ds_read_b128 v[100:103], v132 offset:13056
	ds_read_b128 v[104:107], v132 offset:13120
	s_waitcnt vmcnt(6) lgkmcnt(7)
	v_mfma_f32_16x16x32_bf16 v[72:75], v[64:67], v[36:39], 0
	s_mov_b64 s[0:1], s[72:73]
	v_readlane_b32 s2, v254, 32
	v_readlane_b32 s6, v254, 19
	s_waitcnt lgkmcnt(5)
; #define LAS __attribute__((address_space(3)))
; #define GAS __attribute__((address_space(1)))
; __device__ __forceinline__ void a_unit(Frame& F, int L, int u, bool dry) {
;     ...
;     for (int ks = 0; ks < 4; ++ks) {
;         bf16x8 bfv[4];
; #pragma unroll
;         for (int nb = 0; nb < 4; ++nb) bfv[nb] = *(const LAS bf16x8*)(VT + (nb * 16 + fr) * 272 + (ks * 32 + 8 * fq) * 2);
; #pragma unroll
;         for (int qb = 0; qb < 4; ++qb)
; #pragma unroll
;             for (int nb = 0; nb < 4; ++nb) acc[qb][nb] = __builtin_amdgcn_mfma_f32_16x16x32_bf16(bfv[nb], af[ks][qb], acc[qb][nb], 0, 0, 0);
;     }
;     bf16_t* UA = (bf16_t*)(ws_ + WS_UA);
;     const float* bs = kin(7) + (size_t)(L * 8 + w) * 128 + 64 * qh;
;     u32x4 uav[4][2]; float bsv[4];
; #pragma unroll
;     for (int qb = 0; qb < 4; ++qb) { const int ql = qb * 16 + fr; const size_t tok = (size_t)b * SEQ + chunk * 128 + 64 * qh + ql; bsv[qb] = bs[ql];
; #pragma unroll
;         for (int p = 0; p < 2; ++p) uav[qb][p] = *(const GAS u32x4*)(UA + tok * 512 + 64 * w + 32 * p + 8 * fq); }
	v_mfma_f32_16x16x32_bf16 v[84:87], v[76:79], v[36:39], 0
	v_readlane_b32 s7, v254, 20
	v_lshlrev_b32_e32 v192, 4, v173
	s_waitcnt lgkmcnt(3)
	v_mfma_f32_16x16x32_bf16 v[96:99], v[88:91], v[36:39], 0
	s_waitcnt lgkmcnt(1)
	v_mfma_f32_16x16x32_bf16 v[36:39], v[100:103], v[36:39], 0
	v_mfma_f32_16x16x32_bf16 v[108:111], v[64:67], v[8:11], 0
	v_mfma_f32_16x16x32_bf16 v[112:115], v[76:79], v[8:11], 0
	v_mfma_f32_16x16x32_bf16 v[116:119], v[88:91], v[8:11], 0
	v_mfma_f32_16x16x32_bf16 v[8:11], v[100:103], v[8:11], 0
	v_mfma_f32_16x16x32_bf16 v[120:123], v[64:67], v[4:7], 0
	v_mfma_f32_16x16x32_bf16 v[124:127], v[76:79], v[4:7], 0
	v_mfma_f32_16x16x32_bf16 v[128:131], v[88:91], v[4:7], 0
	v_mfma_f32_16x16x32_bf16 v[4:7], v[100:103], v[4:7], 0
	v_mfma_f32_16x16x32_bf16 v[64:67], v[64:67], v[0:3], 0
	v_mfma_f32_16x16x32_bf16 v[76:79], v[76:79], v[0:3], 0
	v_mfma_f32_16x16x32_bf16 v[88:91], v[88:91], v[0:3], 0
	v_mfma_f32_16x16x32_bf16 v[0:3], v[100:103], v[0:3], 0
	v_mfma_f32_16x16x32_bf16 v[72:75], v[68:71], v[24:27], v[72:75]
	v_mfma_f32_16x16x32_bf16 v[84:87], v[80:83], v[24:27], v[84:87]
	v_mfma_f32_16x16x32_bf16 v[96:99], v[92:95], v[24:27], v[96:99]
	s_waitcnt lgkmcnt(0)
	v_mfma_f32_16x16x32_bf16 v[24:27], v[104:107], v[24:27], v[36:39]
	v_mfma_f32_16x16x32_bf16 v[36:39], v[68:71], v[20:23], v[108:111]
	v_mfma_f32_16x16x32_bf16 v[100:103], v[80:83], v[20:23], v[112:115]
	v_mfma_f32_16x16x32_bf16 v[108:111], v[92:95], v[20:23], v[116:119]
	v_mfma_f32_16x16x32_bf16 v[8:11], v[104:107], v[20:23], v[8:11]
	v_mfma_f32_16x16x32_bf16 v[20:23], v[68:71], v[16:19], v[120:123]
	v_mfma_f32_16x16x32_bf16 v[112:115], v[80:83], v[16:19], v[124:127]
	v_mfma_f32_16x16x32_bf16 v[116:119], v[92:95], v[16:19], v[128:131]
	v_mfma_f32_16x16x32_bf16 v[4:7], v[104:107], v[16:19], v[4:7]
	v_mfma_f32_16x16x32_bf16 v[16:19], v[68:71], v[12:15], v[64:67]
	v_mfma_f32_16x16x32_bf16 v[64:67], v[80:83], v[12:15], v[76:79]
	v_mfma_f32_16x16x32_bf16 v[68:71], v[92:95], v[12:15], v[88:91]
	v_mfma_f32_16x16x32_bf16 v[0:3], v[104:107], v[12:15], v[0:3]
	ds_read_b128 v[12:15], v132 offset:128
	ds_read_b128 v[76:79], v132 offset:192
	ds_read_b128 v[80:83], v132 offset:4480
	ds_read_b128 v[88:91], v132 offset:4544
	ds_read_b128 v[92:95], v132 offset:8832
	ds_read_b128 v[104:107], v132 offset:8896
	ds_read_b128 v[120:123], v132 offset:13184
	ds_read_b128 v[124:127], v132 offset:13248
	s_load_dwordx2 s[0:1], s[0:1], 0x38
	s_waitcnt lgkmcnt(0)
	v_mfma_f32_16x16x32_bf16 v[4:7], v[120:123], v[32:35], v[4:7]
	s_add_u32 s0, s0, s42
	s_addc_u32 s1, s1, s43
	s_add_u32 s0, s0, s2
	s_addc_u32 s1, s1, 0
	s_lshl_b64 s[2:3], s[70:71], 1
	s_waitcnt vmcnt(1)
	v_mfma_f32_16x16x32_bf16 v[72:75], v[12:15], v[56:59], v[72:75]
	s_add_u32 s2, s28, s2
	s_addc_u32 s3, s29, s3
	v_mfma_f32_16x16x32_bf16 v[84:87], v[80:83], v[56:59], v[84:87]
	v_mfma_f32_16x16x32_bf16 v[96:99], v[92:95], v[56:59], v[96:99]
	v_mfma_f32_16x16x32_bf16 v[24:27], v[120:123], v[56:59], v[24:27]
	v_mfma_f32_16x16x32_bf16 v[36:39], v[12:15], v[28:31], v[36:39]
	v_mfma_f32_16x16x32_bf16 v[56:59], v[80:83], v[28:31], v[100:103]
	v_mfma_f32_16x16x32_bf16 v[100:103], v[92:95], v[28:31], v[108:111]
	v_mfma_f32_16x16x32_bf16 v[8:11], v[120:123], v[28:31], v[8:11]
	v_mfma_f32_16x16x32_bf16 v[28:31], v[80:83], v[32:35], v[112:115]
	v_mfma_f32_16x16x32_bf16 v[20:23], v[12:15], v[32:35], v[20:23]
	v_mfma_f32_16x16x32_bf16 v[108:111], v[92:95], v[32:35], v[116:119]
	v_mfma_f32_16x16x32_bf16 v[12:15], v[12:15], v[40:43], v[16:19]
	v_mfma_f32_16x16x32_bf16 v[32:35], v[80:83], v[40:43], v[64:67]
	v_mfma_f32_16x16x32_bf16 v[64:67], v[92:95], v[40:43], v[68:71]
	v_mfma_f32_16x16x32_bf16 v[40:43], v[120:123], v[40:43], v[0:3]
	v_mfma_f32_16x16x32_bf16 v[16:19], v[124:127], v[48:51], v[4:7]
	s_nop 1
	v_lshl_add_u64 v[0:1], s[2:3], 0, v[192:193]
	s_mov_b64 s[2:3], 0x5000000
	v_or_b32_e32 v4, s6, v190
	v_mov_b32_e32 v5, s7
	v_lshl_add_u64 v[6:7], v[0:1], 0, s[2:3]
	v_lshlrev_b64 v[0:1], 10, v[4:5]
	s_waitcnt vmcnt(0)
	v_mfma_f32_16x16x32_bf16 v[68:71], v[76:79], v[60:63], v[72:75]
	s_mov_b64 s[2:3], s[82:83]
	s_mul_i32 s6, s58, 0x3e00
	v_mfma_f32_16x16x32_bf16 v[72:75], v[88:91], v[60:63], v[84:87]
	v_mfma_f32_16x16x32_bf16 v[80:83], v[104:107], v[60:63], v[96:99]
	v_mfma_f32_16x16x32_bf16 v[84:87], v[104:107], v[52:55], v[100:103]
	v_mfma_f32_16x16x32_bf16 v[96:99], v[88:91], v[48:51], v[28:31]
	s_nop 1
	v_lshl_add_u64 v[102:103], v[6:7], 0, v[0:1]
	v_lshlrev_b32_e32 v30, 2, v190
	v_mfma_f32_16x16x32_bf16 v[92:95], v[76:79], v[48:51], v[20:23]
	global_load_dword v100, v30, s[0:1]
	v_or_b32_e32 v28, 32, v4
	v_mov_b32_e32 v29, v5
	v_mfma_f32_16x16x32_bf16 v[20:23], v[104:107], v[48:51], v[108:111]
	global_load_dwordx4 v[48:51], v[102:103], off sc1
	v_lshlrev_b64 v[28:29], 10, v[28:29]
	v_mfma_f32_16x16x32_bf16 v[36:39], v[76:79], v[52:55], v[36:39]
	v_lshl_add_u64 v[108:109], v[6:7], 0, v[28:29]
	v_mfma_f32_16x16x32_bf16 v[56:59], v[88:91], v[52:55], v[56:59]
	v_mfma_f32_16x16x32_bf16 v[52:55], v[124:127], v[52:55], v[8:11]
	v_mfma_f32_16x16x32_bf16 v[8:11], v[76:79], v[44:47], v[12:15]
	global_load_dwordx4 v[76:79], v[102:103], off offset:64 sc1
	s_waitcnt vmcnt(1)
; #define GAS __attribute__((address_space(1)))
; __device__ __forceinline__ unsigned cvtpk(float lo, float hi) { f32x2 v = {lo, hi}; bf16x2_t b = __builtin_convertvector(v, bf16x2_t); return __builtin_bit_cast(unsigned, b); }
; __device__ __forceinline__ float bflo(unsigned w) { return __uint_as_float(w << 16); }
; __device__ __forceinline__ float bfhi(unsigned w) { return __uint_as_float(w & 0xffff0000u); }
; __device__ __forceinline__ void a_unit(Frame& F, int L, int u, bool dry) {
;     ...
;     for (int qb = 0; qb < 4; ++qb) { const int ql = qb * 16 + fr; const size_t tok = (size_t)b * SEQ + chunk * 128 + 64 * qh + ql; bsv[qb] = bs[ql];
; #pragma unroll
;         for (int p = 0; p < 2; ++p) uav[qb][p] = *(const GAS u32x4*)(UA + tok * 512 + 64 * w + 32 * p + 8 * fq); }
; #pragma unroll
;     for (int qb = 0; qb < 4; ++qb) { const int ql = qb * 16 + fr; const size_t tok = (size_t)b * SEQ + chunk * 128 + 64 * qh + ql;
; #pragma unroll
;         for (int p = 0; p < 2; ++p) { const u32x4 ua = uav[qb][p]; const f32x4 a0 = acc[qb][2 * p] + bsv[qb], a1 = acc[qb][2 * p + 1] + bsv[qb];
;             u32x4 o; o.x = cvtpk(bflo(ua.x) * a0[0], bfhi(ua.x) * a0[1]); o.y = cvtpk(bflo(ua.y) * a0[2], bfhi(ua.y) * a0[3]); o.z = cvtpk(bflo(ua.z) * a1[0], bfhi(ua.z) * a1[1]); o.w = cvtpk(bflo(ua.w) * a1[2], bfhi(ua.w) * a1[3]);
;             if (!dry) *(GAS u32x4*)(UA + tok * 512 + 64 * w + 32 * p + 8 * fq) = o; } }
	v_lshlrev_b32_e32 v112, 16, v48
	v_or_b32_e32 v12, 16, v4
	v_mov_b32_e32 v13, s7
	v_lshlrev_b64 v[12:13], 10, v[12:13]
	v_mfma_f32_16x16x32_bf16 v[0:3], v[104:107], v[44:47], v[64:67]
	v_lshl_add_u64 v[106:107], v[6:7], 0, v[12:13]
	global_load_dword v104, v30, s[0:1] offset:64
	v_or_b32_e32 v4, 48, v4
	global_load_dwordx4 v[64:67], v[106:107], off sc1
	v_mfma_f32_16x16x32_bf16 v[12:15], v[124:127], v[44:47], v[40:43]
	v_lshlrev_b64 v[4:5], 10, v[4:5]
	v_pk_add_f32 v[68:69], v[68:69], v[100:101] op_sel_hi:[1,0]
	v_and_b32_e32 v113, 0xffff0000, v48
	global_load_dwordx4 v[40:43], v[106:107], off offset:64 sc1
	v_mfma_f32_16x16x32_bf16 v[60:63], v[124:127], v[60:63], v[24:27]
	v_mul_f32_e64 v68, v68, v112
	v_mul_f32_e64 v69, v69, v113
	v_pk_add_f32 v[70:71], v[70:71], v[100:101] op_sel_hi:[1,0]
	v_cvt_pk_bf16_f32 v48, v68, v69
	v_mfma_f32_16x16x32_bf16 v[24:27], v[88:91], v[44:47], v[32:35]
	global_load_dwordx4 v[44:47], v[108:109], off sc1
	global_load_dwordx4 v[88:91], v[108:109], off offset:64 sc1
	global_load_dword v110, v30, s[0:1] offset:128
	global_load_dword v34, v30, s[0:1] offset:192
	v_lshl_add_u64 v[32:33], v[6:7], 0, v[4:5]
	global_load_dwordx4 v[28:31], v[32:33], off sc1
	global_load_dwordx4 v[4:7], v[32:33], off offset:64 sc1
	v_lshlrev_b32_e32 v68, 16, v49
	v_and_b32_e32 v69, 0xffff0000, v49
	v_pk_mul_f32 v[68:69], v[70:71], v[68:69]
	v_pk_add_f32 v[72:73], v[72:73], v[100:101] op_sel_hi:[1,0]
	v_cvt_pk_bf16_f32 v49, v68, v69
	v_lshlrev_b32_e32 v68, 16, v50
	v_and_b32_e32 v69, 0xffff0000, v50
	v_pk_mul_f32 v[68:69], v[72:73], v[68:69]
	v_pk_add_f32 v[74:75], v[74:75], v[100:101] op_sel_hi:[1,0]
	v_cvt_pk_bf16_f32 v50, v68, v69
	v_lshlrev_b32_e32 v68, 16, v51
	v_and_b32_e32 v69, 0xffff0000, v51
	v_pk_mul_f32 v[68:69], v[74:75], v[68:69]
	v_pk_add_f32 v[60:61], v[60:61], v[100:101] op_sel_hi:[1,0]
	v_cvt_pk_bf16_f32 v51, v68, v69
	global_store_dwordx4 v[102:103], v[48:51], off
	s_waitcnt vmcnt(10)
	v_lshlrev_b32_e32 v68, 16, v76
	v_and_b32_e32 v69, 0xffff0000, v76
	v_pk_add_f32 v[48:49], v[80:81], v[100:101] op_sel_hi:[1,0]
	v_pk_add_f32 v[50:51], v[82:83], v[100:101] op_sel_hi:[1,0]
	v_pk_mul_f32 v[48:49], v[48:49], v[68:69]
	v_lshlrev_b32_e32 v68, 16, v77
	v_and_b32_e32 v69, 0xffff0000, v77
	v_pk_mul_f32 v[50:51], v[50:51], v[68:69]
	v_cvt_pk_bf16_f32 v48, v48, v49
	v_cvt_pk_bf16_f32 v49, v50, v51
	v_lshlrev_b32_e32 v50, 16, v78
	v_and_b32_e32 v51, 0xffff0000, v78
	v_pk_add_f32 v[62:63], v[62:63], v[100:101] op_sel_hi:[1,0]
	v_pk_mul_f32 v[50:51], v[60:61], v[50:51]
	v_lshlrev_b32_e32 v60, 16, v79
	v_and_b32_e32 v61, 0xffff0000, v79
	v_pk_mul_f32 v[60:61], v[62:63], v[60:61]
	v_cvt_pk_bf16_f32 v50, v50, v51
	v_cvt_pk_bf16_f32 v51, v60, v61
	global_store_dwordx4 v[102:103], v[48:51], off offset:64
	s_mov_b64 s[0:1], s[72:73]
	s_mov_b32 s7, s79
	s_lshl_b64 s[6:7], s[6:7], 2
	v_mov_b32_e32 v100, 0
	v_mov_b32_e32 v101, 0
	s_waitcnt vmcnt(10)
	v_pk_add_f32 v[36:37], v[36:37], v[104:105] op_sel_hi:[1,0]
	v_pk_add_f32 v[50:51], v[56:57], v[104:105] op_sel_hi:[1,0]
	s_waitcnt vmcnt(9)
	v_lshlrev_b32_e32 v56, 16, v64
	v_and_b32_e32 v57, 0xffff0000, v64
	v_pk_add_f32 v[38:39], v[38:39], v[104:105] op_sel_hi:[1,0]
	v_pk_mul_f32 v[36:37], v[36:37], v[56:57]
	v_lshlrev_b32_e32 v56, 16, v65
	v_and_b32_e32 v57, 0xffff0000, v65
	v_pk_mul_f32 v[38:39], v[38:39], v[56:57]
	v_cvt_pk_bf16_f32 v36, v36, v37
	v_cvt_pk_bf16_f32 v37, v38, v39
	v_lshlrev_b32_e32 v38, 16, v66
	v_and_b32_e32 v39, 0xffff0000, v66
	v_pk_add_f32 v[48:49], v[58:59], v[104:105] op_sel_hi:[1,0]
	v_pk_mul_f32 v[38:39], v[50:51], v[38:39]
	v_lshlrev_b32_e32 v50, 16, v67
	v_and_b32_e32 v51, 0xffff0000, v67
	v_pk_mul_f32 v[48:49], v[48:49], v[50:51]
	v_cvt_pk_bf16_f32 v38, v38, v39
	v_cvt_pk_bf16_f32 v39, v48, v49
	global_store_dwordx4 v[106:107], v[36:39], off
	v_pk_add_f32 v[50:51], v[52:53], v[104:105] op_sel_hi:[1,0]
	s_waitcnt vmcnt(9)
	v_lshlrev_b32_e32 v52, 16, v40
	v_pk_add_f32 v[38:39], v[86:87], v[104:105] op_sel_hi:[1,0]
	v_pk_add_f32 v[36:37], v[84:85], v[104:105] op_sel_hi:[1,0]
	v_and_b32_e32 v53, 0xffff0000, v40
	v_lshlrev_b32_e32 v40, 16, v41
	v_and_b32_e32 v41, 0xffff0000, v41
	v_pk_mul_f32 v[36:37], v[36:37], v[52:53]
	v_pk_mul_f32 v[38:39], v[38:39], v[40:41]
	v_pk_add_f32 v[48:49], v[54:55], v[104:105] op_sel_hi:[1,0]
	v_cvt_pk_bf16_f32 v36, v36, v37
	v_cvt_pk_bf16_f32 v37, v38, v39
	v_lshlrev_b32_e32 v38, 16, v42
	v_and_b32_e32 v39, 0xffff0000, v42
	v_lshlrev_b32_e32 v40, 16, v43
	v_and_b32_e32 v41, 0xffff0000, v43
	v_pk_mul_f32 v[38:39], v[50:51], v[38:39]
	v_pk_mul_f32 v[40:41], v[48:49], v[40:41]
	v_cvt_pk_bf16_f32 v38, v38, v39
	v_cvt_pk_bf16_f32 v39, v40, v41
	global_store_dwordx4 v[106:107], v[36:39], off offset:64
	s_waitcnt vmcnt(9)
	v_lshlrev_b32_e32 v48, 16, v44
	v_and_b32_e32 v49, 0xffff0000, v44
	s_waitcnt vmcnt(7)
	v_pk_add_f32 v[38:39], v[94:95], v[110:111] op_sel_hi:[1,0]
	v_pk_add_f32 v[36:37], v[92:93], v[110:111] op_sel_hi:[1,0]
	v_lshlrev_b32_e32 v44, 16, v45
	v_and_b32_e32 v45, 0xffff0000, v45
	v_pk_mul_f32 v[36:37], v[36:37], v[48:49]
	v_pk_mul_f32 v[38:39], v[38:39], v[44:45]
	v_pk_add_f32 v[42:43], v[96:97], v[110:111] op_sel_hi:[1,0]
	v_cvt_pk_bf16_f32 v36, v36, v37
	v_cvt_pk_bf16_f32 v37, v38, v39
	v_lshlrev_b32_e32 v38, 16, v46
	v_and_b32_e32 v39, 0xffff0000, v46
	v_pk_add_f32 v[40:41], v[98:99], v[110:111] op_sel_hi:[1,0]
	v_pk_mul_f32 v[38:39], v[42:43], v[38:39]
	v_lshlrev_b32_e32 v42, 16, v47
	v_and_b32_e32 v43, 0xffff0000, v47
	v_pk_mul_f32 v[40:41], v[40:41], v[42:43]
	v_cvt_pk_bf16_f32 v38, v38, v39
	v_cvt_pk_bf16_f32 v39, v40, v41
	global_store_dwordx4 v[108:109], v[36:39], off
	v_pk_add_f32 v[20:21], v[20:21], v[110:111] op_sel_hi:[1,0]
	v_pk_add_f32 v[22:23], v[22:23], v[110:111] op_sel_hi:[1,0]
	v_pk_add_f32 v[36:37], v[18:19], v[110:111] op_sel_hi:[1,0]
	v_pk_add_f32 v[18:19], v[16:17], v[110:111] op_sel_hi:[1,0]
	v_lshlrev_b32_e32 v16, 16, v88
	v_and_b32_e32 v17, 0xffff0000, v88
	v_pk_mul_f32 v[16:17], v[20:21], v[16:17]
	v_lshlrev_b32_e32 v20, 16, v89
	v_and_b32_e32 v21, 0xffff0000, v89
	v_pk_mul_f32 v[20:21], v[22:23], v[20:21]
	v_cvt_pk_bf16_f32 v16, v16, v17
	v_cvt_pk_bf16_f32 v17, v20, v21
	v_lshlrev_b32_e32 v20, 16, v90
	v_and_b32_e32 v21, 0xffff0000, v90
	v_pk_mul_f32 v[18:19], v[18:19], v[20:21]
	v_lshlrev_b32_e32 v20, 16, v91
	v_and_b32_e32 v21, 0xffff0000, v91
	v_pk_mul_f32 v[20:21], v[36:37], v[20:21]
	v_cvt_pk_bf16_f32 v18, v18, v19
	v_cvt_pk_bf16_f32 v19, v20, v21
	s_waitcnt vmcnt(7)
; #define GAS __attribute__((address_space(1)))
; __device__ __forceinline__ int otid(int wave) { return wave * 64 + olane(); }
; __device__ __forceinline__ unsigned cvtpk(float lo, float hi) { f32x2 v = {lo, hi}; bf16x2_t b = __builtin_convertvector(v, bf16x2_t); return __builtin_bit_cast(unsigned, b); }
; __device__ __forceinline__ float bflo(unsigned w) { return __uint_as_float(w << 16); }
; __device__ __forceinline__ float bfhi(unsigned w) { return __uint_as_float(w & 0xffff0000u); }
; __device__ __forceinline__ void a_unit(Frame& F, int L, int u, bool dry) {
;     ...
;     for (int qb = 0; qb < 4; ++qb) { const int ql = qb * 16 + fr; const size_t tok = (size_t)b * SEQ + chunk * 128 + 64 * qh + ql;
; #pragma unroll
;         for (int p = 0; p < 2; ++p) { const u32x4 ua = uav[qb][p]; const f32x4 a0 = acc[qb][2 * p] + bsv[qb], a1 = acc[qb][2 * p + 1] + bsv[qb];
;             u32x4 o; o.x = cvtpk(bflo(ua.x) * a0[0], bfhi(ua.x) * a0[1]); o.y = cvtpk(bflo(ua.y) * a0[2], bfhi(ua.y) * a0[3]); o.z = cvtpk(bflo(ua.z) * a1[0], bfhi(ua.z) * a1[1]); o.w = cvtpk(bflo(ua.w) * a1[2], bfhi(ua.w) * a1[3]);
;             if (!dry) *(GAS u32x4*)(UA + tok * 512 + 64 * w + 32 * p + 8 * fq) = o; } }
;     __syncthreads();
; __device__ __forceinline__ void c_unit(Frame& F, int L, int u, bool dry) {
;     ...
;     const int b = u >> 5, t0 = 64 * (u & 31), tid = otid(F.wave), cp = tid & 255, th = tid >> 8;
;     const bf16_t* H = (const bf16_t*)(ws_ + WS_H) + (size_t)b * SEQ * 512 + 2 * cp;
;     bf16_t* SCG = (bf16_t*)(ws_ + WS_SCG) + (size_t)b * SEQ * 512 + 2 * cp;
;     const float* cw = kin(8) + (size_t)L * CONVW * 512 + 2 * cp;
;     f32x2 wv[CONVW];
; #pragma unroll
;     for (int j = 0; j < CONVW; ++j) wv[j] = *(const GAS f32x2*)(cw + j * 512);
;     const f32x2 cbv = *(const GAS f32x2*)(kin(9) + L * 512 + 2 * cp);
;     const f32x2 gv = *(const GAS f32x2*)(kin(10) + L * 512 + 2 * cp), bv = *(const GAS f32x2*)(kin(11) + L * 512 + 2 * cp);
;     const int tb0 = t0 + 32 * th;
;     unsigned hv[62], sc[32];
; #pragma unroll
;     for (int i = 0; i < 62; ++i) { const int tl = tb0 + i - 15; hv[i] = 0u; if (tl >= 0 && tl < SEQ) hv[i] = *(const GAS unsigned*)(H + (size_t)tl * 512); }
	v_pk_add_f32 v[8:9], v[8:9], v[34:35] op_sel_hi:[1,0]
	s_waitcnt vmcnt(6)
	v_lshlrev_b32_e32 v20, 16, v28
	v_and_b32_e32 v21, 0xffff0000, v28
	v_pk_add_f32 v[10:11], v[10:11], v[34:35] op_sel_hi:[1,0]
	v_pk_mul_f32 v[8:9], v[8:9], v[20:21]
	v_lshlrev_b32_e32 v20, 16, v29
	v_and_b32_e32 v21, 0xffff0000, v29
	v_pk_mul_f32 v[10:11], v[10:11], v[20:21]
	global_store_dwordx4 v[108:109], v[16:19], off offset:64
	v_cvt_pk_bf16_f32 v8, v8, v9
	v_cvt_pk_bf16_f32 v9, v10, v11
	v_pk_add_f32 v[18:19], v[24:25], v[34:35] op_sel_hi:[1,0]
	v_lshlrev_b32_e32 v10, 16, v30
	v_and_b32_e32 v11, 0xffff0000, v30
	v_pk_add_f32 v[16:17], v[26:27], v[34:35] op_sel_hi:[1,0]
	v_pk_mul_f32 v[10:11], v[18:19], v[10:11]
	v_lshlrev_b32_e32 v18, 16, v31
	v_and_b32_e32 v19, 0xffff0000, v31
	v_pk_mul_f32 v[16:17], v[16:17], v[18:19]
	v_cvt_pk_bf16_f32 v10, v10, v11
	v_cvt_pk_bf16_f32 v11, v16, v17
	global_store_dwordx4 v[32:33], v[8:11], off
	v_pk_add_f32 v[2:3], v[2:3], v[34:35] op_sel_hi:[1,0]
	v_pk_add_f32 v[0:1], v[0:1], v[34:35] op_sel_hi:[1,0]
	v_pk_add_f32 v[10:11], v[12:13], v[34:35] op_sel_hi:[1,0]
	s_waitcnt vmcnt(7)
	v_lshlrev_b32_e32 v12, 16, v4
	v_and_b32_e32 v13, 0xffff0000, v4
	v_lshlrev_b32_e32 v4, 16, v5
	v_and_b32_e32 v5, 0xffff0000, v5
	v_pk_mul_f32 v[0:1], v[0:1], v[12:13]
	v_pk_mul_f32 v[2:3], v[2:3], v[4:5]
	v_pk_add_f32 v[8:9], v[14:15], v[34:35] op_sel_hi:[1,0]
	v_cvt_pk_bf16_f32 v0, v0, v1
	v_cvt_pk_bf16_f32 v1, v2, v3
	v_lshlrev_b32_e32 v2, 16, v6
	v_and_b32_e32 v3, 0xffff0000, v6
	v_lshlrev_b32_e32 v4, 16, v7
	v_and_b32_e32 v5, 0xffff0000, v7
	v_pk_mul_f32 v[2:3], v[10:11], v[2:3]
	v_pk_mul_f32 v[4:5], v[8:9], v[4:5]
	v_cvt_pk_bf16_f32 v2, v2, v3
	v_cvt_pk_bf16_f32 v3, v4, v5
	global_store_dwordx4 v[32:33], v[0:3], off offset:64
	s_barrier
	s_nop 0
	v_mbcnt_lo_u32_b32 v0, -1, 0
	v_mbcnt_hi_u32_b32 v0, -1, v0
	s_load_dwordx2 s[0:1], s[0:1], 0x40
	v_add_u32_e32 v64, s70, v0
	v_lshlrev_b32_e32 v0, 1, v64
	v_and_b32_e32 v40, 0x1fe, v0
	v_lshlrev_b32_e32 v192, 2, v40
	s_waitcnt lgkmcnt(0)
	s_add_u32 s0, s0, s6
	s_addc_u32 s1, s1, s7
	v_lshl_add_u64 v[0:1], s[0:1], 0, v[192:193]
	s_movk_i32 s6, 0x1000
	v_add_co_u32_e32 v2, vcc, s6, v0
	s_movk_i32 s6, 0x2000
	s_nop 0
	v_addc_co_u32_e32 v3, vcc, 0, v1, vcc
	v_add_co_u32_e32 v4, vcc, s6, v0
	v_readlane_b32 s6, v254, 33
	s_nop 0
	v_addc_co_u32_e32 v5, vcc, 0, v1, vcc
	global_load_dwordx2 v[66:67], v192, s[0:1]
	global_load_dwordx2 v[68:69], v192, s[0:1] offset:2048
	global_load_dwordx2 v[70:71], v[4:5], off offset:-4096
	global_load_dwordx2 v[36:37], v[4:5], off
	s_movk_i32 s0, 0x3000
	v_add_co_u32_e32 v6, vcc, s0, v0
	s_movk_i32 s0, 0x4000
	s_nop 0
	v_addc_co_u32_e32 v7, vcc, 0, v1, vcc
	v_add_co_u32_e32 v8, vcc, s0, v0
	s_movk_i32 s0, 0x5000
	s_nop 0
	v_addc_co_u32_e32 v9, vcc, 0, v1, vcc
	global_load_dwordx2 v[38:39], v[4:5], off offset:2048
	global_load_dwordx2 v[42:43], v[8:9], off offset:-4096
	global_load_dwordx2 v[44:45], v[8:9], off
	global_load_dwordx2 v[46:47], v[8:9], off offset:2048
	v_add_co_u32_e32 v4, vcc, s0, v0
	s_movk_i32 s0, 0x6000
	s_nop 0
	v_addc_co_u32_e32 v5, vcc, 0, v1, vcc
	v_add_co_u32_e32 v8, vcc, s0, v0
	s_movk_i32 s0, 0x7000
	s_nop 0
	v_addc_co_u32_e32 v9, vcc, 0, v1, vcc
	v_add_co_u32_e32 v10, vcc, s0, v0
	s_mov_b32 s0, 0x8000
	s_nop 0
	v_addc_co_u32_e32 v11, vcc, 0, v1, vcc
	v_add_co_u32_e32 v12, vcc, s0, v0
	s_mov_b32 s0, 0x9000
	s_nop 0
	v_addc_co_u32_e32 v13, vcc, 0, v1, vcc
	global_load_dwordx2 v[54:55], v[8:9], off offset:-4096
	global_load_dwordx2 v[50:51], v[8:9], off
	global_load_dwordx2 v[52:53], v[8:9], off offset:2048
	global_load_dwordx2 v[56:57], v[12:13], off offset:-4096
	global_load_dwordx2 v[72:73], v[2:3], off offset:2048
	global_load_dwordx2 v[60:61], v[6:7], off offset:2048
	global_load_dwordx2 v[58:59], v[4:5], off offset:2048
	global_load_dwordx2 v[22:23], v[10:11], off offset:2048
	v_add_co_u32_e32 v8, vcc, s0, v0
	s_mov_b32 s0, 0xa000
	s_nop 0
	v_addc_co_u32_e32 v9, vcc, 0, v1, vcc
	v_add_co_u32_e32 v2, vcc, s0, v0
	s_mov_b32 s0, 0xb000
	s_nop 0
	v_addc_co_u32_e32 v3, vcc, 0, v1, vcc
	v_add_co_u32_e32 v10, vcc, s0, v0
	s_mov_b32 s0, 0xc000
	s_nop 0
	v_addc_co_u32_e32 v11, vcc, 0, v1, vcc
	v_add_co_u32_e32 v4, vcc, s0, v0
	s_mov_b32 s0, 0xd000
	s_nop 0
	v_addc_co_u32_e32 v5, vcc, 0, v1, vcc
	global_load_dwordx2 v[26:27], v[12:13], off
	global_load_dwordx2 v[28:29], v[12:13], off offset:2048
	global_load_dwordx2 v[30:31], v[2:3], off offset:-4096
	global_load_dwordx2 v[32:33], v[2:3], off
	v_add_co_u32_e32 v12, vcc, s0, v0
	s_mov_b32 s0, 0xe000
	s_nop 0
	v_addc_co_u32_e32 v13, vcc, 0, v1, vcc
	v_add_co_u32_e32 v6, vcc, s0, v0
	s_mov_b32 s0, 0xf000
	s_nop 0
	v_addc_co_u32_e32 v7, vcc, 0, v1, vcc
	v_add_co_u32_e32 v0, vcc, s0, v0
	s_mov_b64 s[0:1], s[72:73]
	global_load_dwordx2 v[18:19], v[2:3], off offset:2048
	global_load_dwordx2 v[20:21], v[4:5], off offset:-4096
	global_load_dwordx2 v[16:17], v[4:5], off
	global_load_dwordx2 v[14:15], v[4:5], off offset:2048
	s_nop 0
	global_load_dwordx2 v[2:3], v[6:7], off offset:-4096
	global_load_dwordx2 v[4:5], v[6:7], off
	s_nop 0
	global_load_dwordx2 v[6:7], v[6:7], off offset:2048
	v_addc_co_u32_e32 v1, vcc, 0, v1, vcc
	global_load_dwordx2 v[34:35], v[8:9], off offset:2048
	global_load_dwordx2 v[24:25], v[10:11], off offset:2048
	s_nop 0
	global_load_dwordx2 v[10:11], v[12:13], off offset:2048
	s_nop 0
	global_load_dwordx2 v[12:13], v[0:1], off
	s_load_dwordx2 s[0:1], s[0:1], 0x48
	v_readlane_b32 s7, v254, 34
	s_add_u32 s6, s2, s6
	s_addc_u32 s7, s3, s7
	v_lshlrev_b32_e32 v48, 1, v40
	s_waitcnt lgkmcnt(0)
	s_add_u32 s0, s0, s30
	s_addc_u32 s1, s1, s31
	global_load_dwordx2 v[78:79], v192, s[0:1]
	s_mov_b64 s[0:1], s[72:73]
	s_load_dwordx2 s[0:1], s[0:1], 0x50
	v_mov_b32_e32 v49, v193
	v_lshl_add_u64 v[40:41], s[6:7], 0, v[48:49]
	s_waitcnt lgkmcnt(0)
	s_add_u32 s0, s0, s30
	s_addc_u32 s1, s1, s31
	global_load_dwordx2 v[0:1], v192, s[0:1]
	s_mov_b64 s[0:1], s[72:73]
	s_load_dwordx2 s[0:1], s[0:1], 0x58
	s_waitcnt lgkmcnt(0)
	s_add_u32 s0, s0, s30
	s_addc_u32 s1, s1, s31
	global_load_dwordx2 v[8:9], v192, s[0:1]
	s_mov_b64 s[0:1], 0x7000000
	v_lshl_add_u64 v[62:63], v[40:41], 0, s[0:1]
	v_ashrrev_i32_e32 v40, 3, v64
	v_and_b32_e32 v40, 0xffffffe0, v40
	v_readlane_b32 s0, v253, 58
	s_nop 1
	v_add_u32_e32 v40, s0, v40
	v_add_u32_e32 v41, -15, v40
	v_cmp_gt_u32_e32 vcc, s33, v41
	s_and_saveexec_b64 s[0:1], vcc
	s_cbranch_execz .LBB0_473
	v_lshlrev_b32_e32 v192, 10, v41
	v_lshl_add_u64 v[64:65], v[62:63], 0, v[192:193]
	global_load_dword v101, v[64:65], off sc1
; #define GAS __attribute__((address_space(1)))
; __device__ __forceinline__ void c_unit(Frame& F, int L, int u, bool dry) {
;     ...
;     for (int i = 0; i < 62; ++i) { const int tl = tb0 + i - 15; hv[i] = 0u; if (tl >= 0 && tl < SEQ) hv[i] = *(const GAS unsigned*)(H + (size_t)tl * 512); }
.LBB0_473:
	s_or_b64 exec, exec, s[0:1]
	v_add_u32_e32 v41, -14, v40
	v_cmp_gt_u32_e32 vcc, s33, v41
	s_and_saveexec_b64 s[0:1], vcc
	s_cbranch_execz .LBB0_475
	v_lshlrev_b32_e32 v192, 10, v41
	v_lshl_add_u64 v[64:65], v[62:63], 0, v[192:193]
	global_load_dword v100, v[64:65], off sc1
.LBB0_475:
	s_or_b64 exec, exec, s[0:1]
	v_add_u32_e32 v41, -13, v40
	v_cmp_gt_u32_e32 vcc, s33, v41
	v_mov_b32_e32 v102, 0
	v_mov_b32_e32 v103, 0
	s_and_saveexec_b64 s[0:1], vcc
	s_cbranch_execz .LBB0_477
	v_lshlrev_b32_e32 v192, 10, v41
	v_lshl_add_u64 v[64:65], v[62:63], 0, v[192:193]
	global_load_dword v103, v[64:65], off sc1
.LBB0_477:
	s_or_b64 exec, exec, s[0:1]
	v_add_u32_e32 v41, -12, v40
	v_cmp_gt_u32_e32 vcc, s33, v41
	s_and_saveexec_b64 s[0:1], vcc
	s_cbranch_execz .LBB0_479
	v_lshlrev_b32_e32 v192, 10, v41
	v_lshl_add_u64 v[64:65], v[62:63], 0, v[192:193]
	global_load_dword v102, v[64:65], off sc1
.LBB0_479:
	s_or_b64 exec, exec, s[0:1]
	v_add_u32_e32 v41, -11, v40
	v_cmp_gt_u32_e32 vcc, s33, v41
	v_mov_b32_e32 v105, 0
	v_mov_b32_e32 v107, 0
	s_and_saveexec_b64 s[0:1], vcc
	s_cbranch_execz .LBB0_481
	v_lshlrev_b32_e32 v192, 10, v41
	v_lshl_add_u64 v[64:65], v[62:63], 0, v[192:193]
	global_load_dword v107, v[64:65], off sc1
.LBB0_481:
	s_or_b64 exec, exec, s[0:1]
	v_add_u32_e32 v41, -10, v40
	v_cmp_gt_u32_e32 vcc, s33, v41
	s_and_saveexec_b64 s[0:1], vcc
	s_cbranch_execz .LBB0_483
	v_lshlrev_b32_e32 v192, 10, v41
	v_lshl_add_u64 v[64:65], v[62:63], 0, v[192:193]
	global_load_dword v105, v[64:65], off sc1
.LBB0_483:
	s_or_b64 exec, exec, s[0:1]
	v_add_u32_e32 v41, -9, v40
	v_cmp_gt_u32_e32 vcc, s33, v41
	v_mov_b32_e32 v111, 0
	v_mov_b32_e32 v112, 0
	s_and_saveexec_b64 s[0:1], vcc
	s_cbranch_execz .LBB0_485
	v_lshlrev_b32_e32 v192, 10, v41
	v_lshl_add_u64 v[64:65], v[62:63], 0, v[192:193]
	global_load_dword v112, v[64:65], off sc1
.LBB0_485:
	s_or_b64 exec, exec, s[0:1]
	v_add_u32_e32 v41, -8, v40
	v_cmp_gt_u32_e32 vcc, s33, v41
	s_and_saveexec_b64 s[0:1], vcc
	s_cbranch_execz .LBB0_487
	v_lshlrev_b32_e32 v192, 10, v41
	v_lshl_add_u64 v[64:65], v[62:63], 0, v[192:193]
	global_load_dword v111, v[64:65], off sc1
.LBB0_487:
	s_or_b64 exec, exec, s[0:1]
	v_add_u32_e32 v41, -7, v40
	v_cmp_gt_u32_e32 vcc, s33, v41
	v_mov_b32_e32 v124, 0
	v_mov_b32_e32 v126, 0
	s_and_saveexec_b64 s[0:1], vcc
	s_cbranch_execz .LBB0_489
	v_lshlrev_b32_e32 v192, 10, v41
	v_lshl_add_u64 v[64:65], v[62:63], 0, v[192:193]
	global_load_dword v126, v[64:65], off sc1
.LBB0_489:
	s_or_b64 exec, exec, s[0:1]
	v_add_u32_e32 v41, -6, v40
	v_cmp_gt_u32_e32 vcc, s33, v41
	s_and_saveexec_b64 s[0:1], vcc
	s_cbranch_execz .LBB0_491
	v_lshlrev_b32_e32 v192, 10, v41
	v_lshl_add_u64 v[64:65], v[62:63], 0, v[192:193]
	global_load_dword v124, v[64:65], off sc1
.LBB0_491:
	s_or_b64 exec, exec, s[0:1]
	v_add_u32_e32 v41, -5, v40
	v_cmp_gt_u32_e32 vcc, s33, v41
	v_mov_b32_e32 v130, 0
	v_mov_b32_e32 v131, 0
	s_and_saveexec_b64 s[0:1], vcc
	s_cbranch_execz .LBB0_493
	v_lshlrev_b32_e32 v192, 10, v41
	v_lshl_add_u64 v[64:65], v[62:63], 0, v[192:193]
	global_load_dword v131, v[64:65], off sc1
.LBB0_493:
	s_or_b64 exec, exec, s[0:1]
	v_add_u32_e32 v41, -4, v40
	v_cmp_gt_u32_e32 vcc, s33, v41
	s_and_saveexec_b64 s[0:1], vcc
	s_cbranch_execz .LBB0_495
	v_lshlrev_b32_e32 v192, 10, v41
	v_lshl_add_u64 v[64:65], v[62:63], 0, v[192:193]
	global_load_dword v130, v[64:65], off sc1
.LBB0_495:
	s_or_b64 exec, exec, s[0:1]
	v_add_u32_e32 v41, -3, v40
	v_cmp_gt_u32_e32 vcc, s33, v41
	v_mov_b32_e32 v138, 0
	v_mov_b32_e32 v139, 0
	s_and_saveexec_b64 s[0:1], vcc
	s_cbranch_execz .LBB0_497
	v_lshlrev_b32_e32 v192, 10, v41
	v_lshl_add_u64 v[64:65], v[62:63], 0, v[192:193]
	global_load_dword v139, v[64:65], off sc1
.LBB0_497:
	s_or_b64 exec, exec, s[0:1]
	v_add_u32_e32 v41, -2, v40
	v_cmp_gt_u32_e32 vcc, s33, v41
	s_and_saveexec_b64 s[0:1], vcc
	s_cbranch_execz .LBB0_499
	v_lshlrev_b32_e32 v192, 10, v41
	v_lshl_add_u64 v[64:65], v[62:63], 0, v[192:193]
	global_load_dword v138, v[64:65], off sc1
.LBB0_499:
	s_or_b64 exec, exec, s[0:1]
	v_add_u32_e32 v41, -1, v40
	v_cmp_gt_u32_e32 vcc, s33, v41
	v_mov_b32_e32 v127, 0
	v_mov_b32_e32 v142, 0
	s_and_saveexec_b64 s[0:1], vcc
	s_cbranch_execz .LBB0_501
	v_lshlrev_b32_e32 v192, 10, v41
	v_lshl_add_u64 v[64:65], v[62:63], 0, v[192:193]
	global_load_dword v142, v[64:65], off sc1
.LBB0_501:
	s_or_b64 exec, exec, s[0:1]
	v_cmp_gt_u32_e64 s[38:39], s33, v40
	v_lshlrev_b32_e32 v192, 10, v40
	v_mov_b32_e32 v128, 0
	v_mov_b32_e32 v129, 0
	v_mov_b32_e32 v134, 0
	s_and_saveexec_b64 s[0:1], s[38:39]
	s_cbranch_execz .LBB0_503
	v_lshl_add_u64 v[64:65], v[62:63], 0, v[192:193]
	global_load_dword v134, v[64:65], off sc1
	global_load_dword v129, v[64:65], off offset:1024 sc1
	global_load_dword v128, v[64:65], off offset:2048 sc1
	global_load_dword v127, v[64:65], off offset:3072 sc1
.LBB0_503:
	s_or_b64 exec, exec, s[0:1]
	v_mov_b32_e32 v135, 0
	v_mov_b32_e32 v136, 0
	v_mov_b32_e32 v137, 0
	s_and_saveexec_b64 s[0:1], s[38:39]
	s_cbranch_execz .LBB0_505
	v_lshl_add_u64 v[64:65], v[62:63], 0, v[192:193]
	v_add_co_u32_e32 v64, vcc, 0x1000, v64
	s_nop 1
	v_addc_co_u32_e32 v65, vcc, 0, v65, vcc
	global_load_dword v137, v[64:65], off sc1
	global_load_dword v136, v[64:65], off offset:1024 sc1
.LBB0_505:
	s_or_b64 exec, exec, s[0:1]
	v_mov_b32_e32 v144, 0
	s_and_saveexec_b64 s[0:1], s[38:39]
	s_cbranch_execz .LBB0_507
	v_lshl_add_u64 v[64:65], v[62:63], 0, v[192:193]
	v_add_co_u32_e32 v64, vcc, 0x1000, v64
	s_nop 1
	v_addc_co_u32_e32 v65, vcc, 0, v65, vcc
	global_load_dword v144, v[64:65], off offset:2048 sc1
	global_load_dword v135, v[64:65], off offset:3072 sc1
; #define GAS __attribute__((address_space(1)))
; __device__ __forceinline__ void c_unit(Frame& F, int L, int u, bool dry) {
;     ...
;     for (int i = 0; i < 62; ++i) { const int tl = tb0 + i - 15; hv[i] = 0u; if (tl >= 0 && tl < SEQ) hv[i] = *(const GAS unsigned*)(H + (size_t)tl * 512); }
.LBB0_507:
	s_or_b64 exec, exec, s[0:1]
	v_mov_b32_e32 v106, 0
	v_mov_b32_e32 v145, 0
	v_mov_b32_e32 v146, 0
	s_and_saveexec_b64 s[0:1], s[38:39]
	s_cbranch_execz .LBB0_509
	v_lshl_add_u64 v[64:65], v[62:63], 0, v[192:193]
	v_add_co_u32_e32 v64, vcc, 0x2000, v64
	s_nop 1
	v_addc_co_u32_e32 v65, vcc, 0, v65, vcc
	global_load_dword v146, v[64:65], off sc1
	global_load_dword v145, v[64:65], off offset:1024 sc1
.LBB0_509:
	s_or_b64 exec, exec, s[0:1]
	v_mov_b32_e32 v147, 0
	s_and_saveexec_b64 s[0:1], s[38:39]
	s_cbranch_execz .LBB0_511
	v_lshl_add_u64 v[64:65], v[62:63], 0, v[192:193]
	v_add_co_u32_e32 v64, vcc, 0x2000, v64
	s_nop 1
	v_addc_co_u32_e32 v65, vcc, 0, v65, vcc
	global_load_dword v147, v[64:65], off offset:2048 sc1
	global_load_dword v106, v[64:65], off offset:3072 sc1
.LBB0_511:
	s_or_b64 exec, exec, s[0:1]
	v_mov_b32_e32 v108, 0
	v_mov_b32_e32 v109, 0
	v_mov_b32_e32 v110, 0
	s_and_saveexec_b64 s[0:1], s[38:39]
	s_cbranch_execz .LBB0_513
	v_lshl_add_u64 v[64:65], v[62:63], 0, v[192:193]
	v_add_co_u32_e32 v64, vcc, 0x3000, v64
	s_nop 1
	v_addc_co_u32_e32 v65, vcc, 0, v65, vcc
	global_load_dword v110, v[64:65], off sc1
	global_load_dword v109, v[64:65], off offset:1024 sc1
.LBB0_513:
	s_or_b64 exec, exec, s[0:1]
	v_mov_b32_e32 v113, 0
	s_and_saveexec_b64 s[0:1], s[38:39]
	s_cbranch_execz .LBB0_515
	v_lshl_add_u64 v[64:65], v[62:63], 0, v[192:193]
	v_add_co_u32_e32 v64, vcc, 0x3000, v64
	s_nop 1
	v_addc_co_u32_e32 v65, vcc, 0, v65, vcc
	global_load_dword v113, v[64:65], off offset:2048 sc1
	global_load_dword v108, v[64:65], off offset:3072 sc1
.LBB0_515:
	s_or_b64 exec, exec, s[0:1]
	v_mov_b32_e32 v118, 0
	v_mov_b32_e32 v119, 0
	v_mov_b32_e32 v125, 0
	s_and_saveexec_b64 s[0:1], s[38:39]
	s_cbranch_execz .LBB0_517
	v_lshl_add_u64 v[64:65], v[62:63], 0, v[192:193]
	v_add_co_u32_e32 v64, vcc, 0x4000, v64
	s_nop 1
	v_addc_co_u32_e32 v65, vcc, 0, v65, vcc
	global_load_dword v125, v[64:65], off sc1
	global_load_dword v119, v[64:65], off offset:1024 sc1
.LBB0_517:
	s_or_b64 exec, exec, s[0:1]
	v_mov_b32_e32 v132, 0
	s_and_saveexec_b64 s[0:1], s[38:39]
	s_cbranch_execz .LBB0_519
	v_lshl_add_u64 v[64:65], v[62:63], 0, v[192:193]
	v_add_co_u32_e32 v64, vcc, 0x4000, v64
	s_nop 1
	v_addc_co_u32_e32 v65, vcc, 0, v65, vcc
	global_load_dword v132, v[64:65], off offset:2048 sc1
	global_load_dword v118, v[64:65], off offset:3072 sc1
.LBB0_519:
	s_or_b64 exec, exec, s[0:1]
	v_mov_b32_e32 v242, 0
	v_mov_b32_e32 v243, 0
	v_mov_b32_e32 v133, 0
	s_and_saveexec_b64 s[0:1], s[38:39]
	s_cbranch_execz .LBB0_521
	v_lshl_add_u64 v[64:65], v[62:63], 0, v[192:193]
	v_add_co_u32_e32 v64, vcc, 0x5000, v64
	s_nop 1
	v_addc_co_u32_e32 v65, vcc, 0, v65, vcc
	global_load_dword v133, v[64:65], off sc1
	global_load_dword v243, v[64:65], off offset:1024 sc1
.LBB0_521:
	s_or_b64 exec, exec, s[0:1]
	v_mov_b32_e32 v245, 0
	s_and_saveexec_b64 s[0:1], s[38:39]
	s_cbranch_execz .LBB0_523
	v_lshl_add_u64 v[64:65], v[62:63], 0, v[192:193]
	v_add_co_u32_e32 v64, vcc, 0x5000, v64
	s_nop 1
	v_addc_co_u32_e32 v65, vcc, 0, v65, vcc
	global_load_dword v245, v[64:65], off offset:2048 sc1
	global_load_dword v242, v[64:65], off offset:3072 sc1
.LBB0_523:
	s_or_b64 exec, exec, s[0:1]
	v_mov_b32_e32 v104, 0
	v_mov_b32_e32 v251, 0
	v_mov_b32_e32 v252, 0
	s_and_saveexec_b64 s[0:1], s[38:39]
	s_cbranch_execz .LBB0_525
	v_lshl_add_u64 v[64:65], v[62:63], 0, v[192:193]
	v_add_co_u32_e32 v64, vcc, 0x6000, v64
	s_nop 1
	v_addc_co_u32_e32 v65, vcc, 0, v65, vcc
	global_load_dword v252, v[64:65], off sc1
	global_load_dword v251, v[64:65], off offset:1024 sc1
.LBB0_525:
	s_or_b64 exec, exec, s[0:1]
	v_mov_b32_e32 v246, 0
	s_and_saveexec_b64 s[0:1], s[38:39]
	s_cbranch_execz .LBB0_527
	v_lshl_add_u64 v[64:65], v[62:63], 0, v[192:193]
	v_add_co_u32_e32 v64, vcc, 0x6000, v64
	s_nop 1
	v_addc_co_u32_e32 v65, vcc, 0, v65, vcc
	global_load_dword v246, v[64:65], off offset:2048 sc1
	global_load_dword v104, v[64:65], off offset:3072 sc1
.LBB0_527:
	s_or_b64 exec, exec, s[0:1]
	v_mov_b32_e32 v224, 0
	v_mov_b32_e32 v240, 0
	v_mov_b32_e32 v241, 0
	s_and_saveexec_b64 s[0:1], s[38:39]
	s_cbranch_execz .LBB0_529
	v_lshl_add_u64 v[64:65], v[62:63], 0, v[192:193]
	v_add_co_u32_e32 v64, vcc, 0x7000, v64
	s_nop 1
	v_addc_co_u32_e32 v65, vcc, 0, v65, vcc
	global_load_dword v241, v[64:65], off sc1
	global_load_dword v240, v[64:65], off offset:1024 sc1
.LBB0_529:
	s_or_b64 exec, exec, s[0:1]
	v_mov_b32_e32 v239, 0
	s_and_saveexec_b64 s[0:1], s[38:39]
	s_cbranch_execz .LBB0_531
	v_lshl_add_u64 v[64:65], v[62:63], 0, v[192:193]
	v_add_co_u32_e32 v64, vcc, 0x7000, v64
	s_nop 1
	v_addc_co_u32_e32 v65, vcc, 0, v65, vcc
	global_load_dword v239, v[64:65], off offset:2048 sc1
	global_load_dword v224, v[64:65], off offset:3072 sc1
.LBB0_531:
	s_or_b64 exec, exec, s[0:1]
	v_add_u32_e32 v41, 32, v40
	v_cmp_gt_u32_e32 vcc, s33, v41
	v_mov_b32_e32 v225, 0
	v_mov_b32_e32 v226, 0
	s_and_saveexec_b64 s[0:1], vcc
	s_cbranch_execz .LBB0_533
	v_lshlrev_b32_e32 v192, 10, v41
	v_lshl_add_u64 v[64:65], v[62:63], 0, v[192:193]
	global_load_dword v226, v[64:65], off sc1
.LBB0_533:
	s_or_b64 exec, exec, s[0:1]
	v_add_u32_e32 v41, 33, v40
	v_cmp_gt_u32_e32 vcc, s33, v41
	s_and_saveexec_b64 s[0:1], vcc
	s_cbranch_execz .LBB0_535
	v_lshlrev_b32_e32 v192, 10, v41
	v_lshl_add_u64 v[64:65], v[62:63], 0, v[192:193]
	global_load_dword v225, v[64:65], off sc1
.LBB0_535:
	s_or_b64 exec, exec, s[0:1]
	v_add_u32_e32 v41, 34, v40
	v_cmp_gt_u32_e32 vcc, s33, v41
	v_mov_b32_e32 v227, 0
	v_mov_b32_e32 v228, 0
	s_and_saveexec_b64 s[0:1], vcc
	s_cbranch_execz .LBB0_537
	v_lshlrev_b32_e32 v192, 10, v41
	v_lshl_add_u64 v[64:65], v[62:63], 0, v[192:193]
	global_load_dword v228, v[64:65], off sc1
; #define GAS __attribute__((address_space(1)))
; __device__ __forceinline__ void c_unit(Frame& F, int L, int u, bool dry) {
;     ...
;     for (int i = 0; i < 62; ++i) { const int tl = tb0 + i - 15; hv[i] = 0u; if (tl >= 0 && tl < SEQ) hv[i] = *(const GAS unsigned*)(H + (size_t)tl * 512); }
; #pragma unroll
;     for (int t = 0; t < 32; ++t) sc[t] = *(const GAS unsigned*)(SCG + (size_t)(tb0 + t) * 512);
.LBB0_537:
	s_or_b64 exec, exec, s[0:1]
	v_add_u32_e32 v41, 35, v40
	v_cmp_gt_u32_e32 vcc, s33, v41
	s_and_saveexec_b64 s[0:1], vcc
	s_cbranch_execz .LBB0_539
	v_lshlrev_b32_e32 v192, 10, v41
	v_lshl_add_u64 v[64:65], v[62:63], 0, v[192:193]
	global_load_dword v227, v[64:65], off sc1
.LBB0_539:
	s_or_b64 exec, exec, s[0:1]
	v_add_u32_e32 v41, 36, v40
	v_cmp_gt_u32_e32 vcc, s33, v41
	v_mov_b32_e32 v229, 0
	v_mov_b32_e32 v230, 0
	s_and_saveexec_b64 s[0:1], vcc
	s_cbranch_execz .LBB0_541
	v_lshlrev_b32_e32 v192, 10, v41
	v_lshl_add_u64 v[64:65], v[62:63], 0, v[192:193]
	global_load_dword v230, v[64:65], off sc1
.LBB0_541:
	s_or_b64 exec, exec, s[0:1]
	v_add_u32_e32 v41, 37, v40
	v_cmp_gt_u32_e32 vcc, s33, v41
	s_and_saveexec_b64 s[0:1], vcc
	s_cbranch_execz .LBB0_543
	v_lshlrev_b32_e32 v192, 10, v41
	v_lshl_add_u64 v[64:65], v[62:63], 0, v[192:193]
	global_load_dword v229, v[64:65], off sc1
.LBB0_543:
	s_or_b64 exec, exec, s[0:1]
	v_add_u32_e32 v41, 38, v40
	v_cmp_gt_u32_e32 vcc, s33, v41
	v_mov_b32_e32 v231, 0
	v_mov_b32_e32 v232, 0
	s_and_saveexec_b64 s[0:1], vcc
	s_cbranch_execz .LBB0_545
	v_lshlrev_b32_e32 v192, 10, v41
	v_lshl_add_u64 v[64:65], v[62:63], 0, v[192:193]
	global_load_dword v232, v[64:65], off sc1
.LBB0_545:
	s_or_b64 exec, exec, s[0:1]
	v_add_u32_e32 v41, 39, v40
	v_cmp_gt_u32_e32 vcc, s33, v41
	s_and_saveexec_b64 s[0:1], vcc
	s_cbranch_execz .LBB0_547
	v_lshlrev_b32_e32 v192, 10, v41
	v_lshl_add_u64 v[64:65], v[62:63], 0, v[192:193]
	global_load_dword v231, v[64:65], off sc1
.LBB0_547:
	s_or_b64 exec, exec, s[0:1]
	v_add_u32_e32 v41, 40, v40
	v_cmp_gt_u32_e32 vcc, s33, v41
	v_mov_b32_e32 v233, 0
	v_mov_b32_e32 v234, 0
	s_and_saveexec_b64 s[0:1], vcc
	s_cbranch_execz .LBB0_549
	v_lshlrev_b32_e32 v192, 10, v41
	v_lshl_add_u64 v[64:65], v[62:63], 0, v[192:193]
	global_load_dword v234, v[64:65], off sc1
.LBB0_549:
	s_or_b64 exec, exec, s[0:1]
	v_add_u32_e32 v41, 41, v40
	v_cmp_gt_u32_e32 vcc, s33, v41
	s_and_saveexec_b64 s[0:1], vcc
	s_cbranch_execz .LBB0_551
	v_lshlrev_b32_e32 v192, 10, v41
	v_lshl_add_u64 v[64:65], v[62:63], 0, v[192:193]
	global_load_dword v233, v[64:65], off sc1
.LBB0_551:
	s_or_b64 exec, exec, s[0:1]
	v_add_u32_e32 v41, 42, v40
	v_cmp_gt_u32_e32 vcc, s33, v41
	v_mov_b32_e32 v235, 0
	v_mov_b32_e32 v236, 0
	s_and_saveexec_b64 s[0:1], vcc
	s_cbranch_execz .LBB0_553
	v_lshlrev_b32_e32 v192, 10, v41
	v_lshl_add_u64 v[64:65], v[62:63], 0, v[192:193]
	global_load_dword v236, v[64:65], off sc1
.LBB0_553:
	s_or_b64 exec, exec, s[0:1]
	v_add_u32_e32 v41, 43, v40
	v_cmp_gt_u32_e32 vcc, s33, v41
	s_and_saveexec_b64 s[0:1], vcc
	s_cbranch_execz .LBB0_555
	v_lshlrev_b32_e32 v192, 10, v41
	v_lshl_add_u64 v[64:65], v[62:63], 0, v[192:193]
	global_load_dword v235, v[64:65], off sc1
.LBB0_555:
	s_or_b64 exec, exec, s[0:1]
	v_add_u32_e32 v41, 44, v40
	v_cmp_gt_u32_e32 vcc, s33, v41
	v_mov_b32_e32 v237, 0
	v_mov_b32_e32 v238, 0
	s_and_saveexec_b64 s[0:1], vcc
	s_cbranch_execz .LBB0_557
	v_lshlrev_b32_e32 v192, 10, v41
	v_lshl_add_u64 v[64:65], v[62:63], 0, v[192:193]
	global_load_dword v238, v[64:65], off sc1
.LBB0_557:
	s_or_b64 exec, exec, s[0:1]
	v_add_u32_e32 v41, 45, v40
	v_cmp_gt_u32_e32 vcc, s33, v41
	s_and_saveexec_b64 s[0:1], vcc
	s_cbranch_execz .LBB0_559
	v_lshlrev_b32_e32 v192, 10, v41
	v_lshl_add_u64 v[64:65], v[62:63], 0, v[192:193]
	global_load_dword v237, v[64:65], off sc1
.LBB0_559:
	s_or_b64 exec, exec, s[0:1]
	v_add_u32_e32 v41, 46, v40
	v_cmp_gt_u32_e32 vcc, s33, v41
	v_mov_b32_e32 v192, 0
	s_and_saveexec_b64 s[0:1], vcc
	s_cbranch_execz .LBB0_561
	v_lshlrev_b32_e32 v192, 10, v41
	v_lshl_add_u64 v[62:63], v[62:63], 0, v[192:193]
	global_load_dword v192, v[62:63], off sc1
.LBB0_561:
	s_or_b64 exec, exec, s[0:1]
	v_readlane_b32 s0, v254, 33
	v_readlane_b32 s1, v254, 34
	s_add_u32 s0, s2, s0
	s_addc_u32 s1, s3, s1
	v_mov_b32_e32 v49, v193
	v_lshl_add_u64 v[48:49], s[0:1], 0, v[48:49]
	s_mov_b64 s[0:1], 0xb000000
	v_ashrrev_i32_e32 v41, 31, v40
	v_lshl_add_u64 v[148:149], v[48:49], 0, s[0:1]
	v_lshlrev_b64 v[48:49], 10, v[40:41]
	v_lshl_add_u64 v[218:219], v[148:149], 0, v[48:49]
	v_or_b32_e32 v48, 1, v40
	v_ashrrev_i32_e32 v49, 31, v48
	v_lshlrev_b64 v[48:49], 10, v[48:49]
	v_lshl_add_u64 v[212:213], v[148:149], 0, v[48:49]
	v_or_b32_e32 v48, 2, v40
	v_ashrrev_i32_e32 v49, 31, v48
	v_lshlrev_b64 v[48:49], 10, v[48:49]
	v_lshl_add_u64 v[208:209], v[148:149], 0, v[48:49]
	v_or_b32_e32 v48, 3, v40
	v_ashrrev_i32_e32 v49, 31, v48
	v_lshlrev_b64 v[48:49], 10, v[48:49]
	v_lshl_add_u64 v[204:205], v[148:149], 0, v[48:49]
	v_or_b32_e32 v48, 4, v40
	v_ashrrev_i32_e32 v49, 31, v48
	v_lshlrev_b64 v[48:49], 10, v[48:49]
	v_lshl_add_u64 v[180:181], v[148:149], 0, v[48:49]
	v_or_b32_e32 v48, 5, v40
	v_ashrrev_i32_e32 v49, 31, v48
	v_lshlrev_b64 v[48:49], 10, v[48:49]
	v_lshl_add_u64 v[178:179], v[148:149], 0, v[48:49]
	v_or_b32_e32 v48, 6, v40
	v_ashrrev_i32_e32 v49, 31, v48
	v_lshlrev_b64 v[48:49], 10, v[48:49]
	v_lshl_add_u64 v[176:177], v[148:149], 0, v[48:49]
	v_or_b32_e32 v48, 7, v40
	v_ashrrev_i32_e32 v49, 31, v48
	v_lshlrev_b64 v[48:49], 10, v[48:49]
	v_lshl_add_u64 v[174:175], v[148:149], 0, v[48:49]
	v_or_b32_e32 v48, 8, v40
	v_ashrrev_i32_e32 v49, 31, v48
	v_lshlrev_b64 v[48:49], 10, v[48:49]
	v_lshl_add_u64 v[172:173], v[148:149], 0, v[48:49]
	v_or_b32_e32 v48, 9, v40
	v_ashrrev_i32_e32 v49, 31, v48
	v_lshlrev_b64 v[48:49], 10, v[48:49]
	v_lshl_add_u64 v[170:171], v[148:149], 0, v[48:49]
	v_or_b32_e32 v48, 10, v40
	v_ashrrev_i32_e32 v49, 31, v48
	v_lshlrev_b64 v[48:49], 10, v[48:49]
	v_lshl_add_u64 v[156:157], v[148:149], 0, v[48:49]
	v_or_b32_e32 v48, 11, v40
	v_ashrrev_i32_e32 v49, 31, v48
; #define GAS __attribute__((address_space(1)))
; __device__ __forceinline__ float bflo(unsigned w) { return __uint_as_float(w << 16); }
; __device__ __forceinline__ float bfhi(unsigned w) { return __uint_as_float(w & 0xffff0000u); }
; __device__ __forceinline__ void c_unit(Frame& F, int L, int u, bool dry) {
;     ...
;     for (int i = 0; i < 62; ++i) { const int tl = tb0 + i - 15; hv[i] = 0u; if (tl >= 0 && tl < SEQ) hv[i] = *(const GAS unsigned*)(H + (size_t)tl * 512); }
; #pragma unroll
;     for (int t = 0; t < 32; ++t) sc[t] = *(const GAS unsigned*)(SCG + (size_t)(tb0 + t) * 512);
; #pragma unroll
;     for (int sub = 0; sub < 2; ++sub) {
;         const int tb = tb0 + 16 * sub;
;         f32x2 acc[16];
; #pragma unroll
;         for (int t = 0; t < 16; ++t) acc[t] = cbv;
; #pragma unroll
;         for (int i = 0; i < 46; ++i) {
;             const float h0 = bflo(hv[16 * sub + i]), h1 = bfhi(hv[16 * sub + i]);
; #pragma unroll
;             for (int t = 0; t < 16; ++t) { const int j = i - t; if (j >= 0 && j < CONVW) { acc[t].x = fmaf(h0, wv[j].x, acc[t].x); acc[t].y = fmaf(h1, wv[j].y, acc[t].y); } }
	v_lshlrev_b64 v[48:49], 10, v[48:49]
	v_lshl_add_u64 v[140:141], v[148:149], 0, v[48:49]
	v_or_b32_e32 v48, 12, v40
	v_ashrrev_i32_e32 v49, 31, v48
	v_lshlrev_b64 v[48:49], 10, v[48:49]
	v_lshl_add_u64 v[122:123], v[148:149], 0, v[48:49]
	v_or_b32_e32 v48, 13, v40
	v_ashrrev_i32_e32 v49, 31, v48
	v_lshlrev_b64 v[48:49], 10, v[48:49]
	v_lshl_add_u64 v[120:121], v[148:149], 0, v[48:49]
	v_or_b32_e32 v48, 14, v40
	v_ashrrev_i32_e32 v49, 31, v48
	v_lshlrev_b64 v[48:49], 10, v[48:49]
	v_lshl_add_u64 v[116:117], v[148:149], 0, v[48:49]
	v_or_b32_e32 v48, 15, v40
	v_ashrrev_i32_e32 v49, 31, v48
	v_lshlrev_b64 v[48:49], 10, v[48:49]
	v_lshl_add_u64 v[114:115], v[148:149], 0, v[48:49]
	v_or_b32_e32 v48, 16, v40
	v_ashrrev_i32_e32 v49, 31, v48
	v_lshlrev_b64 v[48:49], 10, v[48:49]
	v_lshl_add_u64 v[98:99], v[148:149], 0, v[48:49]
	v_or_b32_e32 v48, 17, v40
	v_ashrrev_i32_e32 v49, 31, v48
	v_lshlrev_b64 v[48:49], 10, v[48:49]
	v_lshl_add_u64 v[96:97], v[148:149], 0, v[48:49]
	v_or_b32_e32 v48, 18, v40
	v_ashrrev_i32_e32 v49, 31, v48
	v_lshlrev_b64 v[48:49], 10, v[48:49]
	v_lshl_add_u64 v[94:95], v[148:149], 0, v[48:49]
	v_or_b32_e32 v48, 19, v40
	v_ashrrev_i32_e32 v49, 31, v48
	v_lshlrev_b64 v[48:49], 10, v[48:49]
	v_lshl_add_u64 v[92:93], v[148:149], 0, v[48:49]
	v_or_b32_e32 v48, 20, v40
	v_ashrrev_i32_e32 v49, 31, v48
	v_lshlrev_b64 v[48:49], 10, v[48:49]
	v_lshl_add_u64 v[90:91], v[148:149], 0, v[48:49]
	v_or_b32_e32 v48, 21, v40
	v_ashrrev_i32_e32 v49, 31, v48
	v_lshlrev_b64 v[48:49], 10, v[48:49]
	v_lshl_add_u64 v[88:89], v[148:149], 0, v[48:49]
	v_or_b32_e32 v48, 22, v40
	v_ashrrev_i32_e32 v49, 31, v48
	v_lshlrev_b64 v[48:49], 10, v[48:49]
	v_lshl_add_u64 v[86:87], v[148:149], 0, v[48:49]
	v_or_b32_e32 v48, 23, v40
	v_ashrrev_i32_e32 v49, 31, v48
	v_lshlrev_b64 v[48:49], 10, v[48:49]
	v_lshl_add_u64 v[84:85], v[148:149], 0, v[48:49]
	v_or_b32_e32 v48, 24, v40
	v_ashrrev_i32_e32 v49, 31, v48
	v_lshlrev_b64 v[48:49], 10, v[48:49]
	v_lshl_add_u64 v[82:83], v[148:149], 0, v[48:49]
	v_or_b32_e32 v48, 25, v40
	v_ashrrev_i32_e32 v49, 31, v48
	v_lshlrev_b64 v[48:49], 10, v[48:49]
	v_lshl_add_u64 v[80:81], v[148:149], 0, v[48:49]
	v_or_b32_e32 v48, 26, v40
	global_load_dword v247, v[218:219], off sc1
	global_load_dword v244, v[212:213], off sc1
	v_ashrrev_i32_e32 v49, 31, v48
	v_lshlrev_b64 v[48:49], 10, v[48:49]
	v_lshl_add_u64 v[76:77], v[148:149], 0, v[48:49]
	v_or_b32_e32 v48, 27, v40
	v_ashrrev_i32_e32 v49, 31, v48
	v_lshlrev_b64 v[48:49], 10, v[48:49]
	v_lshl_add_u64 v[74:75], v[148:149], 0, v[48:49]
	v_or_b32_e32 v48, 28, v40
	v_ashrrev_i32_e32 v49, 31, v48
	v_lshlrev_b64 v[48:49], 10, v[48:49]
	v_lshl_add_u64 v[64:65], v[148:149], 0, v[48:49]
	v_or_b32_e32 v48, 29, v40
	v_ashrrev_i32_e32 v49, 31, v48
	v_lshlrev_b64 v[48:49], 10, v[48:49]
	v_lshl_add_u64 v[62:63], v[148:149], 0, v[48:49]
	v_or_b32_e32 v48, 30, v40
	v_or_b32_e32 v40, 31, v40
	v_ashrrev_i32_e32 v49, 31, v48
	v_ashrrev_i32_e32 v41, 31, v40
	v_lshlrev_b64 v[48:49], 10, v[48:49]
	v_lshlrev_b64 v[40:41], 10, v[40:41]
	v_lshl_add_u64 v[48:49], v[148:149], 0, v[48:49]
	v_lshl_add_u64 v[40:41], v[148:149], 0, v[40:41]
	s_waitcnt vmcnt(2)
	v_and_b32_e32 v149, 0xffff0000, v101
	v_lshlrev_b32_e32 v148, 16, v101
	v_lshlrev_b32_e32 v222, 16, v100
	v_and_b32_e32 v223, 0xffff0000, v100
	v_pk_fma_f32 v[100:101], v[148:149], v[66:67], v[78:79]
	v_lshlrev_b32_e32 v220, 16, v103
	v_and_b32_e32 v221, 0xffff0000, v103
	v_pk_fma_f32 v[100:101], v[222:223], v[68:69], v[100:101]
	v_lshlrev_b32_e32 v216, 16, v102
	v_and_b32_e32 v217, 0xffff0000, v102
	v_pk_fma_f32 v[100:101], v[220:221], v[70:71], v[100:101]
	v_lshlrev_b32_e32 v214, 16, v107
	v_pk_fma_f32 v[100:101], v[216:217], v[72:73], v[100:101]
	v_and_b32_e32 v215, 0xffff0000, v107
	v_lshlrev_b32_e32 v210, 16, v105
	v_and_b32_e32 v211, 0xffff0000, v105
	v_pk_fma_f32 v[100:101], v[214:215], v[36:37], v[100:101]
	v_lshlrev_b32_e32 v206, 16, v112
	v_and_b32_e32 v207, 0xffff0000, v112
	v_pk_fma_f32 v[100:101], v[210:211], v[38:39], v[100:101]
	v_lshlrev_b32_e32 v200, 16, v111
	v_and_b32_e32 v201, 0xffff0000, v111
	v_pk_fma_f32 v[100:101], v[206:207], v[42:43], v[100:101]
	v_lshlrev_b32_e32 v198, 16, v126
	v_and_b32_e32 v199, 0xffff0000, v126
	v_pk_fma_f32 v[100:101], v[200:201], v[60:61], v[100:101]
	v_lshlrev_b32_e32 v196, 16, v124
	v_and_b32_e32 v197, 0xffff0000, v124
	v_pk_fma_f32 v[100:101], v[198:199], v[44:45], v[100:101]
	v_lshlrev_b32_e32 v190, 16, v131
	v_and_b32_e32 v191, 0xffff0000, v131
	v_pk_fma_f32 v[100:101], v[196:197], v[46:47], v[100:101]
	v_lshlrev_b32_e32 v188, 16, v130
	v_and_b32_e32 v189, 0xffff0000, v130
	v_pk_fma_f32 v[100:101], v[190:191], v[54:55], v[100:101]
	v_lshlrev_b32_e32 v186, 16, v139
	v_and_b32_e32 v187, 0xffff0000, v139
	v_pk_fma_f32 v[100:101], v[188:189], v[58:59], v[100:101]
	v_lshlrev_b32_e32 v184, 16, v138
	v_and_b32_e32 v185, 0xffff0000, v138
	v_pk_fma_f32 v[100:101], v[186:187], v[50:51], v[100:101]
	v_lshlrev_b32_e32 v182, 16, v142
	v_and_b32_e32 v183, 0xffff0000, v142
	v_pk_fma_f32 v[100:101], v[184:185], v[52:53], v[100:101]
	v_lshlrev_b32_e32 v202, 16, v134
	v_pk_fma_f32 v[100:101], v[182:183], v[56:57], v[100:101]
	v_and_b32_e32 v203, 0xffff0000, v134
	v_lshlrev_b32_e32 v154, 16, v129
	v_and_b32_e32 v155, 0xffff0000, v129
	v_pk_fma_f32 v[100:101], v[202:203], v[22:23], v[100:101]
	v_lshlrev_b32_e32 v152, 16, v128
	v_and_b32_e32 v153, 0xffff0000, v128
	v_pk_fma_f32 v[100:101], v[154:155], v[26:27], v[100:101]
	v_lshlrev_b32_e32 v150, 16, v127
	v_and_b32_e32 v151, 0xffff0000, v127
	v_pk_fma_f32 v[100:101], v[152:153], v[28:29], v[100:101]
	v_lshlrev_b32_e32 v148, 16, v137
	v_and_b32_e32 v149, 0xffff0000, v137
; #define GAS __attribute__((address_space(1)))
; __device__ __forceinline__ unsigned cvtpk(float lo, float hi) { f32x2 v = {lo, hi}; bf16x2_t b = __builtin_convertvector(v, bf16x2_t); return __builtin_bit_cast(unsigned, b); }
; __device__ __forceinline__ float bflo(unsigned w) { return __uint_as_float(w << 16); }
; __device__ __forceinline__ float bfhi(unsigned w) { return __uint_as_float(w & 0xffff0000u); }
; __device__ __forceinline__ float fsilu(float x) { return x * fsigmoid(x); }
; __device__ __forceinline__ void c_unit(Frame& F, int L, int u, bool dry) {
;     ...
;         for (int i = 0; i < 46; ++i) {
;             const float h0 = bflo(hv[16 * sub + i]), h1 = bfhi(hv[16 * sub + i]);
; #pragma unroll
;             for (int t = 0; t < 16; ++t) { const int j = i - t; if (j >= 0 && j < CONVW) { acc[t].x = fmaf(h0, wv[j].x, acc[t].x); acc[t].y = fmaf(h1, wv[j].y, acc[t].y); } }
;         }
; #pragma unroll
;         for (int t = 0; t < 16; ++t) {
;             float s = acc[t].x + acc[t].y, qq = acc[t].x * acc[t].x + acc[t].y * acc[t].y;
;             s = half_wave_sum(s); qq = half_wave_sum(qq);
;             const float mu = __builtin_ldexpf(s, -6), rstd = rsqrtf(fmaxf(__builtin_ldexpf(qq, -6) - mu * mu, 0.f) + LN_EPS);
;             const float h0 = (acc[t].x - mu) * rstd * gv.x + bv.x, h1 = (acc[t].y - mu) * rstd * gv.y + bv.y;
;             const unsigned ov = cvtpk(fsilu(h0) * bflo(sc[16 * sub + t]), fsilu(h1) * bfhi(sc[16 * sub + t])); if (!dry) *(GAS unsigned*)(SCG + (size_t)(tb + t) * 512) = ov;
	v_pk_fma_f32 v[100:101], v[150:151], v[30:31], v[100:101]
	v_lshlrev_b32_e32 v142, 16, v136
	v_and_b32_e32 v143, 0xffff0000, v136
	v_pk_fma_f32 v[100:101], v[148:149], v[34:35], v[100:101]
	v_lshlrev_b32_e32 v138, 16, v144
	v_and_b32_e32 v139, 0xffff0000, v144
	v_pk_fma_f32 v[100:101], v[142:143], v[32:33], v[100:101]
	v_lshlrev_b32_e32 v134, 16, v135
	v_and_b32_e32 v135, 0xffff0000, v135
	v_pk_fma_f32 v[100:101], v[138:139], v[18:19], v[100:101]
	v_lshlrev_b32_e32 v130, 16, v146
	v_and_b32_e32 v131, 0xffff0000, v146
	v_pk_fma_f32 v[100:101], v[134:135], v[20:21], v[100:101]
	v_lshlrev_b32_e32 v128, 16, v145
	v_and_b32_e32 v129, 0xffff0000, v145
	v_pk_fma_f32 v[100:101], v[130:131], v[24:25], v[100:101]
	v_lshlrev_b32_e32 v126, 16, v147
	v_and_b32_e32 v127, 0xffff0000, v147
	v_pk_fma_f32 v[100:101], v[128:129], v[16:17], v[100:101]
	v_lshlrev_b32_e32 v164, 16, v106
	v_pk_fma_f32 v[100:101], v[126:127], v[14:15], v[100:101]
	v_and_b32_e32 v165, 0xffff0000, v106
	v_lshlrev_b32_e32 v168, 16, v110
	v_and_b32_e32 v169, 0xffff0000, v110
	v_pk_fma_f32 v[100:101], v[164:165], v[2:3], v[100:101]
	v_lshlrev_b32_e32 v166, 16, v109
	v_and_b32_e32 v167, 0xffff0000, v109
	v_pk_fma_f32 v[100:101], v[168:169], v[10:11], v[100:101]
	v_lshlrev_b32_e32 v162, 16, v113
	v_and_b32_e32 v163, 0xffff0000, v113
	v_pk_fma_f32 v[100:101], v[166:167], v[4:5], v[100:101]
	v_lshlrev_b32_e32 v160, 16, v108
	v_and_b32_e32 v161, 0xffff0000, v108
	v_pk_fma_f32 v[100:101], v[162:163], v[6:7], v[100:101]
	v_pk_fma_f32 v[222:223], v[222:223], v[66:67], v[78:79]
	v_pk_fma_f32 v[100:101], v[160:161], v[12:13], v[100:101]
	v_pk_fma_f32 v[222:223], v[220:221], v[68:69], v[222:223]
	v_add_f32_e32 v105, v100, v101
	v_pk_mul_f32 v[106:107], v[100:101], v[100:101]
	v_pk_fma_f32 v[222:223], v[216:217], v[70:71], v[222:223]
	v_add_f32_dpp v105, v105, v105 quad_perm:[1,0,3,2] row_mask:0xf bank_mask:0xf bound_ctrl:1
	v_add_f32_e32 v106, v106, v107
	v_pk_fma_f32 v[222:223], v[214:215], v[72:73], v[222:223]
	v_add_f32_dpp v105, v105, v105 quad_perm:[2,3,0,1] row_mask:0xf bank_mask:0xf bound_ctrl:1
	v_add_f32_dpp v106, v106, v106 quad_perm:[1,0,3,2] row_mask:0xf bank_mask:0xf bound_ctrl:1
	v_pk_fma_f32 v[222:223], v[210:211], v[36:37], v[222:223]
	v_add_f32_dpp v105, v105, v105 row_half_mirror row_mask:0xf bank_mask:0xf bound_ctrl:1
	v_add_f32_dpp v106, v106, v106 quad_perm:[2,3,0,1] row_mask:0xf bank_mask:0xf bound_ctrl:1
	v_pk_fma_f32 v[222:223], v[206:207], v[38:39], v[222:223]
	v_add_f32_dpp v105, v105, v105 row_mirror row_mask:0xf bank_mask:0xf bound_ctrl:1
	v_mov_b32_e32 v107, v105
	v_add_f32_dpp v106, v106, v106 row_half_mirror row_mask:0xf bank_mask:0xf bound_ctrl:1
	s_nop 1
	v_permlane16_swap_b32 v105, v107
	v_pk_fma_f32 v[222:223], v[200:201], v[42:43], v[222:223]
	v_add_f32_e32 v105, v105, v107
	v_add_f32_dpp v106, v106, v106 row_mirror row_mask:0xf bank_mask:0xf bound_ctrl:1
	v_mov_b32_e32 v107, v106
	s_nop 1
	v_permlane16_swap_b32 v106, v107
	v_ldexp_f32 v194, v105, -6
	v_add_f32_e32 v106, v106, v107
	v_ldexp_f32 v105, v106, -6
	v_fma_f32 v105, -v194, v194, v105
	v_pk_fma_f32 v[222:223], v[198:199], v[60:61], v[222:223]
	v_max_f32_e32 v105, 0, v105
	v_pk_fma_f32 v[222:223], v[196:197], v[44:45], v[222:223]
	v_add_f32_e32 v105, 0x3727c5ac, v105
	s_mov_b32 s0, 0x800000
	v_pk_fma_f32 v[222:223], v[190:191], v[46:47], v[222:223]
	v_mul_f32_e32 v106, 0x4b800000, v105
	v_cmp_gt_f32_e32 vcc, s0, v105
	v_pk_fma_f32 v[222:223], v[188:189], v[54:55], v[222:223]
	v_and_b32_e32 v107, 0xffff0000, v104
	v_cndmask_b32_e32 v105, v105, v106, vcc
	v_pk_fma_f32 v[222:223], v[186:187], v[58:59], v[222:223]
	v_rsq_f32_e32 v105, v105
	v_pk_fma_f32 v[222:223], v[184:185], v[50:51], v[222:223]
	v_lshlrev_b32_e32 v106, 16, v104
	v_pk_fma_f32 v[222:223], v[182:183], v[52:53], v[222:223]
	v_mul_f32_e32 v104, 0x45800000, v105
	v_pk_fma_f32 v[222:223], v[202:203], v[56:57], v[222:223]
	v_pk_add_f32 v[100:101], v[100:101], v[194:195] op_sel_hi:[1,0] neg_lo:[0,1] neg_hi:[0,1]
	v_pk_fma_f32 v[222:223], v[154:155], v[22:23], v[222:223]
	v_cndmask_b32_e32 v104, v105, v104, vcc
	v_pk_fma_f32 v[222:223], v[152:153], v[26:27], v[222:223]
	v_pk_mul_f32 v[100:101], v[100:101], v[104:105] op_sel_hi:[1,0]
	v_pk_fma_f32 v[222:223], v[150:151], v[28:29], v[222:223]
	v_pk_fma_f32 v[194:195], v[0:1], v[100:101], v[8:9]
	v_pk_fma_f32 v[222:223], v[148:149], v[30:31], v[222:223]
	v_mul_f32_e32 v100, 0xbfb8aa3b, v194
	v_pk_fma_f32 v[222:223], v[142:143], v[34:35], v[222:223]
	v_mul_f32_e32 v101, 0xbfb8aa3b, v195
	v_pk_fma_f32 v[222:223], v[138:139], v[32:33], v[222:223]
	v_exp_f32_e32 v100, v100
	v_exp_f32_e32 v101, v101
	v_pk_fma_f32 v[222:223], v[134:135], v[18:19], v[222:223]
	v_lshlrev_b32_e32 v158, 16, v125
	v_pk_fma_f32 v[222:223], v[130:131], v[20:21], v[222:223]
	v_add_f32_e32 v100, 1.0, v100
	v_pk_fma_f32 v[222:223], v[128:129], v[24:25], v[222:223]
	v_add_f32_e32 v101, 1.0, v101
	v_pk_fma_f32 v[222:223], v[126:127], v[16:17], v[222:223]
	v_and_b32_e32 v159, 0xffff0000, v125
	v_pk_fma_f32 v[222:223], v[164:165], v[14:15], v[222:223]
	v_lshlrev_b32_e32 v124, 16, v243
	v_and_b32_e32 v125, 0xffff0000, v243
	v_lshlrev_b32_e32 v112, 16, v242
	v_and_b32_e32 v113, 0xffff0000, v242
	v_rcp_f32_e32 v242, v100
	v_rcp_f32_e32 v243, v101
	v_pk_fma_f32 v[222:223], v[168:169], v[2:3], v[222:223]
	v_lshlrev_b32_e32 v104, 16, v241
	v_pk_fma_f32 v[222:223], v[166:167], v[10:11], v[222:223]
	v_and_b32_e32 v105, 0xffff0000, v241
	v_pk_fma_f32 v[222:223], v[162:163], v[4:5], v[222:223]
	v_lshlrev_b32_e32 v100, 16, v240
	v_pk_fma_f32 v[222:223], v[160:161], v[6:7], v[222:223]
	v_and_b32_e32 v101, 0xffff0000, v240
	v_pk_mul_f32 v[194:195], v[194:195], v[242:243]
	s_waitcnt vmcnt(1)
; #define GAS __attribute__((address_space(1)))
; __device__ __forceinline__ unsigned cvtpk(float lo, float hi) { f32x2 v = {lo, hi}; bf16x2_t b = __builtin_convertvector(v, bf16x2_t); return __builtin_bit_cast(unsigned, b); }
; __device__ __forceinline__ float bflo(unsigned w) { return __uint_as_float(w << 16); }
; __device__ __forceinline__ float bfhi(unsigned w) { return __uint_as_float(w & 0xffff0000u); }
; __device__ __forceinline__ float fsilu(float x) { return x * fsigmoid(x); }
; __device__ __forceinline__ void c_unit(Frame& F, int L, int u, bool dry) {
;     ...
;         for (int i = 0; i < 46; ++i) {
;             const float h0 = bflo(hv[16 * sub + i]), h1 = bfhi(hv[16 * sub + i]);
; #pragma unroll
;             for (int t = 0; t < 16; ++t) { const int j = i - t; if (j >= 0 && j < CONVW) { acc[t].x = fmaf(h0, wv[j].x, acc[t].x); acc[t].y = fmaf(h1, wv[j].y, acc[t].y); } }
;         }
; #pragma unroll
;         for (int t = 0; t < 16; ++t) {
;             float s = acc[t].x + acc[t].y, qq = acc[t].x * acc[t].x + acc[t].y * acc[t].y;
;             s = half_wave_sum(s); qq = half_wave_sum(qq);
;             const float mu = __builtin_ldexpf(s, -6), rstd = rsqrtf(fmaxf(__builtin_ldexpf(qq, -6) - mu * mu, 0.f) + LN_EPS);
;             const float h0 = (acc[t].x - mu) * rstd * gv.x + bv.x, h1 = (acc[t].y - mu) * rstd * gv.y + bv.y;
;             const unsigned ov = cvtpk(fsilu(h0) * bflo(sc[16 * sub + t]), fsilu(h1) * bfhi(sc[16 * sub + t])); if (!dry) *(GAS unsigned*)(SCG + (size_t)(tb + t) * 512) = ov;
	v_lshlrev_b32_e32 v240, 16, v247
	v_and_b32_e32 v241, 0xffff0000, v247
	v_pk_fma_f32 v[222:223], v[158:159], v[12:13], v[222:223]
	v_pk_mul_f32 v[194:195], v[194:195], v[240:241]
	v_add_f32_e32 v242, v222, v223
	v_pk_mul_f32 v[240:241], v[222:223], v[222:223]
	v_pk_fma_f32 v[220:221], v[220:221], v[66:67], v[78:79]
	v_add_f32_e32 v240, v240, v241
	v_add_f32_dpp v241, v242, v242 quad_perm:[1,0,3,2] row_mask:0xf bank_mask:0xf bound_ctrl:1
	v_pk_fma_f32 v[220:221], v[216:217], v[68:69], v[220:221]
	v_add_f32_dpp v240, v240, v240 quad_perm:[1,0,3,2] row_mask:0xf bank_mask:0xf bound_ctrl:1
	v_add_f32_dpp v241, v241, v241 quad_perm:[2,3,0,1] row_mask:0xf bank_mask:0xf bound_ctrl:1
	v_pk_fma_f32 v[220:221], v[214:215], v[70:71], v[220:221]
	v_add_f32_dpp v240, v240, v240 quad_perm:[2,3,0,1] row_mask:0xf bank_mask:0xf bound_ctrl:1
	v_add_f32_dpp v241, v241, v241 row_half_mirror row_mask:0xf bank_mask:0xf bound_ctrl:1
	v_pk_fma_f32 v[220:221], v[210:211], v[72:73], v[220:221]
	v_add_f32_dpp v240, v240, v240 row_half_mirror row_mask:0xf bank_mask:0xf bound_ctrl:1
	v_add_f32_dpp v241, v241, v241 row_mirror row_mask:0xf bank_mask:0xf bound_ctrl:1
	v_mov_b32_e32 v242, v241
	s_nop 1
	v_permlane16_swap_b32 v241, v242
	v_add_f32_dpp v240, v240, v240 row_mirror row_mask:0xf bank_mask:0xf bound_ctrl:1
	v_add_f32_e32 v241, v241, v242
	v_mov_b32_e32 v242, v240
	s_nop 1
	v_permlane16_swap_b32 v240, v242
	v_pk_fma_f32 v[220:221], v[206:207], v[36:37], v[220:221]
	v_add_f32_e32 v242, v240, v242
	v_pk_fma_f32 v[220:221], v[200:201], v[38:39], v[220:221]
	v_ldexp_f32 v240, v241, -6
	v_ldexp_f32 v241, v242, -6
	v_pk_fma_f32 v[220:221], v[198:199], v[42:43], v[220:221]
	v_fma_f32 v242, -v240, v240, v241
	v_pk_add_f32 v[240:241], v[222:223], v[240:241] op_sel_hi:[1,0] neg_lo:[0,1] neg_hi:[0,1]
	global_load_dword v222, v[208:209], off sc1
	global_load_dword v247, v[180:181], off sc1
	v_pk_fma_f32 v[220:221], v[196:197], v[60:61], v[220:221]
	v_max_f32_e32 v223, 0, v242
	v_pk_fma_f32 v[220:221], v[190:191], v[44:45], v[220:221]
	v_add_f32_e32 v223, 0x3727c5ac, v223
	v_pk_fma_f32 v[220:221], v[188:189], v[46:47], v[220:221]
	v_mul_f32_e32 v242, 0x4b800000, v223
	v_pk_fma_f32 v[220:221], v[186:187], v[54:55], v[220:221]
	v_cmp_gt_f32_e32 vcc, s0, v223
	v_pk_fma_f32 v[220:221], v[184:185], v[58:59], v[220:221]
	v_lshlrev_b32_e32 v146, 16, v119
	v_pk_fma_f32 v[220:221], v[182:183], v[50:51], v[220:221]
	v_cndmask_b32_e32 v223, v223, v242, vcc
	v_pk_fma_f32 v[220:221], v[202:203], v[52:53], v[220:221]
	v_rsq_f32_e32 v223, v223
	v_pk_fma_f32 v[220:221], v[154:155], v[56:57], v[220:221]
	v_cvt_pk_bf16_f32 v242, v194, v195
	v_pk_fma_f32 v[220:221], v[152:153], v[22:23], v[220:221]
	v_mul_f32_e32 v194, 0x45800000, v223
	v_pk_fma_f32 v[220:221], v[150:151], v[26:27], v[220:221]
	v_cndmask_b32_e32 v194, v223, v194, vcc
	v_pk_fma_f32 v[220:221], v[148:149], v[28:29], v[220:221]
	v_pk_mul_f32 v[194:195], v[240:241], v[194:195] op_sel_hi:[1,0]
	v_pk_fma_f32 v[220:221], v[142:143], v[30:31], v[220:221]
	v_pk_fma_f32 v[194:195], v[0:1], v[194:195], v[8:9]
	v_pk_fma_f32 v[220:221], v[138:139], v[34:35], v[220:221]
	v_mul_f32_e32 v223, 0xbfb8aa3b, v194
	v_pk_fma_f32 v[220:221], v[134:135], v[32:33], v[220:221]
	v_exp_f32_e32 v223, v223
	v_pk_fma_f32 v[220:221], v[130:131], v[18:19], v[220:221]
	v_mul_f32_e32 v240, 0xbfb8aa3b, v195
	v_pk_fma_f32 v[220:221], v[128:129], v[20:21], v[220:221]
	v_exp_f32_e32 v240, v240
	v_pk_fma_f32 v[220:221], v[126:127], v[24:25], v[220:221]
	v_and_b32_e32 v147, 0xffff0000, v119
	v_pk_fma_f32 v[220:221], v[164:165], v[16:17], v[220:221]
	global_store_dword v[218:219], v242, off
	v_pk_fma_f32 v[220:221], v[168:169], v[14:15], v[220:221]
	v_add_f32_e32 v218, 1.0, v223
	v_pk_fma_f32 v[220:221], v[166:167], v[2:3], v[220:221]
	v_add_f32_e32 v219, 1.0, v240
	v_pk_fma_f32 v[220:221], v[162:163], v[10:11], v[220:221]
	v_rcp_f32_e32 v218, v218
	v_pk_fma_f32 v[220:221], v[160:161], v[4:5], v[220:221]
	v_rcp_f32_e32 v219, v219
	v_pk_fma_f32 v[220:221], v[158:159], v[6:7], v[220:221]
	v_lshlrev_b32_e32 v110, 16, v252
	v_pk_fma_f32 v[220:221], v[146:147], v[12:13], v[220:221]
	v_pk_mul_f32 v[194:195], v[194:195], v[218:219]
	v_add_f32_e32 v223, v220, v221
	v_pk_mul_f32 v[240:241], v[220:221], v[220:221]
	s_waitcnt vmcnt(3)
; #define GAS __attribute__((address_space(1)))
; __device__ __forceinline__ unsigned cvtpk(float lo, float hi) { f32x2 v = {lo, hi}; bf16x2_t b = __builtin_convertvector(v, bf16x2_t); return __builtin_bit_cast(unsigned, b); }
; __device__ __forceinline__ float bflo(unsigned w) { return __uint_as_float(w << 16); }
; __device__ __forceinline__ float bfhi(unsigned w) { return __uint_as_float(w & 0xffff0000u); }
; __device__ __forceinline__ float fsilu(float x) { return x * fsigmoid(x); }
; __device__ __forceinline__ void c_unit(Frame& F, int L, int u, bool dry) {
;     ...
;         for (int i = 0; i < 46; ++i) {
;             const float h0 = bflo(hv[16 * sub + i]), h1 = bfhi(hv[16 * sub + i]);
; #pragma unroll
;             for (int t = 0; t < 16; ++t) { const int j = i - t; if (j >= 0 && j < CONVW) { acc[t].x = fmaf(h0, wv[j].x, acc[t].x); acc[t].y = fmaf(h1, wv[j].y, acc[t].y); } }
;         }
; #pragma unroll
;         for (int t = 0; t < 16; ++t) {
;             float s = acc[t].x + acc[t].y, qq = acc[t].x * acc[t].x + acc[t].y * acc[t].y;
;             s = half_wave_sum(s); qq = half_wave_sum(qq);
;             const float mu = __builtin_ldexpf(s, -6), rstd = rsqrtf(fmaxf(__builtin_ldexpf(qq, -6) - mu * mu, 0.f) + LN_EPS);
;             const float h0 = (acc[t].x - mu) * rstd * gv.x + bv.x, h1 = (acc[t].y - mu) * rstd * gv.y + bv.y;
;             const unsigned ov = cvtpk(fsilu(h0) * bflo(sc[16 * sub + t]), fsilu(h1) * bfhi(sc[16 * sub + t])); if (!dry) *(GAS unsigned*)(SCG + (size_t)(tb + t) * 512) = ov;
	v_lshlrev_b32_e32 v218, 16, v244
	v_add_f32_dpp v223, v223, v223 quad_perm:[1,0,3,2] row_mask:0xf bank_mask:0xf bound_ctrl:1
	v_add_f32_e32 v240, v240, v241
	v_and_b32_e32 v219, 0xffff0000, v244
	v_add_f32_dpp v223, v223, v223 quad_perm:[2,3,0,1] row_mask:0xf bank_mask:0xf bound_ctrl:1
	v_add_f32_dpp v240, v240, v240 quad_perm:[1,0,3,2] row_mask:0xf bank_mask:0xf bound_ctrl:1
	v_pk_mul_f32 v[218:219], v[194:195], v[218:219]
	v_add_f32_dpp v223, v223, v223 row_half_mirror row_mask:0xf bank_mask:0xf bound_ctrl:1
	v_add_f32_dpp v240, v240, v240 quad_perm:[2,3,0,1] row_mask:0xf bank_mask:0xf bound_ctrl:1
	v_and_b32_e32 v111, 0xffff0000, v252
	v_add_f32_dpp v223, v223, v223 row_mirror row_mask:0xf bank_mask:0xf bound_ctrl:1
	v_mov_b32_e32 v241, v223
	v_add_f32_dpp v240, v240, v240 row_half_mirror row_mask:0xf bank_mask:0xf bound_ctrl:1
	s_nop 1
	v_permlane16_swap_b32 v223, v241
	global_load_dword v252, v[204:205], off sc1
	v_add_f32_e32 v223, v223, v241
	v_add_f32_dpp v240, v240, v240 row_mirror row_mask:0xf bank_mask:0xf bound_ctrl:1
	v_mov_b32_e32 v241, v240
	s_nop 1
	v_permlane16_swap_b32 v240, v241
	v_ldexp_f32 v194, v223, -6
	v_add_f32_e32 v240, v240, v241
	v_ldexp_f32 v195, v240, -6
	v_fma_f32 v195, -v194, v194, v195
	v_max_f32_e32 v195, 0, v195
	v_add_f32_e32 v195, 0x3727c5ac, v195
	v_mul_f32_e32 v223, 0x4b800000, v195
	v_cmp_gt_f32_e32 vcc, s0, v195
	v_lshlrev_b32_e32 v144, 16, v132
	v_and_b32_e32 v145, 0xffff0000, v132
	v_cndmask_b32_e32 v195, v195, v223, vcc
	v_cvt_pk_bf16_f32 v223, v218, v219
	global_store_dword v[212:213], v223, off
	v_pk_fma_f32 v[212:213], v[216:217], v[66:67], v[78:79]
	v_rsq_f32_e32 v195, v195
	v_pk_fma_f32 v[212:213], v[214:215], v[68:69], v[212:213]
	v_lshlrev_b32_e32 v136, 16, v118
	v_pk_fma_f32 v[212:213], v[210:211], v[70:71], v[212:213]
	v_pk_add_f32 v[220:221], v[220:221], v[194:195] op_sel_hi:[1,0] neg_lo:[0,1] neg_hi:[0,1]
	v_pk_fma_f32 v[212:213], v[206:207], v[72:73], v[212:213]
	v_mul_f32_e32 v194, 0x45800000, v195
	v_pk_fma_f32 v[212:213], v[200:201], v[36:37], v[212:213]
	v_cndmask_b32_e32 v194, v195, v194, vcc
	v_pk_fma_f32 v[212:213], v[198:199], v[38:39], v[212:213]
	v_pk_mul_f32 v[194:195], v[220:221], v[194:195] op_sel_hi:[1,0]
	v_pk_fma_f32 v[212:213], v[196:197], v[42:43], v[212:213]
	v_pk_fma_f32 v[194:195], v[0:1], v[194:195], v[8:9]
	v_pk_fma_f32 v[212:213], v[190:191], v[60:61], v[212:213]
	v_mul_f32_e32 v220, 0xbfb8aa3b, v194
	v_pk_fma_f32 v[212:213], v[188:189], v[44:45], v[212:213]
	v_mul_f32_e32 v221, 0xbfb8aa3b, v195
	v_pk_fma_f32 v[212:213], v[186:187], v[46:47], v[212:213]
	v_exp_f32_e32 v220, v220
	v_pk_fma_f32 v[212:213], v[184:185], v[54:55], v[212:213]
	v_exp_f32_e32 v221, v221
	v_pk_fma_f32 v[212:213], v[182:183], v[58:59], v[212:213]
	v_add_f32_e32 v218, 1.0, v220
	v_pk_fma_f32 v[212:213], v[202:203], v[50:51], v[212:213]
	v_add_f32_e32 v219, 1.0, v221
	v_pk_fma_f32 v[212:213], v[154:155], v[52:53], v[212:213]
	v_rcp_f32_e32 v218, v218
	v_pk_fma_f32 v[212:213], v[152:153], v[56:57], v[212:213]
	v_rcp_f32_e32 v219, v219
	v_pk_fma_f32 v[212:213], v[150:151], v[22:23], v[212:213]
	v_and_b32_e32 v137, 0xffff0000, v118
	v_pk_fma_f32 v[212:213], v[148:149], v[26:27], v[212:213]
	v_pk_mul_f32 v[194:195], v[194:195], v[218:219]
	v_pk_fma_f32 v[212:213], v[142:143], v[28:29], v[212:213]
	v_lshlrev_b32_e32 v118, 16, v245
	v_pk_fma_f32 v[212:213], v[138:139], v[30:31], v[212:213]
	v_and_b32_e32 v119, 0xffff0000, v245
	v_pk_fma_f32 v[212:213], v[134:135], v[34:35], v[212:213]
	v_lshlrev_b32_e32 v108, 16, v251
	v_pk_fma_f32 v[212:213], v[130:131], v[32:33], v[212:213]
	v_and_b32_e32 v109, 0xffff0000, v251
	v_pk_fma_f32 v[212:213], v[128:129], v[18:19], v[212:213]
	v_lshlrev_b32_e32 v102, 16, v246
	v_pk_fma_f32 v[212:213], v[126:127], v[20:21], v[212:213]
	v_and_b32_e32 v103, 0xffff0000, v246
	v_pk_fma_f32 v[212:213], v[164:165], v[24:25], v[212:213]
	global_load_dword v246, v[178:179], off sc1
	global_load_dword v245, v[176:177], off sc1
	global_load_dword v240, v[174:175], off sc1
	global_load_dword v251, v[172:173], off sc1
	global_load_dword v242, v[170:171], off sc1
	global_load_dword v243, v[156:157], off sc1
	global_load_dword v241, v[140:141], off sc1
	global_load_dword v223, v[122:123], off sc1
	v_pk_fma_f32 v[212:213], v[168:169], v[16:17], v[212:213]
	v_lshlrev_b32_e32 v132, 16, v133
	v_pk_fma_f32 v[212:213], v[166:167], v[14:15], v[212:213]
	v_and_b32_e32 v133, 0xffff0000, v133
	v_pk_fma_f32 v[212:213], v[162:163], v[2:3], v[212:213]
	s_waitcnt vmcnt(6)
; #define GAS __attribute__((address_space(1)))
; __device__ __forceinline__ unsigned cvtpk(float lo, float hi) { f32x2 v = {lo, hi}; bf16x2_t b = __builtin_convertvector(v, bf16x2_t); return __builtin_bit_cast(unsigned, b); }
; __device__ __forceinline__ float bflo(unsigned w) { return __uint_as_float(w << 16); }
; __device__ __forceinline__ float bfhi(unsigned w) { return __uint_as_float(w & 0xffff0000u); }
; __device__ __forceinline__ float fsilu(float x) { return x * fsigmoid(x); }
; __device__ __forceinline__ void c_unit(Frame& F, int L, int u, bool dry) {
;     ...
;         for (int i = 0; i < 46; ++i) {
;             const float h0 = bflo(hv[16 * sub + i]), h1 = bfhi(hv[16 * sub + i]);
; #pragma unroll
;             for (int t = 0; t < 16; ++t) { const int j = i - t; if (j >= 0 && j < CONVW) { acc[t].x = fmaf(h0, wv[j].x, acc[t].x); acc[t].y = fmaf(h1, wv[j].y, acc[t].y); } }
;         }
; #pragma unroll
;         for (int t = 0; t < 16; ++t) {
;             float s = acc[t].x + acc[t].y, qq = acc[t].x * acc[t].x + acc[t].y * acc[t].y;
;             s = half_wave_sum(s); qq = half_wave_sum(qq);
;             const float mu = __builtin_ldexpf(s, -6), rstd = rsqrtf(fmaxf(__builtin_ldexpf(qq, -6) - mu * mu, 0.f) + LN_EPS);
;             const float h0 = (acc[t].x - mu) * rstd * gv.x + bv.x, h1 = (acc[t].y - mu) * rstd * gv.y + bv.y;
;             const unsigned ov = cvtpk(fsilu(h0) * bflo(sc[16 * sub + t]), fsilu(h1) * bfhi(sc[16 * sub + t])); if (!dry) *(GAS unsigned*)(SCG + (size_t)(tb + t) * 512) = ov;
	v_lshlrev_b32_e32 v244, 16, v245
	v_pk_fma_f32 v[212:213], v[160:161], v[10:11], v[212:213]
	v_and_b32_e32 v245, 0xffff0000, v245
	v_pk_fma_f32 v[212:213], v[158:159], v[4:5], v[212:213]
	s_nop 0
	v_pk_fma_f32 v[212:213], v[146:147], v[6:7], v[212:213]
	s_nop 0
	v_pk_fma_f32 v[212:213], v[144:145], v[12:13], v[212:213]
	s_nop 0
	v_add_f32_e32 v218, v212, v213
	v_pk_mul_f32 v[216:217], v[212:213], v[212:213]
	s_nop 0
	v_add_f32_e32 v216, v216, v217
	v_add_f32_dpp v217, v218, v218 quad_perm:[1,0,3,2] row_mask:0xf bank_mask:0xf bound_ctrl:1
	s_nop 0
	v_add_f32_dpp v216, v216, v216 quad_perm:[1,0,3,2] row_mask:0xf bank_mask:0xf bound_ctrl:1
	v_add_f32_dpp v217, v217, v217 quad_perm:[2,3,0,1] row_mask:0xf bank_mask:0xf bound_ctrl:1
	s_nop 0
	v_add_f32_dpp v216, v216, v216 quad_perm:[2,3,0,1] row_mask:0xf bank_mask:0xf bound_ctrl:1
	v_add_f32_dpp v217, v217, v217 row_half_mirror row_mask:0xf bank_mask:0xf bound_ctrl:1
	s_nop 0
	v_add_f32_dpp v216, v216, v216 row_half_mirror row_mask:0xf bank_mask:0xf bound_ctrl:1
	v_add_f32_dpp v217, v217, v217 row_mirror row_mask:0xf bank_mask:0xf bound_ctrl:1
	v_mov_b32_e32 v218, v217
	s_nop 1
	v_permlane16_swap_b32 v217, v218
	v_add_f32_dpp v216, v216, v216 row_mirror row_mask:0xf bank_mask:0xf bound_ctrl:1
	v_add_f32_e32 v218, v217, v218
	v_mov_b32_e32 v217, v216
	s_nop 1
	v_permlane16_swap_b32 v216, v217
	s_nop 0
	v_add_f32_e32 v219, v216, v217
	v_lshlrev_b32_e32 v216, 16, v222
	v_and_b32_e32 v217, 0xffff0000, v222
	v_pk_mul_f32 v[194:195], v[194:195], v[216:217]
	v_ldexp_f32 v216, v218, -6
	v_ldexp_f32 v217, v219, -6
	v_fma_f32 v217, -v216, v216, v217
	v_max_f32_e32 v217, 0, v217
	v_add_f32_e32 v217, 0x3727c5ac, v217
	v_mul_f32_e32 v218, 0x4b800000, v217
	v_cmp_gt_f32_e32 vcc, s0, v217
	global_load_dword v222, v[120:121], off sc1
	global_load_dword v220, v[116:117], off sc1
	v_cndmask_b32_e32 v217, v217, v218, vcc
	v_rsq_f32_e32 v217, v217
	global_load_dword v221, v[114:115], off sc1
	global_load_dword v219, v[98:99], off sc1
	global_load_dword v218, v[96:97], off sc1
	v_pk_add_f32 v[212:213], v[212:213], v[216:217] op_sel_hi:[1,0] neg_lo:[0,1] neg_hi:[0,1]
	v_mul_f32_e32 v216, 0x45800000, v217
	v_cndmask_b32_e32 v216, v217, v216, vcc
	v_pk_mul_f32 v[212:213], v[212:213], v[216:217] op_sel_hi:[1,0]
	v_cvt_pk_bf16_f32 v216, v194, v195
	v_pk_fma_f32 v[194:195], v[0:1], v[212:213], v[8:9]
	global_store_dword v[208:209], v216, off
	v_mul_f32_e32 v212, 0xbfb8aa3b, v194
	v_exp_f32_e32 v212, v212
	v_mul_f32_e32 v208, 0xbfb8aa3b, v195
	v_exp_f32_e32 v209, v208
	global_load_dword v217, v[94:95], off sc1
	global_load_dword v216, v[92:93], off sc1
	v_add_f32_e32 v208, 1.0, v212
	v_pk_fma_f32 v[212:213], v[214:215], v[66:67], v[78:79]
	v_add_f32_e32 v209, 1.0, v209
	v_pk_fma_f32 v[212:213], v[210:211], v[68:69], v[212:213]
	v_rcp_f32_e32 v208, v208
	v_pk_fma_f32 v[212:213], v[206:207], v[70:71], v[212:213]
	v_rcp_f32_e32 v209, v209
	v_pk_fma_f32 v[212:213], v[200:201], v[72:73], v[212:213]
	global_load_dword v215, v[80:81], off sc1
	v_pk_fma_f32 v[212:213], v[198:199], v[36:37], v[212:213]
	v_pk_mul_f32 v[194:195], v[194:195], v[208:209]
	v_pk_fma_f32 v[212:213], v[196:197], v[38:39], v[212:213]
	v_lshlrev_b32_e32 v208, 16, v252
	v_pk_fma_f32 v[212:213], v[190:191], v[42:43], v[212:213]
	v_and_b32_e32 v209, 0xffff0000, v252
	v_pk_fma_f32 v[212:213], v[188:189], v[60:61], v[212:213]
	v_pk_mul_f32 v[194:195], v[194:195], v[208:209]
	v_pk_fma_f32 v[212:213], v[186:187], v[44:45], v[212:213]
	v_cvt_pk_bf16_f32 v194, v194, v195
	v_pk_fma_f32 v[212:213], v[184:185], v[46:47], v[212:213]
	global_store_dword v[204:205], v194, off
	v_pk_fma_f32 v[212:213], v[182:183], v[54:55], v[212:213]
	s_nop 0
	v_pk_fma_f32 v[212:213], v[202:203], v[58:59], v[212:213]
	s_nop 0
	v_pk_fma_f32 v[212:213], v[154:155], v[50:51], v[212:213]
	s_nop 0
	v_pk_fma_f32 v[212:213], v[152:153], v[52:53], v[212:213]
	s_nop 0
	v_pk_fma_f32 v[212:213], v[150:151], v[56:57], v[212:213]
	s_nop 0
	v_pk_fma_f32 v[212:213], v[148:149], v[22:23], v[212:213]
	s_nop 0
	v_pk_fma_f32 v[212:213], v[142:143], v[26:27], v[212:213]
	s_nop 0
	v_pk_fma_f32 v[212:213], v[138:139], v[28:29], v[212:213]
	s_nop 0
	v_pk_fma_f32 v[212:213], v[134:135], v[30:31], v[212:213]
	s_nop 0
	v_pk_fma_f32 v[212:213], v[130:131], v[34:35], v[212:213]
	s_nop 0
	v_pk_fma_f32 v[212:213], v[128:129], v[32:33], v[212:213]
	s_nop 0
	v_pk_fma_f32 v[212:213], v[126:127], v[18:19], v[212:213]
	s_nop 0
	v_pk_fma_f32 v[212:213], v[164:165], v[20:21], v[212:213]
	s_nop 0
	v_pk_fma_f32 v[212:213], v[168:169], v[24:25], v[212:213]
	s_nop 0
	v_pk_fma_f32 v[212:213], v[166:167], v[16:17], v[212:213]
	s_nop 0
	v_pk_fma_f32 v[212:213], v[162:163], v[14:15], v[212:213]
	s_nop 0
	v_pk_fma_f32 v[208:209], v[160:161], v[2:3], v[212:213]
	s_nop 0
	v_pk_fma_f32 v[208:209], v[158:159], v[10:11], v[208:209]
	s_nop 0
	v_pk_fma_f32 v[208:209], v[146:147], v[4:5], v[208:209]
	s_nop 0
	v_pk_fma_f32 v[208:209], v[144:145], v[6:7], v[208:209]
	s_nop 0
	v_pk_fma_f32 v[208:209], v[136:137], v[12:13], v[208:209]
	s_nop 0
	v_add_f32_e32 v214, v208, v209
	v_pk_mul_f32 v[212:213], v[208:209], v[208:209]
	s_nop 0
	v_add_f32_e32 v212, v212, v213
	v_add_f32_dpp v213, v214, v214 quad_perm:[1,0,3,2] row_mask:0xf bank_mask:0xf bound_ctrl:1
	s_nop 0
	v_add_f32_dpp v212, v212, v212 quad_perm:[1,0,3,2] row_mask:0xf bank_mask:0xf bound_ctrl:1
	v_add_f32_dpp v213, v213, v213 quad_perm:[2,3,0,1] row_mask:0xf bank_mask:0xf bound_ctrl:1
	s_nop 0
	v_add_f32_dpp v212, v212, v212 quad_perm:[2,3,0,1] row_mask:0xf bank_mask:0xf bound_ctrl:1
	v_add_f32_dpp v213, v213, v213 row_half_mirror row_mask:0xf bank_mask:0xf bound_ctrl:1
	s_nop 0
; #define GAS __attribute__((address_space(1)))
; __device__ __forceinline__ unsigned cvtpk(float lo, float hi) { f32x2 v = {lo, hi}; bf16x2_t b = __builtin_convertvector(v, bf16x2_t); return __builtin_bit_cast(unsigned, b); }
; __device__ __forceinline__ float bflo(unsigned w) { return __uint_as_float(w << 16); }
; __device__ __forceinline__ float bfhi(unsigned w) { return __uint_as_float(w & 0xffff0000u); }
; __device__ __forceinline__ float fsilu(float x) { return x * fsigmoid(x); }
; __device__ __forceinline__ void c_unit(Frame& F, int L, int u, bool dry) {
;     ...
;         for (int i = 0; i < 46; ++i) {
;             const float h0 = bflo(hv[16 * sub + i]), h1 = bfhi(hv[16 * sub + i]);
; #pragma unroll
;             for (int t = 0; t < 16; ++t) { const int j = i - t; if (j >= 0 && j < CONVW) { acc[t].x = fmaf(h0, wv[j].x, acc[t].x); acc[t].y = fmaf(h1, wv[j].y, acc[t].y); } }
;         }
; #pragma unroll
;         for (int t = 0; t < 16; ++t) {
;             float s = acc[t].x + acc[t].y, qq = acc[t].x * acc[t].x + acc[t].y * acc[t].y;
;             s = half_wave_sum(s); qq = half_wave_sum(qq);
;             const float mu = __builtin_ldexpf(s, -6), rstd = rsqrtf(fmaxf(__builtin_ldexpf(qq, -6) - mu * mu, 0.f) + LN_EPS);
;             const float h0 = (acc[t].x - mu) * rstd * gv.x + bv.x, h1 = (acc[t].y - mu) * rstd * gv.y + bv.y;
;             const unsigned ov = cvtpk(fsilu(h0) * bflo(sc[16 * sub + t]), fsilu(h1) * bfhi(sc[16 * sub + t])); if (!dry) *(GAS unsigned*)(SCG + (size_t)(tb + t) * 512) = ov;
	v_add_f32_dpp v212, v212, v212 row_half_mirror row_mask:0xf bank_mask:0xf bound_ctrl:1
	v_add_f32_dpp v213, v213, v213 row_mirror row_mask:0xf bank_mask:0xf bound_ctrl:1
	v_mov_b32_e32 v214, v213
	s_nop 1
	v_permlane16_swap_b32 v213, v214
	v_add_f32_dpp v212, v212, v212 row_mirror row_mask:0xf bank_mask:0xf bound_ctrl:1
	v_add_f32_e32 v213, v213, v214
	v_mov_b32_e32 v214, v212
	s_nop 1
	v_permlane16_swap_b32 v212, v214
	s_nop 0
	v_add_f32_e32 v214, v212, v214
	v_ldexp_f32 v212, v213, -6
	v_ldexp_f32 v213, v214, -6
	v_fma_f32 v213, -v212, v212, v213
	v_max_f32_e32 v213, 0, v213
	v_add_f32_e32 v213, 0x3727c5ac, v213
	v_mul_f32_e32 v214, 0x4b800000, v213
	v_cmp_gt_f32_e32 vcc, s0, v213
	s_nop 1
	v_cndmask_b32_e32 v213, v213, v214, vcc
	v_rsq_f32_e32 v213, v213
	global_load_dword v214, v[90:91], off sc1
	v_pk_add_f32 v[208:209], v[208:209], v[212:213] op_sel_hi:[1,0] neg_lo:[0,1] neg_hi:[0,1]
	v_mul_f32_e32 v212, 0x45800000, v213
	v_cndmask_b32_e32 v212, v213, v212, vcc
	v_pk_mul_f32 v[208:209], v[208:209], v[212:213] op_sel_hi:[1,0]
	global_load_dword v212, v[88:89], off sc1
	v_pk_fma_f32 v[208:209], v[0:1], v[208:209], v[8:9]
	s_nop 0
	v_mul_f32_e32 v195, 0xbfb8aa3b, v208
	v_mul_f32_e32 v194, 0xbfb8aa3b, v209
	v_exp_f32_e32 v195, v195
	v_exp_f32_e32 v204, v194
	v_add_f32_e32 v194, 1.0, v195
	v_add_f32_e32 v195, 1.0, v204
	v_pk_fma_f32 v[204:205], v[210:211], v[66:67], v[78:79]
	v_rcp_f32_e32 v194, v194
	v_pk_fma_f32 v[204:205], v[206:207], v[68:69], v[204:205]
	v_rcp_f32_e32 v195, v195
	v_pk_fma_f32 v[204:205], v[200:201], v[70:71], v[204:205]
	v_pk_fma_f32 v[206:207], v[206:207], v[66:67], v[78:79]
	v_pk_fma_f32 v[204:205], v[198:199], v[72:73], v[204:205]
	v_pk_mul_f32 v[194:195], v[208:209], v[194:195]
	v_pk_fma_f32 v[204:205], v[196:197], v[36:37], v[204:205]
	v_lshlrev_b32_e32 v208, 16, v247
	v_pk_fma_f32 v[204:205], v[190:191], v[38:39], v[204:205]
	v_and_b32_e32 v209, 0xffff0000, v247
	v_pk_fma_f32 v[204:205], v[188:189], v[42:43], v[204:205]
	v_pk_mul_f32 v[194:195], v[194:195], v[208:209]
	v_pk_fma_f32 v[204:205], v[186:187], v[60:61], v[204:205]
	v_cvt_pk_bf16_f32 v194, v194, v195
	v_pk_fma_f32 v[204:205], v[184:185], v[44:45], v[204:205]
	global_store_dword v[180:181], v194, off
	v_pk_fma_f32 v[204:205], v[182:183], v[46:47], v[204:205]
	v_pk_fma_f32 v[206:207], v[200:201], v[68:69], v[206:207]
	v_pk_fma_f32 v[204:205], v[202:203], v[54:55], v[204:205]
	v_pk_fma_f32 v[206:207], v[198:199], v[70:71], v[206:207]
	v_pk_fma_f32 v[204:205], v[154:155], v[58:59], v[204:205]
	v_pk_fma_f32 v[206:207], v[196:197], v[72:73], v[206:207]
	v_pk_fma_f32 v[204:205], v[152:153], v[50:51], v[204:205]
	v_pk_fma_f32 v[206:207], v[190:191], v[36:37], v[206:207]
	v_pk_fma_f32 v[204:205], v[150:151], v[52:53], v[204:205]
	v_pk_fma_f32 v[206:207], v[188:189], v[38:39], v[206:207]
	v_pk_fma_f32 v[204:205], v[148:149], v[56:57], v[204:205]
	v_pk_fma_f32 v[206:207], v[186:187], v[42:43], v[206:207]
	v_pk_fma_f32 v[204:205], v[142:143], v[22:23], v[204:205]
	v_pk_fma_f32 v[206:207], v[184:185], v[60:61], v[206:207]
	v_pk_fma_f32 v[204:205], v[138:139], v[26:27], v[204:205]
	v_pk_fma_f32 v[206:207], v[182:183], v[44:45], v[206:207]
	v_pk_fma_f32 v[204:205], v[134:135], v[28:29], v[204:205]
	v_pk_fma_f32 v[206:207], v[202:203], v[46:47], v[206:207]
	v_pk_fma_f32 v[204:205], v[130:131], v[30:31], v[204:205]
	v_pk_fma_f32 v[206:207], v[154:155], v[54:55], v[206:207]
	v_pk_fma_f32 v[204:205], v[128:129], v[34:35], v[204:205]
	v_pk_fma_f32 v[206:207], v[152:153], v[58:59], v[206:207]
	v_pk_fma_f32 v[204:205], v[126:127], v[32:33], v[204:205]
	v_pk_fma_f32 v[206:207], v[150:151], v[50:51], v[206:207]
	v_pk_fma_f32 v[204:205], v[164:165], v[18:19], v[204:205]
	v_pk_fma_f32 v[206:207], v[148:149], v[52:53], v[206:207]
	v_pk_fma_f32 v[204:205], v[168:169], v[20:21], v[204:205]
	v_pk_fma_f32 v[206:207], v[142:143], v[56:57], v[206:207]
	v_pk_fma_f32 v[204:205], v[166:167], v[24:25], v[204:205]
	v_pk_fma_f32 v[206:207], v[138:139], v[22:23], v[206:207]
	v_pk_fma_f32 v[204:205], v[162:163], v[16:17], v[204:205]
	v_pk_fma_f32 v[206:207], v[134:135], v[26:27], v[206:207]
	v_pk_fma_f32 v[204:205], v[160:161], v[14:15], v[204:205]
	v_pk_fma_f32 v[206:207], v[130:131], v[28:29], v[206:207]
	v_pk_fma_f32 v[204:205], v[158:159], v[2:3], v[204:205]
	v_pk_fma_f32 v[206:207], v[128:129], v[30:31], v[206:207]
	v_pk_fma_f32 v[204:205], v[146:147], v[10:11], v[204:205]
	v_pk_fma_f32 v[206:207], v[126:127], v[34:35], v[206:207]
	v_pk_fma_f32 v[204:205], v[144:145], v[4:5], v[204:205]
	v_pk_fma_f32 v[206:207], v[164:165], v[32:33], v[206:207]
	v_pk_fma_f32 v[204:205], v[136:137], v[6:7], v[204:205]
	v_pk_fma_f32 v[206:207], v[168:169], v[18:19], v[206:207]
	v_pk_fma_f32 v[204:205], v[132:133], v[12:13], v[204:205]
	v_pk_fma_f32 v[206:207], v[166:167], v[20:21], v[206:207]
	v_add_f32_e32 v210, v204, v205
	v_pk_mul_f32 v[208:209], v[204:205], v[204:205]
	v_pk_fma_f32 v[206:207], v[162:163], v[24:25], v[206:207]
	v_add_f32_e32 v208, v208, v209
	v_add_f32_dpp v209, v210, v210 quad_perm:[1,0,3,2] row_mask:0xf bank_mask:0xf bound_ctrl:1
	v_pk_fma_f32 v[206:207], v[160:161], v[16:17], v[206:207]
	v_add_f32_dpp v208, v208, v208 quad_perm:[1,0,3,2] row_mask:0xf bank_mask:0xf bound_ctrl:1
	v_add_f32_dpp v209, v209, v209 quad_perm:[2,3,0,1] row_mask:0xf bank_mask:0xf bound_ctrl:1
	v_pk_fma_f32 v[206:207], v[158:159], v[14:15], v[206:207]
	v_add_f32_dpp v208, v208, v208 quad_perm:[2,3,0,1] row_mask:0xf bank_mask:0xf bound_ctrl:1
	v_add_f32_dpp v209, v209, v209 row_half_mirror row_mask:0xf bank_mask:0xf bound_ctrl:1
	global_load_dword v211, v[86:87], off sc1
; #define GAS __attribute__((address_space(1)))
; __device__ __forceinline__ unsigned cvtpk(float lo, float hi) { f32x2 v = {lo, hi}; bf16x2_t b = __builtin_convertvector(v, bf16x2_t); return __builtin_bit_cast(unsigned, b); }
; __device__ __forceinline__ float bflo(unsigned w) { return __uint_as_float(w << 16); }
; __device__ __forceinline__ float bfhi(unsigned w) { return __uint_as_float(w & 0xffff0000u); }
; __device__ __forceinline__ float fsilu(float x) { return x * fsigmoid(x); }
; __device__ __forceinline__ void c_unit(Frame& F, int L, int u, bool dry) {
;     ...
;         for (int i = 0; i < 46; ++i) {
;             const float h0 = bflo(hv[16 * sub + i]), h1 = bfhi(hv[16 * sub + i]);
; #pragma unroll
;             for (int t = 0; t < 16; ++t) { const int j = i - t; if (j >= 0 && j < CONVW) { acc[t].x = fmaf(h0, wv[j].x, acc[t].x); acc[t].y = fmaf(h1, wv[j].y, acc[t].y); } }
;         }
; #pragma unroll
;         for (int t = 0; t < 16; ++t) {
;             float s = acc[t].x + acc[t].y, qq = acc[t].x * acc[t].x + acc[t].y * acc[t].y;
;             s = half_wave_sum(s); qq = half_wave_sum(qq);
;             const float mu = __builtin_ldexpf(s, -6), rstd = rsqrtf(fmaxf(__builtin_ldexpf(qq, -6) - mu * mu, 0.f) + LN_EPS);
;             const float h0 = (acc[t].x - mu) * rstd * gv.x + bv.x, h1 = (acc[t].y - mu) * rstd * gv.y + bv.y;
;             const unsigned ov = cvtpk(fsilu(h0) * bflo(sc[16 * sub + t]), fsilu(h1) * bfhi(sc[16 * sub + t])); if (!dry) *(GAS unsigned*)(SCG + (size_t)(tb + t) * 512) = ov;
;         }
	v_add_f32_dpp v208, v208, v208 row_half_mirror row_mask:0xf bank_mask:0xf bound_ctrl:1
	v_add_f32_dpp v209, v209, v209 row_mirror row_mask:0xf bank_mask:0xf bound_ctrl:1
	v_mov_b32_e32 v210, v209
	s_nop 1
	v_permlane16_swap_b32 v209, v210
	v_add_f32_dpp v208, v208, v208 row_mirror row_mask:0xf bank_mask:0xf bound_ctrl:1
	v_add_f32_e32 v209, v209, v210
	v_mov_b32_e32 v210, v208
	s_nop 1
	v_permlane16_swap_b32 v208, v210
	v_ldexp_f32 v194, v209, -6
	v_add_f32_e32 v208, v208, v210
	v_ldexp_f32 v180, v208, -6
	v_fma_f32 v180, -v194, v194, v180
	v_max_f32_e32 v180, 0, v180
	v_add_f32_e32 v180, 0x3727c5ac, v180
	v_mul_f32_e32 v181, 0x4b800000, v180
	v_cmp_gt_f32_e32 vcc, s0, v180
	v_pk_add_f32 v[194:195], v[204:205], v[194:195] op_sel_hi:[1,0] neg_lo:[0,1] neg_hi:[0,1]
	v_lshlrev_b32_e32 v204, 16, v246
	v_cndmask_b32_e32 v181, v180, v181, vcc
	v_rsq_f32_e32 v208, v181
	global_load_dword v210, v[84:85], off sc1
	v_lshlrev_b32_e32 v180, 16, v239
	v_and_b32_e32 v181, 0xffff0000, v239
	v_mul_f32_e32 v205, 0x45800000, v208
	v_cndmask_b32_e32 v208, v208, v205, vcc
	v_pk_mul_f32 v[194:195], v[194:195], v[208:209] op_sel_hi:[1,0]
	s_nop 0
	v_pk_fma_f32 v[194:195], v[0:1], v[194:195], v[8:9]
	s_nop 0
	v_mul_f32_e32 v205, 0xbfb8aa3b, v194
	v_exp_f32_e32 v208, v205
	v_mul_f32_e32 v205, 0xbfb8aa3b, v195
	v_exp_f32_e32 v209, v205
	v_and_b32_e32 v205, 0xffff0000, v246
	v_add_f32_e32 v208, 1.0, v208
	v_rcp_f32_e32 v246, v208
	v_add_f32_e32 v208, 1.0, v209
	v_rcp_f32_e32 v247, v208
	global_load_dword v209, v[82:83], off sc1
	v_pk_mul_f32 v[194:195], v[194:195], v[246:247]
	s_nop 0
	v_pk_mul_f32 v[194:195], v[194:195], v[204:205]
	v_pk_fma_f32 v[204:205], v[146:147], v[2:3], v[206:207]
	s_nop 0
	v_pk_fma_f32 v[204:205], v[144:145], v[10:11], v[204:205]
	s_nop 0
	v_pk_fma_f32 v[204:205], v[136:137], v[4:5], v[204:205]
	s_nop 0
	v_pk_fma_f32 v[204:205], v[132:133], v[6:7], v[204:205]
	s_nop 0
	v_pk_fma_f32 v[204:205], v[124:125], v[12:13], v[204:205]
	s_nop 0
	v_add_f32_e32 v208, v204, v205
	v_pk_mul_f32 v[206:207], v[204:205], v[204:205]
	s_nop 0
	v_add_f32_e32 v206, v206, v207
	v_add_f32_dpp v207, v208, v208 quad_perm:[1,0,3,2] row_mask:0xf bank_mask:0xf bound_ctrl:1
	s_nop 0
	v_add_f32_dpp v206, v206, v206 quad_perm:[1,0,3,2] row_mask:0xf bank_mask:0xf bound_ctrl:1
	v_add_f32_dpp v207, v207, v207 quad_perm:[2,3,0,1] row_mask:0xf bank_mask:0xf bound_ctrl:1
	s_nop 0
	v_add_f32_dpp v206, v206, v206 quad_perm:[2,3,0,1] row_mask:0xf bank_mask:0xf bound_ctrl:1
	v_add_f32_dpp v207, v207, v207 row_half_mirror row_mask:0xf bank_mask:0xf bound_ctrl:1
	s_nop 0
	v_add_f32_dpp v206, v206, v206 row_half_mirror row_mask:0xf bank_mask:0xf bound_ctrl:1
	v_add_f32_dpp v207, v207, v207 row_mirror row_mask:0xf bank_mask:0xf bound_ctrl:1
	v_mov_b32_e32 v208, v207
	s_nop 1
	v_permlane16_swap_b32 v207, v208
	v_add_f32_dpp v206, v206, v206 row_mirror row_mask:0xf bank_mask:0xf bound_ctrl:1
	v_add_f32_e32 v207, v207, v208
	v_mov_b32_e32 v208, v206
	s_nop 1
	v_permlane16_swap_b32 v206, v208
	s_nop 0
	v_add_f32_e32 v208, v206, v208
	v_ldexp_f32 v206, v207, -6
	v_ldexp_f32 v207, v208, -6
	v_fma_f32 v207, -v206, v206, v207
	v_max_f32_e32 v207, 0, v207
	v_add_f32_e32 v207, 0x3727c5ac, v207
	v_mul_f32_e32 v208, 0x4b800000, v207
	v_cmp_gt_f32_e32 vcc, s0, v207
	s_nop 1
	v_cndmask_b32_e32 v207, v207, v208, vcc
	v_rsq_f32_e32 v207, v207
	global_load_dword v213, v[76:77], off sc1
	global_load_dword v208, v[74:75], off sc1
	v_pk_add_f32 v[204:205], v[204:205], v[206:207] op_sel_hi:[1,0] neg_lo:[0,1] neg_hi:[0,1]
	v_cvt_pk_bf16_f32 v206, v194, v195
	v_mul_f32_e32 v194, 0x45800000, v207
	v_cndmask_b32_e32 v194, v207, v194, vcc
	v_pk_mul_f32 v[194:195], v[204:205], v[194:195] op_sel_hi:[1,0]
	global_store_dword v[178:179], v206, off
	v_pk_fma_f32 v[194:195], v[0:1], v[194:195], v[8:9]
	s_nop 0
	v_mul_f32_e32 v204, 0xbfb8aa3b, v194
	v_mul_f32_e32 v205, 0xbfb8aa3b, v195
	v_exp_f32_e32 v204, v204
	v_exp_f32_e32 v205, v205
	v_add_f32_e32 v178, 1.0, v204
	v_add_f32_e32 v179, 1.0, v205
	v_rcp_f32_e32 v178, v178
	v_rcp_f32_e32 v179, v179
	global_load_dword v207, v[64:65], off sc1
	global_load_dword v206, v[62:63], off sc1
	global_load_dword v204, v[48:49], off sc1
	global_load_dword v205, v[40:41], off sc1
	v_pk_mul_f32 v[194:195], v[194:195], v[178:179]
	v_pk_fma_f32 v[178:179], v[200:201], v[66:67], v[78:79]
	v_pk_fma_f32 v[200:201], v[202:203], v[66:67], v[78:79]
	v_pk_fma_f32 v[178:179], v[198:199], v[68:69], v[178:179]
	v_pk_fma_f32 v[198:199], v[198:199], v[66:67], v[78:79]
	v_pk_fma_f32 v[178:179], v[196:197], v[70:71], v[178:179]
	v_pk_fma_f32 v[198:199], v[196:197], v[68:69], v[198:199]
	v_pk_fma_f32 v[178:179], v[190:191], v[72:73], v[178:179]
	v_pk_fma_f32 v[196:197], v[196:197], v[66:67], v[78:79]
	v_pk_fma_f32 v[178:179], v[188:189], v[36:37], v[178:179]
	v_pk_fma_f32 v[198:199], v[190:191], v[70:71], v[198:199]
	v_pk_fma_f32 v[178:179], v[186:187], v[38:39], v[178:179]
	v_pk_fma_f32 v[196:197], v[190:191], v[68:69], v[196:197]
	v_pk_fma_f32 v[178:179], v[184:185], v[42:43], v[178:179]
	v_pk_fma_f32 v[190:191], v[190:191], v[66:67], v[78:79]
	v_pk_fma_f32 v[178:179], v[182:183], v[60:61], v[178:179]
	v_pk_fma_f32 v[198:199], v[188:189], v[72:73], v[198:199]
	v_pk_fma_f32 v[196:197], v[188:189], v[70:71], v[196:197]
	v_pk_fma_f32 v[190:191], v[188:189], v[68:69], v[190:191]
	v_pk_fma_f32 v[188:189], v[188:189], v[66:67], v[78:79]
	v_pk_fma_f32 v[178:179], v[202:203], v[44:45], v[178:179]
	v_pk_fma_f32 v[196:197], v[186:187], v[72:73], v[196:197]
	v_pk_fma_f32 v[190:191], v[186:187], v[70:71], v[190:191]
	v_pk_fma_f32 v[188:189], v[186:187], v[68:69], v[188:189]
; __device__ __forceinline__ float bflo(unsigned w) { return __uint_as_float(w << 16); }
; __device__ __forceinline__ float bfhi(unsigned w) { return __uint_as_float(w & 0xffff0000u); }
; __device__ __forceinline__ void c_unit(Frame& F, int L, int u, bool dry) {
;     ...
;         for (int i = 0; i < 46; ++i) {
;             const float h0 = bflo(hv[16 * sub + i]), h1 = bfhi(hv[16 * sub + i]);
; #pragma unroll
;             for (int t = 0; t < 16; ++t) { const int j = i - t; if (j >= 0 && j < CONVW) { acc[t].x = fmaf(h0, wv[j].x, acc[t].x); acc[t].y = fmaf(h1, wv[j].y, acc[t].y); } }
;         }
	v_pk_fma_f32 v[198:199], v[186:187], v[36:37], v[198:199]
	v_pk_fma_f32 v[186:187], v[186:187], v[66:67], v[78:79]
	v_pk_fma_f32 v[178:179], v[154:155], v[46:47], v[178:179]
	v_pk_fma_f32 v[190:191], v[184:185], v[72:73], v[190:191]
	v_pk_fma_f32 v[188:189], v[184:185], v[70:71], v[188:189]
	v_pk_fma_f32 v[186:187], v[184:185], v[68:69], v[186:187]
	v_pk_fma_f32 v[198:199], v[184:185], v[38:39], v[198:199]
	v_pk_fma_f32 v[196:197], v[184:185], v[36:37], v[196:197]
	v_pk_fma_f32 v[184:185], v[184:185], v[66:67], v[78:79]
	v_pk_fma_f32 v[178:179], v[152:153], v[54:55], v[178:179]
	v_pk_fma_f32 v[188:189], v[182:183], v[72:73], v[188:189]
	v_pk_fma_f32 v[186:187], v[182:183], v[70:71], v[186:187]
	v_pk_fma_f32 v[184:185], v[182:183], v[68:69], v[184:185]
	v_pk_fma_f32 v[198:199], v[182:183], v[42:43], v[198:199]
	v_pk_fma_f32 v[196:197], v[182:183], v[38:39], v[196:197]
	v_pk_fma_f32 v[190:191], v[182:183], v[36:37], v[190:191]
	v_pk_fma_f32 v[182:183], v[182:183], v[66:67], v[78:79]
	v_pk_fma_f32 v[178:179], v[150:151], v[58:59], v[178:179]
	v_pk_fma_f32 v[182:183], v[202:203], v[68:69], v[182:183]
	v_pk_fma_f32 v[178:179], v[148:149], v[50:51], v[178:179]
	v_pk_fma_f32 v[182:183], v[154:155], v[70:71], v[182:183]
	v_pk_fma_f32 v[178:179], v[142:143], v[52:53], v[178:179]
	v_pk_fma_f32 v[182:183], v[152:153], v[72:73], v[182:183]
	v_pk_fma_f32 v[178:179], v[138:139], v[56:57], v[178:179]
	v_pk_fma_f32 v[182:183], v[150:151], v[36:37], v[182:183]
	v_pk_fma_f32 v[178:179], v[134:135], v[22:23], v[178:179]
	v_pk_fma_f32 v[182:183], v[148:149], v[38:39], v[182:183]
	v_pk_fma_f32 v[178:179], v[130:131], v[26:27], v[178:179]
	v_pk_fma_f32 v[198:199], v[202:203], v[60:61], v[198:199]
	v_pk_fma_f32 v[182:183], v[142:143], v[42:43], v[182:183]
	v_pk_fma_f32 v[178:179], v[128:129], v[28:29], v[178:179]
	v_pk_fma_f32 v[198:199], v[154:155], v[44:45], v[198:199]
	v_pk_fma_f32 v[182:183], v[138:139], v[60:61], v[182:183]
	v_pk_fma_f32 v[178:179], v[126:127], v[30:31], v[178:179]
	v_pk_fma_f32 v[198:199], v[152:153], v[46:47], v[198:199]
	v_pk_fma_f32 v[182:183], v[134:135], v[44:45], v[182:183]
	v_pk_fma_f32 v[178:179], v[164:165], v[34:35], v[178:179]
	v_pk_fma_f32 v[198:199], v[150:151], v[54:55], v[198:199]
	v_pk_fma_f32 v[182:183], v[130:131], v[46:47], v[182:183]
	v_pk_fma_f32 v[178:179], v[168:169], v[32:33], v[178:179]
	v_pk_fma_f32 v[198:199], v[148:149], v[58:59], v[198:199]
	v_pk_fma_f32 v[182:183], v[128:129], v[54:55], v[182:183]
	v_pk_fma_f32 v[178:179], v[166:167], v[18:19], v[178:179]
	v_pk_fma_f32 v[200:201], v[154:155], v[68:69], v[200:201]
	v_pk_fma_f32 v[198:199], v[142:143], v[50:51], v[198:199]
	v_pk_fma_f32 v[182:183], v[126:127], v[58:59], v[182:183]
	v_pk_fma_f32 v[178:179], v[162:163], v[20:21], v[178:179]
	v_pk_fma_f32 v[200:201], v[152:153], v[70:71], v[200:201]
	v_pk_fma_f32 v[198:199], v[138:139], v[52:53], v[198:199]
	v_pk_fma_f32 v[182:183], v[164:165], v[50:51], v[182:183]
	v_pk_fma_f32 v[178:179], v[160:161], v[24:25], v[178:179]
	v_pk_fma_f32 v[200:201], v[150:151], v[72:73], v[200:201]
	v_pk_fma_f32 v[198:199], v[134:135], v[56:57], v[198:199]
	v_pk_fma_f32 v[182:183], v[168:169], v[52:53], v[182:183]
	v_pk_fma_f32 v[178:179], v[158:159], v[16:17], v[178:179]
	v_pk_fma_f32 v[246:247], v[166:167], v[56:57], v[182:183]
	v_pk_fma_f32 v[182:183], v[148:149], v[36:37], v[200:201]
	v_pk_fma_f32 v[200:201], v[146:147], v[14:15], v[178:179]
	v_pk_fma_f32 v[178:179], v[130:131], v[22:23], v[198:199]
	v_pk_fma_f32 v[196:197], v[202:203], v[42:43], v[196:197]
	v_pk_fma_f32 v[178:179], v[128:129], v[26:27], v[178:179]
	v_pk_fma_f32 v[196:197], v[154:155], v[60:61], v[196:197]
	v_pk_fma_f32 v[178:179], v[126:127], v[28:29], v[178:179]
	v_pk_fma_f32 v[196:197], v[152:153], v[44:45], v[196:197]
	v_pk_fma_f32 v[178:179], v[164:165], v[30:31], v[178:179]
	v_pk_fma_f32 v[196:197], v[150:151], v[46:47], v[196:197]
	v_pk_fma_f32 v[178:179], v[168:169], v[34:35], v[178:179]
	v_pk_fma_f32 v[196:197], v[148:149], v[54:55], v[196:197]
	v_pk_fma_f32 v[178:179], v[166:167], v[32:33], v[178:179]
	v_pk_fma_f32 v[196:197], v[142:143], v[58:59], v[196:197]
	v_pk_fma_f32 v[178:179], v[162:163], v[18:19], v[178:179]
	v_pk_fma_f32 v[196:197], v[138:139], v[50:51], v[196:197]
	v_pk_fma_f32 v[178:179], v[160:161], v[20:21], v[178:179]
	v_pk_fma_f32 v[196:197], v[134:135], v[52:53], v[196:197]
	v_pk_fma_f32 v[178:179], v[158:159], v[24:25], v[178:179]
	v_pk_fma_f32 v[196:197], v[130:131], v[56:57], v[196:197]
	v_pk_fma_f32 v[178:179], v[146:147], v[16:17], v[178:179]
	v_pk_fma_f32 v[190:191], v[202:203], v[38:39], v[190:191]
	v_pk_fma_f32 v[198:199], v[144:145], v[14:15], v[178:179]
	v_pk_fma_f32 v[178:179], v[128:129], v[22:23], v[196:197]
	v_pk_fma_f32 v[190:191], v[154:155], v[42:43], v[190:191]
	v_pk_fma_f32 v[178:179], v[126:127], v[26:27], v[178:179]
	v_pk_fma_f32 v[190:191], v[152:153], v[60:61], v[190:191]
	v_pk_fma_f32 v[178:179], v[164:165], v[28:29], v[178:179]
	v_pk_fma_f32 v[190:191], v[150:151], v[44:45], v[190:191]
	v_pk_fma_f32 v[178:179], v[168:169], v[30:31], v[178:179]
	v_pk_fma_f32 v[190:191], v[148:149], v[46:47], v[190:191]
	v_pk_fma_f32 v[178:179], v[166:167], v[34:35], v[178:179]
	v_pk_fma_f32 v[190:191], v[142:143], v[54:55], v[190:191]
	v_pk_fma_f32 v[178:179], v[162:163], v[32:33], v[178:179]
	v_pk_fma_f32 v[190:191], v[138:139], v[58:59], v[190:191]
	v_pk_fma_f32 v[178:179], v[160:161], v[18:19], v[178:179]
	v_pk_fma_f32 v[190:191], v[134:135], v[50:51], v[190:191]
	v_pk_fma_f32 v[178:179], v[158:159], v[20:21], v[178:179]
	v_pk_fma_f32 v[184:185], v[202:203], v[70:71], v[184:185]
	v_pk_fma_f32 v[190:191], v[130:131], v[52:53], v[190:191]
; #define GAS __attribute__((address_space(1)))
; __device__ __forceinline__ unsigned cvtpk(float lo, float hi) { f32x2 v = {lo, hi}; bf16x2_t b = __builtin_convertvector(v, bf16x2_t); return __builtin_bit_cast(unsigned, b); }
; __device__ __forceinline__ float bflo(unsigned w) { return __uint_as_float(w << 16); }
; __device__ __forceinline__ float bfhi(unsigned w) { return __uint_as_float(w & 0xffff0000u); }
; __device__ __forceinline__ float fsilu(float x) { return x * fsigmoid(x); }
; __device__ __forceinline__ void c_unit(Frame& F, int L, int u, bool dry) {
;     ...
;         for (int i = 0; i < 46; ++i) {
;             const float h0 = bflo(hv[16 * sub + i]), h1 = bfhi(hv[16 * sub + i]);
; #pragma unroll
;             for (int t = 0; t < 16; ++t) { const int j = i - t; if (j >= 0 && j < CONVW) { acc[t].x = fmaf(h0, wv[j].x, acc[t].x); acc[t].y = fmaf(h1, wv[j].y, acc[t].y); } }
;         }
; #pragma unroll
;         for (int t = 0; t < 16; ++t) {
;             float s = acc[t].x + acc[t].y, qq = acc[t].x * acc[t].x + acc[t].y * acc[t].y;
;             s = half_wave_sum(s); qq = half_wave_sum(qq);
;             const float mu = __builtin_ldexpf(s, -6), rstd = rsqrtf(fmaxf(__builtin_ldexpf(qq, -6) - mu * mu, 0.f) + LN_EPS);
;             const float h0 = (acc[t].x - mu) * rstd * gv.x + bv.x, h1 = (acc[t].y - mu) * rstd * gv.y + bv.y;
;             const unsigned ov = cvtpk(fsilu(h0) * bflo(sc[16 * sub + t]), fsilu(h1) * bfhi(sc[16 * sub + t])); if (!dry) *(GAS unsigned*)(SCG + (size_t)(tb + t) * 512) = ov;
	v_pk_fma_f32 v[178:179], v[146:147], v[24:25], v[178:179]
	v_pk_fma_f32 v[184:185], v[154:155], v[72:73], v[184:185]
	v_pk_fma_f32 v[188:189], v[202:203], v[36:37], v[188:189]
	v_pk_fma_f32 v[190:191], v[128:129], v[56:57], v[190:191]
	v_pk_fma_f32 v[178:179], v[144:145], v[16:17], v[178:179]
	v_pk_fma_f32 v[188:189], v[154:155], v[38:39], v[188:189]
	v_pk_fma_f32 v[184:185], v[152:153], v[36:37], v[184:185]
	v_pk_fma_f32 v[196:197], v[136:137], v[14:15], v[178:179]
	v_pk_fma_f32 v[178:179], v[126:127], v[22:23], v[190:191]
	v_pk_fma_f32 v[188:189], v[152:153], v[42:43], v[188:189]
	v_pk_fma_f32 v[184:185], v[150:151], v[38:39], v[184:185]
	v_pk_fma_f32 v[178:179], v[164:165], v[26:27], v[178:179]
	v_pk_fma_f32 v[188:189], v[150:151], v[60:61], v[188:189]
	v_pk_fma_f32 v[184:185], v[148:149], v[42:43], v[184:185]
	v_pk_fma_f32 v[178:179], v[168:169], v[28:29], v[178:179]
	v_pk_fma_f32 v[188:189], v[148:149], v[44:45], v[188:189]
	v_pk_fma_f32 v[184:185], v[142:143], v[60:61], v[184:185]
	v_pk_fma_f32 v[178:179], v[166:167], v[30:31], v[178:179]
	v_pk_fma_f32 v[188:189], v[142:143], v[46:47], v[188:189]
	v_pk_fma_f32 v[184:185], v[138:139], v[44:45], v[184:185]
	v_pk_fma_f32 v[178:179], v[162:163], v[34:35], v[178:179]
	v_pk_fma_f32 v[188:189], v[138:139], v[54:55], v[188:189]
	v_pk_fma_f32 v[184:185], v[134:135], v[46:47], v[184:185]
	v_pk_fma_f32 v[178:179], v[160:161], v[32:33], v[178:179]
	v_pk_fma_f32 v[188:189], v[134:135], v[58:59], v[188:189]
	v_pk_fma_f32 v[184:185], v[130:131], v[54:55], v[184:185]
	v_pk_fma_f32 v[178:179], v[158:159], v[18:19], v[178:179]
	v_pk_fma_f32 v[188:189], v[130:131], v[50:51], v[188:189]
	v_pk_fma_f32 v[184:185], v[128:129], v[58:59], v[184:185]
	v_pk_fma_f32 v[178:179], v[146:147], v[20:21], v[178:179]
	v_pk_fma_f32 v[188:189], v[128:129], v[52:53], v[188:189]
	v_pk_fma_f32 v[184:185], v[126:127], v[50:51], v[184:185]
	v_pk_fma_f32 v[178:179], v[144:145], v[24:25], v[178:179]
	v_pk_fma_f32 v[188:189], v[126:127], v[56:57], v[188:189]
	v_pk_fma_f32 v[184:185], v[164:165], v[52:53], v[184:185]
	v_pk_fma_f32 v[178:179], v[136:137], v[16:17], v[178:179]
	v_pk_fma_f32 v[186:187], v[202:203], v[72:73], v[186:187]
	v_pk_fma_f32 v[202:203], v[168:169], v[56:57], v[184:185]
	v_pk_fma_f32 v[184:185], v[132:133], v[14:15], v[178:179]
	v_pk_fma_f32 v[178:179], v[164:165], v[22:23], v[188:189]
	v_pk_mul_f32 v[188:189], v[194:195], v[244:245]
	v_pk_fma_f32 v[186:187], v[154:155], v[36:37], v[186:187]
	v_cvt_pk_bf16_f32 v188, v188, v189
	global_store_dword v[176:177], v188, off
	v_pk_fma_f32 v[176:177], v[144:145], v[2:3], v[200:201]
	v_pk_fma_f32 v[186:187], v[152:153], v[38:39], v[186:187]
	v_pk_fma_f32 v[176:177], v[136:137], v[10:11], v[176:177]
	v_pk_fma_f32 v[186:187], v[150:151], v[42:43], v[186:187]
	v_pk_fma_f32 v[176:177], v[132:133], v[4:5], v[176:177]
	v_pk_fma_f32 v[186:187], v[148:149], v[60:61], v[186:187]
	v_pk_fma_f32 v[176:177], v[124:125], v[6:7], v[176:177]
	v_pk_fma_f32 v[186:187], v[142:143], v[44:45], v[186:187]
	v_pk_fma_f32 v[176:177], v[118:119], v[12:13], v[176:177]
	v_pk_fma_f32 v[186:187], v[138:139], v[46:47], v[186:187]
	v_add_f32_e32 v194, v176, v177
	v_pk_mul_f32 v[190:191], v[176:177], v[176:177]
	v_pk_fma_f32 v[186:187], v[134:135], v[54:55], v[186:187]
	v_add_f32_e32 v190, v190, v191
	v_add_f32_dpp v191, v194, v194 quad_perm:[1,0,3,2] row_mask:0xf bank_mask:0xf bound_ctrl:1
	v_pk_fma_f32 v[186:187], v[130:131], v[58:59], v[186:187]
	v_add_f32_dpp v190, v190, v190 quad_perm:[1,0,3,2] row_mask:0xf bank_mask:0xf bound_ctrl:1
	v_add_f32_dpp v191, v191, v191 quad_perm:[2,3,0,1] row_mask:0xf bank_mask:0xf bound_ctrl:1
	v_pk_fma_f32 v[186:187], v[128:129], v[50:51], v[186:187]
	v_add_f32_dpp v190, v190, v190 quad_perm:[2,3,0,1] row_mask:0xf bank_mask:0xf bound_ctrl:1
	v_add_f32_dpp v191, v191, v191 row_half_mirror row_mask:0xf bank_mask:0xf bound_ctrl:1
	v_pk_fma_f32 v[186:187], v[126:127], v[52:53], v[186:187]
	v_add_f32_dpp v190, v190, v190 row_half_mirror row_mask:0xf bank_mask:0xf bound_ctrl:1
	v_add_f32_dpp v191, v191, v191 row_mirror row_mask:0xf bank_mask:0xf bound_ctrl:1
	v_mov_b32_e32 v194, v191
	s_nop 1
	v_permlane16_swap_b32 v191, v194
	v_add_f32_dpp v190, v190, v190 row_mirror row_mask:0xf bank_mask:0xf bound_ctrl:1
	v_add_f32_e32 v191, v191, v194
	v_mov_b32_e32 v194, v190
	s_nop 1
	v_permlane16_swap_b32 v190, v194
	v_pk_fma_f32 v[186:187], v[164:165], v[56:57], v[186:187]
	v_add_f32_e32 v194, v190, v194
	v_ldexp_f32 v190, v191, -6
	v_ldexp_f32 v191, v194, -6
	v_fma_f32 v191, -v190, v190, v191
	v_max_f32_e32 v191, 0, v191
	v_add_f32_e32 v191, 0x3727c5ac, v191
	v_mul_f32_e32 v194, 0x4b800000, v191
	v_cmp_gt_f32_e32 vcc, s0, v191
	v_pk_fma_f32 v[186:187], v[168:169], v[22:23], v[186:187]
	s_waitcnt vmcnt(29)
; #define GAS __attribute__((address_space(1)))
; __device__ __forceinline__ unsigned cvtpk(float lo, float hi) { f32x2 v = {lo, hi}; bf16x2_t b = __builtin_convertvector(v, bf16x2_t); return __builtin_bit_cast(unsigned, b); }
; __device__ __forceinline__ float bflo(unsigned w) { return __uint_as_float(w << 16); }
; __device__ __forceinline__ float bfhi(unsigned w) { return __uint_as_float(w & 0xffff0000u); }
; __device__ __forceinline__ float fsilu(float x) { return x * fsigmoid(x); }
; __device__ __forceinline__ void c_unit(Frame& F, int L, int u, bool dry) {
;     ...
;         for (int i = 0; i < 46; ++i) {
;             const float h0 = bflo(hv[16 * sub + i]), h1 = bfhi(hv[16 * sub + i]);
; #pragma unroll
;             for (int t = 0; t < 16; ++t) { const int j = i - t; if (j >= 0 && j < CONVW) { acc[t].x = fmaf(h0, wv[j].x, acc[t].x); acc[t].y = fmaf(h1, wv[j].y, acc[t].y); } }
;         }
; #pragma unroll
;         for (int t = 0; t < 16; ++t) {
;             float s = acc[t].x + acc[t].y, qq = acc[t].x * acc[t].x + acc[t].y * acc[t].y;
;             s = half_wave_sum(s); qq = half_wave_sum(qq);
;             const float mu = __builtin_ldexpf(s, -6), rstd = rsqrtf(fmaxf(__builtin_ldexpf(qq, -6) - mu * mu, 0.f) + LN_EPS);
;             const float h0 = (acc[t].x - mu) * rstd * gv.x + bv.x, h1 = (acc[t].y - mu) * rstd * gv.y + bv.y;
;             const unsigned ov = cvtpk(fsilu(h0) * bflo(sc[16 * sub + t]), fsilu(h1) * bfhi(sc[16 * sub + t])); if (!dry) *(GAS unsigned*)(SCG + (size_t)(tb + t) * 512) = ov;
	v_lshlrev_b32_e32 v188, 16, v240
	v_cndmask_b32_e32 v191, v191, v194, vcc
	v_rsq_f32_e32 v191, v191
	v_pk_fma_f32 v[186:187], v[166:167], v[26:27], v[186:187]
	v_and_b32_e32 v189, 0xffff0000, v240
	v_pk_fma_f32 v[186:187], v[162:163], v[28:29], v[186:187]
	v_mul_f32_e32 v194, 0x45800000, v191
	v_cndmask_b32_e32 v194, v191, v194, vcc
	v_pk_add_f32 v[176:177], v[176:177], v[190:191] op_sel_hi:[1,0] neg_lo:[0,1] neg_hi:[0,1]
	v_pk_fma_f32 v[186:187], v[160:161], v[30:31], v[186:187]
	v_pk_mul_f32 v[176:177], v[176:177], v[194:195] op_sel_hi:[1,0]
	v_pk_fma_f32 v[186:187], v[158:159], v[34:35], v[186:187]
	v_pk_fma_f32 v[190:191], v[0:1], v[176:177], v[8:9]
	v_pk_fma_f32 v[186:187], v[146:147], v[32:33], v[186:187]
	v_mul_f32_e32 v176, 0xbfb8aa3b, v190
	v_exp_f32_e32 v194, v176
	v_mul_f32_e32 v176, 0xbfb8aa3b, v191
	v_exp_f32_e32 v195, v176
	v_pk_fma_f32 v[186:187], v[144:145], v[18:19], v[186:187]
	v_pk_fma_f32 v[184:185], v[124:125], v[2:3], v[184:185]
	v_pk_fma_f32 v[176:177], v[136:137], v[20:21], v[186:187]
	v_add_f32_e32 v186, 1.0, v194
	v_add_f32_e32 v187, 1.0, v195
	v_rcp_f32_e32 v186, v186
	v_rcp_f32_e32 v187, v187
	v_pk_fma_f32 v[184:185], v[118:119], v[10:11], v[184:185]
	v_pk_fma_f32 v[178:179], v[168:169], v[26:27], v[178:179]
	v_pk_fma_f32 v[184:185], v[112:113], v[4:5], v[184:185]
	v_pk_mul_f32 v[186:187], v[190:191], v[186:187]
	v_pk_fma_f32 v[184:185], v[110:111], v[6:7], v[184:185]
	v_pk_mul_f32 v[186:187], v[186:187], v[188:189]
	v_pk_fma_f32 v[188:189], v[166:167], v[22:23], v[202:203]
	v_cvt_pk_bf16_f32 v186, v186, v187
	global_store_dword v[174:175], v186, off
	v_pk_fma_f32 v[174:175], v[136:137], v[2:3], v[198:199]
	v_pk_fma_f32 v[188:189], v[162:163], v[26:27], v[188:189]
	v_pk_fma_f32 v[174:175], v[132:133], v[10:11], v[174:175]
	v_pk_fma_f32 v[188:189], v[160:161], v[28:29], v[188:189]
	v_pk_fma_f32 v[174:175], v[124:125], v[4:5], v[174:175]
	v_pk_fma_f32 v[188:189], v[158:159], v[30:31], v[188:189]
	v_pk_fma_f32 v[174:175], v[118:119], v[6:7], v[174:175]
	v_pk_fma_f32 v[188:189], v[146:147], v[34:35], v[188:189]
	v_pk_fma_f32 v[174:175], v[112:113], v[12:13], v[174:175]
	v_pk_fma_f32 v[188:189], v[144:145], v[32:33], v[188:189]
	v_add_f32_e32 v194, v174, v175
	v_pk_mul_f32 v[190:191], v[174:175], v[174:175]
	v_pk_fma_f32 v[188:189], v[136:137], v[18:19], v[188:189]
	v_add_f32_e32 v190, v190, v191
	v_add_f32_dpp v191, v194, v194 quad_perm:[1,0,3,2] row_mask:0xf bank_mask:0xf bound_ctrl:1
	s_waitcnt vmcnt(29)
	v_lshlrev_b32_e32 v186, 16, v251
	v_add_f32_dpp v190, v190, v190 quad_perm:[1,0,3,2] row_mask:0xf bank_mask:0xf bound_ctrl:1
	v_add_f32_dpp v191, v191, v191 quad_perm:[2,3,0,1] row_mask:0xf bank_mask:0xf bound_ctrl:1
	v_and_b32_e32 v187, 0xffff0000, v251
	v_add_f32_dpp v190, v190, v190 quad_perm:[2,3,0,1] row_mask:0xf bank_mask:0xf bound_ctrl:1
	v_add_f32_dpp v191, v191, v191 row_half_mirror row_mask:0xf bank_mask:0xf bound_ctrl:1
	v_pk_fma_f32 v[184:185], v[108:109], v[12:13], v[184:185]
	v_add_f32_dpp v190, v190, v190 row_half_mirror row_mask:0xf bank_mask:0xf bound_ctrl:1
	v_add_f32_dpp v191, v191, v191 row_mirror row_mask:0xf bank_mask:0xf bound_ctrl:1
	v_mov_b32_e32 v194, v191
	s_nop 1
	v_permlane16_swap_b32 v191, v194
	v_add_f32_dpp v190, v190, v190 row_mirror row_mask:0xf bank_mask:0xf bound_ctrl:1
	v_add_f32_e32 v191, v191, v194
	v_mov_b32_e32 v194, v190
	s_nop 1
	v_permlane16_swap_b32 v190, v194
	v_pk_fma_f32 v[178:179], v[166:167], v[28:29], v[178:179]
	v_add_f32_e32 v194, v190, v194
	v_ldexp_f32 v190, v191, -6
	v_ldexp_f32 v191, v194, -6
	v_fma_f32 v191, -v190, v190, v191
	v_max_f32_e32 v191, 0, v191
	v_add_f32_e32 v191, 0x3727c5ac, v191
	v_mul_f32_e32 v194, 0x4b800000, v191
	v_cmp_gt_f32_e32 vcc, s0, v191
	v_pk_fma_f32 v[178:179], v[162:163], v[30:31], v[178:179]
	v_pk_fma_f32 v[176:177], v[132:133], v[24:25], v[176:177]
	v_cndmask_b32_e32 v191, v191, v194, vcc
	v_rsq_f32_e32 v191, v191
	v_pk_fma_f32 v[178:179], v[160:161], v[34:35], v[178:179]
	v_pk_fma_f32 v[176:177], v[124:125], v[16:17], v[176:177]
	v_pk_fma_f32 v[178:179], v[158:159], v[32:33], v[178:179]
	v_mul_f32_e32 v194, 0x45800000, v191
	v_cndmask_b32_e32 v194, v191, v194, vcc
	v_pk_add_f32 v[174:175], v[174:175], v[190:191] op_sel_hi:[1,0] neg_lo:[0,1] neg_hi:[0,1]
	v_pk_fma_f32 v[178:179], v[146:147], v[18:19], v[178:179]
	v_pk_mul_f32 v[174:175], v[174:175], v[194:195] op_sel_hi:[1,0]
	v_pk_fma_f32 v[178:179], v[144:145], v[20:21], v[178:179]
	v_pk_fma_f32 v[190:191], v[0:1], v[174:175], v[8:9]
	v_pk_fma_f32 v[178:179], v[136:137], v[24:25], v[178:179]
	v_mul_f32_e32 v174, 0xbfb8aa3b, v190
	v_exp_f32_e32 v194, v174
	v_mul_f32_e32 v174, 0xbfb8aa3b, v191
	v_exp_f32_e32 v195, v174
	v_pk_fma_f32 v[174:175], v[132:133], v[20:21], v[188:189]
	v_add_f32_e32 v188, 1.0, v194
	v_rcp_f32_e32 v188, v188
	v_add_f32_e32 v189, 1.0, v195
	v_rcp_f32_e32 v189, v189
	v_pk_fma_f32 v[178:179], v[132:133], v[16:17], v[178:179]
	v_pk_fma_f32 v[176:177], v[118:119], v[14:15], v[176:177]
	v_pk_fma_f32 v[178:179], v[124:125], v[14:15], v[178:179]
	v_pk_mul_f32 v[188:189], v[190:191], v[188:189]
	v_pk_fma_f32 v[178:179], v[118:119], v[2:3], v[178:179]
	v_pk_mul_f32 v[186:187], v[188:189], v[186:187]
	v_pk_fma_f32 v[188:189], v[162:163], v[22:23], v[246:247]
	v_cvt_pk_bf16_f32 v186, v186, v187
	global_store_dword v[172:173], v186, off
	v_pk_fma_f32 v[172:173], v[132:133], v[2:3], v[196:197]
	v_pk_fma_f32 v[188:189], v[160:161], v[26:27], v[188:189]
	v_pk_fma_f32 v[172:173], v[124:125], v[10:11], v[172:173]
	v_pk_fma_f32 v[188:189], v[158:159], v[28:29], v[188:189]
	v_pk_fma_f32 v[172:173], v[118:119], v[4:5], v[172:173]
	v_pk_fma_f32 v[188:189], v[146:147], v[30:31], v[188:189]
	v_pk_fma_f32 v[172:173], v[112:113], v[6:7], v[172:173]
	v_pk_fma_f32 v[188:189], v[144:145], v[34:35], v[188:189]
	v_pk_fma_f32 v[172:173], v[110:111], v[12:13], v[172:173]
	v_pk_fma_f32 v[188:189], v[136:137], v[32:33], v[188:189]
	v_add_f32_e32 v194, v172, v173
	v_pk_mul_f32 v[190:191], v[172:173], v[172:173]
	v_pk_fma_f32 v[188:189], v[132:133], v[18:19], v[188:189]
	v_add_f32_e32 v190, v190, v191
	v_add_f32_dpp v191, v194, v194 quad_perm:[1,0,3,2] row_mask:0xf bank_mask:0xf bound_ctrl:1
	s_waitcnt vmcnt(29)
; #define GAS __attribute__((address_space(1)))
; __device__ __forceinline__ unsigned cvtpk(float lo, float hi) { f32x2 v = {lo, hi}; bf16x2_t b = __builtin_convertvector(v, bf16x2_t); return __builtin_bit_cast(unsigned, b); }
; __device__ __forceinline__ float bflo(unsigned w) { return __uint_as_float(w << 16); }
; __device__ __forceinline__ float bfhi(unsigned w) { return __uint_as_float(w & 0xffff0000u); }
; __device__ __forceinline__ float fsilu(float x) { return x * fsigmoid(x); }
; __device__ __forceinline__ void c_unit(Frame& F, int L, int u, bool dry) {
;     ...
;         for (int i = 0; i < 46; ++i) {
;             const float h0 = bflo(hv[16 * sub + i]), h1 = bfhi(hv[16 * sub + i]);
; #pragma unroll
;             for (int t = 0; t < 16; ++t) { const int j = i - t; if (j >= 0 && j < CONVW) { acc[t].x = fmaf(h0, wv[j].x, acc[t].x); acc[t].y = fmaf(h1, wv[j].y, acc[t].y); } }
;         }
; #pragma unroll
;         for (int t = 0; t < 16; ++t) {
;             float s = acc[t].x + acc[t].y, qq = acc[t].x * acc[t].x + acc[t].y * acc[t].y;
;             s = half_wave_sum(s); qq = half_wave_sum(qq);
;             const float mu = __builtin_ldexpf(s, -6), rstd = rsqrtf(fmaxf(__builtin_ldexpf(qq, -6) - mu * mu, 0.f) + LN_EPS);
;             const float h0 = (acc[t].x - mu) * rstd * gv.x + bv.x, h1 = (acc[t].y - mu) * rstd * gv.y + bv.y;
;             const unsigned ov = cvtpk(fsilu(h0) * bflo(sc[16 * sub + t]), fsilu(h1) * bfhi(sc[16 * sub + t])); if (!dry) *(GAS unsigned*)(SCG + (size_t)(tb + t) * 512) = ov;
	v_lshlrev_b32_e32 v186, 16, v242
	v_add_f32_dpp v190, v190, v190 quad_perm:[1,0,3,2] row_mask:0xf bank_mask:0xf bound_ctrl:1
	v_add_f32_dpp v191, v191, v191 quad_perm:[2,3,0,1] row_mask:0xf bank_mask:0xf bound_ctrl:1
	v_and_b32_e32 v187, 0xffff0000, v242
	v_add_f32_dpp v190, v190, v190 quad_perm:[2,3,0,1] row_mask:0xf bank_mask:0xf bound_ctrl:1
	v_add_f32_dpp v191, v191, v191 row_half_mirror row_mask:0xf bank_mask:0xf bound_ctrl:1
	v_pk_fma_f32 v[178:179], v[112:113], v[10:11], v[178:179]
	v_add_f32_dpp v190, v190, v190 row_half_mirror row_mask:0xf bank_mask:0xf bound_ctrl:1
	v_add_f32_dpp v191, v191, v191 row_mirror row_mask:0xf bank_mask:0xf bound_ctrl:1
	v_mov_b32_e32 v194, v191
	s_nop 1
	v_permlane16_swap_b32 v191, v194
	v_add_f32_dpp v190, v190, v190 row_mirror row_mask:0xf bank_mask:0xf bound_ctrl:1
	v_add_f32_e32 v191, v191, v194
	v_mov_b32_e32 v194, v190
	s_nop 1
	v_permlane16_swap_b32 v190, v194
	v_pk_fma_f32 v[178:179], v[110:111], v[4:5], v[178:179]
	v_add_f32_e32 v194, v190, v194
	v_ldexp_f32 v190, v191, -6
	v_ldexp_f32 v191, v194, -6
	v_fma_f32 v191, -v190, v190, v191
	v_max_f32_e32 v191, 0, v191
	v_add_f32_e32 v191, 0x3727c5ac, v191
	v_mul_f32_e32 v194, 0x4b800000, v191
	v_cmp_gt_f32_e32 vcc, s0, v191
	v_pk_fma_f32 v[178:179], v[108:109], v[6:7], v[178:179]
	v_pk_fma_f32 v[176:177], v[112:113], v[2:3], v[176:177]
	v_cndmask_b32_e32 v191, v191, v194, vcc
	v_rsq_f32_e32 v191, v191
	v_pk_fma_f32 v[178:179], v[102:103], v[12:13], v[178:179]
	v_pk_fma_f32 v[176:177], v[110:111], v[10:11], v[176:177]
	v_pk_fma_f32 v[174:175], v[124:125], v[24:25], v[174:175]
	v_mul_f32_e32 v194, 0x45800000, v191
	v_cndmask_b32_e32 v194, v191, v194, vcc
	v_pk_add_f32 v[172:173], v[172:173], v[190:191] op_sel_hi:[1,0] neg_lo:[0,1] neg_hi:[0,1]
	v_pk_fma_f32 v[176:177], v[108:109], v[4:5], v[176:177]
	v_pk_mul_f32 v[172:173], v[172:173], v[194:195] op_sel_hi:[1,0]
	v_pk_fma_f32 v[176:177], v[102:103], v[6:7], v[176:177]
	v_pk_fma_f32 v[190:191], v[0:1], v[172:173], v[8:9]
	v_pk_fma_f32 v[176:177], v[106:107], v[12:13], v[176:177]
	v_mul_f32_e32 v172, 0xbfb8aa3b, v190
	v_exp_f32_e32 v194, v172
	v_mul_f32_e32 v172, 0xbfb8aa3b, v191
	v_exp_f32_e32 v195, v172
	v_pk_fma_f32 v[172:173], v[124:125], v[20:21], v[188:189]
	v_add_f32_e32 v188, 1.0, v194
	v_rcp_f32_e32 v188, v188
	v_add_f32_e32 v189, 1.0, v195
	v_rcp_f32_e32 v189, v189
	v_pk_fma_f32 v[174:175], v[118:119], v[16:17], v[174:175]
	v_pk_fma_f32 v[172:173], v[118:119], v[24:25], v[172:173]
	v_pk_fma_f32 v[174:175], v[112:113], v[14:15], v[174:175]
	v_pk_mul_f32 v[188:189], v[190:191], v[188:189]
	v_add_f32_e32 v190, v178, v179
	v_pk_mul_f32 v[186:187], v[188:189], v[186:187]
	v_add_f32_e32 v188, v184, v185
	v_cvt_pk_bf16_f32 v186, v186, v187
	global_store_dword v[170:171], v186, off
	v_pk_mul_f32 v[186:187], v[184:185], v[184:185]
	s_waitcnt vmcnt(29)
	v_lshlrev_b32_e32 v170, 16, v243
	v_add_f32_e32 v186, v186, v187
	v_add_f32_dpp v187, v188, v188 quad_perm:[1,0,3,2] row_mask:0xf bank_mask:0xf bound_ctrl:1
	v_and_b32_e32 v171, 0xffff0000, v243
	v_add_f32_dpp v186, v186, v186 quad_perm:[1,0,3,2] row_mask:0xf bank_mask:0xf bound_ctrl:1
	v_add_f32_dpp v187, v187, v187 quad_perm:[2,3,0,1] row_mask:0xf bank_mask:0xf bound_ctrl:1
	v_pk_fma_f32 v[174:175], v[110:111], v[2:3], v[174:175]
	v_add_f32_dpp v186, v186, v186 quad_perm:[2,3,0,1] row_mask:0xf bank_mask:0xf bound_ctrl:1
	v_add_f32_dpp v187, v187, v187 row_half_mirror row_mask:0xf bank_mask:0xf bound_ctrl:1
	v_pk_fma_f32 v[174:175], v[108:109], v[10:11], v[174:175]
	v_add_f32_dpp v186, v186, v186 row_half_mirror row_mask:0xf bank_mask:0xf bound_ctrl:1
	v_add_f32_dpp v187, v187, v187 row_mirror row_mask:0xf bank_mask:0xf bound_ctrl:1
	v_mov_b32_e32 v188, v187
	s_nop 1
	v_permlane16_swap_b32 v187, v188
	v_add_f32_dpp v186, v186, v186 row_mirror row_mask:0xf bank_mask:0xf bound_ctrl:1
	v_add_f32_e32 v187, v187, v188
	v_mov_b32_e32 v188, v186
	s_nop 1
	v_permlane16_swap_b32 v186, v188
	v_pk_fma_f32 v[174:175], v[102:103], v[4:5], v[174:175]
	v_add_f32_e32 v188, v186, v188
	v_ldexp_f32 v186, v187, -6
	v_ldexp_f32 v187, v188, -6
	v_fma_f32 v187, -v186, v186, v187
	v_max_f32_e32 v187, 0, v187
	v_add_f32_e32 v187, 0x3727c5ac, v187
	v_mul_f32_e32 v188, 0x4b800000, v187
	v_cmp_gt_f32_e32 vcc, s0, v187
	v_pk_fma_f32 v[174:175], v[106:107], v[6:7], v[174:175]
	v_pk_fma_f32 v[172:173], v[112:113], v[16:17], v[172:173]
	v_cndmask_b32_e32 v187, v187, v188, vcc
	v_rsq_f32_e32 v187, v187
	v_pk_fma_f32 v[174:175], v[104:105], v[12:13], v[174:175]
	v_pk_fma_f32 v[172:173], v[110:111], v[14:15], v[172:173]
	v_pk_fma_f32 v[182:183], v[142:143], v[38:39], v[182:183]
	v_mul_f32_e32 v188, 0x45800000, v187
	v_cndmask_b32_e32 v188, v187, v188, vcc
	v_pk_add_f32 v[184:185], v[184:185], v[186:187] op_sel_hi:[1,0] neg_lo:[0,1] neg_hi:[0,1]
	v_pk_fma_f32 v[182:183], v[138:139], v[42:43], v[182:183]
	v_pk_mul_f32 v[184:185], v[184:185], v[188:189] op_sel_hi:[1,0]
	v_pk_mul_f32 v[188:189], v[178:179], v[178:179]
	v_pk_fma_f32 v[184:185], v[0:1], v[184:185], v[8:9]
	v_add_f32_e32 v188, v188, v189
	v_add_f32_dpp v189, v190, v190 quad_perm:[1,0,3,2] row_mask:0xf bank_mask:0xf bound_ctrl:1
	v_mul_f32_e32 v186, 0xbfb8aa3b, v184
	v_add_f32_dpp v188, v188, v188 quad_perm:[1,0,3,2] row_mask:0xf bank_mask:0xf bound_ctrl:1
	v_add_f32_dpp v189, v189, v189 quad_perm:[2,3,0,1] row_mask:0xf bank_mask:0xf bound_ctrl:1
	v_mul_f32_e32 v187, 0xbfb8aa3b, v185
	v_add_f32_dpp v188, v188, v188 quad_perm:[2,3,0,1] row_mask:0xf bank_mask:0xf bound_ctrl:1
	v_add_f32_dpp v189, v189, v189 row_half_mirror row_mask:0xf bank_mask:0xf bound_ctrl:1
	v_exp_f32_e32 v186, v186
; #define GAS __attribute__((address_space(1)))
; __device__ __forceinline__ unsigned cvtpk(float lo, float hi) { f32x2 v = {lo, hi}; bf16x2_t b = __builtin_convertvector(v, bf16x2_t); return __builtin_bit_cast(unsigned, b); }
; __device__ __forceinline__ float bflo(unsigned w) { return __uint_as_float(w << 16); }
; __device__ __forceinline__ float bfhi(unsigned w) { return __uint_as_float(w & 0xffff0000u); }
; __device__ __forceinline__ float fsilu(float x) { return x * fsigmoid(x); }
; __device__ __forceinline__ void c_unit(Frame& F, int L, int u, bool dry) {
;     ...
;         for (int i = 0; i < 46; ++i) {
;             const float h0 = bflo(hv[16 * sub + i]), h1 = bfhi(hv[16 * sub + i]);
; #pragma unroll
;             for (int t = 0; t < 16; ++t) { const int j = i - t; if (j >= 0 && j < CONVW) { acc[t].x = fmaf(h0, wv[j].x, acc[t].x); acc[t].y = fmaf(h1, wv[j].y, acc[t].y); } }
;         }
; #pragma unroll
;         for (int t = 0; t < 16; ++t) {
;             float s = acc[t].x + acc[t].y, qq = acc[t].x * acc[t].x + acc[t].y * acc[t].y;
;             s = half_wave_sum(s); qq = half_wave_sum(qq);
;             const float mu = __builtin_ldexpf(s, -6), rstd = rsqrtf(fmaxf(__builtin_ldexpf(qq, -6) - mu * mu, 0.f) + LN_EPS);
;             const float h0 = (acc[t].x - mu) * rstd * gv.x + bv.x, h1 = (acc[t].y - mu) * rstd * gv.y + bv.y;
;             const unsigned ov = cvtpk(fsilu(h0) * bflo(sc[16 * sub + t]), fsilu(h1) * bfhi(sc[16 * sub + t])); if (!dry) *(GAS unsigned*)(SCG + (size_t)(tb + t) * 512) = ov;
	v_add_f32_dpp v188, v188, v188 row_half_mirror row_mask:0xf bank_mask:0xf bound_ctrl:1
	v_add_f32_dpp v189, v189, v189 row_mirror row_mask:0xf bank_mask:0xf bound_ctrl:1
	v_mov_b32_e32 v190, v189
	s_nop 1
	v_permlane16_swap_b32 v189, v190
	v_add_f32_dpp v188, v188, v188 row_mirror row_mask:0xf bank_mask:0xf bound_ctrl:1
	v_add_f32_e32 v189, v189, v190
	v_mov_b32_e32 v190, v188
	s_nop 1
	v_permlane16_swap_b32 v188, v190
	v_exp_f32_e32 v187, v187
	v_add_f32_e32 v190, v188, v190
	v_ldexp_f32 v188, v189, -6
	v_ldexp_f32 v189, v190, -6
	v_fma_f32 v189, -v188, v188, v189
	v_max_f32_e32 v189, 0, v189
	v_add_f32_e32 v189, 0x3727c5ac, v189
	v_add_f32_e32 v186, 1.0, v186
	v_add_f32_e32 v187, 1.0, v187
	v_mul_f32_e32 v190, 0x4b800000, v189
	v_cmp_gt_f32_e32 vcc, s0, v189
	v_rcp_f32_e32 v186, v186
	v_rcp_f32_e32 v187, v187
	v_cndmask_b32_e32 v189, v189, v190, vcc
	v_rsq_f32_e32 v189, v189
	v_pk_fma_f32 v[182:183], v[134:135], v[60:61], v[182:183]
	v_pk_mul_f32 v[184:185], v[184:185], v[186:187]
	v_pk_fma_f32 v[182:183], v[130:131], v[44:45], v[182:183]
	v_pk_mul_f32 v[170:171], v[184:185], v[170:171]
	v_mul_f32_e32 v184, 0x45800000, v189
	v_cndmask_b32_e32 v184, v189, v184, vcc
	v_pk_add_f32 v[178:179], v[178:179], v[188:189] op_sel_hi:[1,0] neg_lo:[0,1] neg_hi:[0,1]
	v_cvt_pk_bf16_f32 v186, v170, v171
	v_pk_mul_f32 v[178:179], v[178:179], v[184:185] op_sel_hi:[1,0]
	global_store_dword v[156:157], v186, off
	v_pk_fma_f32 v[178:179], v[0:1], v[178:179], v[8:9]
	s_waitcnt vmcnt(29)
	v_lshlrev_b32_e32 v156, 16, v241
	v_mul_f32_e32 v184, 0xbfb8aa3b, v178
	v_mul_f32_e32 v185, 0xbfb8aa3b, v179
	v_exp_f32_e32 v184, v184
	v_exp_f32_e32 v185, v185
	v_and_b32_e32 v157, 0xffff0000, v241
	v_pk_fma_f32 v[182:183], v[128:129], v[46:47], v[182:183]
	v_add_f32_e32 v170, 1.0, v184
	v_add_f32_e32 v171, 1.0, v185
	v_rcp_f32_e32 v170, v170
	v_rcp_f32_e32 v171, v171
	v_add_f32_e32 v184, v176, v177
	v_pk_fma_f32 v[182:183], v[126:127], v[54:55], v[182:183]
	v_pk_mul_f32 v[170:171], v[178:179], v[170:171]
	v_pk_mul_f32 v[178:179], v[176:177], v[176:177]
	v_pk_mul_f32 v[156:157], v[170:171], v[156:157]
	v_add_f32_e32 v178, v178, v179
	v_add_f32_dpp v179, v184, v184 quad_perm:[1,0,3,2] row_mask:0xf bank_mask:0xf bound_ctrl:1
	v_cvt_pk_bf16_f32 v156, v156, v157
	v_add_f32_dpp v178, v178, v178 quad_perm:[1,0,3,2] row_mask:0xf bank_mask:0xf bound_ctrl:1
	v_add_f32_dpp v179, v179, v179 quad_perm:[2,3,0,1] row_mask:0xf bank_mask:0xf bound_ctrl:1
	global_store_dword v[140:141], v156, off
	v_add_f32_dpp v178, v178, v178 quad_perm:[2,3,0,1] row_mask:0xf bank_mask:0xf bound_ctrl:1
	v_add_f32_dpp v179, v179, v179 row_half_mirror row_mask:0xf bank_mask:0xf bound_ctrl:1
	v_pk_fma_f32 v[182:183], v[164:165], v[58:59], v[182:183]
	v_add_f32_dpp v178, v178, v178 row_half_mirror row_mask:0xf bank_mask:0xf bound_ctrl:1
	v_add_f32_dpp v179, v179, v179 row_mirror row_mask:0xf bank_mask:0xf bound_ctrl:1
	v_mov_b32_e32 v184, v179
	s_nop 1
	v_permlane16_swap_b32 v179, v184
	v_add_f32_dpp v178, v178, v178 row_mirror row_mask:0xf bank_mask:0xf bound_ctrl:1
	v_add_f32_e32 v179, v179, v184
	v_mov_b32_e32 v184, v178
	s_nop 1
	v_permlane16_swap_b32 v178, v184
	v_pk_fma_f32 v[182:183], v[168:169], v[50:51], v[182:183]
	v_add_f32_e32 v184, v178, v184
	v_ldexp_f32 v178, v179, -6
	v_ldexp_f32 v179, v184, -6
	v_fma_f32 v179, -v178, v178, v179
	v_max_f32_e32 v179, 0, v179
	v_add_f32_e32 v179, 0x3727c5ac, v179
	v_mul_f32_e32 v184, 0x4b800000, v179
	v_cmp_gt_f32_e32 vcc, s0, v179
	v_pk_fma_f32 v[182:183], v[166:167], v[52:53], v[182:183]
	s_nop 0
	v_cndmask_b32_e32 v179, v179, v184, vcc
	v_rsq_f32_e32 v179, v179
	v_pk_fma_f32 v[182:183], v[162:163], v[56:57], v[182:183]
	v_mul_f32_e32 v140, 0x45800000, v179
	v_cndmask_b32_e32 v140, v179, v140, vcc
	v_pk_add_f32 v[156:157], v[176:177], v[178:179] op_sel_hi:[1,0] neg_lo:[0,1] neg_hi:[0,1]
	v_pk_mul_f32 v[176:177], v[174:175], v[174:175]
	v_pk_mul_f32 v[140:141], v[156:157], v[140:141] op_sel_hi:[1,0]
	v_add_f32_e32 v176, v176, v177
	v_pk_fma_f32 v[140:141], v[0:1], v[140:141], v[8:9]
	v_pk_fma_f32 v[182:183], v[160:161], v[22:23], v[182:183]
	v_mul_f32_e32 v156, 0xbfb8aa3b, v140
	v_exp_f32_e32 v157, v156
	v_mul_f32_e32 v156, 0xbfb8aa3b, v141
	v_exp_f32_e32 v171, v156
	v_add_f32_dpp v176, v176, v176 quad_perm:[1,0,3,2] row_mask:0xf bank_mask:0xf bound_ctrl:1
	v_add_f32_e32 v157, 1.0, v157
	v_rcp_f32_e32 v170, v157
	v_add_f32_e32 v157, 1.0, v171
	v_rcp_f32_e32 v171, v157
	v_add_f32_e32 v157, v174, v175
	v_add_f32_dpp v176, v176, v176 quad_perm:[2,3,0,1] row_mask:0xf bank_mask:0xf bound_ctrl:1
	s_waitcnt vmcnt(29)
	v_lshlrev_b32_e32 v156, 16, v223
	v_add_f32_dpp v157, v157, v157 quad_perm:[1,0,3,2] row_mask:0xf bank_mask:0xf bound_ctrl:1
	v_add_f32_dpp v176, v176, v176 row_half_mirror row_mask:0xf bank_mask:0xf bound_ctrl:1
	v_pk_mul_f32 v[140:141], v[140:141], v[170:171]
	v_add_f32_dpp v157, v157, v157 quad_perm:[2,3,0,1] row_mask:0xf bank_mask:0xf bound_ctrl:1
	v_add_f32_dpp v176, v176, v176 row_mirror row_mask:0xf bank_mask:0xf bound_ctrl:1
	v_pk_fma_f32 v[182:183], v[158:159], v[26:27], v[182:183]
	v_add_f32_dpp v157, v157, v157 row_half_mirror row_mask:0xf bank_mask:0xf bound_ctrl:1
	v_pk_fma_f32 v[182:183], v[146:147], v[28:29], v[182:183]
	s_nop 0
	v_add_f32_dpp v157, v157, v157 row_mirror row_mask:0xf bank_mask:0xf bound_ctrl:1
	v_mov_b32_e32 v177, v157
	s_nop 1
	v_permlane16_swap_b32 v157, v177
	v_pk_fma_f32 v[182:183], v[144:145], v[30:31], v[182:183]
	v_add_f32_e32 v157, v157, v177
	v_mov_b32_e32 v177, v176
	s_nop 1
	v_permlane16_swap_b32 v176, v177
	v_pk_fma_f32 v[182:183], v[136:137], v[34:35], v[182:183]
	v_add_f32_e32 v177, v176, v177
	v_ldexp_f32 v176, v157, -6
	v_ldexp_f32 v157, v177, -6
	v_fma_f32 v157, -v176, v176, v157
	v_max_f32_e32 v157, 0, v157
	v_add_f32_e32 v157, 0x3727c5ac, v157
	v_mul_f32_e32 v177, 0x4b800000, v157
	v_cmp_gt_f32_e32 vcc, s0, v157
	v_pk_fma_f32 v[182:183], v[132:133], v[32:33], v[182:183]
	s_nop 0
	v_cndmask_b32_e32 v157, v157, v177, vcc
	v_rsq_f32_e32 v177, v157
	v_and_b32_e32 v157, 0xffff0000, v223
	v_pk_mul_f32 v[140:141], v[140:141], v[156:157]
	v_pk_fma_f32 v[182:183], v[124:125], v[18:19], v[182:183]
	v_mul_f32_e32 v156, 0x45800000, v177
	v_cndmask_b32_e32 v156, v177, v156, vcc
	v_pk_add_f32 v[170:171], v[174:175], v[176:177] op_sel_hi:[1,0] neg_lo:[0,1] neg_hi:[0,1]
	v_cvt_pk_bf16_f32 v174, v140, v141
	v_pk_mul_f32 v[156:157], v[170:171], v[156:157] op_sel_hi:[1,0]
	global_store_dword v[122:123], v174, off
	v_pk_fma_f32 v[156:157], v[0:1], v[156:157], v[8:9]
	s_waitcnt vmcnt(29)
; #define GAS __attribute__((address_space(1)))
; __device__ __forceinline__ unsigned cvtpk(float lo, float hi) { f32x2 v = {lo, hi}; bf16x2_t b = __builtin_convertvector(v, bf16x2_t); return __builtin_bit_cast(unsigned, b); }
; __device__ __forceinline__ float bflo(unsigned w) { return __uint_as_float(w << 16); }
; __device__ __forceinline__ float bfhi(unsigned w) { return __uint_as_float(w & 0xffff0000u); }
; __device__ __forceinline__ float fsilu(float x) { return x * fsigmoid(x); }
; __device__ __forceinline__ void c_unit(Frame& F, int L, int u, bool dry) {
;     ...
;         for (int i = 0; i < 46; ++i) {
;             const float h0 = bflo(hv[16 * sub + i]), h1 = bfhi(hv[16 * sub + i]);
; #pragma unroll
;             for (int t = 0; t < 16; ++t) { const int j = i - t; if (j >= 0 && j < CONVW) { acc[t].x = fmaf(h0, wv[j].x, acc[t].x); acc[t].y = fmaf(h1, wv[j].y, acc[t].y); } }
;         }
; #pragma unroll
;         for (int t = 0; t < 16; ++t) {
;             float s = acc[t].x + acc[t].y, qq = acc[t].x * acc[t].x + acc[t].y * acc[t].y;
;             s = half_wave_sum(s); qq = half_wave_sum(qq);
;             const float mu = __builtin_ldexpf(s, -6), rstd = rsqrtf(fmaxf(__builtin_ldexpf(qq, -6) - mu * mu, 0.f) + LN_EPS);
;             const float h0 = (acc[t].x - mu) * rstd * gv.x + bv.x, h1 = (acc[t].y - mu) * rstd * gv.y + bv.y;
;             const unsigned ov = cvtpk(fsilu(h0) * bflo(sc[16 * sub + t]), fsilu(h1) * bfhi(sc[16 * sub + t])); if (!dry) *(GAS unsigned*)(SCG + (size_t)(tb + t) * 512) = ov;
	v_lshlrev_b32_e32 v122, 16, v222
	v_mul_f32_e32 v170, 0xbfb8aa3b, v156
	v_mul_f32_e32 v171, 0xbfb8aa3b, v157
	v_exp_f32_e32 v170, v170
	v_exp_f32_e32 v171, v171
	v_and_b32_e32 v123, 0xffff0000, v222
	v_pk_fma_f32 v[182:183], v[118:119], v[20:21], v[182:183]
	v_add_f32_e32 v140, 1.0, v170
	v_add_f32_e32 v141, 1.0, v171
	v_rcp_f32_e32 v140, v140
	v_rcp_f32_e32 v141, v141
	v_pk_fma_f32 v[182:183], v[112:113], v[24:25], v[182:183]
	v_pk_mul_f32 v[140:141], v[156:157], v[140:141]
	v_pk_fma_f32 v[156:157], v[108:109], v[2:3], v[172:173]
	v_pk_mul_f32 v[122:123], v[140:141], v[122:123]
	v_pk_fma_f32 v[156:157], v[102:103], v[10:11], v[156:157]
	v_cvt_pk_bf16_f32 v122, v122, v123
	v_pk_fma_f32 v[156:157], v[106:107], v[4:5], v[156:157]
	global_store_dword v[120:121], v122, off
	v_pk_fma_f32 v[156:157], v[104:105], v[6:7], v[156:157]
	v_pk_fma_f32 v[182:183], v[110:111], v[16:17], v[182:183]
	v_pk_fma_f32 v[156:157], v[100:101], v[12:13], v[156:157]
	v_pk_fma_f32 v[182:183], v[108:109], v[14:15], v[182:183]
	v_add_f32_e32 v172, v156, v157
	v_pk_mul_f32 v[170:171], v[156:157], v[156:157]
	s_nop 0
	v_add_f32_e32 v170, v170, v171
	v_add_f32_dpp v171, v172, v172 quad_perm:[1,0,3,2] row_mask:0xf bank_mask:0xf bound_ctrl:1
	s_nop 0
	v_add_f32_dpp v170, v170, v170 quad_perm:[1,0,3,2] row_mask:0xf bank_mask:0xf bound_ctrl:1
	v_add_f32_dpp v171, v171, v171 quad_perm:[2,3,0,1] row_mask:0xf bank_mask:0xf bound_ctrl:1
	s_nop 0
	v_add_f32_dpp v170, v170, v170 quad_perm:[2,3,0,1] row_mask:0xf bank_mask:0xf bound_ctrl:1
	v_add_f32_dpp v171, v171, v171 row_half_mirror row_mask:0xf bank_mask:0xf bound_ctrl:1
	s_nop 0
	v_add_f32_dpp v170, v170, v170 row_half_mirror row_mask:0xf bank_mask:0xf bound_ctrl:1
	v_add_f32_dpp v171, v171, v171 row_mirror row_mask:0xf bank_mask:0xf bound_ctrl:1
	v_mov_b32_e32 v172, v171
	s_nop 1
	v_permlane16_swap_b32 v171, v172
	v_add_f32_dpp v170, v170, v170 row_mirror row_mask:0xf bank_mask:0xf bound_ctrl:1
	v_add_f32_e32 v171, v171, v172
	v_mov_b32_e32 v172, v170
	s_nop 1
	v_permlane16_swap_b32 v170, v172
	s_nop 0
	v_add_f32_e32 v172, v170, v172
	v_ldexp_f32 v170, v171, -6
	v_ldexp_f32 v171, v172, -6
	v_fma_f32 v171, -v170, v170, v171
	v_max_f32_e32 v171, 0, v171
	v_add_f32_e32 v171, 0x3727c5ac, v171
	v_mul_f32_e32 v172, 0x4b800000, v171
	v_cmp_gt_f32_e32 vcc, s0, v171
	s_nop 1
	v_cndmask_b32_e32 v171, v171, v172, vcc
	v_rsq_f32_e32 v171, v171
	s_nop 0
	v_mul_f32_e32 v120, 0x45800000, v171
	v_cndmask_b32_e32 v120, v171, v120, vcc
	v_pk_add_f32 v[122:123], v[156:157], v[170:171] op_sel_hi:[1,0] neg_lo:[0,1] neg_hi:[0,1]
	v_pk_fma_f32 v[156:157], v[102:103], v[2:3], v[182:183]
	v_pk_mul_f32 v[120:121], v[122:123], v[120:121] op_sel_hi:[1,0]
	v_pk_fma_f32 v[156:157], v[106:107], v[10:11], v[156:157]
	v_pk_fma_f32 v[120:121], v[0:1], v[120:121], v[8:9]
	v_pk_fma_f32 v[156:157], v[104:105], v[4:5], v[156:157]
	v_mul_f32_e32 v122, 0xbfb8aa3b, v120
	v_exp_f32_e32 v123, v122
	v_mul_f32_e32 v122, 0xbfb8aa3b, v121
	v_exp_f32_e32 v141, v122
	v_pk_fma_f32 v[156:157], v[100:101], v[6:7], v[156:157]
	v_add_f32_e32 v123, 1.0, v123
	v_rcp_f32_e32 v140, v123
	v_add_f32_e32 v123, 1.0, v141
	v_pk_fma_f32 v[156:157], v[180:181], v[12:13], v[156:157]
	v_rcp_f32_e32 v141, v123
	v_add_f32_e32 v123, v156, v157
	v_pk_mul_f32 v[170:171], v[156:157], v[156:157]
	s_waitcnt vmcnt(29)
	v_lshlrev_b32_e32 v122, 16, v220
	v_add_f32_dpp v123, v123, v123 quad_perm:[1,0,3,2] row_mask:0xf bank_mask:0xf bound_ctrl:1
	v_add_f32_e32 v170, v170, v171
	v_pk_mul_f32 v[120:121], v[120:121], v[140:141]
	v_add_f32_dpp v123, v123, v123 quad_perm:[2,3,0,1] row_mask:0xf bank_mask:0xf bound_ctrl:1
	v_add_f32_dpp v170, v170, v170 quad_perm:[1,0,3,2] row_mask:0xf bank_mask:0xf bound_ctrl:1
	s_nop 0
	v_add_f32_dpp v123, v123, v123 row_half_mirror row_mask:0xf bank_mask:0xf bound_ctrl:1
	v_add_f32_dpp v170, v170, v170 quad_perm:[2,3,0,1] row_mask:0xf bank_mask:0xf bound_ctrl:1
	s_nop 0
	v_add_f32_dpp v123, v123, v123 row_mirror row_mask:0xf bank_mask:0xf bound_ctrl:1
	v_mov_b32_e32 v171, v123
	v_add_f32_dpp v170, v170, v170 row_half_mirror row_mask:0xf bank_mask:0xf bound_ctrl:1
	s_nop 1
	v_permlane16_swap_b32 v123, v171
	s_nop 0
	v_add_f32_e32 v123, v123, v171
	v_add_f32_dpp v170, v170, v170 row_mirror row_mask:0xf bank_mask:0xf bound_ctrl:1
	v_mov_b32_e32 v171, v170
	s_nop 1
	v_permlane16_swap_b32 v170, v171
	s_nop 0
	v_add_f32_e32 v171, v170, v171
	v_ldexp_f32 v170, v123, -6
	v_ldexp_f32 v123, v171, -6
	v_fma_f32 v123, -v170, v170, v123
	v_max_f32_e32 v123, 0, v123
	v_add_f32_e32 v123, 0x3727c5ac, v123
	v_mul_f32_e32 v171, 0x4b800000, v123
	v_cmp_gt_f32_e32 vcc, s0, v123
	s_nop 1
	v_cndmask_b32_e32 v123, v123, v171, vcc
	v_rsq_f32_e32 v171, v123
	v_and_b32_e32 v123, 0xffff0000, v220
	v_pk_mul_f32 v[120:121], v[120:121], v[122:123]
	v_mul_f32_e32 v122, 0x45800000, v171
	v_cndmask_b32_e32 v122, v171, v122, vcc
	v_pk_add_f32 v[140:141], v[156:157], v[170:171] op_sel_hi:[1,0] neg_lo:[0,1] neg_hi:[0,1]
	v_cvt_pk_bf16_f32 v156, v120, v121
	v_pk_mul_f32 v[122:123], v[140:141], v[122:123] op_sel_hi:[1,0]
	global_store_dword v[116:117], v156, off
	v_pk_fma_f32 v[122:123], v[0:1], v[122:123], v[8:9]
	s_waitcnt vmcnt(29)
; __device__ __forceinline__ float bflo(unsigned w) { return __uint_as_float(w << 16); }
; __device__ __forceinline__ float bfhi(unsigned w) { return __uint_as_float(w & 0xffff0000u); }
; __device__ __forceinline__ void c_unit(Frame& F, int L, int u, bool dry) {
;     ...
;         for (int t = 0; t < 16; ++t) acc[t] = cbv;
; #pragma unroll
;         for (int i = 0; i < 46; ++i) {
;             const float h0 = bflo(hv[16 * sub + i]), h1 = bfhi(hv[16 * sub + i]);
; #pragma unroll
;             for (int t = 0; t < 16; ++t) { const int j = i - t; if (j >= 0 && j < CONVW) { acc[t].x = fmaf(h0, wv[j].x, acc[t].x); acc[t].y = fmaf(h1, wv[j].y, acc[t].y); } }
;         }
	v_lshlrev_b32_e32 v116, 16, v221
	v_mul_f32_e32 v140, 0xbfb8aa3b, v122
	v_mul_f32_e32 v141, 0xbfb8aa3b, v123
	v_exp_f32_e32 v140, v140
	v_exp_f32_e32 v141, v141
	v_and_b32_e32 v117, 0xffff0000, v221
	v_pk_fma_f32 v[156:157], v[126:127], v[66:67], v[78:79]
	v_add_f32_e32 v120, 1.0, v140
	v_add_f32_e32 v121, 1.0, v141
	v_rcp_f32_e32 v120, v120
	v_rcp_f32_e32 v121, v121
	v_pk_fma_f32 v[140:141], v[142:143], v[66:67], v[78:79]
	v_pk_fma_f32 v[170:171], v[164:165], v[66:67], v[78:79]
	v_pk_fma_f32 v[140:141], v[138:139], v[68:69], v[140:141]
	v_pk_mul_f32 v[120:121], v[122:123], v[120:121]
	v_pk_fma_f32 v[122:123], v[148:149], v[66:67], v[78:79]
	v_pk_mul_f32 v[116:117], v[120:121], v[116:117]
	v_pk_fma_f32 v[122:123], v[142:143], v[68:69], v[122:123]
	v_cvt_pk_bf16_f32 v116, v116, v117
	v_pk_fma_f32 v[122:123], v[138:139], v[70:71], v[122:123]
	global_store_dword v[114:115], v116, off
	v_pk_fma_f32 v[122:123], v[134:135], v[72:73], v[122:123]
	v_pk_fma_f32 v[114:115], v[154:155], v[66:67], v[78:79]
	v_pk_fma_f32 v[122:123], v[130:131], v[36:37], v[122:123]
	v_pk_fma_f32 v[114:115], v[152:153], v[68:69], v[114:115]
	v_pk_fma_f32 v[122:123], v[128:129], v[38:39], v[122:123]
	v_pk_fma_f32 v[116:117], v[152:153], v[66:67], v[78:79]
	v_pk_fma_f32 v[122:123], v[126:127], v[42:43], v[122:123]
	v_pk_fma_f32 v[114:115], v[150:151], v[70:71], v[114:115]
	v_pk_fma_f32 v[122:123], v[164:165], v[60:61], v[122:123]
	v_pk_fma_f32 v[116:117], v[150:151], v[68:69], v[116:117]
	v_pk_fma_f32 v[122:123], v[168:169], v[44:45], v[122:123]
	v_pk_fma_f32 v[120:121], v[150:151], v[66:67], v[78:79]
	v_pk_fma_f32 v[122:123], v[166:167], v[46:47], v[122:123]
	v_pk_fma_f32 v[114:115], v[148:149], v[72:73], v[114:115]
	v_pk_fma_f32 v[122:123], v[162:163], v[54:55], v[122:123]
	v_pk_fma_f32 v[116:117], v[148:149], v[70:71], v[116:117]
	v_pk_fma_f32 v[120:121], v[148:149], v[68:69], v[120:121]
	v_pk_fma_f32 v[148:149], v[138:139], v[66:67], v[78:79]
	v_pk_fma_f32 v[122:123], v[160:161], v[58:59], v[122:123]
	v_pk_fma_f32 v[116:117], v[142:143], v[72:73], v[116:117]
	v_pk_fma_f32 v[120:121], v[142:143], v[70:71], v[120:121]
	v_pk_fma_f32 v[148:149], v[134:135], v[68:69], v[148:149]
	v_pk_fma_f32 v[114:115], v[142:143], v[36:37], v[114:115]
	v_pk_fma_f32 v[122:123], v[158:159], v[50:51], v[122:123]
	v_pk_fma_f32 v[120:121], v[138:139], v[72:73], v[120:121]
	v_pk_fma_f32 v[148:149], v[130:131], v[70:71], v[148:149]
	v_pk_fma_f32 v[114:115], v[138:139], v[38:39], v[114:115]
	v_pk_fma_f32 v[116:117], v[138:139], v[36:37], v[116:117]
	v_pk_fma_f32 v[122:123], v[146:147], v[52:53], v[122:123]
	v_pk_fma_f32 v[140:141], v[134:135], v[70:71], v[140:141]
	v_pk_fma_f32 v[148:149], v[128:129], v[72:73], v[148:149]
	v_pk_fma_f32 v[150:151], v[134:135], v[66:67], v[78:79]
	v_pk_fma_f32 v[152:153], v[130:131], v[66:67], v[78:79]
	v_pk_fma_f32 v[154:155], v[128:129], v[66:67], v[78:79]
	v_pk_fma_f32 v[114:115], v[134:135], v[42:43], v[114:115]
	v_pk_fma_f32 v[142:143], v[168:169], v[66:67], v[78:79]
	v_pk_fma_f32 v[116:117], v[134:135], v[38:39], v[116:117]
	v_pk_fma_f32 v[138:139], v[166:167], v[66:67], v[78:79]
	v_pk_fma_f32 v[120:121], v[134:135], v[36:37], v[120:121]
	v_pk_fma_f32 v[134:135], v[162:163], v[66:67], v[78:79]
	v_pk_fma_f32 v[178:179], v[144:145], v[56:57], v[122:123]
	v_pk_fma_f32 v[122:123], v[160:161], v[66:67], v[78:79]
	v_pk_fma_f32 v[66:67], v[158:159], v[66:67], v[78:79]
	v_pk_fma_f32 v[150:151], v[130:131], v[68:69], v[150:151]
	v_pk_fma_f32 v[152:153], v[128:129], v[68:69], v[152:153]
	v_pk_fma_f32 v[154:155], v[126:127], v[68:69], v[154:155]
	v_pk_fma_f32 v[156:157], v[164:165], v[68:69], v[156:157]
	v_pk_fma_f32 v[170:171], v[168:169], v[68:69], v[170:171]
	v_pk_fma_f32 v[142:143], v[166:167], v[68:69], v[142:143]
	v_pk_fma_f32 v[138:139], v[162:163], v[68:69], v[138:139]
	v_pk_fma_f32 v[134:135], v[160:161], v[68:69], v[134:135]
	v_pk_fma_f32 v[122:123], v[158:159], v[68:69], v[122:123]
	v_pk_fma_f32 v[66:67], v[146:147], v[68:69], v[66:67]
	v_pk_fma_f32 v[68:69], v[126:127], v[36:37], v[148:149]
	v_pk_fma_f32 v[150:151], v[128:129], v[70:71], v[150:151]
	v_pk_fma_f32 v[68:69], v[164:165], v[38:39], v[68:69]
	v_pk_fma_f32 v[150:151], v[126:127], v[72:73], v[150:151]
	v_pk_fma_f32 v[68:69], v[168:169], v[42:43], v[68:69]
	v_pk_fma_f32 v[152:153], v[126:127], v[70:71], v[152:153]
	v_pk_fma_f32 v[68:69], v[166:167], v[60:61], v[68:69]
	v_pk_fma_f32 v[152:153], v[164:165], v[72:73], v[152:153]
	v_pk_fma_f32 v[68:69], v[162:163], v[44:45], v[68:69]
	v_pk_fma_f32 v[142:143], v[162:163], v[70:71], v[142:143]
	v_pk_fma_f32 v[68:69], v[160:161], v[46:47], v[68:69]
	v_pk_fma_f32 v[172:173], v[160:161], v[72:73], v[142:143]
	v_pk_fma_f32 v[68:69], v[158:159], v[54:55], v[68:69]
	v_pk_fma_f32 v[154:155], v[164:165], v[70:71], v[154:155]
	v_pk_fma_f32 v[68:69], v[146:147], v[58:59], v[68:69]
	v_pk_fma_f32 v[154:155], v[168:169], v[72:73], v[154:155]
	v_pk_fma_f32 v[68:69], v[144:145], v[50:51], v[68:69]
	v_pk_fma_f32 v[138:139], v[160:161], v[70:71], v[138:139]
	v_pk_fma_f32 v[68:69], v[136:137], v[52:53], v[68:69]
	v_pk_fma_f32 v[174:175], v[158:159], v[72:73], v[138:139]
	v_pk_fma_f32 v[148:149], v[132:133], v[56:57], v[68:69]
	v_pk_fma_f32 v[68:69], v[164:165], v[36:37], v[150:151]
	v_pk_fma_f32 v[156:157], v[168:169], v[70:71], v[156:157]
	v_pk_fma_f32 v[68:69], v[168:169], v[38:39], v[68:69]
	v_pk_fma_f32 v[156:157], v[166:167], v[72:73], v[156:157]
	v_pk_fma_f32 v[68:69], v[166:167], v[42:43], v[68:69]
	v_pk_fma_f32 v[134:135], v[158:159], v[70:71], v[134:135]
	v_pk_fma_f32 v[68:69], v[162:163], v[60:61], v[68:69]
	v_pk_fma_f32 v[176:177], v[146:147], v[72:73], v[134:135]
; __device__ __forceinline__ float bflo(unsigned w) { return __uint_as_float(w << 16); }
; __device__ __forceinline__ float bfhi(unsigned w) { return __uint_as_float(w & 0xffff0000u); }
; __device__ __forceinline__ void c_unit(Frame& F, int L, int u, bool dry) {
;     ...
;         for (int i = 0; i < 46; ++i) {
;             const float h0 = bflo(hv[16 * sub + i]), h1 = bfhi(hv[16 * sub + i]);
; #pragma unroll
;             for (int t = 0; t < 16; ++t) { const int j = i - t; if (j >= 0 && j < CONVW) { acc[t].x = fmaf(h0, wv[j].x, acc[t].x); acc[t].y = fmaf(h1, wv[j].y, acc[t].y); } }
;         }
	v_pk_fma_f32 v[68:69], v[160:161], v[44:45], v[68:69]
	v_pk_fma_f32 v[170:171], v[166:167], v[70:71], v[170:171]
	v_pk_fma_f32 v[68:69], v[158:159], v[46:47], v[68:69]
	v_pk_fma_f32 v[170:171], v[162:163], v[72:73], v[170:171]
	v_pk_fma_f32 v[68:69], v[146:147], v[54:55], v[68:69]
	v_pk_fma_f32 v[140:141], v[130:131], v[72:73], v[140:141]
	v_pk_fma_f32 v[68:69], v[144:145], v[58:59], v[68:69]
	v_pk_fma_f32 v[114:115], v[130:131], v[60:61], v[114:115]
	v_pk_fma_f32 v[68:69], v[136:137], v[50:51], v[68:69]
	v_pk_fma_f32 v[116:117], v[130:131], v[42:43], v[116:117]
	v_pk_fma_f32 v[68:69], v[132:133], v[52:53], v[68:69]
	v_pk_fma_f32 v[120:121], v[130:131], v[38:39], v[120:121]
	v_pk_fma_f32 v[142:143], v[124:125], v[56:57], v[68:69]
	v_pk_fma_f32 v[68:69], v[168:169], v[36:37], v[152:153]
	v_pk_fma_f32 v[114:115], v[128:129], v[44:45], v[114:115]
	v_pk_fma_f32 v[68:69], v[166:167], v[38:39], v[68:69]
	v_pk_fma_f32 v[114:115], v[126:127], v[46:47], v[114:115]
	v_pk_fma_f32 v[68:69], v[162:163], v[42:43], v[68:69]
	v_pk_fma_f32 v[114:115], v[164:165], v[54:55], v[114:115]
	v_pk_fma_f32 v[68:69], v[160:161], v[60:61], v[68:69]
	v_pk_fma_f32 v[114:115], v[168:169], v[58:59], v[114:115]
	v_pk_fma_f32 v[68:69], v[158:159], v[44:45], v[68:69]
	v_pk_fma_f32 v[114:115], v[166:167], v[50:51], v[114:115]
	v_pk_fma_f32 v[68:69], v[146:147], v[46:47], v[68:69]
	v_pk_fma_f32 v[114:115], v[162:163], v[52:53], v[114:115]
	v_pk_fma_f32 v[68:69], v[144:145], v[54:55], v[68:69]
	v_pk_fma_f32 v[114:115], v[160:161], v[56:57], v[114:115]
	v_pk_fma_f32 v[68:69], v[136:137], v[58:59], v[68:69]
	v_pk_fma_f32 v[122:123], v[146:147], v[70:71], v[122:123]
	v_pk_fma_f32 v[68:69], v[132:133], v[50:51], v[68:69]
	v_pk_fma_f32 v[116:117], v[128:129], v[60:61], v[116:117]
	v_pk_fma_f32 v[68:69], v[124:125], v[52:53], v[68:69]
	v_pk_fma_f32 v[120:121], v[128:129], v[42:43], v[120:121]
	v_pk_fma_f32 v[138:139], v[118:119], v[56:57], v[68:69]
	v_pk_fma_f32 v[68:69], v[166:167], v[36:37], v[154:155]
	v_pk_fma_f32 v[182:183], v[144:145], v[72:73], v[122:123]
	v_pk_fma_f32 v[68:69], v[162:163], v[38:39], v[68:69]
	v_pk_fma_f32 v[122:123], v[128:129], v[36:37], v[140:141]
	v_pk_fma_f32 v[68:69], v[160:161], v[42:43], v[68:69]
	v_pk_fma_f32 v[116:117], v[126:127], v[44:45], v[116:117]
	v_pk_fma_f32 v[68:69], v[158:159], v[60:61], v[68:69]
	v_pk_fma_f32 v[116:117], v[164:165], v[46:47], v[116:117]
	v_pk_fma_f32 v[68:69], v[146:147], v[44:45], v[68:69]
	v_pk_fma_f32 v[116:117], v[168:169], v[54:55], v[116:117]
	v_pk_fma_f32 v[68:69], v[144:145], v[46:47], v[68:69]
	v_pk_fma_f32 v[116:117], v[166:167], v[58:59], v[116:117]
	v_pk_fma_f32 v[68:69], v[136:137], v[54:55], v[68:69]
	v_pk_fma_f32 v[116:117], v[162:163], v[50:51], v[116:117]
	v_pk_fma_f32 v[68:69], v[132:133], v[58:59], v[68:69]
	v_pk_fma_f32 v[116:117], v[160:161], v[52:53], v[116:117]
	v_pk_fma_f32 v[68:69], v[124:125], v[50:51], v[68:69]
	v_pk_fma_f32 v[116:117], v[158:159], v[56:57], v[116:117]
	v_pk_fma_f32 v[68:69], v[118:119], v[52:53], v[68:69]
	v_pk_fma_f32 v[120:121], v[126:127], v[60:61], v[120:121]
	v_pk_fma_f32 v[134:135], v[112:113], v[56:57], v[68:69]
	v_pk_fma_f32 v[68:69], v[162:163], v[36:37], v[156:157]
	v_pk_fma_f32 v[122:123], v[126:127], v[38:39], v[122:123]
	v_pk_fma_f32 v[68:69], v[160:161], v[38:39], v[68:69]
	v_pk_fma_f32 v[122:123], v[164:165], v[42:43], v[122:123]
	v_pk_fma_f32 v[68:69], v[158:159], v[42:43], v[68:69]
	v_pk_fma_f32 v[120:121], v[164:165], v[44:45], v[120:121]
	v_pk_fma_f32 v[68:69], v[146:147], v[60:61], v[68:69]
	v_pk_fma_f32 v[122:123], v[168:169], v[60:61], v[122:123]
	v_pk_fma_f32 v[68:69], v[144:145], v[44:45], v[68:69]
	v_pk_fma_f32 v[120:121], v[168:169], v[46:47], v[120:121]
	v_pk_fma_f32 v[68:69], v[136:137], v[46:47], v[68:69]
	v_pk_fma_f32 v[122:123], v[166:167], v[44:45], v[122:123]
	v_pk_fma_f32 v[68:69], v[132:133], v[54:55], v[68:69]
	v_pk_fma_f32 v[120:121], v[166:167], v[54:55], v[120:121]
	v_pk_fma_f32 v[68:69], v[124:125], v[58:59], v[68:69]
	v_pk_fma_f32 v[122:123], v[162:163], v[46:47], v[122:123]
	v_pk_fma_f32 v[68:69], v[118:119], v[50:51], v[68:69]
	v_pk_fma_f32 v[120:121], v[162:163], v[58:59], v[120:121]
	v_pk_fma_f32 v[68:69], v[112:113], v[52:53], v[68:69]
	v_pk_fma_f32 v[122:123], v[160:161], v[54:55], v[122:123]
	v_pk_fma_f32 v[130:131], v[110:111], v[56:57], v[68:69]
	v_pk_fma_f32 v[68:69], v[160:161], v[36:37], v[170:171]
	v_pk_fma_f32 v[120:121], v[160:161], v[50:51], v[120:121]
	v_pk_fma_f32 v[68:69], v[158:159], v[38:39], v[68:69]
	v_pk_fma_f32 v[122:123], v[158:159], v[58:59], v[122:123]
	v_pk_fma_f32 v[68:69], v[146:147], v[42:43], v[68:69]
	v_pk_fma_f32 v[120:121], v[158:159], v[52:53], v[120:121]
	v_pk_fma_f32 v[68:69], v[144:145], v[60:61], v[68:69]
	v_pk_fma_f32 v[122:123], v[146:147], v[50:51], v[122:123]
	v_pk_fma_f32 v[68:69], v[136:137], v[44:45], v[68:69]
	v_pk_fma_f32 v[120:121], v[146:147], v[56:57], v[120:121]
	v_pk_fma_f32 v[68:69], v[132:133], v[46:47], v[68:69]
	v_pk_fma_f32 v[122:123], v[144:145], v[52:53], v[122:123]
	v_pk_fma_f32 v[68:69], v[124:125], v[54:55], v[68:69]
	v_pk_fma_f32 v[184:185], v[136:137], v[56:57], v[122:123]
	v_pk_fma_f32 v[68:69], v[118:119], v[58:59], v[68:69]
	v_pk_fma_f32 v[66:67], v[144:145], v[70:71], v[66:67]
	v_pk_fma_f32 v[68:69], v[112:113], v[50:51], v[68:69]
	v_pk_fma_f32 v[66:67], v[136:137], v[72:73], v[66:67]
	v_pk_fma_f32 v[68:69], v[110:111], v[52:53], v[68:69]
	v_lshlrev_b32_e32 v70, 16, v225
	v_pk_fma_f32 v[128:129], v[108:109], v[56:57], v[68:69]
	v_pk_fma_f32 v[68:69], v[158:159], v[22:23], v[114:115]
	v_and_b32_e32 v71, 0xffff0000, v225
	v_pk_fma_f32 v[68:69], v[146:147], v[26:27], v[68:69]
; __device__ __forceinline__ float bflo(unsigned w) { return __uint_as_float(w << 16); }
; __device__ __forceinline__ float bfhi(unsigned w) { return __uint_as_float(w & 0xffff0000u); }
; __device__ __forceinline__ void c_unit(Frame& F, int L, int u, bool dry) {
;     ...
;         for (int i = 0; i < 46; ++i) {
;             const float h0 = bflo(hv[16 * sub + i]), h1 = bfhi(hv[16 * sub + i]);
; #pragma unroll
;             for (int t = 0; t < 16; ++t) { const int j = i - t; if (j >= 0 && j < CONVW) { acc[t].x = fmaf(h0, wv[j].x, acc[t].x); acc[t].y = fmaf(h1, wv[j].y, acc[t].y); } }
;         }
; #pragma unroll
;         for (int t = 0; t < 16; ++t) {
;             float s = acc[t].x + acc[t].y, qq = acc[t].x * acc[t].x + acc[t].y * acc[t].y;
	v_lshlrev_b32_e32 v72, 16, v228
	v_pk_fma_f32 v[68:69], v[144:145], v[28:29], v[68:69]
	v_and_b32_e32 v73, 0xffff0000, v228
	v_pk_fma_f32 v[68:69], v[136:137], v[30:31], v[68:69]
	v_lshlrev_b32_e32 v78, 16, v227
	v_pk_fma_f32 v[68:69], v[132:133], v[34:35], v[68:69]
	v_and_b32_e32 v79, 0xffff0000, v227
	v_pk_fma_f32 v[68:69], v[124:125], v[32:33], v[68:69]
	v_lshlrev_b32_e32 v114, 16, v230
	v_pk_fma_f32 v[68:69], v[118:119], v[18:19], v[68:69]
	v_and_b32_e32 v115, 0xffff0000, v230
	v_pk_fma_f32 v[68:69], v[112:113], v[20:21], v[68:69]
	s_nop 0
	v_pk_fma_f32 v[68:69], v[110:111], v[24:25], v[68:69]
	s_nop 0
	v_pk_fma_f32 v[68:69], v[108:109], v[16:17], v[68:69]
	s_nop 0
	v_pk_fma_f32 v[150:151], v[102:103], v[14:15], v[68:69]
	v_pk_fma_f32 v[68:69], v[158:159], v[36:37], v[172:173]
	s_nop 0
	v_pk_fma_f32 v[68:69], v[146:147], v[38:39], v[68:69]
	s_nop 0
	v_pk_fma_f32 v[68:69], v[144:145], v[42:43], v[68:69]
	s_nop 0
	v_pk_fma_f32 v[68:69], v[136:137], v[60:61], v[68:69]
	s_nop 0
	v_pk_fma_f32 v[68:69], v[132:133], v[44:45], v[68:69]
	s_nop 0
	v_pk_fma_f32 v[68:69], v[124:125], v[46:47], v[68:69]
	s_nop 0
	v_pk_fma_f32 v[68:69], v[118:119], v[54:55], v[68:69]
	s_nop 0
	v_pk_fma_f32 v[68:69], v[112:113], v[58:59], v[68:69]
	s_nop 0
	v_pk_fma_f32 v[68:69], v[110:111], v[50:51], v[68:69]
	s_nop 0
	v_pk_fma_f32 v[68:69], v[108:109], v[52:53], v[68:69]
	s_nop 0
	v_pk_fma_f32 v[126:127], v[102:103], v[56:57], v[68:69]
	v_pk_fma_f32 v[68:69], v[146:147], v[22:23], v[116:117]
	s_nop 0
	v_pk_fma_f32 v[68:69], v[144:145], v[26:27], v[68:69]
	s_nop 0
	v_pk_fma_f32 v[68:69], v[136:137], v[28:29], v[68:69]
	s_nop 0
	v_pk_fma_f32 v[68:69], v[132:133], v[30:31], v[68:69]
	s_nop 0
	v_pk_fma_f32 v[68:69], v[124:125], v[34:35], v[68:69]
	s_nop 0
	v_pk_fma_f32 v[68:69], v[118:119], v[32:33], v[68:69]
	s_nop 0
	v_pk_fma_f32 v[68:69], v[112:113], v[18:19], v[68:69]
	s_nop 0
	v_pk_fma_f32 v[68:69], v[110:111], v[20:21], v[68:69]
	s_nop 0
	v_pk_fma_f32 v[68:69], v[108:109], v[24:25], v[68:69]
	s_nop 0
	v_pk_fma_f32 v[68:69], v[102:103], v[16:17], v[68:69]
	s_nop 0
	v_pk_fma_f32 v[152:153], v[106:107], v[14:15], v[68:69]
	v_pk_fma_f32 v[68:69], v[146:147], v[36:37], v[174:175]
	s_nop 0
	v_pk_fma_f32 v[68:69], v[144:145], v[38:39], v[68:69]
	s_nop 0
	v_pk_fma_f32 v[68:69], v[136:137], v[42:43], v[68:69]
	s_nop 0
	v_pk_fma_f32 v[68:69], v[132:133], v[60:61], v[68:69]
	s_nop 0
	v_pk_fma_f32 v[68:69], v[124:125], v[44:45], v[68:69]
	s_nop 0
	v_pk_fma_f32 v[68:69], v[118:119], v[46:47], v[68:69]
	s_nop 0
	v_pk_fma_f32 v[68:69], v[112:113], v[54:55], v[68:69]
	s_nop 0
	v_pk_fma_f32 v[68:69], v[110:111], v[58:59], v[68:69]
	s_nop 0
	v_pk_fma_f32 v[68:69], v[108:109], v[50:51], v[68:69]
	s_nop 0
	v_pk_fma_f32 v[68:69], v[102:103], v[52:53], v[68:69]
	s_nop 0
	v_pk_fma_f32 v[122:123], v[106:107], v[56:57], v[68:69]
	v_pk_fma_f32 v[68:69], v[144:145], v[22:23], v[120:121]
	s_nop 0
	v_pk_fma_f32 v[68:69], v[136:137], v[26:27], v[68:69]
	s_nop 0
	v_pk_fma_f32 v[68:69], v[132:133], v[28:29], v[68:69]
	s_nop 0
	v_pk_fma_f32 v[68:69], v[124:125], v[30:31], v[68:69]
	s_nop 0
	v_pk_fma_f32 v[68:69], v[118:119], v[34:35], v[68:69]
	s_nop 0
	v_pk_fma_f32 v[68:69], v[112:113], v[32:33], v[68:69]
	s_nop 0
	v_pk_fma_f32 v[68:69], v[110:111], v[18:19], v[68:69]
	s_nop 0
	v_pk_fma_f32 v[68:69], v[108:109], v[20:21], v[68:69]
	s_nop 0
	v_pk_fma_f32 v[68:69], v[102:103], v[24:25], v[68:69]
	s_nop 0
	v_pk_fma_f32 v[68:69], v[106:107], v[16:17], v[68:69]
	s_nop 0
	v_pk_fma_f32 v[146:147], v[104:105], v[14:15], v[68:69]
	v_pk_fma_f32 v[68:69], v[144:145], v[36:37], v[176:177]
	v_pk_fma_f32 v[144:145], v[106:107], v[2:3], v[150:151]
	v_pk_fma_f32 v[68:69], v[136:137], v[38:39], v[68:69]
	v_pk_fma_f32 v[144:145], v[104:105], v[10:11], v[144:145]
	v_pk_fma_f32 v[68:69], v[132:133], v[42:43], v[68:69]
	v_pk_fma_f32 v[144:145], v[100:101], v[4:5], v[144:145]
	v_pk_fma_f32 v[68:69], v[124:125], v[60:61], v[68:69]
	v_pk_fma_f32 v[144:145], v[180:181], v[6:7], v[144:145]
	v_pk_fma_f32 v[68:69], v[118:119], v[44:45], v[68:69]
	s_nop 0
	v_pk_fma_f32 v[68:69], v[112:113], v[46:47], v[68:69]
	s_nop 0
	v_pk_fma_f32 v[68:69], v[110:111], v[54:55], v[68:69]
	s_nop 0
	v_pk_fma_f32 v[68:69], v[108:109], v[58:59], v[68:69]
	s_nop 0
	v_pk_fma_f32 v[68:69], v[102:103], v[50:51], v[68:69]
	s_nop 0
	v_pk_fma_f32 v[68:69], v[106:107], v[52:53], v[68:69]
	s_nop 0
	v_pk_fma_f32 v[120:121], v[104:105], v[56:57], v[68:69]
	v_pk_fma_f32 v[68:69], v[136:137], v[22:23], v[178:179]
	s_nop 0
	v_pk_fma_f32 v[68:69], v[132:133], v[26:27], v[68:69]
	s_nop 0
	v_pk_fma_f32 v[68:69], v[124:125], v[28:29], v[68:69]
	s_nop 0
	v_pk_fma_f32 v[68:69], v[118:119], v[30:31], v[68:69]
	s_nop 0
	v_pk_fma_f32 v[68:69], v[112:113], v[34:35], v[68:69]
	s_nop 0
	v_pk_fma_f32 v[68:69], v[110:111], v[32:33], v[68:69]
	s_nop 0
	v_pk_fma_f32 v[68:69], v[108:109], v[18:19], v[68:69]
	s_nop 0
	v_pk_fma_f32 v[68:69], v[102:103], v[20:21], v[68:69]
	s_nop 0
	v_pk_fma_f32 v[68:69], v[106:107], v[24:25], v[68:69]
	s_nop 0
	v_pk_fma_f32 v[68:69], v[104:105], v[16:17], v[68:69]
	s_nop 0
	v_pk_fma_f32 v[140:141], v[100:101], v[14:15], v[68:69]
	v_pk_fma_f32 v[68:69], v[136:137], v[36:37], v[182:183]
	v_pk_fma_f32 v[36:37], v[132:133], v[36:37], v[66:67]
	v_pk_fma_f32 v[68:69], v[132:133], v[38:39], v[68:69]
	v_lshlrev_b32_e32 v66, 16, v224
	v_pk_fma_f32 v[68:69], v[124:125], v[42:43], v[68:69]
	v_and_b32_e32 v67, 0xffff0000, v224
	v_pk_fma_f32 v[68:69], v[118:119], v[60:61], v[68:69]
	v_pk_fma_f32 v[144:145], v[66:67], v[12:13], v[144:145]
	v_pk_fma_f32 v[68:69], v[112:113], v[44:45], v[68:69]
	v_pk_fma_f32 v[36:37], v[124:125], v[38:39], v[36:37]
	v_pk_fma_f32 v[68:69], v[110:111], v[46:47], v[68:69]
	v_add_f32_e32 v150, v144, v145
	v_pk_fma_f32 v[68:69], v[108:109], v[54:55], v[68:69]
	v_pk_fma_f32 v[36:37], v[118:119], v[42:43], v[36:37]
	v_pk_fma_f32 v[68:69], v[102:103], v[58:59], v[68:69]
	v_pk_fma_f32 v[36:37], v[112:113], v[60:61], v[36:37]
	v_pk_fma_f32 v[68:69], v[106:107], v[50:51], v[68:69]
	v_pk_fma_f32 v[36:37], v[110:111], v[44:45], v[36:37]
	v_pk_fma_f32 v[68:69], v[104:105], v[52:53], v[68:69]
	v_pk_fma_f32 v[36:37], v[108:109], v[46:47], v[36:37]
	v_pk_fma_f32 v[116:117], v[100:101], v[56:57], v[68:69]
	v_pk_fma_f32 v[68:69], v[132:133], v[22:23], v[184:185]
	s_waitcnt vmcnt(29)
; #define GAS __attribute__((address_space(1)))
; __device__ __forceinline__ unsigned cvtpk(float lo, float hi) { f32x2 v = {lo, hi}; bf16x2_t b = __builtin_convertvector(v, bf16x2_t); return __builtin_bit_cast(unsigned, b); }
; __device__ __forceinline__ float bflo(unsigned w) { return __uint_as_float(w << 16); }
; __device__ __forceinline__ float bfhi(unsigned w) { return __uint_as_float(w & 0xffff0000u); }
; __device__ __forceinline__ float fsilu(float x) { return x * fsigmoid(x); }
; __device__ __forceinline__ void c_unit(Frame& F, int L, int u, bool dry) {
;     ...
; #pragma unroll
;         for (int t = 0; t < 16; ++t) {
;             float s = acc[t].x + acc[t].y, qq = acc[t].x * acc[t].x + acc[t].y * acc[t].y;
;             s = half_wave_sum(s); qq = half_wave_sum(qq);
;             const float mu = __builtin_ldexpf(s, -6), rstd = rsqrtf(fmaxf(__builtin_ldexpf(qq, -6) - mu * mu, 0.f) + LN_EPS);
;             const float h0 = (acc[t].x - mu) * rstd * gv.x + bv.x, h1 = (acc[t].y - mu) * rstd * gv.y + bv.y;
;             const unsigned ov = cvtpk(fsilu(h0) * bflo(sc[16 * sub + t]), fsilu(h1) * bfhi(sc[16 * sub + t])); if (!dry) *(GAS unsigned*)(SCG + (size_t)(tb + t) * 512) = ov;
	v_lshlrev_b32_e32 v132, 16, v219
	v_pk_fma_f32 v[68:69], v[124:125], v[26:27], v[68:69]
	v_pk_fma_f32 v[124:125], v[124:125], v[22:23], v[148:149]
	v_pk_mul_f32 v[148:149], v[144:145], v[144:145]
	v_pk_fma_f32 v[68:69], v[118:119], v[28:29], v[68:69]
	v_add_f32_e32 v148, v148, v149
	v_add_f32_dpp v149, v150, v150 quad_perm:[1,0,3,2] row_mask:0xf bank_mask:0xf bound_ctrl:1
	v_pk_fma_f32 v[68:69], v[112:113], v[30:31], v[68:69]
	v_add_f32_dpp v148, v148, v148 quad_perm:[1,0,3,2] row_mask:0xf bank_mask:0xf bound_ctrl:1
	v_add_f32_dpp v149, v149, v149 quad_perm:[2,3,0,1] row_mask:0xf bank_mask:0xf bound_ctrl:1
	v_pk_fma_f32 v[68:69], v[110:111], v[34:35], v[68:69]
	v_add_f32_dpp v148, v148, v148 quad_perm:[2,3,0,1] row_mask:0xf bank_mask:0xf bound_ctrl:1
	v_add_f32_dpp v149, v149, v149 row_half_mirror row_mask:0xf bank_mask:0xf bound_ctrl:1
	v_and_b32_e32 v133, 0xffff0000, v219
	v_add_f32_dpp v148, v148, v148 row_half_mirror row_mask:0xf bank_mask:0xf bound_ctrl:1
	v_add_f32_dpp v149, v149, v149 row_mirror row_mask:0xf bank_mask:0xf bound_ctrl:1
	v_mov_b32_e32 v150, v149
	s_nop 1
	v_permlane16_swap_b32 v149, v150
	v_add_f32_dpp v148, v148, v148 row_mirror row_mask:0xf bank_mask:0xf bound_ctrl:1
	v_add_f32_e32 v149, v149, v150
	v_mov_b32_e32 v150, v148
	s_nop 1
	v_permlane16_swap_b32 v148, v150
	v_pk_fma_f32 v[68:69], v[108:109], v[32:33], v[68:69]
	v_add_f32_e32 v150, v148, v150
	v_ldexp_f32 v148, v149, -6
	v_ldexp_f32 v149, v150, -6
	v_fma_f32 v149, -v148, v148, v149
	v_max_f32_e32 v149, 0, v149
	v_add_f32_e32 v149, 0x3727c5ac, v149
	v_mul_f32_e32 v150, 0x4b800000, v149
	v_cmp_gt_f32_e32 vcc, s0, v149
	v_pk_fma_f32 v[68:69], v[102:103], v[18:19], v[68:69]
	v_pk_fma_f32 v[124:125], v[118:119], v[26:27], v[124:125]
	v_cndmask_b32_e32 v149, v149, v150, vcc
	v_rsq_f32_e32 v149, v149
	v_pk_fma_f32 v[68:69], v[106:107], v[20:21], v[68:69]
	v_pk_fma_f32 v[118:119], v[118:119], v[22:23], v[142:143]
	v_pk_fma_f32 v[68:69], v[104:105], v[24:25], v[68:69]
	v_mul_f32_e32 v150, 0x45800000, v149
	v_cndmask_b32_e32 v150, v149, v150, vcc
	v_pk_add_f32 v[144:145], v[144:145], v[148:149] op_sel_hi:[1,0] neg_lo:[0,1] neg_hi:[0,1]
	v_pk_fma_f32 v[68:69], v[100:101], v[16:17], v[68:69]
	v_pk_mul_f32 v[144:145], v[144:145], v[150:151] op_sel_hi:[1,0]
	v_pk_fma_f32 v[136:137], v[180:181], v[14:15], v[68:69]
	v_pk_fma_f32 v[144:145], v[0:1], v[144:145], v[8:9]
	v_lshlrev_b32_e32 v68, 16, v226
	v_mul_f32_e32 v148, 0xbfb8aa3b, v144
	v_mul_f32_e32 v149, 0xbfb8aa3b, v145
	v_exp_f32_e32 v148, v148
	v_exp_f32_e32 v149, v149
	v_and_b32_e32 v69, 0xffff0000, v226
	v_pk_fma_f32 v[118:119], v[112:113], v[26:27], v[118:119]
	v_add_f32_e32 v148, 1.0, v148
	v_add_f32_e32 v149, 1.0, v149
	v_rcp_f32_e32 v148, v148
	v_rcp_f32_e32 v149, v149
	v_pk_fma_f32 v[118:119], v[110:111], v[28:29], v[118:119]
	v_pk_fma_f32 v[124:125], v[112:113], v[28:29], v[124:125]
	v_pk_fma_f32 v[118:119], v[108:109], v[30:31], v[118:119]
	v_pk_mul_f32 v[144:145], v[144:145], v[148:149]
	v_pk_fma_f32 v[118:119], v[102:103], v[34:35], v[118:119]
	v_pk_mul_f32 v[132:133], v[144:145], v[132:133]
	v_pk_fma_f32 v[118:119], v[106:107], v[32:33], v[118:119]
	v_cvt_pk_bf16_f32 v132, v132, v133
	global_store_dword v[98:99], v132, off
	v_pk_fma_f32 v[98:99], v[104:105], v[2:3], v[152:153]
	v_pk_fma_f32 v[118:119], v[104:105], v[18:19], v[118:119]
	v_pk_fma_f32 v[98:99], v[100:101], v[10:11], v[98:99]
	s_waitcnt vmcnt(29)
	v_lshlrev_b32_e32 v132, 16, v218
	v_pk_fma_f32 v[98:99], v[180:181], v[4:5], v[98:99]
	v_and_b32_e32 v133, 0xffff0000, v218
	v_pk_fma_f32 v[98:99], v[66:67], v[6:7], v[98:99]
	v_pk_fma_f32 v[112:113], v[112:113], v[22:23], v[138:139]
	v_pk_fma_f32 v[98:99], v[68:69], v[12:13], v[98:99]
	v_pk_fma_f32 v[112:113], v[110:111], v[26:27], v[112:113]
	v_add_f32_e32 v144, v98, v99
	v_pk_mul_f32 v[142:143], v[98:99], v[98:99]
	v_pk_fma_f32 v[112:113], v[108:109], v[28:29], v[112:113]
	v_add_f32_e32 v142, v142, v143
	v_add_f32_dpp v143, v144, v144 quad_perm:[1,0,3,2] row_mask:0xf bank_mask:0xf bound_ctrl:1
	v_pk_fma_f32 v[112:113], v[102:103], v[30:31], v[112:113]
	v_add_f32_dpp v142, v142, v142 quad_perm:[1,0,3,2] row_mask:0xf bank_mask:0xf bound_ctrl:1
	v_add_f32_dpp v143, v143, v143 quad_perm:[2,3,0,1] row_mask:0xf bank_mask:0xf bound_ctrl:1
	v_pk_fma_f32 v[112:113], v[106:107], v[34:35], v[112:113]
	v_add_f32_dpp v142, v142, v142 quad_perm:[2,3,0,1] row_mask:0xf bank_mask:0xf bound_ctrl:1
	v_add_f32_dpp v143, v143, v143 row_half_mirror row_mask:0xf bank_mask:0xf bound_ctrl:1
	v_pk_fma_f32 v[112:113], v[104:105], v[32:33], v[112:113]
	v_add_f32_dpp v142, v142, v142 row_half_mirror row_mask:0xf bank_mask:0xf bound_ctrl:1
	v_add_f32_dpp v143, v143, v143 row_mirror row_mask:0xf bank_mask:0xf bound_ctrl:1
	v_mov_b32_e32 v144, v143
	s_nop 1
	v_permlane16_swap_b32 v143, v144
	v_add_f32_dpp v142, v142, v142 row_mirror row_mask:0xf bank_mask:0xf bound_ctrl:1
	v_add_f32_e32 v143, v143, v144
	v_mov_b32_e32 v144, v142
	s_nop 1
	v_permlane16_swap_b32 v142, v144
	v_pk_fma_f32 v[112:113], v[100:101], v[18:19], v[112:113]
	v_add_f32_e32 v144, v142, v144
	v_ldexp_f32 v142, v143, -6
	v_ldexp_f32 v143, v144, -6
	v_fma_f32 v143, -v142, v142, v143
	v_max_f32_e32 v143, 0, v143
	v_add_f32_e32 v143, 0x3727c5ac, v143
	v_mul_f32_e32 v144, 0x4b800000, v143
	v_cmp_gt_f32_e32 vcc, s0, v143
	v_pk_fma_f32 v[124:125], v[110:111], v[30:31], v[124:125]
	v_pk_fma_f32 v[110:111], v[110:111], v[22:23], v[134:135]
	v_cndmask_b32_e32 v143, v143, v144, vcc
	v_rsq_f32_e32 v143, v143
	v_pk_fma_f32 v[110:111], v[108:109], v[26:27], v[110:111]
	v_pk_fma_f32 v[124:125], v[108:109], v[34:35], v[124:125]
	v_pk_fma_f32 v[110:111], v[102:103], v[28:29], v[110:111]
	v_mul_f32_e32 v144, 0x45800000, v143
	v_cndmask_b32_e32 v144, v143, v144, vcc
	v_pk_add_f32 v[98:99], v[98:99], v[142:143] op_sel_hi:[1,0] neg_lo:[0,1] neg_hi:[0,1]
	v_pk_fma_f32 v[110:111], v[106:107], v[30:31], v[110:111]
	v_pk_mul_f32 v[98:99], v[98:99], v[144:145] op_sel_hi:[1,0]
	v_pk_fma_f32 v[110:111], v[104:105], v[34:35], v[110:111]
	v_pk_fma_f32 v[142:143], v[0:1], v[98:99], v[8:9]
	v_pk_fma_f32 v[110:111], v[100:101], v[32:33], v[110:111]
	v_mul_f32_e32 v98, 0xbfb8aa3b, v142
	v_exp_f32_e32 v144, v98
	v_mul_f32_e32 v98, 0xbfb8aa3b, v143
	v_exp_f32_e32 v145, v98
	v_pk_fma_f32 v[98:99], v[100:101], v[20:21], v[118:119]
	v_add_f32_e32 v118, 1.0, v144
	v_rcp_f32_e32 v118, v118
	v_add_f32_e32 v119, 1.0, v145
	v_rcp_f32_e32 v119, v119
	v_pk_fma_f32 v[110:111], v[180:181], v[18:19], v[110:111]
	v_pk_fma_f32 v[108:109], v[108:109], v[22:23], v[130:131]
	v_pk_fma_f32 v[124:125], v[102:103], v[32:33], v[124:125]
	v_pk_mul_f32 v[118:119], v[142:143], v[118:119]
	v_pk_fma_f32 v[108:109], v[102:103], v[26:27], v[108:109]
	v_pk_mul_f32 v[118:119], v[118:119], v[132:133]
	v_pk_fma_f32 v[108:109], v[106:107], v[28:29], v[108:109]
	v_cvt_pk_bf16_f32 v118, v118, v119
	global_store_dword v[96:97], v118, off
	v_pk_fma_f32 v[96:97], v[100:101], v[2:3], v[146:147]
	s_waitcnt vmcnt(28)
; #define GAS __attribute__((address_space(1)))
; __device__ __forceinline__ unsigned cvtpk(float lo, float hi) { f32x2 v = {lo, hi}; bf16x2_t b = __builtin_convertvector(v, bf16x2_t); return __builtin_bit_cast(unsigned, b); }
; __device__ __forceinline__ float bflo(unsigned w) { return __uint_as_float(w << 16); }
; __device__ __forceinline__ float bfhi(unsigned w) { return __uint_as_float(w & 0xffff0000u); }
; __device__ __forceinline__ float fsilu(float x) { return x * fsigmoid(x); }
; __device__ __forceinline__ void c_unit(Frame& F, int L, int u, bool dry) {
;     ...
; #pragma unroll
;         for (int t = 0; t < 16; ++t) {
;             float s = acc[t].x + acc[t].y, qq = acc[t].x * acc[t].x + acc[t].y * acc[t].y;
;             s = half_wave_sum(s); qq = half_wave_sum(qq);
;             const float mu = __builtin_ldexpf(s, -6), rstd = rsqrtf(fmaxf(__builtin_ldexpf(qq, -6) - mu * mu, 0.f) + LN_EPS);
;             const float h0 = (acc[t].x - mu) * rstd * gv.x + bv.x, h1 = (acc[t].y - mu) * rstd * gv.y + bv.y;
;             const unsigned ov = cvtpk(fsilu(h0) * bflo(sc[16 * sub + t]), fsilu(h1) * bfhi(sc[16 * sub + t])); if (!dry) *(GAS unsigned*)(SCG + (size_t)(tb + t) * 512) = ov;
	v_lshlrev_b32_e32 v118, 16, v217
	v_pk_fma_f32 v[96:97], v[180:181], v[10:11], v[96:97]
	v_and_b32_e32 v119, 0xffff0000, v217
	v_pk_fma_f32 v[96:97], v[66:67], v[4:5], v[96:97]
	v_pk_fma_f32 v[108:109], v[104:105], v[30:31], v[108:109]
	v_pk_fma_f32 v[96:97], v[68:69], v[6:7], v[96:97]
	v_pk_fma_f32 v[108:109], v[100:101], v[34:35], v[108:109]
	v_pk_fma_f32 v[96:97], v[70:71], v[12:13], v[96:97]
	v_pk_fma_f32 v[108:109], v[180:181], v[32:33], v[108:109]
	v_add_f32_e32 v138, v96, v97
	v_pk_mul_f32 v[132:133], v[96:97], v[96:97]
	v_pk_fma_f32 v[108:109], v[66:67], v[18:19], v[108:109]
	v_add_f32_e32 v132, v132, v133
	v_add_f32_dpp v133, v138, v138 quad_perm:[1,0,3,2] row_mask:0xf bank_mask:0xf bound_ctrl:1
	v_pk_fma_f32 v[124:125], v[106:107], v[18:19], v[124:125]
	v_add_f32_dpp v132, v132, v132 quad_perm:[1,0,3,2] row_mask:0xf bank_mask:0xf bound_ctrl:1
	v_add_f32_dpp v133, v133, v133 quad_perm:[2,3,0,1] row_mask:0xf bank_mask:0xf bound_ctrl:1
	v_pk_fma_f32 v[124:125], v[104:105], v[20:21], v[124:125]
	v_add_f32_dpp v132, v132, v132 quad_perm:[2,3,0,1] row_mask:0xf bank_mask:0xf bound_ctrl:1
	v_add_f32_dpp v133, v133, v133 row_half_mirror row_mask:0xf bank_mask:0xf bound_ctrl:1
	v_pk_fma_f32 v[124:125], v[100:101], v[24:25], v[124:125]
	v_add_f32_dpp v132, v132, v132 row_half_mirror row_mask:0xf bank_mask:0xf bound_ctrl:1
	v_add_f32_dpp v133, v133, v133 row_mirror row_mask:0xf bank_mask:0xf bound_ctrl:1
	v_mov_b32_e32 v138, v133
	s_nop 1
	v_permlane16_swap_b32 v133, v138
	v_add_f32_dpp v132, v132, v132 row_mirror row_mask:0xf bank_mask:0xf bound_ctrl:1
	v_add_f32_e32 v133, v133, v138
	v_mov_b32_e32 v138, v132
	s_nop 1
	v_permlane16_swap_b32 v132, v138
	v_pk_fma_f32 v[124:125], v[180:181], v[16:17], v[124:125]
	v_add_f32_e32 v138, v132, v138
	v_ldexp_f32 v132, v133, -6
	v_ldexp_f32 v133, v138, -6
	v_fma_f32 v133, -v132, v132, v133
	v_max_f32_e32 v133, 0, v133
	v_add_f32_e32 v133, 0x3727c5ac, v133
	v_mul_f32_e32 v138, 0x4b800000, v133
	v_cmp_gt_f32_e32 vcc, s0, v133
	v_pk_fma_f32 v[124:125], v[66:67], v[14:15], v[124:125]
	v_pk_fma_f32 v[36:37], v[102:103], v[54:55], v[36:37]
	v_cndmask_b32_e32 v133, v133, v138, vcc
	v_rsq_f32_e32 v133, v133
	v_pk_fma_f32 v[102:103], v[102:103], v[22:23], v[128:129]
	v_pk_fma_f32 v[98:99], v[180:181], v[24:25], v[98:99]
	v_pk_fma_f32 v[102:103], v[106:107], v[26:27], v[102:103]
	v_mul_f32_e32 v138, 0x45800000, v133
	v_cndmask_b32_e32 v138, v133, v138, vcc
	v_pk_add_f32 v[96:97], v[96:97], v[132:133] op_sel_hi:[1,0] neg_lo:[0,1] neg_hi:[0,1]
	v_pk_fma_f32 v[102:103], v[104:105], v[28:29], v[102:103]
	v_pk_mul_f32 v[96:97], v[96:97], v[138:139] op_sel_hi:[1,0]
	v_pk_fma_f32 v[102:103], v[100:101], v[30:31], v[102:103]
	v_pk_fma_f32 v[132:133], v[0:1], v[96:97], v[8:9]
	v_pk_fma_f32 v[102:103], v[180:181], v[34:35], v[102:103]
	v_mul_f32_e32 v96, 0xbfb8aa3b, v132
	v_exp_f32_e32 v138, v96
	v_mul_f32_e32 v96, 0xbfb8aa3b, v133
	v_exp_f32_e32 v139, v96
	v_pk_fma_f32 v[96:97], v[180:181], v[20:21], v[112:113]
	v_add_f32_e32 v112, 1.0, v138
	v_rcp_f32_e32 v112, v112
	v_add_f32_e32 v113, 1.0, v139
	v_rcp_f32_e32 v113, v113
	v_pk_fma_f32 v[102:103], v[66:67], v[32:33], v[102:103]
	v_pk_fma_f32 v[98:99], v[66:67], v[16:17], v[98:99]
	v_pk_fma_f32 v[102:103], v[68:69], v[18:19], v[102:103]
	v_pk_mul_f32 v[112:113], v[132:133], v[112:113]
	v_pk_fma_f32 v[98:99], v[68:69], v[14:15], v[98:99]
	v_pk_mul_f32 v[112:113], v[112:113], v[118:119]
	v_pk_fma_f32 v[36:37], v[106:107], v[58:59], v[36:37]
	v_cvt_pk_bf16_f32 v112, v112, v113
	global_store_dword v[94:95], v112, off
	v_pk_fma_f32 v[94:95], v[180:181], v[2:3], v[140:141]
	s_waitcnt vmcnt(28)
	v_lshlrev_b32_e32 v112, 16, v216
	v_pk_fma_f32 v[94:95], v[66:67], v[10:11], v[94:95]
	v_and_b32_e32 v113, 0xffff0000, v216
	v_pk_fma_f32 v[94:95], v[68:69], v[4:5], v[94:95]
	v_lshlrev_b32_e32 v58, 16, v229
	v_pk_fma_f32 v[94:95], v[70:71], v[6:7], v[94:95]
	v_and_b32_e32 v59, 0xffff0000, v229
	v_pk_fma_f32 v[94:95], v[72:73], v[12:13], v[94:95]
	v_pk_fma_f32 v[96:97], v[66:67], v[24:25], v[96:97]
	v_add_f32_e32 v132, v94, v95
	v_pk_mul_f32 v[118:119], v[94:95], v[94:95]
	v_pk_fma_f32 v[96:97], v[68:69], v[16:17], v[96:97]
	v_add_f32_e32 v118, v118, v119
	v_add_f32_dpp v119, v132, v132 quad_perm:[1,0,3,2] row_mask:0xf bank_mask:0xf bound_ctrl:1
	v_pk_fma_f32 v[96:97], v[70:71], v[14:15], v[96:97]
	v_add_f32_dpp v118, v118, v118 quad_perm:[1,0,3,2] row_mask:0xf bank_mask:0xf bound_ctrl:1
	v_add_f32_dpp v119, v119, v119 quad_perm:[2,3,0,1] row_mask:0xf bank_mask:0xf bound_ctrl:1
	v_pk_fma_f32 v[36:37], v[104:105], v[50:51], v[36:37]
	v_add_f32_dpp v118, v118, v118 quad_perm:[2,3,0,1] row_mask:0xf bank_mask:0xf bound_ctrl:1
	v_add_f32_dpp v119, v119, v119 row_half_mirror row_mask:0xf bank_mask:0xf bound_ctrl:1
	v_pk_fma_f32 v[36:37], v[100:101], v[52:53], v[36:37]
	v_add_f32_dpp v118, v118, v118 row_half_mirror row_mask:0xf bank_mask:0xf bound_ctrl:1
	v_add_f32_dpp v119, v119, v119 row_mirror row_mask:0xf bank_mask:0xf bound_ctrl:1
	v_mov_b32_e32 v132, v119
	s_nop 1
	v_permlane16_swap_b32 v119, v132
	v_add_f32_dpp v118, v118, v118 row_mirror row_mask:0xf bank_mask:0xf bound_ctrl:1
	v_add_f32_e32 v119, v119, v132
	v_mov_b32_e32 v132, v118
	s_nop 1
	v_permlane16_swap_b32 v118, v132
	v_pk_fma_f32 v[60:61], v[180:181], v[56:57], v[36:37]
	v_add_f32_e32 v132, v118, v132
	v_ldexp_f32 v118, v119, -6
	v_ldexp_f32 v119, v132, -6
	v_fma_f32 v119, -v118, v118, v119
	v_max_f32_e32 v119, 0, v119
	v_add_f32_e32 v119, 0x3727c5ac, v119
	v_mul_f32_e32 v132, 0x4b800000, v119
	v_cmp_gt_f32_e32 vcc, s0, v119
	v_lshlrev_b32_e32 v56, 16, v232
	v_and_b32_e32 v57, 0xffff0000, v232
	v_cndmask_b32_e32 v119, v119, v132, vcc
	v_rsq_f32_e32 v119, v119
	v_lshlrev_b32_e32 v54, 16, v231
	v_and_b32_e32 v55, 0xffff0000, v231
	v_lshlrev_b32_e32 v52, 16, v234
	v_mul_f32_e32 v132, 0x45800000, v119
	v_cndmask_b32_e32 v132, v119, v132, vcc
	v_pk_add_f32 v[94:95], v[94:95], v[118:119] op_sel_hi:[1,0] neg_lo:[0,1] neg_hi:[0,1]
	v_and_b32_e32 v53, 0xffff0000, v234
	v_pk_mul_f32 v[94:95], v[94:95], v[132:133] op_sel_hi:[1,0]
	v_lshlrev_b32_e32 v50, 16, v233
	v_pk_fma_f32 v[118:119], v[0:1], v[94:95], v[8:9]
	v_and_b32_e32 v51, 0xffff0000, v233
	v_mul_f32_e32 v94, 0xbfb8aa3b, v118
	v_exp_f32_e32 v132, v94
	v_mul_f32_e32 v94, 0xbfb8aa3b, v119
	v_exp_f32_e32 v133, v94
	v_pk_fma_f32 v[94:95], v[66:67], v[20:21], v[110:111]
	v_add_f32_e32 v110, 1.0, v132
	v_rcp_f32_e32 v110, v110
	v_add_f32_e32 v111, 1.0, v133
	v_rcp_f32_e32 v111, v111
	v_pk_fma_f32 v[94:95], v[68:69], v[24:25], v[94:95]
	v_lshlrev_b32_e32 v36, 16, v236
	v_pk_fma_f32 v[94:95], v[70:71], v[16:17], v[94:95]
	v_pk_mul_f32 v[110:111], v[118:119], v[110:111]
	v_pk_fma_f32 v[94:95], v[72:73], v[14:15], v[94:95]
	v_pk_mul_f32 v[110:111], v[110:111], v[112:113]
	v_and_b32_e32 v37, 0xffff0000, v236
	v_cvt_pk_bf16_f32 v110, v110, v111
	global_store_dword v[92:93], v110, off
	v_pk_fma_f32 v[92:93], v[66:67], v[2:3], v[136:137]
	s_waitcnt vmcnt(26)
; #define GAS __attribute__((address_space(1)))
; __device__ __forceinline__ unsigned cvtpk(float lo, float hi) { f32x2 v = {lo, hi}; bf16x2_t b = __builtin_convertvector(v, bf16x2_t); return __builtin_bit_cast(unsigned, b); }
; __device__ __forceinline__ float bflo(unsigned w) { return __uint_as_float(w << 16); }
; __device__ __forceinline__ float bfhi(unsigned w) { return __uint_as_float(w & 0xffff0000u); }
; __device__ __forceinline__ float fsilu(float x) { return x * fsigmoid(x); }
; __device__ __forceinline__ void c_unit(Frame& F, int L, int u, bool dry) {
;     ...
; #pragma unroll
;         for (int t = 0; t < 16; ++t) {
;             float s = acc[t].x + acc[t].y, qq = acc[t].x * acc[t].x + acc[t].y * acc[t].y;
;             s = half_wave_sum(s); qq = half_wave_sum(qq);
;             const float mu = __builtin_ldexpf(s, -6), rstd = rsqrtf(fmaxf(__builtin_ldexpf(qq, -6) - mu * mu, 0.f) + LN_EPS);
;             const float h0 = (acc[t].x - mu) * rstd * gv.x + bv.x, h1 = (acc[t].y - mu) * rstd * gv.y + bv.y;
;             const unsigned ov = cvtpk(fsilu(h0) * bflo(sc[16 * sub + t]), fsilu(h1) * bfhi(sc[16 * sub + t])); if (!dry) *(GAS unsigned*)(SCG + (size_t)(tb + t) * 512) = ov;
	v_lshlrev_b32_e32 v110, 16, v214
	v_pk_fma_f32 v[92:93], v[68:69], v[10:11], v[92:93]
	v_and_b32_e32 v111, 0xffff0000, v214
	v_pk_fma_f32 v[92:93], v[70:71], v[4:5], v[92:93]
	v_lshlrev_b32_e32 v38, 16, v235
	v_pk_fma_f32 v[92:93], v[72:73], v[6:7], v[92:93]
	v_and_b32_e32 v39, 0xffff0000, v235
	v_pk_fma_f32 v[92:93], v[78:79], v[12:13], v[92:93]
	v_lshlrev_b32_e32 v42, 16, v238
	v_add_f32_e32 v118, v92, v93
	v_pk_mul_f32 v[112:113], v[92:93], v[92:93]
	v_and_b32_e32 v43, 0xffff0000, v238
	v_add_f32_e32 v112, v112, v113
	v_add_f32_dpp v113, v118, v118 quad_perm:[1,0,3,2] row_mask:0xf bank_mask:0xf bound_ctrl:1
	v_lshlrev_b32_e32 v44, 16, v237
	v_add_f32_dpp v112, v112, v112 quad_perm:[1,0,3,2] row_mask:0xf bank_mask:0xf bound_ctrl:1
	v_add_f32_dpp v113, v113, v113 quad_perm:[2,3,0,1] row_mask:0xf bank_mask:0xf bound_ctrl:1
	v_and_b32_e32 v45, 0xffff0000, v237
	v_add_f32_dpp v112, v112, v112 quad_perm:[2,3,0,1] row_mask:0xf bank_mask:0xf bound_ctrl:1
	v_add_f32_dpp v113, v113, v113 row_half_mirror row_mask:0xf bank_mask:0xf bound_ctrl:1
	v_lshlrev_b32_e32 v46, 16, v192
	v_add_f32_dpp v112, v112, v112 row_half_mirror row_mask:0xf bank_mask:0xf bound_ctrl:1
	v_add_f32_dpp v113, v113, v113 row_mirror row_mask:0xf bank_mask:0xf bound_ctrl:1
	v_mov_b32_e32 v118, v113
	s_nop 1
	v_permlane16_swap_b32 v113, v118
	v_add_f32_dpp v112, v112, v112 row_mirror row_mask:0xf bank_mask:0xf bound_ctrl:1
	v_add_f32_e32 v113, v113, v118
	v_mov_b32_e32 v118, v112
	s_nop 1
	v_permlane16_swap_b32 v112, v118
	v_and_b32_e32 v47, 0xffff0000, v192
	v_add_f32_e32 v118, v112, v118
	v_ldexp_f32 v112, v113, -6
	v_ldexp_f32 v113, v118, -6
	v_fma_f32 v113, -v112, v112, v113
	v_max_f32_e32 v113, 0, v113
	v_add_f32_e32 v113, 0x3727c5ac, v113
	v_mul_f32_e32 v118, 0x4b800000, v113
	v_cmp_gt_f32_e32 vcc, s0, v113
	s_nop 1
	v_cndmask_b32_e32 v113, v113, v118, vcc
	v_rsq_f32_e32 v113, v113
	s_nop 0
	v_mul_f32_e32 v118, 0x45800000, v113
	v_cndmask_b32_e32 v118, v113, v118, vcc
	v_pk_add_f32 v[92:93], v[92:93], v[112:113] op_sel_hi:[1,0] neg_lo:[0,1] neg_hi:[0,1]
	s_nop 0
	v_pk_mul_f32 v[92:93], v[92:93], v[118:119] op_sel_hi:[1,0]
	s_nop 0
	v_pk_fma_f32 v[112:113], v[0:1], v[92:93], v[8:9]
	s_nop 0
	v_mul_f32_e32 v92, 0xbfb8aa3b, v112
	v_exp_f32_e32 v118, v92
	v_mul_f32_e32 v92, 0xbfb8aa3b, v113
	v_exp_f32_e32 v119, v92
	v_pk_fma_f32 v[92:93], v[68:69], v[20:21], v[108:109]
	v_add_f32_e32 v108, 1.0, v118
	v_rcp_f32_e32 v108, v108
	v_add_f32_e32 v109, 1.0, v119
	v_rcp_f32_e32 v109, v109
	v_pk_fma_f32 v[92:93], v[70:71], v[24:25], v[92:93]
	v_pk_mul_f32 v[108:109], v[112:113], v[108:109]
	s_nop 0
	v_pk_mul_f32 v[108:109], v[108:109], v[110:111]
	v_pk_fma_f32 v[92:93], v[72:73], v[16:17], v[92:93]
	v_cvt_pk_bf16_f32 v108, v108, v109
	global_store_dword v[90:91], v108, off
	v_pk_fma_f32 v[90:91], v[68:69], v[2:3], v[124:125]
	s_waitcnt vmcnt(26)
	v_lshlrev_b32_e32 v108, 16, v212
	v_pk_fma_f32 v[90:91], v[70:71], v[10:11], v[90:91]
	v_and_b32_e32 v109, 0xffff0000, v212
	v_pk_fma_f32 v[90:91], v[72:73], v[4:5], v[90:91]
	v_pk_fma_f32 v[92:93], v[78:79], v[14:15], v[92:93]
	v_pk_fma_f32 v[90:91], v[78:79], v[6:7], v[90:91]
	s_nop 0
	v_pk_fma_f32 v[90:91], v[114:115], v[12:13], v[90:91]
	s_nop 0
	v_add_f32_e32 v112, v90, v91
	v_pk_mul_f32 v[110:111], v[90:91], v[90:91]
	s_nop 0
	v_add_f32_e32 v110, v110, v111
	v_add_f32_dpp v111, v112, v112 quad_perm:[1,0,3,2] row_mask:0xf bank_mask:0xf bound_ctrl:1
	s_nop 0
	v_add_f32_dpp v110, v110, v110 quad_perm:[1,0,3,2] row_mask:0xf bank_mask:0xf bound_ctrl:1
	v_add_f32_dpp v111, v111, v111 quad_perm:[2,3,0,1] row_mask:0xf bank_mask:0xf bound_ctrl:1
	s_nop 0
	v_add_f32_dpp v110, v110, v110 quad_perm:[2,3,0,1] row_mask:0xf bank_mask:0xf bound_ctrl:1
	v_add_f32_dpp v111, v111, v111 row_half_mirror row_mask:0xf bank_mask:0xf bound_ctrl:1
	s_nop 0
	v_add_f32_dpp v110, v110, v110 row_half_mirror row_mask:0xf bank_mask:0xf bound_ctrl:1
	v_add_f32_dpp v111, v111, v111 row_mirror row_mask:0xf bank_mask:0xf bound_ctrl:1
	v_mov_b32_e32 v112, v111
	s_nop 1
	v_permlane16_swap_b32 v111, v112
	v_add_f32_dpp v110, v110, v110 row_mirror row_mask:0xf bank_mask:0xf bound_ctrl:1
	v_add_f32_e32 v111, v111, v112
	v_mov_b32_e32 v112, v110
	s_nop 1
	v_permlane16_swap_b32 v110, v112
	s_nop 0
	v_add_f32_e32 v112, v110, v112
	v_ldexp_f32 v110, v111, -6
	v_ldexp_f32 v111, v112, -6
	v_fma_f32 v111, -v110, v110, v111
	v_max_f32_e32 v111, 0, v111
	v_add_f32_e32 v111, 0x3727c5ac, v111
	v_mul_f32_e32 v112, 0x4b800000, v111
	v_cmp_gt_f32_e32 vcc, s0, v111
	s_nop 1
	v_cndmask_b32_e32 v111, v111, v112, vcc
	v_rsq_f32_e32 v111, v111
	s_nop 0
	v_mul_f32_e32 v112, 0x45800000, v111
	v_cndmask_b32_e32 v112, v111, v112, vcc
	v_pk_add_f32 v[90:91], v[90:91], v[110:111] op_sel_hi:[1,0] neg_lo:[0,1] neg_hi:[0,1]
	s_nop 0
	v_pk_mul_f32 v[90:91], v[90:91], v[112:113] op_sel_hi:[1,0]
	s_nop 0
	v_pk_fma_f32 v[110:111], v[0:1], v[90:91], v[8:9]
	s_nop 0
	v_mul_f32_e32 v90, 0xbfb8aa3b, v110
	v_exp_f32_e32 v112, v90
	v_mul_f32_e32 v90, 0xbfb8aa3b, v111
	v_exp_f32_e32 v113, v90
	v_pk_fma_f32 v[90:91], v[70:71], v[20:21], v[102:103]
	v_add_f32_e32 v102, 1.0, v112
	v_rcp_f32_e32 v102, v102
	v_add_f32_e32 v103, 1.0, v113
	v_rcp_f32_e32 v103, v103
	v_pk_fma_f32 v[90:91], v[72:73], v[24:25], v[90:91]
	v_pk_mul_f32 v[102:103], v[110:111], v[102:103]
	s_nop 0
	v_pk_mul_f32 v[102:103], v[102:103], v[108:109]
	v_pk_fma_f32 v[90:91], v[78:79], v[16:17], v[90:91]
	v_cvt_pk_bf16_f32 v102, v102, v103
	global_store_dword v[88:89], v102, off
	v_pk_fma_f32 v[88:89], v[70:71], v[2:3], v[98:99]
	v_pk_fma_f32 v[98:99], v[106:107], v[22:23], v[126:127]
	v_pk_fma_f32 v[88:89], v[72:73], v[10:11], v[88:89]
	v_pk_fma_f32 v[98:99], v[104:105], v[26:27], v[98:99]
	v_pk_fma_f32 v[88:89], v[78:79], v[4:5], v[88:89]
	v_pk_fma_f32 v[98:99], v[100:101], v[28:29], v[98:99]
	v_pk_fma_f32 v[88:89], v[114:115], v[6:7], v[88:89]
	v_pk_fma_f32 v[98:99], v[180:181], v[30:31], v[98:99]
	v_pk_fma_f32 v[88:89], v[58:59], v[12:13], v[88:89]
	v_pk_fma_f32 v[98:99], v[66:67], v[34:35], v[98:99]
	v_add_f32_e32 v108, v88, v89
	v_pk_mul_f32 v[106:107], v[88:89], v[88:89]
	v_pk_fma_f32 v[98:99], v[68:69], v[32:33], v[98:99]
	v_add_f32_e32 v106, v106, v107
	v_add_f32_dpp v107, v108, v108 quad_perm:[1,0,3,2] row_mask:0xf bank_mask:0xf bound_ctrl:1
	v_pk_fma_f32 v[98:99], v[70:71], v[18:19], v[98:99]
	v_add_f32_dpp v106, v106, v106 quad_perm:[1,0,3,2] row_mask:0xf bank_mask:0xf bound_ctrl:1
	v_add_f32_dpp v107, v107, v107 quad_perm:[2,3,0,1] row_mask:0xf bank_mask:0xf bound_ctrl:1
	s_waitcnt vmcnt(25)
; #define GAS __attribute__((address_space(1)))
; __device__ __forceinline__ unsigned cvtpk(float lo, float hi) { f32x2 v = {lo, hi}; bf16x2_t b = __builtin_convertvector(v, bf16x2_t); return __builtin_bit_cast(unsigned, b); }
; __device__ __forceinline__ float bflo(unsigned w) { return __uint_as_float(w << 16); }
; __device__ __forceinline__ float bfhi(unsigned w) { return __uint_as_float(w & 0xffff0000u); }
; __device__ __forceinline__ float fsilu(float x) { return x * fsigmoid(x); }
; __device__ __forceinline__ void c_unit(Frame& F, int L, int u, bool dry) {
;     ...
; #pragma unroll
;         for (int t = 0; t < 16; ++t) {
;             float s = acc[t].x + acc[t].y, qq = acc[t].x * acc[t].x + acc[t].y * acc[t].y;
;             s = half_wave_sum(s); qq = half_wave_sum(qq);
;             const float mu = __builtin_ldexpf(s, -6), rstd = rsqrtf(fmaxf(__builtin_ldexpf(qq, -6) - mu * mu, 0.f) + LN_EPS);
;             const float h0 = (acc[t].x - mu) * rstd * gv.x + bv.x, h1 = (acc[t].y - mu) * rstd * gv.y + bv.y;
;             const unsigned ov = cvtpk(fsilu(h0) * bflo(sc[16 * sub + t]), fsilu(h1) * bfhi(sc[16 * sub + t])); if (!dry) *(GAS unsigned*)(SCG + (size_t)(tb + t) * 512) = ov;
	v_lshlrev_b32_e32 v102, 16, v211
	v_add_f32_dpp v106, v106, v106 quad_perm:[2,3,0,1] row_mask:0xf bank_mask:0xf bound_ctrl:1
	v_add_f32_dpp v107, v107, v107 row_half_mirror row_mask:0xf bank_mask:0xf bound_ctrl:1
	v_and_b32_e32 v103, 0xffff0000, v211
	v_add_f32_dpp v106, v106, v106 row_half_mirror row_mask:0xf bank_mask:0xf bound_ctrl:1
	v_add_f32_dpp v107, v107, v107 row_mirror row_mask:0xf bank_mask:0xf bound_ctrl:1
	v_mov_b32_e32 v108, v107
	s_nop 1
	v_permlane16_swap_b32 v107, v108
	v_add_f32_dpp v106, v106, v106 row_mirror row_mask:0xf bank_mask:0xf bound_ctrl:1
	v_add_f32_e32 v107, v107, v108
	v_mov_b32_e32 v108, v106
	s_nop 1
	v_permlane16_swap_b32 v106, v108
	v_pk_fma_f32 v[90:91], v[114:115], v[14:15], v[90:91]
	v_add_f32_e32 v108, v106, v108
	v_ldexp_f32 v106, v107, -6
	v_ldexp_f32 v107, v108, -6
	v_fma_f32 v107, -v106, v106, v107
	v_max_f32_e32 v107, 0, v107
	v_add_f32_e32 v107, 0x3727c5ac, v107
	v_mul_f32_e32 v108, 0x4b800000, v107
	v_cmp_gt_f32_e32 vcc, s0, v107
	v_pk_fma_f32 v[90:91], v[58:59], v[2:3], v[90:91]
	s_nop 0
	v_cndmask_b32_e32 v107, v107, v108, vcc
	v_rsq_f32_e32 v107, v107
	v_pk_fma_f32 v[90:91], v[56:57], v[10:11], v[90:91]
	v_mul_f32_e32 v108, 0x45800000, v107
	v_cndmask_b32_e32 v108, v107, v108, vcc
	v_pk_add_f32 v[88:89], v[88:89], v[106:107] op_sel_hi:[1,0] neg_lo:[0,1] neg_hi:[0,1]
	v_pk_fma_f32 v[90:91], v[54:55], v[4:5], v[90:91]
	v_pk_mul_f32 v[88:89], v[88:89], v[108:109] op_sel_hi:[1,0]
	v_pk_fma_f32 v[90:91], v[52:53], v[6:7], v[90:91]
	v_pk_fma_f32 v[106:107], v[0:1], v[88:89], v[8:9]
	v_pk_fma_f32 v[90:91], v[50:51], v[12:13], v[90:91]
	v_mul_f32_e32 v88, 0xbfb8aa3b, v106
	v_exp_f32_e32 v108, v88
	v_mul_f32_e32 v88, 0xbfb8aa3b, v107
	v_exp_f32_e32 v109, v88
	v_pk_fma_f32 v[88:89], v[72:73], v[20:21], v[98:99]
	v_add_f32_e32 v98, 1.0, v108
	v_rcp_f32_e32 v98, v98
	v_add_f32_e32 v99, 1.0, v109
	v_rcp_f32_e32 v99, v99
	v_pk_fma_f32 v[88:89], v[78:79], v[24:25], v[88:89]
	v_pk_mul_f32 v[98:99], v[106:107], v[98:99]
	s_nop 0
	v_pk_mul_f32 v[98:99], v[98:99], v[102:103]
	v_pk_fma_f32 v[88:89], v[114:115], v[16:17], v[88:89]
	v_cvt_pk_bf16_f32 v98, v98, v99
	global_store_dword v[86:87], v98, off
	v_pk_fma_f32 v[86:87], v[72:73], v[2:3], v[96:97]
	v_pk_fma_f32 v[96:97], v[104:105], v[22:23], v[122:123]
	v_pk_fma_f32 v[86:87], v[78:79], v[10:11], v[86:87]
	v_pk_fma_f32 v[96:97], v[100:101], v[26:27], v[96:97]
	v_pk_fma_f32 v[86:87], v[114:115], v[4:5], v[86:87]
	v_pk_fma_f32 v[96:97], v[180:181], v[28:29], v[96:97]
	v_pk_fma_f32 v[86:87], v[58:59], v[6:7], v[86:87]
	v_pk_fma_f32 v[96:97], v[66:67], v[30:31], v[96:97]
	v_pk_fma_f32 v[86:87], v[56:57], v[12:13], v[86:87]
	v_pk_fma_f32 v[96:97], v[68:69], v[34:35], v[96:97]
	v_add_f32_e32 v104, v86, v87
	v_pk_mul_f32 v[102:103], v[86:87], v[86:87]
	v_pk_fma_f32 v[96:97], v[70:71], v[32:33], v[96:97]
	v_add_f32_e32 v102, v102, v103
	v_add_f32_dpp v103, v104, v104 quad_perm:[1,0,3,2] row_mask:0xf bank_mask:0xf bound_ctrl:1
	v_pk_fma_f32 v[96:97], v[72:73], v[18:19], v[96:97]
	v_add_f32_dpp v102, v102, v102 quad_perm:[1,0,3,2] row_mask:0xf bank_mask:0xf bound_ctrl:1
	v_add_f32_dpp v103, v103, v103 quad_perm:[2,3,0,1] row_mask:0xf bank_mask:0xf bound_ctrl:1
	s_waitcnt vmcnt(25)
	v_lshlrev_b32_e32 v98, 16, v210
	v_add_f32_dpp v102, v102, v102 quad_perm:[2,3,0,1] row_mask:0xf bank_mask:0xf bound_ctrl:1
	v_add_f32_dpp v103, v103, v103 row_half_mirror row_mask:0xf bank_mask:0xf bound_ctrl:1
	v_and_b32_e32 v99, 0xffff0000, v210
	v_add_f32_dpp v102, v102, v102 row_half_mirror row_mask:0xf bank_mask:0xf bound_ctrl:1
	v_add_f32_dpp v103, v103, v103 row_mirror row_mask:0xf bank_mask:0xf bound_ctrl:1
	v_mov_b32_e32 v104, v103
	s_nop 1
	v_permlane16_swap_b32 v103, v104
	v_add_f32_dpp v102, v102, v102 row_mirror row_mask:0xf bank_mask:0xf bound_ctrl:1
	v_add_f32_e32 v103, v103, v104
	v_mov_b32_e32 v104, v102
	s_nop 1
	v_permlane16_swap_b32 v102, v104
	v_pk_fma_f32 v[88:89], v[58:59], v[14:15], v[88:89]
	v_add_f32_e32 v104, v102, v104
	v_ldexp_f32 v102, v103, -6
	v_ldexp_f32 v103, v104, -6
	v_fma_f32 v103, -v102, v102, v103
	v_max_f32_e32 v103, 0, v103
	v_add_f32_e32 v103, 0x3727c5ac, v103
	v_mul_f32_e32 v104, 0x4b800000, v103
	v_cmp_gt_f32_e32 vcc, s0, v103
	s_nop 1
	v_cndmask_b32_e32 v103, v103, v104, vcc
	v_rsq_f32_e32 v103, v103
	s_nop 0
	v_mul_f32_e32 v104, 0x45800000, v103
	v_cndmask_b32_e32 v104, v103, v104, vcc
	v_pk_add_f32 v[86:87], v[86:87], v[102:103] op_sel_hi:[1,0] neg_lo:[0,1] neg_hi:[0,1]
	s_nop 0
	v_pk_mul_f32 v[86:87], v[86:87], v[104:105] op_sel_hi:[1,0]
	s_nop 0
	v_pk_fma_f32 v[102:103], v[0:1], v[86:87], v[8:9]
	s_nop 0
	v_mul_f32_e32 v86, 0xbfb8aa3b, v102
	v_exp_f32_e32 v104, v86
	v_mul_f32_e32 v86, 0xbfb8aa3b, v103
	v_exp_f32_e32 v105, v86
	v_pk_fma_f32 v[86:87], v[78:79], v[20:21], v[96:97]
	v_add_f32_e32 v96, 1.0, v104
	v_rcp_f32_e32 v96, v96
	v_add_f32_e32 v97, 1.0, v105
	v_rcp_f32_e32 v97, v97
	v_pk_fma_f32 v[86:87], v[114:115], v[24:25], v[86:87]
	v_pk_mul_f32 v[96:97], v[102:103], v[96:97]
	s_nop 0
	v_pk_mul_f32 v[96:97], v[96:97], v[98:99]
	v_pk_fma_f32 v[86:87], v[58:59], v[16:17], v[86:87]
	v_cvt_pk_bf16_f32 v96, v96, v97
	global_store_dword v[84:85], v96, off
	v_pk_fma_f32 v[84:85], v[78:79], v[2:3], v[94:95]
	v_pk_fma_f32 v[94:95], v[100:101], v[22:23], v[120:121]
	v_pk_fma_f32 v[84:85], v[114:115], v[10:11], v[84:85]
	v_pk_fma_f32 v[94:95], v[180:181], v[26:27], v[94:95]
	v_pk_fma_f32 v[84:85], v[58:59], v[4:5], v[84:85]
	v_pk_fma_f32 v[94:95], v[66:67], v[28:29], v[94:95]
	v_pk_fma_f32 v[84:85], v[56:57], v[6:7], v[84:85]
	v_pk_fma_f32 v[94:95], v[68:69], v[30:31], v[94:95]
	v_pk_fma_f32 v[84:85], v[54:55], v[12:13], v[84:85]
	v_pk_fma_f32 v[94:95], v[70:71], v[34:35], v[94:95]
	v_add_f32_e32 v100, v84, v85
	v_pk_mul_f32 v[98:99], v[84:85], v[84:85]
	v_pk_fma_f32 v[94:95], v[72:73], v[32:33], v[94:95]
	v_add_f32_e32 v98, v98, v99
	v_add_f32_dpp v99, v100, v100 quad_perm:[1,0,3,2] row_mask:0xf bank_mask:0xf bound_ctrl:1
	v_pk_fma_f32 v[94:95], v[78:79], v[18:19], v[94:95]
	v_add_f32_dpp v98, v98, v98 quad_perm:[1,0,3,2] row_mask:0xf bank_mask:0xf bound_ctrl:1
	v_add_f32_dpp v99, v99, v99 quad_perm:[2,3,0,1] row_mask:0xf bank_mask:0xf bound_ctrl:1
	s_waitcnt vmcnt(25)
; #define GAS __attribute__((address_space(1)))
; __device__ __forceinline__ unsigned cvtpk(float lo, float hi) { f32x2 v = {lo, hi}; bf16x2_t b = __builtin_convertvector(v, bf16x2_t); return __builtin_bit_cast(unsigned, b); }
; __device__ __forceinline__ float bflo(unsigned w) { return __uint_as_float(w << 16); }
; __device__ __forceinline__ float bfhi(unsigned w) { return __uint_as_float(w & 0xffff0000u); }
; __device__ __forceinline__ float fsilu(float x) { return x * fsigmoid(x); }
; __device__ __forceinline__ void c_unit(Frame& F, int L, int u, bool dry) {
;     ...
; #pragma unroll
;         for (int t = 0; t < 16; ++t) {
;             float s = acc[t].x + acc[t].y, qq = acc[t].x * acc[t].x + acc[t].y * acc[t].y;
;             s = half_wave_sum(s); qq = half_wave_sum(qq);
;             const float mu = __builtin_ldexpf(s, -6), rstd = rsqrtf(fmaxf(__builtin_ldexpf(qq, -6) - mu * mu, 0.f) + LN_EPS);
;             const float h0 = (acc[t].x - mu) * rstd * gv.x + bv.x, h1 = (acc[t].y - mu) * rstd * gv.y + bv.y;
;             const unsigned ov = cvtpk(fsilu(h0) * bflo(sc[16 * sub + t]), fsilu(h1) * bfhi(sc[16 * sub + t])); if (!dry) *(GAS unsigned*)(SCG + (size_t)(tb + t) * 512) = ov;
	v_lshlrev_b32_e32 v96, 16, v209
	v_add_f32_dpp v98, v98, v98 quad_perm:[2,3,0,1] row_mask:0xf bank_mask:0xf bound_ctrl:1
	v_add_f32_dpp v99, v99, v99 row_half_mirror row_mask:0xf bank_mask:0xf bound_ctrl:1
	v_and_b32_e32 v97, 0xffff0000, v209
	v_add_f32_dpp v98, v98, v98 row_half_mirror row_mask:0xf bank_mask:0xf bound_ctrl:1
	v_add_f32_dpp v99, v99, v99 row_mirror row_mask:0xf bank_mask:0xf bound_ctrl:1
	v_mov_b32_e32 v100, v99
	s_nop 1
	v_permlane16_swap_b32 v99, v100
	v_add_f32_dpp v98, v98, v98 row_mirror row_mask:0xf bank_mask:0xf bound_ctrl:1
	v_add_f32_e32 v99, v99, v100
	v_mov_b32_e32 v100, v98
	s_nop 1
	v_permlane16_swap_b32 v98, v100
	v_pk_fma_f32 v[86:87], v[56:57], v[14:15], v[86:87]
	v_add_f32_e32 v100, v98, v100
	v_ldexp_f32 v98, v99, -6
	v_ldexp_f32 v99, v100, -6
	v_fma_f32 v99, -v98, v98, v99
	v_max_f32_e32 v99, 0, v99
	v_add_f32_e32 v99, 0x3727c5ac, v99
	v_mul_f32_e32 v100, 0x4b800000, v99
	v_cmp_gt_f32_e32 vcc, s0, v99
	s_nop 1
	v_cndmask_b32_e32 v99, v99, v100, vcc
	v_rsq_f32_e32 v99, v99
	s_nop 0
	v_mul_f32_e32 v100, 0x45800000, v99
	v_cndmask_b32_e32 v100, v99, v100, vcc
	v_pk_add_f32 v[84:85], v[84:85], v[98:99] op_sel_hi:[1,0] neg_lo:[0,1] neg_hi:[0,1]
	s_nop 0
	v_pk_mul_f32 v[84:85], v[84:85], v[100:101] op_sel_hi:[1,0]
	s_nop 0
	v_pk_fma_f32 v[98:99], v[0:1], v[84:85], v[8:9]
	s_nop 0
	v_mul_f32_e32 v84, 0xbfb8aa3b, v98
	v_exp_f32_e32 v100, v84
	v_mul_f32_e32 v84, 0xbfb8aa3b, v99
	v_exp_f32_e32 v101, v84
	v_pk_fma_f32 v[84:85], v[114:115], v[20:21], v[94:95]
	v_add_f32_e32 v94, 1.0, v100
	v_rcp_f32_e32 v94, v94
	v_add_f32_e32 v95, 1.0, v101
	v_rcp_f32_e32 v95, v95
	v_pk_fma_f32 v[84:85], v[58:59], v[24:25], v[84:85]
	v_pk_mul_f32 v[94:95], v[98:99], v[94:95]
	s_nop 0
	v_pk_mul_f32 v[94:95], v[94:95], v[96:97]
	v_pk_fma_f32 v[84:85], v[56:57], v[16:17], v[84:85]
	v_cvt_pk_bf16_f32 v94, v94, v95
	global_store_dword v[82:83], v94, off
	v_pk_fma_f32 v[82:83], v[114:115], v[2:3], v[92:93]
	v_pk_fma_f32 v[92:93], v[180:181], v[22:23], v[116:117]
	v_pk_fma_f32 v[82:83], v[58:59], v[10:11], v[82:83]
	v_pk_fma_f32 v[22:23], v[66:67], v[22:23], v[60:61]
	v_pk_fma_f32 v[82:83], v[56:57], v[4:5], v[82:83]
	v_pk_fma_f32 v[92:93], v[66:67], v[26:27], v[92:93]
	v_pk_fma_f32 v[82:83], v[54:55], v[6:7], v[82:83]
	v_pk_fma_f32 v[22:23], v[68:69], v[26:27], v[22:23]
	v_pk_fma_f32 v[82:83], v[52:53], v[12:13], v[82:83]
	v_pk_fma_f32 v[92:93], v[68:69], v[28:29], v[92:93]
	v_add_f32_e32 v98, v82, v83
	v_pk_mul_f32 v[96:97], v[82:83], v[82:83]
	v_pk_fma_f32 v[22:23], v[70:71], v[28:29], v[22:23]
	v_add_f32_e32 v96, v96, v97
	v_add_f32_dpp v97, v98, v98 quad_perm:[1,0,3,2] row_mask:0xf bank_mask:0xf bound_ctrl:1
	v_add_f32_e32 v28, v90, v91
	v_add_f32_dpp v96, v96, v96 quad_perm:[1,0,3,2] row_mask:0xf bank_mask:0xf bound_ctrl:1
	v_add_f32_dpp v97, v97, v97 quad_perm:[2,3,0,1] row_mask:0xf bank_mask:0xf bound_ctrl:1
	v_pk_mul_f32 v[26:27], v[90:91], v[90:91]
	v_add_f32_dpp v96, v96, v96 quad_perm:[2,3,0,1] row_mask:0xf bank_mask:0xf bound_ctrl:1
	v_add_f32_dpp v97, v97, v97 row_half_mirror row_mask:0xf bank_mask:0xf bound_ctrl:1
	v_add_f32_e32 v26, v26, v27
	v_add_f32_dpp v96, v96, v96 row_half_mirror row_mask:0xf bank_mask:0xf bound_ctrl:1
	v_add_f32_dpp v97, v97, v97 row_mirror row_mask:0xf bank_mask:0xf bound_ctrl:1
	v_mov_b32_e32 v98, v97
	s_nop 1
	v_permlane16_swap_b32 v97, v98
	v_add_f32_dpp v96, v96, v96 row_mirror row_mask:0xf bank_mask:0xf bound_ctrl:1
	v_add_f32_e32 v97, v97, v98
	v_mov_b32_e32 v98, v96
	s_nop 1
	v_permlane16_swap_b32 v96, v98
	v_add_f32_dpp v27, v28, v28 quad_perm:[1,0,3,2] row_mask:0xf bank_mask:0xf bound_ctrl:1
	v_add_f32_e32 v98, v96, v98
	v_ldexp_f32 v96, v97, -6
	v_add_f32_dpp v27, v27, v27 quad_perm:[2,3,0,1] row_mask:0xf bank_mask:0xf bound_ctrl:1
	v_ldexp_f32 v97, v98, -6
	v_add_f32_dpp v26, v26, v26 quad_perm:[1,0,3,2] row_mask:0xf bank_mask:0xf bound_ctrl:1
	v_add_f32_dpp v27, v27, v27 row_half_mirror row_mask:0xf bank_mask:0xf bound_ctrl:1
	v_fma_f32 v97, -v96, v96, v97
	v_add_f32_dpp v26, v26, v26 quad_perm:[2,3,0,1] row_mask:0xf bank_mask:0xf bound_ctrl:1
	v_add_f32_dpp v27, v27, v27 row_mirror row_mask:0xf bank_mask:0xf bound_ctrl:1
	v_max_f32_e32 v97, 0, v97
	v_mov_b32_e32 v28, v27
	v_add_f32_dpp v26, v26, v26 row_half_mirror row_mask:0xf bank_mask:0xf bound_ctrl:1
	v_add_f32_e32 v97, 0x3727c5ac, v97
	s_nop 1
	v_permlane16_swap_b32 v27, v28
	v_mul_f32_e32 v98, 0x4b800000, v97
	v_add_f32_dpp v26, v26, v26 row_mirror row_mask:0xf bank_mask:0xf bound_ctrl:1
	v_cmp_gt_f32_e32 vcc, s0, v97
	v_add_f32_e32 v27, v27, v28
	v_mov_b32_e32 v28, v26
	v_cndmask_b32_e32 v97, v97, v98, vcc
	s_nop 1
	v_permlane16_swap_b32 v26, v28
	v_rsq_f32_e32 v97, v97
	v_add_f32_e32 v28, v26, v28
	v_ldexp_f32 v26, v27, -6
	v_ldexp_f32 v27, v28, -6
	v_fma_f32 v27, -v26, v26, v27
	v_max_f32_e32 v27, 0, v27
	v_mul_f32_e32 v98, 0x45800000, v97
	v_add_f32_e32 v27, 0x3727c5ac, v27
	v_cndmask_b32_e32 v98, v97, v98, vcc
	v_mul_f32_e32 v28, 0x4b800000, v27
	v_cmp_gt_f32_e32 vcc, s0, v27
	v_pk_add_f32 v[82:83], v[82:83], v[96:97] op_sel_hi:[1,0] neg_lo:[0,1] neg_hi:[0,1]
	v_pk_fma_f32 v[92:93], v[70:71], v[30:31], v[92:93]
	v_cndmask_b32_e32 v27, v27, v28, vcc
	v_pk_mul_f32 v[82:83], v[82:83], v[98:99] op_sel_hi:[1,0]
	v_pk_fma_f32 v[22:23], v[72:73], v[30:31], v[22:23]
	v_rsq_f32_e32 v27, v27
	v_pk_fma_f32 v[92:93], v[72:73], v[34:35], v[92:93]
	v_pk_fma_f32 v[96:97], v[0:1], v[82:83], v[8:9]
	v_pk_fma_f32 v[22:23], v[78:79], v[34:35], v[22:23]
	v_pk_fma_f32 v[92:93], v[78:79], v[32:33], v[92:93]
	v_mul_f32_e32 v82, 0xbfb8aa3b, v96
	v_pk_fma_f32 v[22:23], v[114:115], v[32:33], v[22:23]
	v_pk_fma_f32 v[92:93], v[114:115], v[18:19], v[92:93]
; #define GAS __attribute__((address_space(1)))
; __device__ __forceinline__ unsigned cvtpk(float lo, float hi) { f32x2 v = {lo, hi}; bf16x2_t b = __builtin_convertvector(v, bf16x2_t); return __builtin_bit_cast(unsigned, b); }
; __device__ __forceinline__ float bflo(unsigned w) { return __uint_as_float(w << 16); }
; __device__ __forceinline__ float bfhi(unsigned w) { return __uint_as_float(w & 0xffff0000u); }
; __device__ __forceinline__ float fsilu(float x) { return x * fsigmoid(x); }
; __device__ __forceinline__ void c_unit(Frame& F, int L, int u, bool dry) {
;     ...
;         for (int i = 0; i < 46; ++i) {
;             const float h0 = bflo(hv[16 * sub + i]), h1 = bfhi(hv[16 * sub + i]);
; #pragma unroll
;             for (int t = 0; t < 16; ++t) { const int j = i - t; if (j >= 0 && j < CONVW) { acc[t].x = fmaf(h0, wv[j].x, acc[t].x); acc[t].y = fmaf(h1, wv[j].y, acc[t].y); } }
;         }
; #pragma unroll
;         for (int t = 0; t < 16; ++t) {
;             float s = acc[t].x + acc[t].y, qq = acc[t].x * acc[t].x + acc[t].y * acc[t].y;
;             s = half_wave_sum(s); qq = half_wave_sum(qq);
;             const float mu = __builtin_ldexpf(s, -6), rstd = rsqrtf(fmaxf(__builtin_ldexpf(qq, -6) - mu * mu, 0.f) + LN_EPS);
;             const float h0 = (acc[t].x - mu) * rstd * gv.x + bv.x, h1 = (acc[t].y - mu) * rstd * gv.y + bv.y;
;             const unsigned ov = cvtpk(fsilu(h0) * bflo(sc[16 * sub + t]), fsilu(h1) * bfhi(sc[16 * sub + t])); if (!dry) *(GAS unsigned*)(SCG + (size_t)(tb + t) * 512) = ov;
;         }
	v_exp_f32_e32 v98, v82
	v_mul_f32_e32 v82, 0xbfb8aa3b, v97
	v_pk_fma_f32 v[18:19], v[58:59], v[18:19], v[22:23]
	v_exp_f32_e32 v99, v82
	v_pk_fma_f32 v[82:83], v[58:59], v[20:21], v[92:93]
	v_pk_fma_f32 v[18:19], v[56:57], v[20:21], v[18:19]
	v_mul_f32_e32 v20, 0x45800000, v27
	v_cndmask_b32_e32 v20, v27, v20, vcc
	v_pk_add_f32 v[22:23], v[90:91], v[26:27] op_sel_hi:[1,0] neg_lo:[0,1] neg_hi:[0,1]
	v_pk_fma_f32 v[82:83], v[56:57], v[24:25], v[82:83]
	v_pk_mul_f32 v[20:21], v[22:23], v[20:21] op_sel_hi:[1,0]
	v_pk_fma_f32 v[18:19], v[54:55], v[24:25], v[18:19]
	v_pk_fma_f32 v[20:21], v[0:1], v[20:21], v[8:9]
	v_pk_fma_f32 v[82:83], v[54:55], v[16:17], v[82:83]
	v_mul_f32_e32 v22, 0xbfb8aa3b, v20
	v_mul_f32_e32 v23, 0xbfb8aa3b, v21
	v_exp_f32_e32 v22, v22
	v_exp_f32_e32 v23, v23
	v_pk_fma_f32 v[16:17], v[52:53], v[16:17], v[18:19]
	v_add_f32_e32 v92, 1.0, v98
	v_add_f32_e32 v18, 1.0, v22
	v_add_f32_e32 v19, 1.0, v23
	v_pk_fma_f32 v[22:23], v[56:57], v[2:3], v[88:89]
	v_rcp_f32_e32 v18, v18
	v_pk_fma_f32 v[22:23], v[54:55], v[10:11], v[22:23]
	v_rcp_f32_e32 v19, v19
	v_pk_fma_f32 v[22:23], v[52:53], v[4:5], v[22:23]
	v_add_f32_e32 v93, 1.0, v99
	v_pk_fma_f32 v[22:23], v[50:51], v[6:7], v[22:23]
	v_pk_fma_f32 v[84:85], v[54:55], v[14:15], v[84:85]
	v_pk_fma_f32 v[22:23], v[36:37], v[12:13], v[22:23]
	v_rcp_f32_e32 v92, v92
	v_add_f32_e32 v26, v22, v23
	v_pk_mul_f32 v[24:25], v[22:23], v[22:23]
	v_rcp_f32_e32 v93, v93
	v_add_f32_e32 v24, v24, v25
	v_add_f32_dpp v25, v26, v26 quad_perm:[1,0,3,2] row_mask:0xf bank_mask:0xf bound_ctrl:1
	v_pk_fma_f32 v[82:83], v[52:53], v[14:15], v[82:83]
	v_add_f32_dpp v24, v24, v24 quad_perm:[1,0,3,2] row_mask:0xf bank_mask:0xf bound_ctrl:1
	v_add_f32_dpp v25, v25, v25 quad_perm:[2,3,0,1] row_mask:0xf bank_mask:0xf bound_ctrl:1
	v_pk_fma_f32 v[14:15], v[50:51], v[14:15], v[16:17]
	v_add_f32_dpp v24, v24, v24 quad_perm:[2,3,0,1] row_mask:0xf bank_mask:0xf bound_ctrl:1
	v_add_f32_dpp v25, v25, v25 row_half_mirror row_mask:0xf bank_mask:0xf bound_ctrl:1
	v_pk_mul_f32 v[16:17], v[20:21], v[18:19]
	v_add_f32_dpp v24, v24, v24 row_half_mirror row_mask:0xf bank_mask:0xf bound_ctrl:1
	v_add_f32_dpp v25, v25, v25 row_mirror row_mask:0xf bank_mask:0xf bound_ctrl:1
	v_mov_b32_e32 v26, v25
	s_nop 1
	v_permlane16_swap_b32 v25, v26
	v_add_f32_dpp v24, v24, v24 row_mirror row_mask:0xf bank_mask:0xf bound_ctrl:1
	v_add_f32_e32 v25, v25, v26
	v_mov_b32_e32 v26, v24
	s_nop 1
	v_permlane16_swap_b32 v24, v26
	v_lshlrev_b32_e32 v94, 16, v215
	v_add_f32_e32 v26, v24, v26
	v_ldexp_f32 v24, v25, -6
	v_ldexp_f32 v25, v26, -6
	v_fma_f32 v25, -v24, v24, v25
	v_max_f32_e32 v25, 0, v25
	v_add_f32_e32 v25, 0x3727c5ac, v25
	v_mul_f32_e32 v26, 0x4b800000, v25
	v_cmp_gt_f32_e32 vcc, s0, v25
	v_and_b32_e32 v95, 0xffff0000, v215
	v_pk_mul_f32 v[92:93], v[96:97], v[92:93]
	v_cndmask_b32_e32 v25, v25, v26, vcc
	v_rsq_f32_e32 v25, v25
	v_pk_mul_f32 v[92:93], v[92:93], v[94:95]
	v_mul_f32_e32 v18, 0x45800000, v25
	v_cndmask_b32_e32 v18, v25, v18, vcc
	v_pk_add_f32 v[20:21], v[22:23], v[24:25] op_sel_hi:[1,0] neg_lo:[0,1] neg_hi:[0,1]
	v_cvt_pk_bf16_f32 v92, v92, v93
	v_pk_mul_f32 v[18:19], v[20:21], v[18:19] op_sel_hi:[1,0]
	global_store_dword v[80:81], v92, off
	v_pk_fma_f32 v[18:19], v[0:1], v[18:19], v[8:9]
	s_waitcnt vmcnt(26)
	v_lshlrev_b32_e32 v80, 16, v213
	v_mul_f32_e32 v20, 0xbfb8aa3b, v18
	v_mul_f32_e32 v21, 0xbfb8aa3b, v19
	v_exp_f32_e32 v20, v20
	v_exp_f32_e32 v21, v21
	v_and_b32_e32 v81, 0xffff0000, v213
	v_pk_mul_f32 v[16:17], v[16:17], v[80:81]
	s_nop 0
	v_cvt_pk_bf16_f32 v22, v16, v17
	v_add_f32_e32 v16, 1.0, v20
	v_add_f32_e32 v17, 1.0, v21
	v_rcp_f32_e32 v16, v16
	v_rcp_f32_e32 v17, v17
	global_store_dword v[76:77], v22, off
	s_waitcnt vmcnt(26)
	v_lshlrev_b32_e32 v20, 16, v208
	v_and_b32_e32 v21, 0xffff0000, v208
	v_pk_mul_f32 v[16:17], v[18:19], v[16:17]
	v_pk_fma_f32 v[18:19], v[54:55], v[2:3], v[86:87]
	v_pk_mul_f32 v[16:17], v[16:17], v[20:21]
	v_pk_fma_f32 v[18:19], v[52:53], v[10:11], v[18:19]
	v_cvt_pk_bf16_f32 v16, v16, v17
	v_pk_fma_f32 v[18:19], v[50:51], v[4:5], v[18:19]
	global_store_dword v[74:75], v16, off
	v_pk_fma_f32 v[18:19], v[36:37], v[6:7], v[18:19]
	s_nop 0
	v_pk_fma_f32 v[18:19], v[38:39], v[12:13], v[18:19]
	s_nop 0
	v_add_f32_e32 v24, v18, v19
	v_pk_mul_f32 v[22:23], v[18:19], v[18:19]
	s_nop 0
	v_add_f32_e32 v22, v22, v23
	v_add_f32_dpp v23, v24, v24 quad_perm:[1,0,3,2] row_mask:0xf bank_mask:0xf bound_ctrl:1
	s_nop 0
	v_add_f32_dpp v22, v22, v22 quad_perm:[1,0,3,2] row_mask:0xf bank_mask:0xf bound_ctrl:1
	v_add_f32_dpp v23, v23, v23 quad_perm:[2,3,0,1] row_mask:0xf bank_mask:0xf bound_ctrl:1
	s_nop 0
	v_add_f32_dpp v22, v22, v22 quad_perm:[2,3,0,1] row_mask:0xf bank_mask:0xf bound_ctrl:1
	v_add_f32_dpp v23, v23, v23 row_half_mirror row_mask:0xf bank_mask:0xf bound_ctrl:1
	s_nop 0
	v_add_f32_dpp v22, v22, v22 row_half_mirror row_mask:0xf bank_mask:0xf bound_ctrl:1
	v_add_f32_dpp v23, v23, v23 row_mirror row_mask:0xf bank_mask:0xf bound_ctrl:1
	v_mov_b32_e32 v24, v23
	s_nop 1
	v_permlane16_swap_b32 v23, v24
	v_add_f32_dpp v22, v22, v22 row_mirror row_mask:0xf bank_mask:0xf bound_ctrl:1
	v_add_f32_e32 v23, v23, v24
	v_mov_b32_e32 v24, v22
	s_nop 1
	v_permlane16_swap_b32 v22, v24
	s_nop 0
	v_add_f32_e32 v24, v22, v24
	v_ldexp_f32 v22, v23, -6
	v_ldexp_f32 v23, v24, -6
	v_fma_f32 v23, -v22, v22, v23
	v_max_f32_e32 v23, 0, v23
	v_add_f32_e32 v23, 0x3727c5ac, v23
	v_mul_f32_e32 v24, 0x4b800000, v23
	v_cmp_gt_f32_e32 vcc, s0, v23
	s_nop 1
	v_cndmask_b32_e32 v23, v23, v24, vcc
	v_rsq_f32_e32 v23, v23
	s_nop 0
	v_mul_f32_e32 v16, 0x45800000, v23
	v_cndmask_b32_e32 v16, v23, v16, vcc
	v_pk_add_f32 v[18:19], v[18:19], v[22:23] op_sel_hi:[1,0] neg_lo:[0,1] neg_hi:[0,1]
	v_pk_fma_f32 v[22:23], v[52:53], v[2:3], v[84:85]
	v_pk_mul_f32 v[16:17], v[18:19], v[16:17] op_sel_hi:[1,0]
	v_pk_fma_f32 v[22:23], v[50:51], v[10:11], v[22:23]
	v_pk_fma_f32 v[16:17], v[0:1], v[16:17], v[8:9]
	v_pk_fma_f32 v[22:23], v[36:37], v[4:5], v[22:23]
	v_mul_f32_e32 v18, 0xbfb8aa3b, v16
	v_exp_f32_e32 v19, v18
	v_mul_f32_e32 v18, 0xbfb8aa3b, v17
	v_exp_f32_e32 v21, v18
	v_pk_fma_f32 v[22:23], v[38:39], v[6:7], v[22:23]
	v_add_f32_e32 v19, 1.0, v19
	v_rcp_f32_e32 v20, v19
	v_add_f32_e32 v19, 1.0, v21
	v_pk_fma_f32 v[22:23], v[42:43], v[12:13], v[22:23]
	v_rcp_f32_e32 v21, v19
	v_add_f32_e32 v19, v22, v23
	v_pk_mul_f32 v[24:25], v[22:23], v[22:23]
	s_waitcnt vmcnt(25)
; #define GAS __attribute__((address_space(1)))
; __device__ __forceinline__ unsigned cvtpk(float lo, float hi) { f32x2 v = {lo, hi}; bf16x2_t b = __builtin_convertvector(v, bf16x2_t); return __builtin_bit_cast(unsigned, b); }
; __device__ __forceinline__ float bflo(unsigned w) { return __uint_as_float(w << 16); }
; __device__ __forceinline__ float bfhi(unsigned w) { return __uint_as_float(w & 0xffff0000u); }
; __device__ __forceinline__ float fsilu(float x) { return x * fsigmoid(x); }
; __device__ __forceinline__ void c_unit(Frame& F, int L, int u, bool dry) {
;     ...
;         for (int i = 0; i < 46; ++i) {
;             const float h0 = bflo(hv[16 * sub + i]), h1 = bfhi(hv[16 * sub + i]);
; #pragma unroll
;             for (int t = 0; t < 16; ++t) { const int j = i - t; if (j >= 0 && j < CONVW) { acc[t].x = fmaf(h0, wv[j].x, acc[t].x); acc[t].y = fmaf(h1, wv[j].y, acc[t].y); } }
;         }
; #pragma unroll
;         for (int t = 0; t < 16; ++t) {
;             float s = acc[t].x + acc[t].y, qq = acc[t].x * acc[t].x + acc[t].y * acc[t].y;
;             s = half_wave_sum(s); qq = half_wave_sum(qq);
;             const float mu = __builtin_ldexpf(s, -6), rstd = rsqrtf(fmaxf(__builtin_ldexpf(qq, -6) - mu * mu, 0.f) + LN_EPS);
;             const float h0 = (acc[t].x - mu) * rstd * gv.x + bv.x, h1 = (acc[t].y - mu) * rstd * gv.y + bv.y;
;             const unsigned ov = cvtpk(fsilu(h0) * bflo(sc[16 * sub + t]), fsilu(h1) * bfhi(sc[16 * sub + t])); if (!dry) *(GAS unsigned*)(SCG + (size_t)(tb + t) * 512) = ov;
;         }
	v_lshlrev_b32_e32 v18, 16, v207
	v_add_f32_dpp v19, v19, v19 quad_perm:[1,0,3,2] row_mask:0xf bank_mask:0xf bound_ctrl:1
	v_add_f32_e32 v24, v24, v25
	v_pk_mul_f32 v[16:17], v[16:17], v[20:21]
	v_add_f32_dpp v19, v19, v19 quad_perm:[2,3,0,1] row_mask:0xf bank_mask:0xf bound_ctrl:1
	v_add_f32_dpp v24, v24, v24 quad_perm:[1,0,3,2] row_mask:0xf bank_mask:0xf bound_ctrl:1
	s_nop 0
	v_add_f32_dpp v19, v19, v19 row_half_mirror row_mask:0xf bank_mask:0xf bound_ctrl:1
	v_add_f32_dpp v24, v24, v24 quad_perm:[2,3,0,1] row_mask:0xf bank_mask:0xf bound_ctrl:1
	s_nop 0
	v_add_f32_dpp v19, v19, v19 row_mirror row_mask:0xf bank_mask:0xf bound_ctrl:1
	v_mov_b32_e32 v25, v19
	v_add_f32_dpp v24, v24, v24 row_half_mirror row_mask:0xf bank_mask:0xf bound_ctrl:1
	s_nop 1
	v_permlane16_swap_b32 v19, v25
	s_nop 0
	v_add_f32_e32 v19, v19, v25
	v_add_f32_dpp v24, v24, v24 row_mirror row_mask:0xf bank_mask:0xf bound_ctrl:1
	v_mov_b32_e32 v25, v24
	s_nop 1
	v_permlane16_swap_b32 v24, v25
	s_nop 0
	v_add_f32_e32 v25, v24, v25
	v_ldexp_f32 v24, v19, -6
	v_ldexp_f32 v19, v25, -6
	v_fma_f32 v19, -v24, v24, v19
	v_max_f32_e32 v19, 0, v19
	v_add_f32_e32 v19, 0x3727c5ac, v19
	v_mul_f32_e32 v25, 0x4b800000, v19
	v_cmp_gt_f32_e32 vcc, s0, v19
	s_nop 1
	v_cndmask_b32_e32 v19, v19, v25, vcc
	v_rsq_f32_e32 v25, v19
	v_and_b32_e32 v19, 0xffff0000, v207
	v_pk_mul_f32 v[16:17], v[16:17], v[18:19]
	v_mul_f32_e32 v18, 0x45800000, v25
	v_cndmask_b32_e32 v18, v25, v18, vcc
	v_pk_add_f32 v[20:21], v[22:23], v[24:25] op_sel_hi:[1,0] neg_lo:[0,1] neg_hi:[0,1]
	v_cvt_pk_bf16_f32 v22, v16, v17
	v_pk_mul_f32 v[18:19], v[20:21], v[18:19] op_sel_hi:[1,0]
	global_store_dword v[64:65], v22, off
	v_pk_fma_f32 v[18:19], v[0:1], v[18:19], v[8:9]
	s_nop 0
	v_mul_f32_e32 v20, 0xbfb8aa3b, v18
	v_mul_f32_e32 v21, 0xbfb8aa3b, v19
	v_exp_f32_e32 v20, v20
	v_exp_f32_e32 v21, v21
	v_add_f32_e32 v16, 1.0, v20
	v_add_f32_e32 v17, 1.0, v21
	v_rcp_f32_e32 v16, v16
	v_rcp_f32_e32 v17, v17
	s_waitcnt vmcnt(25)
	v_lshlrev_b32_e32 v20, 16, v206
	v_and_b32_e32 v21, 0xffff0000, v206
	v_pk_mul_f32 v[16:17], v[18:19], v[16:17]
	v_pk_fma_f32 v[18:19], v[50:51], v[2:3], v[82:83]
	v_pk_fma_f32 v[2:3], v[36:37], v[2:3], v[14:15]
	v_pk_fma_f32 v[18:19], v[36:37], v[10:11], v[18:19]
	v_pk_fma_f32 v[2:3], v[38:39], v[10:11], v[2:3]
	v_pk_fma_f32 v[18:19], v[38:39], v[4:5], v[18:19]
	v_pk_fma_f32 v[2:3], v[42:43], v[4:5], v[2:3]
	v_pk_fma_f32 v[18:19], v[42:43], v[6:7], v[18:19]
	v_pk_fma_f32 v[2:3], v[44:45], v[6:7], v[2:3]
	v_pk_fma_f32 v[18:19], v[44:45], v[12:13], v[18:19]
	v_pk_fma_f32 v[2:3], v[46:47], v[12:13], v[2:3]
	v_add_f32_e32 v24, v18, v19
	v_pk_mul_f32 v[22:23], v[18:19], v[18:19]
	v_add_f32_e32 v6, v2, v3
	v_add_f32_e32 v22, v22, v23
	v_add_f32_dpp v23, v24, v24 quad_perm:[1,0,3,2] row_mask:0xf bank_mask:0xf bound_ctrl:1
	v_pk_mul_f32 v[4:5], v[2:3], v[2:3]
	v_add_f32_dpp v22, v22, v22 quad_perm:[1,0,3,2] row_mask:0xf bank_mask:0xf bound_ctrl:1
	v_add_f32_dpp v23, v23, v23 quad_perm:[2,3,0,1] row_mask:0xf bank_mask:0xf bound_ctrl:1
	v_add_f32_e32 v4, v4, v5
	v_add_f32_dpp v22, v22, v22 quad_perm:[2,3,0,1] row_mask:0xf bank_mask:0xf bound_ctrl:1
	v_add_f32_dpp v23, v23, v23 row_half_mirror row_mask:0xf bank_mask:0xf bound_ctrl:1
	v_add_f32_dpp v5, v6, v6 quad_perm:[1,0,3,2] row_mask:0xf bank_mask:0xf bound_ctrl:1
	v_add_f32_dpp v22, v22, v22 row_half_mirror row_mask:0xf bank_mask:0xf bound_ctrl:1
	v_add_f32_dpp v23, v23, v23 row_mirror row_mask:0xf bank_mask:0xf bound_ctrl:1
	v_mov_b32_e32 v24, v23
	s_nop 1
	v_permlane16_swap_b32 v23, v24
	v_add_f32_dpp v22, v22, v22 row_mirror row_mask:0xf bank_mask:0xf bound_ctrl:1
	v_add_f32_e32 v23, v23, v24
	v_mov_b32_e32 v24, v22
	s_nop 1
	v_permlane16_swap_b32 v22, v24
	v_add_f32_dpp v5, v5, v5 quad_perm:[2,3,0,1] row_mask:0xf bank_mask:0xf bound_ctrl:1
	v_add_f32_e32 v24, v22, v24
	v_ldexp_f32 v22, v23, -6
	v_ldexp_f32 v23, v24, -6
	v_add_f32_dpp v5, v5, v5 row_half_mirror row_mask:0xf bank_mask:0xf bound_ctrl:1
	v_add_f32_dpp v4, v4, v4 quad_perm:[1,0,3,2] row_mask:0xf bank_mask:0xf bound_ctrl:1
	v_fma_f32 v23, -v22, v22, v23
	v_add_f32_dpp v5, v5, v5 row_mirror row_mask:0xf bank_mask:0xf bound_ctrl:1
	v_add_f32_dpp v4, v4, v4 quad_perm:[2,3,0,1] row_mask:0xf bank_mask:0xf bound_ctrl:1
	v_max_f32_e32 v23, 0, v23
	v_mov_b32_e32 v6, v5
	v_add_f32_dpp v4, v4, v4 row_half_mirror row_mask:0xf bank_mask:0xf bound_ctrl:1
	v_add_f32_e32 v23, 0x3727c5ac, v23
	s_nop 1
	v_permlane16_swap_b32 v5, v6
	v_mul_f32_e32 v24, 0x4b800000, v23
	v_add_f32_dpp v4, v4, v4 row_mirror row_mask:0xf bank_mask:0xf bound_ctrl:1
	v_cmp_gt_f32_e32 vcc, s0, v23
	v_add_f32_e32 v5, v5, v6
	v_mov_b32_e32 v6, v4
	v_cndmask_b32_e32 v23, v23, v24, vcc
	s_nop 1
	v_permlane16_swap_b32 v4, v6
	v_rsq_f32_e32 v23, v23
	v_add_f32_e32 v6, v4, v6
	v_ldexp_f32 v4, v5, -6
	v_ldexp_f32 v5, v6, -6
	v_pk_mul_f32 v[16:17], v[16:17], v[20:21]
	v_fma_f32 v5, -v4, v4, v5
	v_cvt_pk_bf16_f32 v16, v16, v17
	v_max_f32_e32 v5, 0, v5
	global_store_dword v[62:63], v16, off
	v_mul_f32_e32 v16, 0x45800000, v23
	v_add_f32_e32 v5, 0x3727c5ac, v5
	v_cndmask_b32_e32 v16, v23, v16, vcc
	v_mul_f32_e32 v6, 0x4b800000, v5
	v_cmp_gt_f32_e32 vcc, s0, v5
	v_pk_add_f32 v[18:19], v[18:19], v[22:23] op_sel_hi:[1,0] neg_lo:[0,1] neg_hi:[0,1]
	s_nop 0
	v_cndmask_b32_e32 v5, v5, v6, vcc
	v_rsq_f32_e32 v5, v5
	v_pk_mul_f32 v[16:17], v[18:19], v[16:17] op_sel_hi:[1,0]
	v_mul_f32_e32 v10, 0x45800000, v5
	v_pk_fma_f32 v[16:17], v[0:1], v[16:17], v[8:9]
	v_cndmask_b32_e32 v10, v5, v10, vcc
	v_mul_f32_e32 v18, 0xbfb8aa3b, v16
	v_exp_f32_e32 v19, v18
	v_mul_f32_e32 v18, 0xbfb8aa3b, v17
	v_pk_add_f32 v[2:3], v[2:3], v[4:5] op_sel_hi:[1,0] neg_lo:[0,1] neg_hi:[0,1]
	v_exp_f32_e32 v21, v18
	v_pk_mul_f32 v[2:3], v[2:3], v[10:11] op_sel_hi:[1,0]
	v_add_f32_e32 v19, 1.0, v19
	v_pk_fma_f32 v[0:1], v[0:1], v[2:3], v[8:9]
	v_rcp_f32_e32 v20, v19
	v_mul_f32_e32 v2, 0xbfb8aa3b, v0
	v_mul_f32_e32 v3, 0xbfb8aa3b, v1
	v_exp_f32_e32 v2, v2
	v_exp_f32_e32 v3, v3
	v_add_f32_e32 v19, 1.0, v21
	v_rcp_f32_e32 v21, v19
	v_add_f32_e32 v2, 1.0, v2
	v_add_f32_e32 v3, 1.0, v3
	v_rcp_f32_e32 v2, v2
	v_rcp_f32_e32 v3, v3
	s_waitcnt vmcnt(25)
	v_lshlrev_b32_e32 v18, 16, v204
	v_and_b32_e32 v19, 0xffff0000, v204
	v_pk_mul_f32 v[6:7], v[16:17], v[20:21]
	s_waitcnt vmcnt(24)
	v_and_b32_e32 v5, 0xffff0000, v205
	v_pk_mul_f32 v[6:7], v[6:7], v[18:19]
	v_pk_mul_f32 v[0:1], v[0:1], v[2:3]
	v_cvt_pk_bf16_f32 v4, v6, v7
	global_store_dword v[48:49], v4, off
	v_lshlrev_b32_e32 v4, 16, v205
	v_pk_mul_f32 v[0:1], v[0:1], v[4:5]
	s_nop 0
	v_cvt_pk_bf16_f32 v0, v0, v1
	global_store_dword v[40:41], v0, off
